# also removed the priority drop/raise pair in the middle of each 32-MFMA segment
# baseline (speedup 1.0000x reference)
.LBB0_74:
	s_ashr_i32 s27, s26, 31
	s_lshl_b64 s[28:29], s[26:27], 19
	s_add_u32 s28, s3, s28
	s_addc_u32 s29, s35, s29
	s_and_b64 s[30:31], s[4:5], exec
	s_cselect_b32 s27, s29, s49
	s_cselect_b32 s68, s28, s48
	s_ashr_i32 s23, s22, 31
	s_lshl_b64 s[30:31], s[22:23], 19
	s_add_u32 s30, s50, s30
	s_addc_u32 s31, s51, s31
	s_and_b64 s[70:71], s[4:5], exec
	s_cselect_b32 s69, s31, s47
	s_cselect_b32 s70, s30, s46
	s_lshl_b32 s23, s44, 8
	v_add_u32_e32 v0, s23, v148
	s_add_u32 s71, s46, 0x100
	v_ashrrev_i32_e32 v1, 31, v0
	s_addc_u32 s74, s47, 0
	v_lshl_add_u64 v[144:145], v[0:1], 4, s[12:13]
	s_add_u32 s44, s48, 0x40080
	s_addc_u32 s45, s49, 0
	s_mov_b32 s75, -2
	s_mov_b64 s[46:47], 0
	s_cmp_eq_u32 s59, 1
	s_cbranch_scc1 .Lfa_0
	v_add_u32_e32 v153, s64, v147
	ds_read_b128 v[160:163], v153
	v_xor_b32_e32 v253, 64, v153
	ds_read_b128 v[164:167], v253
	ds_read_b128 v[168:171], v153 offset:2048
	ds_read_b128 v[172:175], v253 offset:2048
	v_add_u32_e32 v153, s65, v147
	ds_read_b128 v[176:179], v153
	v_xor_b32_e32 v253, 64, v153
	ds_read_b128 v[180:183], v253
	ds_read_b128 v[186:189], v153 offset:2048
	ds_read_b128 v[190:193], v253 offset:2048
	s_add_u32 s48, s44, 0xfffc0080
	s_addc_u32 s49, s45, -1
	s_and_b64 s[46:47], s[46:47], exec
	s_cselect_b32 s49, s27, s49
	s_cselect_b32 s48, s68, s48
	s_cselect_b32 s47, s69, s74
	s_cselect_b32 s46, s70, s71
	v_lshl_add_u64 v[154:155], s[44:45], 0, v[138:139]
	s_add_i32 m0, s55, 0xc000
	ds_read_b128 v[194:197], v150
	v_xor_b32_e32 v253, 64, v150
	ds_read_b128 v[198:201], v253
	ds_read_b128 v[202:205], v150 offset:2048
	ds_read_b128 v[206:209], v253 offset:2048
	ds_read_b128 v[210:213], v150 offset:4096
	ds_read_b128 v[214:217], v253 offset:4096
	ds_read_b128 v[218:221], v150 offset:6144
	ds_read_b128 v[222:225], v253 offset:6144
	global_load_lds_dwordx4 v[154:155], off
	v_lshl_add_u64 v[154:155], s[44:45], 0, v[136:137]
	s_add_i32 m0, s55, 0xe000
	s_nop 0
	global_load_lds_dwordx4 v[154:155], off
	s_waitcnt vmcnt(16)
	s_waitcnt lgkmcnt(0)
	s_setprio 1
	s_barrier
	v_mfma_f32_16x16x32_bf16 v[124:127], v[160:163], v[194:197], 0
	v_mfma_f32_16x16x32_bf16 v[116:119], v[168:171], v[194:197], 0
	v_mfma_f32_16x16x32_bf16 v[108:111], v[160:163], v[202:205], 0
	v_mfma_f32_16x16x32_bf16 v[100:103], v[168:171], v[202:205], 0
	v_mfma_f32_16x16x32_bf16 v[92:95], v[160:163], v[210:213], 0
	v_mfma_f32_16x16x32_bf16 v[84:87], v[168:171], v[210:213], 0
	v_mfma_f32_16x16x32_bf16 v[76:79], v[160:163], v[218:221], 0
	v_mfma_f32_16x16x32_bf16 v[68:71], v[168:171], v[218:221], 0
	v_mfma_f32_16x16x32_bf16 v[124:127], v[164:167], v[198:201], v[124:127]
	v_mfma_f32_16x16x32_bf16 v[116:119], v[172:175], v[198:201], v[116:119]
	v_mfma_f32_16x16x32_bf16 v[108:111], v[164:167], v[206:209], v[108:111]
	v_mfma_f32_16x16x32_bf16 v[100:103], v[172:175], v[206:209], v[100:103]
	v_mfma_f32_16x16x32_bf16 v[92:95], v[164:167], v[214:217], v[92:95]
	v_mfma_f32_16x16x32_bf16 v[84:87], v[172:175], v[214:217], v[84:87]
	v_mfma_f32_16x16x32_bf16 v[76:79], v[164:167], v[222:225], v[76:79]
	v_mfma_f32_16x16x32_bf16 v[68:71], v[172:175], v[222:225], v[68:71]
	v_mfma_f32_16x16x32_bf16 v[120:123], v[176:179], v[194:197], 0
	v_mfma_f32_16x16x32_bf16 v[112:115], v[186:189], v[194:197], 0
	v_mfma_f32_16x16x32_bf16 v[104:107], v[176:179], v[202:205], 0
	v_mfma_f32_16x16x32_bf16 v[96:99], v[186:189], v[202:205], 0
	v_mfma_f32_16x16x32_bf16 v[88:91], v[176:179], v[210:213], 0
	v_mfma_f32_16x16x32_bf16 v[80:83], v[186:189], v[210:213], 0
	v_mfma_f32_16x16x32_bf16 v[72:75], v[176:179], v[218:221], 0
	v_mfma_f32_16x16x32_bf16 v[64:67], v[186:189], v[218:221], 0
	v_mfma_f32_16x16x32_bf16 v[120:123], v[180:183], v[198:201], v[120:123]
	v_mfma_f32_16x16x32_bf16 v[112:115], v[190:193], v[198:201], v[112:115]
	v_mfma_f32_16x16x32_bf16 v[104:107], v[180:183], v[206:209], v[104:107]
	v_mfma_f32_16x16x32_bf16 v[96:99], v[190:193], v[206:209], v[96:99]
	v_mfma_f32_16x16x32_bf16 v[88:91], v[180:183], v[214:217], v[88:91]
	v_mfma_f32_16x16x32_bf16 v[80:83], v[190:193], v[214:217], v[80:83]
	v_mfma_f32_16x16x32_bf16 v[72:75], v[180:183], v[222:225], v[72:75]
	v_mfma_f32_16x16x32_bf16 v[64:67], v[190:193], v[222:225], v[64:67]
	s_barrier
	s_setprio 0
	s_add_i32 s76, s64, s52
	v_lshl_add_u64 v[154:155], s[46:47], 0, v[132:133]
	s_mov_b32 m0, s76
	ds_read_b128 v[194:197], v150 offset:16384
	v_xor_b32_e32 v253, 64, v150
	ds_read_b128 v[198:201], v253 offset:16384
	ds_read_b128 v[202:205], v150 offset:18432
	ds_read_b128 v[206:209], v253 offset:18432
	ds_read_b128 v[210:213], v150 offset:20480
	ds_read_b128 v[214:217], v253 offset:20480
	ds_read_b128 v[218:221], v150 offset:22528
	ds_read_b128 v[222:225], v253 offset:22528
	global_load_lds_dwordx4 v[154:155], off
	s_add_i32 m0, s76, 0x2000
	s_add_u32 s76, s46, 0x40000
	v_lshl_add_u64 v[226:227], s[46:47], 0, v[128:129]
	s_addc_u32 s77, s47, 0
	s_add_i32 s78, s65, s52
	global_load_lds_dwordx4 v[226:227], off
	v_lshl_add_u64 v[228:229], s[76:77], 0, v[132:133]
	s_mov_b32 m0, s78
	v_lshl_add_u64 v[230:231], s[48:49], 0, v[130:131]
	global_load_lds_dwordx4 v[228:229], off
	v_lshl_add_u64 v[228:229], s[76:77], 0, v[128:129]
	s_add_i32 m0, s78, 0x2000
	s_nop 0
	global_load_lds_dwordx4 v[228:229], off
	v_lshl_add_u64 v[228:229], s[48:49], 0, v[134:135]
	s_mov_b32 m0, s55
	s_nop 0
	global_load_lds_dwordx4 v[228:229], off
	s_mov_b32 m0, s56
	s_nop 0
	global_load_lds_dwordx4 v[230:231], off
	s_waitcnt vmcnt(16)
	s_waitcnt lgkmcnt(0)
	s_setprio 1
	s_barrier
	v_mfma_f32_16x16x32_bf16 v[60:63], v[160:163], v[194:197], 0
	v_mfma_f32_16x16x32_bf16 v[52:55], v[168:171], v[194:197], 0
	v_mfma_f32_16x16x32_bf16 v[44:47], v[160:163], v[202:205], 0
	v_mfma_f32_16x16x32_bf16 v[36:39], v[168:171], v[202:205], 0
	v_mfma_f32_16x16x32_bf16 v[28:31], v[160:163], v[210:213], 0
	v_mfma_f32_16x16x32_bf16 v[20:23], v[168:171], v[210:213], 0
	v_mfma_f32_16x16x32_bf16 v[12:15], v[160:163], v[218:221], 0
	v_mfma_f32_16x16x32_bf16 v[4:7], v[168:171], v[218:221], 0
	v_mfma_f32_16x16x32_bf16 v[60:63], v[164:167], v[198:201], v[60:63]
	v_mfma_f32_16x16x32_bf16 v[52:55], v[172:175], v[198:201], v[52:55]
	v_mfma_f32_16x16x32_bf16 v[44:47], v[164:167], v[206:209], v[44:47]
	v_mfma_f32_16x16x32_bf16 v[36:39], v[172:175], v[206:209], v[36:39]
	v_mfma_f32_16x16x32_bf16 v[28:31], v[164:167], v[214:217], v[28:31]
	v_mfma_f32_16x16x32_bf16 v[20:23], v[172:175], v[214:217], v[20:23]
	v_mfma_f32_16x16x32_bf16 v[12:15], v[164:167], v[222:225], v[12:15]
	v_mfma_f32_16x16x32_bf16 v[4:7], v[172:175], v[222:225], v[4:7]
	v_mfma_f32_16x16x32_bf16 v[56:59], v[176:179], v[194:197], 0
	v_mfma_f32_16x16x32_bf16 v[48:51], v[186:189], v[194:197], 0
	v_mfma_f32_16x16x32_bf16 v[40:43], v[176:179], v[202:205], 0
	v_mfma_f32_16x16x32_bf16 v[32:35], v[186:189], v[202:205], 0
	v_mfma_f32_16x16x32_bf16 v[24:27], v[176:179], v[210:213], 0
	v_mfma_f32_16x16x32_bf16 v[16:19], v[186:189], v[210:213], 0
	v_mfma_f32_16x16x32_bf16 v[8:11], v[176:179], v[218:221], 0
	v_mfma_f32_16x16x32_bf16 v[0:3], v[186:189], v[218:221], 0
	v_mfma_f32_16x16x32_bf16 v[56:59], v[180:183], v[198:201], v[56:59]
	v_mfma_f32_16x16x32_bf16 v[48:51], v[190:193], v[198:201], v[48:51]
	v_mfma_f32_16x16x32_bf16 v[40:43], v[180:183], v[206:209], v[40:43]
	v_mfma_f32_16x16x32_bf16 v[32:35], v[190:193], v[206:209], v[32:35]
	v_mfma_f32_16x16x32_bf16 v[24:27], v[180:183], v[214:217], v[24:27]
	v_mfma_f32_16x16x32_bf16 v[16:19], v[190:193], v[214:217], v[16:19]
	v_mfma_f32_16x16x32_bf16 v[8:11], v[180:183], v[222:225], v[8:11]
	v_mfma_f32_16x16x32_bf16 v[0:3], v[190:193], v[222:225], v[0:3]
	s_barrier
	s_setprio 0
	s_add_i32 s76, 0, 0x18000
	v_add_u32_e32 v153, s76, v147
	s_add_i32 s77, 0, 0x1c000
	ds_read_b128 v[160:163], v153
	v_xor_b32_e32 v253, 64, v153
	ds_read_b128 v[164:167], v253
	ds_read_b128 v[168:171], v153 offset:2048
	ds_read_b128 v[172:175], v253 offset:2048
	v_add_u32_e32 v153, s77, v147
	ds_read_b128 v[176:179], v153
	v_xor_b32_e32 v253, 64, v153
	ds_read_b128 v[180:183], v253
	ds_read_b128 v[186:189], v153 offset:2048
	ds_read_b128 v[190:193], v253 offset:2048
	s_add_u32 s48, s48, 0x40000
	s_addc_u32 s49, s49, 0
	s_mov_b32 m0, s57
	v_lshl_add_u64 v[232:233], s[48:49], 0, v[134:135]
	ds_read_b128 v[194:197], v150 offset:32768
	v_xor_b32_e32 v253, 64, v150
	ds_read_b128 v[198:201], v253 offset:32768
	ds_read_b128 v[202:205], v150 offset:34816
	ds_read_b128 v[206:209], v253 offset:34816
	ds_read_b128 v[210:213], v150 offset:36864
	ds_read_b128 v[214:217], v253 offset:36864
	ds_read_b128 v[218:221], v150 offset:38912
	ds_read_b128 v[222:225], v253 offset:38912
	global_load_lds_dwordx4 v[232:233], off
	v_lshl_add_u64 v[232:233], s[48:49], 0, v[130:131]
	s_mov_b32 m0, s58
	s_nop 0
	global_load_lds_dwordx4 v[232:233], off
	s_waitcnt vmcnt(8)
	s_waitcnt lgkmcnt(0)
	s_setprio 1
	s_barrier
	v_mfma_f32_16x16x32_bf16 v[124:127], v[160:163], v[194:197], v[124:127]
	v_mfma_f32_16x16x32_bf16 v[124:127], v[164:167], v[198:201], v[124:127]
	v_mfma_f32_16x16x32_bf16 v[116:119], v[172:175], v[198:201], v[116:119]
	v_mfma_f32_16x16x32_bf16 v[116:119], v[168:171], v[194:197], v[116:119]
	v_mfma_f32_16x16x32_bf16 v[100:103], v[168:171], v[202:205], v[100:103]
	v_mfma_f32_16x16x32_bf16 v[100:103], v[172:175], v[206:209], v[100:103]
	v_mfma_f32_16x16x32_bf16 v[108:111], v[164:167], v[206:209], v[108:111]
	v_mfma_f32_16x16x32_bf16 v[108:111], v[160:163], v[202:205], v[108:111]
	v_mfma_f32_16x16x32_bf16 v[92:95], v[160:163], v[210:213], v[92:95]
	v_mfma_f32_16x16x32_bf16 v[92:95], v[164:167], v[214:217], v[92:95]
	v_mfma_f32_16x16x32_bf16 v[84:87], v[172:175], v[214:217], v[84:87]
	v_mfma_f32_16x16x32_bf16 v[84:87], v[168:171], v[210:213], v[84:87]
	v_mfma_f32_16x16x32_bf16 v[68:71], v[168:171], v[218:221], v[68:71]
	v_mfma_f32_16x16x32_bf16 v[68:71], v[172:175], v[222:225], v[68:71]
	v_mfma_f32_16x16x32_bf16 v[76:79], v[164:167], v[222:225], v[76:79]
	v_mfma_f32_16x16x32_bf16 v[76:79], v[160:163], v[218:221], v[76:79]
	v_mfma_f32_16x16x32_bf16 v[120:123], v[176:179], v[194:197], v[120:123]
	v_mfma_f32_16x16x32_bf16 v[120:123], v[180:183], v[198:201], v[120:123]
	v_mfma_f32_16x16x32_bf16 v[112:115], v[190:193], v[198:201], v[112:115]
	v_mfma_f32_16x16x32_bf16 v[112:115], v[186:189], v[194:197], v[112:115]
	v_mfma_f32_16x16x32_bf16 v[96:99], v[186:189], v[202:205], v[96:99]
	v_mfma_f32_16x16x32_bf16 v[96:99], v[190:193], v[206:209], v[96:99]
	v_mfma_f32_16x16x32_bf16 v[104:107], v[180:183], v[206:209], v[104:107]
	v_mfma_f32_16x16x32_bf16 v[104:107], v[176:179], v[202:205], v[104:107]
	v_mfma_f32_16x16x32_bf16 v[88:91], v[176:179], v[210:213], v[88:91]
	v_mfma_f32_16x16x32_bf16 v[88:91], v[180:183], v[214:217], v[88:91]
	v_mfma_f32_16x16x32_bf16 v[80:83], v[190:193], v[214:217], v[80:83]
	v_mfma_f32_16x16x32_bf16 v[80:83], v[186:189], v[210:213], v[80:83]
	v_mfma_f32_16x16x32_bf16 v[64:67], v[186:189], v[218:221], v[64:67]
	v_mfma_f32_16x16x32_bf16 v[64:67], v[190:193], v[222:225], v[64:67]
	v_mfma_f32_16x16x32_bf16 v[72:75], v[180:183], v[222:225], v[72:75]
	v_mfma_f32_16x16x32_bf16 v[72:75], v[176:179], v[218:221], v[72:75]
	s_barrier
	s_setprio 0
	s_add_i32 s48, s76, s52
	v_lshl_add_u64 v[154:155], v[154:155], 0, s[14:15]
	s_mov_b32 m0, s48
	ds_read_b128 v[194:197], v150 offset:49152
	v_xor_b32_e32 v253, 64, v150
	ds_read_b128 v[198:201], v253 offset:49152
	ds_read_b128 v[202:205], v150 offset:51200
	ds_read_b128 v[206:209], v253 offset:51200
	ds_read_b128 v[210:213], v150 offset:53248
	ds_read_b128 v[214:217], v253 offset:53248
	ds_read_b128 v[218:221], v150 offset:55296
	ds_read_b128 v[222:225], v253 offset:55296
	global_load_lds_dwordx4 v[154:155], off
	s_add_i32 m0, s48, 0x2000
	s_add_u32 s46, s46, 0x40080
	v_lshl_add_u64 v[154:155], v[226:227], 0, s[14:15]
	s_addc_u32 s47, s47, 0
	s_add_i32 s48, s77, s52
	global_load_lds_dwordx4 v[154:155], off
	v_lshl_add_u64 v[154:155], s[46:47], 0, v[132:133]
	s_mov_b32 m0, s48
	s_nop 0
	global_load_lds_dwordx4 v[154:155], off
	v_lshl_add_u64 v[154:155], s[46:47], 0, v[128:129]
	s_add_i32 m0, s48, 0x2000
	s_nop 0
	global_load_lds_dwordx4 v[154:155], off
	v_lshl_add_u64 v[154:155], v[228:229], 0, s[14:15]
	s_mov_b32 m0, s60
	s_nop 0
	global_load_lds_dwordx4 v[154:155], off
	v_lshl_add_u64 v[154:155], v[230:231], 0, s[14:15]
	s_mov_b32 m0, s61
	s_nop 0
	global_load_lds_dwordx4 v[154:155], off
	s_waitcnt vmcnt(8)
	s_waitcnt lgkmcnt(0)
	s_setprio 1
	s_barrier
	v_mfma_f32_16x16x32_bf16 v[60:63], v[160:163], v[194:197], v[60:63]
	v_mfma_f32_16x16x32_bf16 v[60:63], v[164:167], v[198:201], v[60:63]
	v_mfma_f32_16x16x32_bf16 v[52:55], v[172:175], v[198:201], v[52:55]
	v_mfma_f32_16x16x32_bf16 v[52:55], v[168:171], v[194:197], v[52:55]
	v_mfma_f32_16x16x32_bf16 v[36:39], v[168:171], v[202:205], v[36:39]
	v_mfma_f32_16x16x32_bf16 v[36:39], v[172:175], v[206:209], v[36:39]
	v_mfma_f32_16x16x32_bf16 v[44:47], v[164:167], v[206:209], v[44:47]
	v_mfma_f32_16x16x32_bf16 v[44:47], v[160:163], v[202:205], v[44:47]
	v_mfma_f32_16x16x32_bf16 v[28:31], v[160:163], v[210:213], v[28:31]
	v_mfma_f32_16x16x32_bf16 v[28:31], v[164:167], v[214:217], v[28:31]
	v_mfma_f32_16x16x32_bf16 v[20:23], v[172:175], v[214:217], v[20:23]
	v_mfma_f32_16x16x32_bf16 v[20:23], v[168:171], v[210:213], v[20:23]
	v_mfma_f32_16x16x32_bf16 v[4:7], v[168:171], v[218:221], v[4:7]
	v_mfma_f32_16x16x32_bf16 v[4:7], v[172:175], v[222:225], v[4:7]
	v_mfma_f32_16x16x32_bf16 v[12:15], v[164:167], v[222:225], v[12:15]
	v_mfma_f32_16x16x32_bf16 v[12:15], v[160:163], v[218:221], v[12:15]
	v_mfma_f32_16x16x32_bf16 v[56:59], v[176:179], v[194:197], v[56:59]
	v_mfma_f32_16x16x32_bf16 v[56:59], v[180:183], v[198:201], v[56:59]
	v_mfma_f32_16x16x32_bf16 v[48:51], v[190:193], v[198:201], v[48:51]
	v_mfma_f32_16x16x32_bf16 v[48:51], v[186:189], v[194:197], v[48:51]
	v_mfma_f32_16x16x32_bf16 v[32:35], v[186:189], v[202:205], v[32:35]
	v_mfma_f32_16x16x32_bf16 v[32:35], v[190:193], v[206:209], v[32:35]
	v_mfma_f32_16x16x32_bf16 v[40:43], v[180:183], v[206:209], v[40:43]
	v_mfma_f32_16x16x32_bf16 v[40:43], v[176:179], v[202:205], v[40:43]
	v_mfma_f32_16x16x32_bf16 v[24:27], v[176:179], v[210:213], v[24:27]
	v_mfma_f32_16x16x32_bf16 v[24:27], v[180:183], v[214:217], v[24:27]
	v_mfma_f32_16x16x32_bf16 v[16:19], v[190:193], v[214:217], v[16:19]
	v_mfma_f32_16x16x32_bf16 v[16:19], v[186:189], v[210:213], v[16:19]
	v_mfma_f32_16x16x32_bf16 v[0:3], v[186:189], v[218:221], v[0:3]
	v_mfma_f32_16x16x32_bf16 v[0:3], v[190:193], v[222:225], v[0:3]
	v_mfma_f32_16x16x32_bf16 v[8:11], v[180:183], v[222:225], v[8:11]
	v_mfma_f32_16x16x32_bf16 v[8:11], v[176:179], v[218:221], v[8:11]
	s_barrier
	s_setprio 0
	s_add_i32 s75, s75, 2
	s_add_u32 s71, s71, 0x100
	s_addc_u32 s74, s74, 0
	s_add_u32 s44, s44, 0x100
	s_addc_u32 s45, s45, 0
	s_branch .LBB0_76
.Lfa_0:
	v_add_u32_e32 v153, s64, v147
	ds_read_b128 v[160:163], v153
	v_xor_b32_e32 v253, 64, v153
	ds_read_b128 v[164:167], v253
	ds_read_b128 v[168:171], v153 offset:2048
	ds_read_b128 v[172:175], v253 offset:2048
	v_add_u32_e32 v153, s65, v147
	ds_read_b128 v[176:179], v153
	v_xor_b32_e32 v253, 64, v153
	ds_read_b128 v[180:183], v253
	ds_read_b128 v[186:189], v153 offset:2048
	ds_read_b128 v[190:193], v253 offset:2048
	s_add_u32 s48, s44, 0xfffc0080
	s_addc_u32 s49, s45, -1
	s_and_b64 s[46:47], s[46:47], exec
	s_cselect_b32 s49, s27, s49
	s_cselect_b32 s48, s68, s48
	s_cselect_b32 s47, s69, s74
	s_cselect_b32 s46, s70, s71
	v_lshl_add_u64 v[154:155], s[44:45], 0, v[138:139]
	s_add_i32 m0, s55, 0xc000
	ds_read_b128 v[194:197], v150
	v_xor_b32_e32 v253, 64, v150
	ds_read_b128 v[198:201], v253
	ds_read_b128 v[202:205], v150 offset:2048
	ds_read_b128 v[206:209], v253 offset:2048
	ds_read_b128 v[210:213], v150 offset:4096
	ds_read_b128 v[214:217], v253 offset:4096
	ds_read_b128 v[218:221], v150 offset:6144
	ds_read_b128 v[222:225], v253 offset:6144
	global_load_lds_dwordx4 v[154:155], off
	v_lshl_add_u64 v[154:155], s[44:45], 0, v[136:137]
	s_add_i32 m0, s55, 0xe000
	s_nop 0
	global_load_lds_dwordx4 v[154:155], off
	s_waitcnt vmcnt(8)
	s_waitcnt lgkmcnt(0)
	s_setprio 1
	s_barrier
	v_mfma_f32_16x16x32_bf16 v[124:127], v[160:163], v[194:197], 0
	v_mfma_f32_16x16x32_bf16 v[116:119], v[168:171], v[194:197], 0
	v_mfma_f32_16x16x32_bf16 v[108:111], v[160:163], v[202:205], 0
	v_mfma_f32_16x16x32_bf16 v[100:103], v[168:171], v[202:205], 0
	v_mfma_f32_16x16x32_bf16 v[92:95], v[160:163], v[210:213], 0
	v_mfma_f32_16x16x32_bf16 v[84:87], v[168:171], v[210:213], 0
	v_mfma_f32_16x16x32_bf16 v[76:79], v[160:163], v[218:221], 0
	v_mfma_f32_16x16x32_bf16 v[68:71], v[168:171], v[218:221], 0
	v_mfma_f32_16x16x32_bf16 v[124:127], v[164:167], v[198:201], v[124:127]
	v_mfma_f32_16x16x32_bf16 v[116:119], v[172:175], v[198:201], v[116:119]
	v_mfma_f32_16x16x32_bf16 v[108:111], v[164:167], v[206:209], v[108:111]
	v_mfma_f32_16x16x32_bf16 v[100:103], v[172:175], v[206:209], v[100:103]
	v_mfma_f32_16x16x32_bf16 v[92:95], v[164:167], v[214:217], v[92:95]
	v_mfma_f32_16x16x32_bf16 v[84:87], v[172:175], v[214:217], v[84:87]
	v_mfma_f32_16x16x32_bf16 v[76:79], v[164:167], v[222:225], v[76:79]
	v_mfma_f32_16x16x32_bf16 v[68:71], v[172:175], v[222:225], v[68:71]
	v_mfma_f32_16x16x32_bf16 v[120:123], v[176:179], v[194:197], 0
	v_mfma_f32_16x16x32_bf16 v[112:115], v[186:189], v[194:197], 0
	v_mfma_f32_16x16x32_bf16 v[104:107], v[176:179], v[202:205], 0
	v_mfma_f32_16x16x32_bf16 v[96:99], v[186:189], v[202:205], 0
	v_mfma_f32_16x16x32_bf16 v[88:91], v[176:179], v[210:213], 0
	v_mfma_f32_16x16x32_bf16 v[80:83], v[186:189], v[210:213], 0
	v_mfma_f32_16x16x32_bf16 v[72:75], v[176:179], v[218:221], 0
	v_mfma_f32_16x16x32_bf16 v[64:67], v[186:189], v[218:221], 0
	v_mfma_f32_16x16x32_bf16 v[120:123], v[180:183], v[198:201], v[120:123]
	v_mfma_f32_16x16x32_bf16 v[112:115], v[190:193], v[198:201], v[112:115]
	v_mfma_f32_16x16x32_bf16 v[104:107], v[180:183], v[206:209], v[104:107]
	v_mfma_f32_16x16x32_bf16 v[96:99], v[190:193], v[206:209], v[96:99]
	v_mfma_f32_16x16x32_bf16 v[88:91], v[180:183], v[214:217], v[88:91]
	v_mfma_f32_16x16x32_bf16 v[80:83], v[190:193], v[214:217], v[80:83]
	v_mfma_f32_16x16x32_bf16 v[72:75], v[180:183], v[222:225], v[72:75]
	v_mfma_f32_16x16x32_bf16 v[64:67], v[190:193], v[222:225], v[64:67]
	s_barrier
	s_setprio 0
	s_add_i32 s76, s64, s52
	v_lshl_add_u64 v[154:155], s[46:47], 0, v[132:133]
	s_mov_b32 m0, s76
	ds_read_b128 v[194:197], v150 offset:16384
	v_xor_b32_e32 v253, 64, v150
	ds_read_b128 v[198:201], v253 offset:16384
	ds_read_b128 v[202:205], v150 offset:18432
	ds_read_b128 v[206:209], v253 offset:18432
	ds_read_b128 v[210:213], v150 offset:20480
	ds_read_b128 v[214:217], v253 offset:20480
	ds_read_b128 v[218:221], v150 offset:22528
	ds_read_b128 v[222:225], v253 offset:22528
	global_load_lds_dwordx4 v[154:155], off
	s_add_i32 m0, s76, 0x2000
	s_add_u32 s76, s46, 0x40000
	v_lshl_add_u64 v[226:227], s[46:47], 0, v[128:129]
	s_addc_u32 s77, s47, 0
	s_add_i32 s78, s65, s52
	global_load_lds_dwordx4 v[226:227], off
	v_lshl_add_u64 v[228:229], s[76:77], 0, v[132:133]
	s_mov_b32 m0, s78
	v_lshl_add_u64 v[230:231], s[48:49], 0, v[130:131]
	global_load_lds_dwordx4 v[228:229], off
	v_lshl_add_u64 v[228:229], s[76:77], 0, v[128:129]
	s_add_i32 m0, s78, 0x2000
	s_nop 0
	global_load_lds_dwordx4 v[228:229], off
	v_lshl_add_u64 v[228:229], s[48:49], 0, v[134:135]
	s_mov_b32 m0, s55
	s_nop 0
	global_load_lds_dwordx4 v[228:229], off
	s_mov_b32 m0, s56
	s_nop 0
	global_load_lds_dwordx4 v[230:231], off
	s_waitcnt vmcnt(8)
	s_waitcnt lgkmcnt(0)
	s_setprio 1
	s_barrier
	v_mfma_f32_16x16x32_bf16 v[60:63], v[160:163], v[194:197], 0
	v_mfma_f32_16x16x32_bf16 v[52:55], v[168:171], v[194:197], 0
	v_mfma_f32_16x16x32_bf16 v[44:47], v[160:163], v[202:205], 0
	v_mfma_f32_16x16x32_bf16 v[36:39], v[168:171], v[202:205], 0
	v_mfma_f32_16x16x32_bf16 v[28:31], v[160:163], v[210:213], 0
	v_mfma_f32_16x16x32_bf16 v[20:23], v[168:171], v[210:213], 0
	v_mfma_f32_16x16x32_bf16 v[12:15], v[160:163], v[218:221], 0
	v_mfma_f32_16x16x32_bf16 v[4:7], v[168:171], v[218:221], 0
	v_mfma_f32_16x16x32_bf16 v[60:63], v[164:167], v[198:201], v[60:63]
	v_mfma_f32_16x16x32_bf16 v[52:55], v[172:175], v[198:201], v[52:55]
	v_mfma_f32_16x16x32_bf16 v[44:47], v[164:167], v[206:209], v[44:47]
	v_mfma_f32_16x16x32_bf16 v[36:39], v[172:175], v[206:209], v[36:39]
	v_mfma_f32_16x16x32_bf16 v[28:31], v[164:167], v[214:217], v[28:31]
	v_mfma_f32_16x16x32_bf16 v[20:23], v[172:175], v[214:217], v[20:23]
	v_mfma_f32_16x16x32_bf16 v[12:15], v[164:167], v[222:225], v[12:15]
	v_mfma_f32_16x16x32_bf16 v[4:7], v[172:175], v[222:225], v[4:7]
	v_mfma_f32_16x16x32_bf16 v[56:59], v[176:179], v[194:197], 0
	v_mfma_f32_16x16x32_bf16 v[48:51], v[186:189], v[194:197], 0
	v_mfma_f32_16x16x32_bf16 v[40:43], v[176:179], v[202:205], 0
	v_mfma_f32_16x16x32_bf16 v[32:35], v[186:189], v[202:205], 0
	v_mfma_f32_16x16x32_bf16 v[24:27], v[176:179], v[210:213], 0
	v_mfma_f32_16x16x32_bf16 v[16:19], v[186:189], v[210:213], 0
	v_mfma_f32_16x16x32_bf16 v[8:11], v[176:179], v[218:221], 0
	v_mfma_f32_16x16x32_bf16 v[0:3], v[186:189], v[218:221], 0
	v_mfma_f32_16x16x32_bf16 v[56:59], v[180:183], v[198:201], v[56:59]
	v_mfma_f32_16x16x32_bf16 v[48:51], v[190:193], v[198:201], v[48:51]
	v_mfma_f32_16x16x32_bf16 v[40:43], v[180:183], v[206:209], v[40:43]
	v_mfma_f32_16x16x32_bf16 v[32:35], v[190:193], v[206:209], v[32:35]
	v_mfma_f32_16x16x32_bf16 v[24:27], v[180:183], v[214:217], v[24:27]
	v_mfma_f32_16x16x32_bf16 v[16:19], v[190:193], v[214:217], v[16:19]
	v_mfma_f32_16x16x32_bf16 v[8:11], v[180:183], v[222:225], v[8:11]
	v_mfma_f32_16x16x32_bf16 v[0:3], v[190:193], v[222:225], v[0:3]
	s_barrier
	s_setprio 0
	s_add_i32 s76, 0, 0x18000
	v_add_u32_e32 v153, s76, v147
	s_add_i32 s77, 0, 0x1c000
	ds_read_b128 v[160:163], v153
	v_xor_b32_e32 v253, 64, v153
	ds_read_b128 v[164:167], v253
	ds_read_b128 v[168:171], v153 offset:2048
	ds_read_b128 v[172:175], v253 offset:2048
	v_add_u32_e32 v153, s77, v147
	ds_read_b128 v[176:179], v153
	v_xor_b32_e32 v253, 64, v153
	ds_read_b128 v[180:183], v253
	ds_read_b128 v[186:189], v153 offset:2048
	ds_read_b128 v[190:193], v253 offset:2048
	s_add_u32 s48, s48, 0x40000
	s_addc_u32 s49, s49, 0
	s_mov_b32 m0, s57
	v_lshl_add_u64 v[232:233], s[48:49], 0, v[134:135]
	ds_read_b128 v[194:197], v150 offset:32768
	v_xor_b32_e32 v253, 64, v150
	ds_read_b128 v[198:201], v253 offset:32768
	ds_read_b128 v[202:205], v150 offset:34816
	ds_read_b128 v[206:209], v253 offset:34816
	ds_read_b128 v[210:213], v150 offset:36864
	ds_read_b128 v[214:217], v253 offset:36864
	ds_read_b128 v[218:221], v150 offset:38912
	ds_read_b128 v[222:225], v253 offset:38912
	global_load_lds_dwordx4 v[232:233], off
	v_lshl_add_u64 v[232:233], s[48:49], 0, v[130:131]
	s_mov_b32 m0, s58
	s_nop 0
	global_load_lds_dwordx4 v[232:233], off
	s_waitcnt vmcnt(8)
	s_waitcnt lgkmcnt(0)
	s_setprio 1
	s_barrier
	v_mfma_f32_16x16x32_bf16 v[124:127], v[160:163], v[194:197], v[124:127]
	v_mfma_f32_16x16x32_bf16 v[124:127], v[164:167], v[198:201], v[124:127]
	v_mfma_f32_16x16x32_bf16 v[116:119], v[172:175], v[198:201], v[116:119]
	v_mfma_f32_16x16x32_bf16 v[116:119], v[168:171], v[194:197], v[116:119]
	v_mfma_f32_16x16x32_bf16 v[100:103], v[168:171], v[202:205], v[100:103]
	v_mfma_f32_16x16x32_bf16 v[100:103], v[172:175], v[206:209], v[100:103]
	v_mfma_f32_16x16x32_bf16 v[108:111], v[164:167], v[206:209], v[108:111]
	v_mfma_f32_16x16x32_bf16 v[108:111], v[160:163], v[202:205], v[108:111]
	v_mfma_f32_16x16x32_bf16 v[92:95], v[160:163], v[210:213], v[92:95]
	v_mfma_f32_16x16x32_bf16 v[92:95], v[164:167], v[214:217], v[92:95]
	v_mfma_f32_16x16x32_bf16 v[84:87], v[172:175], v[214:217], v[84:87]
	v_mfma_f32_16x16x32_bf16 v[84:87], v[168:171], v[210:213], v[84:87]
	v_mfma_f32_16x16x32_bf16 v[68:71], v[168:171], v[218:221], v[68:71]
	v_mfma_f32_16x16x32_bf16 v[68:71], v[172:175], v[222:225], v[68:71]
	v_mfma_f32_16x16x32_bf16 v[76:79], v[164:167], v[222:225], v[76:79]
	v_mfma_f32_16x16x32_bf16 v[76:79], v[160:163], v[218:221], v[76:79]
	v_mfma_f32_16x16x32_bf16 v[120:123], v[176:179], v[194:197], v[120:123]
	v_mfma_f32_16x16x32_bf16 v[120:123], v[180:183], v[198:201], v[120:123]
	v_mfma_f32_16x16x32_bf16 v[112:115], v[190:193], v[198:201], v[112:115]
	v_mfma_f32_16x16x32_bf16 v[112:115], v[186:189], v[194:197], v[112:115]
	v_mfma_f32_16x16x32_bf16 v[96:99], v[186:189], v[202:205], v[96:99]
	v_mfma_f32_16x16x32_bf16 v[96:99], v[190:193], v[206:209], v[96:99]
	v_mfma_f32_16x16x32_bf16 v[104:107], v[180:183], v[206:209], v[104:107]
	v_mfma_f32_16x16x32_bf16 v[104:107], v[176:179], v[202:205], v[104:107]
	v_mfma_f32_16x16x32_bf16 v[88:91], v[176:179], v[210:213], v[88:91]
	v_mfma_f32_16x16x32_bf16 v[88:91], v[180:183], v[214:217], v[88:91]
	v_mfma_f32_16x16x32_bf16 v[80:83], v[190:193], v[214:217], v[80:83]
	v_mfma_f32_16x16x32_bf16 v[80:83], v[186:189], v[210:213], v[80:83]
	v_mfma_f32_16x16x32_bf16 v[64:67], v[186:189], v[218:221], v[64:67]
	v_mfma_f32_16x16x32_bf16 v[64:67], v[190:193], v[222:225], v[64:67]
	v_mfma_f32_16x16x32_bf16 v[72:75], v[180:183], v[222:225], v[72:75]
	v_mfma_f32_16x16x32_bf16 v[72:75], v[176:179], v[218:221], v[72:75]
	s_barrier
	s_setprio 0
	s_add_i32 s48, s76, s52
	v_lshl_add_u64 v[154:155], v[154:155], 0, s[14:15]
	s_mov_b32 m0, s48
	ds_read_b128 v[194:197], v150 offset:49152
	v_xor_b32_e32 v253, 64, v150
	ds_read_b128 v[198:201], v253 offset:49152
	ds_read_b128 v[202:205], v150 offset:51200
	ds_read_b128 v[206:209], v253 offset:51200
	ds_read_b128 v[210:213], v150 offset:53248
	ds_read_b128 v[214:217], v253 offset:53248
	ds_read_b128 v[218:221], v150 offset:55296
	ds_read_b128 v[222:225], v253 offset:55296
	global_load_lds_dwordx4 v[154:155], off
	s_add_i32 m0, s48, 0x2000
	s_add_u32 s46, s46, 0x40080
	v_lshl_add_u64 v[154:155], v[226:227], 0, s[14:15]
	s_addc_u32 s47, s47, 0
	s_add_i32 s48, s77, s52
	global_load_lds_dwordx4 v[154:155], off
	v_lshl_add_u64 v[154:155], s[46:47], 0, v[132:133]
	s_mov_b32 m0, s48
	s_nop 0
	global_load_lds_dwordx4 v[154:155], off
	v_lshl_add_u64 v[154:155], s[46:47], 0, v[128:129]
	s_add_i32 m0, s48, 0x2000
	s_nop 0
	global_load_lds_dwordx4 v[154:155], off
	v_lshl_add_u64 v[154:155], v[228:229], 0, s[14:15]
	s_mov_b32 m0, s60
	s_nop 0
	global_load_lds_dwordx4 v[154:155], off
	v_lshl_add_u64 v[154:155], v[230:231], 0, s[14:15]
	s_mov_b32 m0, s61
	s_nop 0
	global_load_lds_dwordx4 v[154:155], off
	s_waitcnt vmcnt(8)
	s_waitcnt lgkmcnt(0)
	s_setprio 1
	s_barrier
	v_mfma_f32_16x16x32_bf16 v[60:63], v[160:163], v[194:197], v[60:63]
	v_mfma_f32_16x16x32_bf16 v[60:63], v[164:167], v[198:201], v[60:63]
	v_mfma_f32_16x16x32_bf16 v[52:55], v[172:175], v[198:201], v[52:55]
	v_mfma_f32_16x16x32_bf16 v[52:55], v[168:171], v[194:197], v[52:55]
	v_mfma_f32_16x16x32_bf16 v[36:39], v[168:171], v[202:205], v[36:39]
	v_mfma_f32_16x16x32_bf16 v[36:39], v[172:175], v[206:209], v[36:39]
	v_mfma_f32_16x16x32_bf16 v[44:47], v[164:167], v[206:209], v[44:47]
	v_mfma_f32_16x16x32_bf16 v[44:47], v[160:163], v[202:205], v[44:47]
	v_mfma_f32_16x16x32_bf16 v[28:31], v[160:163], v[210:213], v[28:31]
	v_mfma_f32_16x16x32_bf16 v[28:31], v[164:167], v[214:217], v[28:31]
	v_mfma_f32_16x16x32_bf16 v[20:23], v[172:175], v[214:217], v[20:23]
	v_mfma_f32_16x16x32_bf16 v[20:23], v[168:171], v[210:213], v[20:23]
	v_mfma_f32_16x16x32_bf16 v[4:7], v[168:171], v[218:221], v[4:7]
	v_mfma_f32_16x16x32_bf16 v[4:7], v[172:175], v[222:225], v[4:7]
	v_mfma_f32_16x16x32_bf16 v[12:15], v[164:167], v[222:225], v[12:15]
	v_mfma_f32_16x16x32_bf16 v[12:15], v[160:163], v[218:221], v[12:15]
	v_mfma_f32_16x16x32_bf16 v[56:59], v[176:179], v[194:197], v[56:59]
	v_mfma_f32_16x16x32_bf16 v[56:59], v[180:183], v[198:201], v[56:59]
	v_mfma_f32_16x16x32_bf16 v[48:51], v[190:193], v[198:201], v[48:51]
	v_mfma_f32_16x16x32_bf16 v[48:51], v[186:189], v[194:197], v[48:51]
	v_mfma_f32_16x16x32_bf16 v[32:35], v[186:189], v[202:205], v[32:35]
	v_mfma_f32_16x16x32_bf16 v[32:35], v[190:193], v[206:209], v[32:35]
	v_mfma_f32_16x16x32_bf16 v[40:43], v[180:183], v[206:209], v[40:43]
	v_mfma_f32_16x16x32_bf16 v[40:43], v[176:179], v[202:205], v[40:43]
	v_mfma_f32_16x16x32_bf16 v[24:27], v[176:179], v[210:213], v[24:27]
	v_mfma_f32_16x16x32_bf16 v[24:27], v[180:183], v[214:217], v[24:27]
	v_mfma_f32_16x16x32_bf16 v[16:19], v[190:193], v[214:217], v[16:19]
	v_mfma_f32_16x16x32_bf16 v[16:19], v[186:189], v[210:213], v[16:19]
	v_mfma_f32_16x16x32_bf16 v[0:3], v[186:189], v[218:221], v[0:3]
	v_mfma_f32_16x16x32_bf16 v[0:3], v[190:193], v[222:225], v[0:3]
	v_mfma_f32_16x16x32_bf16 v[8:11], v[180:183], v[222:225], v[8:11]
	v_mfma_f32_16x16x32_bf16 v[8:11], v[176:179], v[218:221], v[8:11]
	s_barrier
	s_setprio 0
	s_add_i32 s75, s75, 2
	s_add_u32 s71, s71, 0x100
	s_addc_u32 s74, s74, 0
	s_add_u32 s44, s44, 0x100
	s_addc_u32 s45, s45, 0
	s_branch .LBB0_76
.LBB0_75:
	v_add_u32_e32 v153, s64, v147
	ds_read_b128 v[160:163], v153
	v_xor_b32_e32 v253, 64, v153
	ds_read_b128 v[164:167], v253
	ds_read_b128 v[168:171], v153 offset:2048
	ds_read_b128 v[172:175], v253 offset:2048
	v_add_u32_e32 v153, s65, v147
	ds_read_b128 v[176:179], v153
	v_xor_b32_e32 v253, 64, v153
	ds_read_b128 v[180:183], v253
	ds_read_b128 v[186:189], v153 offset:2048
	ds_read_b128 v[190:193], v253 offset:2048
	s_add_u32 s48, s44, 0xfffc0080
	s_addc_u32 s49, s45, -1
	s_and_b64 s[46:47], s[46:47], exec
	s_cselect_b32 s49, s27, s49
	s_cselect_b32 s48, s68, s48
	s_cselect_b32 s47, s69, s74
	s_cselect_b32 s46, s70, s71
	v_lshl_add_u64 v[154:155], s[44:45], 0, v[138:139]
	s_add_i32 m0, s55, 0xc000
	ds_read_b128 v[194:197], v150
	v_xor_b32_e32 v253, 64, v150
	ds_read_b128 v[198:201], v253
	ds_read_b128 v[202:205], v150 offset:2048
	ds_read_b128 v[206:209], v253 offset:2048
	ds_read_b128 v[210:213], v150 offset:4096
	ds_read_b128 v[214:217], v253 offset:4096
	ds_read_b128 v[218:221], v150 offset:6144
	ds_read_b128 v[222:225], v253 offset:6144
	global_load_lds_dwordx4 v[154:155], off
	v_lshl_add_u64 v[154:155], s[44:45], 0, v[136:137]
	s_add_i32 m0, s55, 0xe000
	s_nop 0
	global_load_lds_dwordx4 v[154:155], off
	s_waitcnt vmcnt(8)
	s_waitcnt lgkmcnt(0)
	s_setprio 1
	s_barrier
	v_mfma_f32_16x16x32_bf16 v[124:127], v[160:163], v[194:197], v[124:127]
	v_mfma_f32_16x16x32_bf16 v[124:127], v[164:167], v[198:201], v[124:127]
	v_mfma_f32_16x16x32_bf16 v[116:119], v[172:175], v[198:201], v[116:119]
	v_mfma_f32_16x16x32_bf16 v[116:119], v[168:171], v[194:197], v[116:119]
	v_mfma_f32_16x16x32_bf16 v[100:103], v[168:171], v[202:205], v[100:103]
	v_mfma_f32_16x16x32_bf16 v[100:103], v[172:175], v[206:209], v[100:103]
	v_mfma_f32_16x16x32_bf16 v[108:111], v[164:167], v[206:209], v[108:111]
	v_mfma_f32_16x16x32_bf16 v[108:111], v[160:163], v[202:205], v[108:111]
	v_mfma_f32_16x16x32_bf16 v[92:95], v[160:163], v[210:213], v[92:95]
	v_mfma_f32_16x16x32_bf16 v[92:95], v[164:167], v[214:217], v[92:95]
	v_mfma_f32_16x16x32_bf16 v[84:87], v[172:175], v[214:217], v[84:87]
	v_mfma_f32_16x16x32_bf16 v[84:87], v[168:171], v[210:213], v[84:87]
	v_mfma_f32_16x16x32_bf16 v[68:71], v[168:171], v[218:221], v[68:71]
	v_mfma_f32_16x16x32_bf16 v[68:71], v[172:175], v[222:225], v[68:71]
	v_mfma_f32_16x16x32_bf16 v[76:79], v[164:167], v[222:225], v[76:79]
	v_mfma_f32_16x16x32_bf16 v[76:79], v[160:163], v[218:221], v[76:79]
	v_mfma_f32_16x16x32_bf16 v[120:123], v[176:179], v[194:197], v[120:123]
	v_mfma_f32_16x16x32_bf16 v[120:123], v[180:183], v[198:201], v[120:123]
	v_mfma_f32_16x16x32_bf16 v[112:115], v[190:193], v[198:201], v[112:115]
	v_mfma_f32_16x16x32_bf16 v[112:115], v[186:189], v[194:197], v[112:115]
	v_mfma_f32_16x16x32_bf16 v[96:99], v[186:189], v[202:205], v[96:99]
	v_mfma_f32_16x16x32_bf16 v[96:99], v[190:193], v[206:209], v[96:99]
	v_mfma_f32_16x16x32_bf16 v[104:107], v[180:183], v[206:209], v[104:107]
	v_mfma_f32_16x16x32_bf16 v[104:107], v[176:179], v[202:205], v[104:107]
	v_mfma_f32_16x16x32_bf16 v[88:91], v[176:179], v[210:213], v[88:91]
	v_mfma_f32_16x16x32_bf16 v[88:91], v[180:183], v[214:217], v[88:91]
	v_mfma_f32_16x16x32_bf16 v[80:83], v[190:193], v[214:217], v[80:83]
	v_mfma_f32_16x16x32_bf16 v[80:83], v[186:189], v[210:213], v[80:83]
	v_mfma_f32_16x16x32_bf16 v[64:67], v[186:189], v[218:221], v[64:67]
	v_mfma_f32_16x16x32_bf16 v[64:67], v[190:193], v[222:225], v[64:67]
	v_mfma_f32_16x16x32_bf16 v[72:75], v[180:183], v[222:225], v[72:75]
	v_mfma_f32_16x16x32_bf16 v[72:75], v[176:179], v[218:221], v[72:75]
	s_barrier
	s_setprio 0
	s_add_i32 s76, s64, s52
	v_lshl_add_u64 v[154:155], s[46:47], 0, v[132:133]
	s_mov_b32 m0, s76
	ds_read_b128 v[194:197], v150 offset:16384
	v_xor_b32_e32 v253, 64, v150
	ds_read_b128 v[198:201], v253 offset:16384
	ds_read_b128 v[202:205], v150 offset:18432
	ds_read_b128 v[206:209], v253 offset:18432
	ds_read_b128 v[210:213], v150 offset:20480
	ds_read_b128 v[214:217], v253 offset:20480
	ds_read_b128 v[218:221], v150 offset:22528
	ds_read_b128 v[222:225], v253 offset:22528
	global_load_lds_dwordx4 v[154:155], off
	s_add_i32 m0, s76, 0x2000
	s_add_u32 s76, s46, 0x40000
	v_lshl_add_u64 v[226:227], s[46:47], 0, v[128:129]
	s_addc_u32 s77, s47, 0
	s_add_i32 s78, s65, s52
	global_load_lds_dwordx4 v[226:227], off
	v_lshl_add_u64 v[228:229], s[76:77], 0, v[132:133]
	s_mov_b32 m0, s78
	v_lshl_add_u64 v[230:231], s[48:49], 0, v[130:131]
	global_load_lds_dwordx4 v[228:229], off
	v_lshl_add_u64 v[228:229], s[76:77], 0, v[128:129]
	s_add_i32 m0, s78, 0x2000
	s_nop 0
	global_load_lds_dwordx4 v[228:229], off
	v_lshl_add_u64 v[228:229], s[48:49], 0, v[134:135]
	s_mov_b32 m0, s55
	s_nop 0
	global_load_lds_dwordx4 v[228:229], off
	s_mov_b32 m0, s56
	s_nop 0
	global_load_lds_dwordx4 v[230:231], off
	s_waitcnt vmcnt(8)
	s_waitcnt lgkmcnt(0)
	s_setprio 1
	s_barrier
	v_mfma_f32_16x16x32_bf16 v[60:63], v[160:163], v[194:197], v[60:63]
	v_mfma_f32_16x16x32_bf16 v[60:63], v[164:167], v[198:201], v[60:63]
	v_mfma_f32_16x16x32_bf16 v[52:55], v[172:175], v[198:201], v[52:55]
	v_mfma_f32_16x16x32_bf16 v[52:55], v[168:171], v[194:197], v[52:55]
	v_mfma_f32_16x16x32_bf16 v[36:39], v[168:171], v[202:205], v[36:39]
	v_mfma_f32_16x16x32_bf16 v[36:39], v[172:175], v[206:209], v[36:39]
	v_mfma_f32_16x16x32_bf16 v[44:47], v[164:167], v[206:209], v[44:47]
	v_mfma_f32_16x16x32_bf16 v[44:47], v[160:163], v[202:205], v[44:47]
	v_mfma_f32_16x16x32_bf16 v[28:31], v[160:163], v[210:213], v[28:31]
	v_mfma_f32_16x16x32_bf16 v[28:31], v[164:167], v[214:217], v[28:31]
	v_mfma_f32_16x16x32_bf16 v[20:23], v[172:175], v[214:217], v[20:23]
	v_mfma_f32_16x16x32_bf16 v[20:23], v[168:171], v[210:213], v[20:23]
	v_mfma_f32_16x16x32_bf16 v[4:7], v[168:171], v[218:221], v[4:7]
	v_mfma_f32_16x16x32_bf16 v[4:7], v[172:175], v[222:225], v[4:7]
	v_mfma_f32_16x16x32_bf16 v[12:15], v[164:167], v[222:225], v[12:15]
	v_mfma_f32_16x16x32_bf16 v[12:15], v[160:163], v[218:221], v[12:15]
	v_mfma_f32_16x16x32_bf16 v[56:59], v[176:179], v[194:197], v[56:59]
	v_mfma_f32_16x16x32_bf16 v[56:59], v[180:183], v[198:201], v[56:59]
	v_mfma_f32_16x16x32_bf16 v[48:51], v[190:193], v[198:201], v[48:51]
	v_mfma_f32_16x16x32_bf16 v[48:51], v[186:189], v[194:197], v[48:51]
	v_mfma_f32_16x16x32_bf16 v[32:35], v[186:189], v[202:205], v[32:35]
	v_mfma_f32_16x16x32_bf16 v[32:35], v[190:193], v[206:209], v[32:35]
	v_mfma_f32_16x16x32_bf16 v[40:43], v[180:183], v[206:209], v[40:43]
	v_mfma_f32_16x16x32_bf16 v[40:43], v[176:179], v[202:205], v[40:43]
	v_mfma_f32_16x16x32_bf16 v[24:27], v[176:179], v[210:213], v[24:27]
	v_mfma_f32_16x16x32_bf16 v[24:27], v[180:183], v[214:217], v[24:27]
	v_mfma_f32_16x16x32_bf16 v[16:19], v[190:193], v[214:217], v[16:19]
	v_mfma_f32_16x16x32_bf16 v[16:19], v[186:189], v[210:213], v[16:19]
	v_mfma_f32_16x16x32_bf16 v[0:3], v[186:189], v[218:221], v[0:3]
	v_mfma_f32_16x16x32_bf16 v[0:3], v[190:193], v[222:225], v[0:3]
	v_mfma_f32_16x16x32_bf16 v[8:11], v[180:183], v[222:225], v[8:11]
	v_mfma_f32_16x16x32_bf16 v[8:11], v[176:179], v[218:221], v[8:11]
	s_barrier
	s_setprio 0
	s_add_i32 s76, 0, 0x18000
	v_add_u32_e32 v153, s76, v147
	s_add_i32 s77, 0, 0x1c000
	ds_read_b128 v[160:163], v153
	v_xor_b32_e32 v253, 64, v153
	ds_read_b128 v[164:167], v253
	ds_read_b128 v[168:171], v153 offset:2048
	ds_read_b128 v[172:175], v253 offset:2048
	v_add_u32_e32 v153, s77, v147
	ds_read_b128 v[176:179], v153
	v_xor_b32_e32 v253, 64, v153
	ds_read_b128 v[180:183], v253
	ds_read_b128 v[186:189], v153 offset:2048
	ds_read_b128 v[190:193], v253 offset:2048
	s_add_u32 s48, s48, 0x40000
	s_addc_u32 s49, s49, 0
	s_mov_b32 m0, s57
	v_lshl_add_u64 v[232:233], s[48:49], 0, v[134:135]
	ds_read_b128 v[194:197], v150 offset:32768
	v_xor_b32_e32 v253, 64, v150
	ds_read_b128 v[198:201], v253 offset:32768
	ds_read_b128 v[202:205], v150 offset:34816
	ds_read_b128 v[206:209], v253 offset:34816
	ds_read_b128 v[210:213], v150 offset:36864
	ds_read_b128 v[214:217], v253 offset:36864
	ds_read_b128 v[218:221], v150 offset:38912
	ds_read_b128 v[222:225], v253 offset:38912
	global_load_lds_dwordx4 v[232:233], off
	v_lshl_add_u64 v[232:233], s[48:49], 0, v[130:131]
	s_mov_b32 m0, s58
	s_nop 0
	global_load_lds_dwordx4 v[232:233], off
	s_waitcnt vmcnt(8)
	s_waitcnt lgkmcnt(0)
	s_setprio 1
	s_barrier
	v_mfma_f32_16x16x32_bf16 v[124:127], v[160:163], v[194:197], v[124:127]
	v_mfma_f32_16x16x32_bf16 v[124:127], v[164:167], v[198:201], v[124:127]
	v_mfma_f32_16x16x32_bf16 v[116:119], v[172:175], v[198:201], v[116:119]
	v_mfma_f32_16x16x32_bf16 v[116:119], v[168:171], v[194:197], v[116:119]
	v_mfma_f32_16x16x32_bf16 v[100:103], v[168:171], v[202:205], v[100:103]
	v_mfma_f32_16x16x32_bf16 v[100:103], v[172:175], v[206:209], v[100:103]
	v_mfma_f32_16x16x32_bf16 v[108:111], v[164:167], v[206:209], v[108:111]
	v_mfma_f32_16x16x32_bf16 v[108:111], v[160:163], v[202:205], v[108:111]
	v_mfma_f32_16x16x32_bf16 v[92:95], v[160:163], v[210:213], v[92:95]
	v_mfma_f32_16x16x32_bf16 v[92:95], v[164:167], v[214:217], v[92:95]
	v_mfma_f32_16x16x32_bf16 v[84:87], v[172:175], v[214:217], v[84:87]
	v_mfma_f32_16x16x32_bf16 v[84:87], v[168:171], v[210:213], v[84:87]
	v_mfma_f32_16x16x32_bf16 v[68:71], v[168:171], v[218:221], v[68:71]
	v_mfma_f32_16x16x32_bf16 v[68:71], v[172:175], v[222:225], v[68:71]
	v_mfma_f32_16x16x32_bf16 v[76:79], v[164:167], v[222:225], v[76:79]
	v_mfma_f32_16x16x32_bf16 v[76:79], v[160:163], v[218:221], v[76:79]
	v_mfma_f32_16x16x32_bf16 v[120:123], v[176:179], v[194:197], v[120:123]
	v_mfma_f32_16x16x32_bf16 v[120:123], v[180:183], v[198:201], v[120:123]
	v_mfma_f32_16x16x32_bf16 v[112:115], v[190:193], v[198:201], v[112:115]
	v_mfma_f32_16x16x32_bf16 v[112:115], v[186:189], v[194:197], v[112:115]
	v_mfma_f32_16x16x32_bf16 v[96:99], v[186:189], v[202:205], v[96:99]
	v_mfma_f32_16x16x32_bf16 v[96:99], v[190:193], v[206:209], v[96:99]
	v_mfma_f32_16x16x32_bf16 v[104:107], v[180:183], v[206:209], v[104:107]
	v_mfma_f32_16x16x32_bf16 v[104:107], v[176:179], v[202:205], v[104:107]
	v_mfma_f32_16x16x32_bf16 v[88:91], v[176:179], v[210:213], v[88:91]
	v_mfma_f32_16x16x32_bf16 v[88:91], v[180:183], v[214:217], v[88:91]
	v_mfma_f32_16x16x32_bf16 v[80:83], v[190:193], v[214:217], v[80:83]
	v_mfma_f32_16x16x32_bf16 v[80:83], v[186:189], v[210:213], v[80:83]
	v_mfma_f32_16x16x32_bf16 v[64:67], v[186:189], v[218:221], v[64:67]
	v_mfma_f32_16x16x32_bf16 v[64:67], v[190:193], v[222:225], v[64:67]
	v_mfma_f32_16x16x32_bf16 v[72:75], v[180:183], v[222:225], v[72:75]
	v_mfma_f32_16x16x32_bf16 v[72:75], v[176:179], v[218:221], v[72:75]
	s_barrier
	s_setprio 0
	s_add_i32 s48, s76, s52
	v_lshl_add_u64 v[154:155], v[154:155], 0, s[14:15]
	s_mov_b32 m0, s48
	ds_read_b128 v[194:197], v150 offset:49152
	v_xor_b32_e32 v253, 64, v150
	ds_read_b128 v[198:201], v253 offset:49152
	ds_read_b128 v[202:205], v150 offset:51200
	ds_read_b128 v[206:209], v253 offset:51200
	ds_read_b128 v[210:213], v150 offset:53248
	ds_read_b128 v[214:217], v253 offset:53248
	ds_read_b128 v[218:221], v150 offset:55296
	ds_read_b128 v[222:225], v253 offset:55296
	global_load_lds_dwordx4 v[154:155], off
	s_add_i32 m0, s48, 0x2000
	s_add_u32 s46, s46, 0x40080
	v_lshl_add_u64 v[154:155], v[226:227], 0, s[14:15]
	s_addc_u32 s47, s47, 0
	s_add_i32 s48, s77, s52
	global_load_lds_dwordx4 v[154:155], off
	v_lshl_add_u64 v[154:155], s[46:47], 0, v[132:133]
	s_mov_b32 m0, s48
	s_nop 0
	global_load_lds_dwordx4 v[154:155], off
	v_lshl_add_u64 v[154:155], s[46:47], 0, v[128:129]
	s_add_i32 m0, s48, 0x2000
	s_nop 0
	global_load_lds_dwordx4 v[154:155], off
	v_lshl_add_u64 v[154:155], v[228:229], 0, s[14:15]
	s_mov_b32 m0, s60
	s_nop 0
	global_load_lds_dwordx4 v[154:155], off
	v_lshl_add_u64 v[154:155], v[230:231], 0, s[14:15]
	s_mov_b32 m0, s61
	s_nop 0
	global_load_lds_dwordx4 v[154:155], off
	s_waitcnt vmcnt(8)
	s_waitcnt lgkmcnt(0)
	s_setprio 1
	s_barrier
	v_mfma_f32_16x16x32_bf16 v[60:63], v[160:163], v[194:197], v[60:63]
	v_mfma_f32_16x16x32_bf16 v[60:63], v[164:167], v[198:201], v[60:63]
	v_mfma_f32_16x16x32_bf16 v[52:55], v[172:175], v[198:201], v[52:55]
	v_mfma_f32_16x16x32_bf16 v[52:55], v[168:171], v[194:197], v[52:55]
	v_mfma_f32_16x16x32_bf16 v[36:39], v[168:171], v[202:205], v[36:39]
	v_mfma_f32_16x16x32_bf16 v[36:39], v[172:175], v[206:209], v[36:39]
	v_mfma_f32_16x16x32_bf16 v[44:47], v[164:167], v[206:209], v[44:47]
	v_mfma_f32_16x16x32_bf16 v[44:47], v[160:163], v[202:205], v[44:47]
	v_mfma_f32_16x16x32_bf16 v[28:31], v[160:163], v[210:213], v[28:31]
	v_mfma_f32_16x16x32_bf16 v[28:31], v[164:167], v[214:217], v[28:31]
	v_mfma_f32_16x16x32_bf16 v[20:23], v[172:175], v[214:217], v[20:23]
	v_mfma_f32_16x16x32_bf16 v[20:23], v[168:171], v[210:213], v[20:23]
	v_mfma_f32_16x16x32_bf16 v[4:7], v[168:171], v[218:221], v[4:7]
	v_mfma_f32_16x16x32_bf16 v[4:7], v[172:175], v[222:225], v[4:7]
	v_mfma_f32_16x16x32_bf16 v[12:15], v[164:167], v[222:225], v[12:15]
	v_mfma_f32_16x16x32_bf16 v[12:15], v[160:163], v[218:221], v[12:15]
	v_mfma_f32_16x16x32_bf16 v[56:59], v[176:179], v[194:197], v[56:59]
	v_mfma_f32_16x16x32_bf16 v[56:59], v[180:183], v[198:201], v[56:59]
	v_mfma_f32_16x16x32_bf16 v[48:51], v[190:193], v[198:201], v[48:51]
	v_mfma_f32_16x16x32_bf16 v[48:51], v[186:189], v[194:197], v[48:51]
	v_mfma_f32_16x16x32_bf16 v[32:35], v[186:189], v[202:205], v[32:35]
	v_mfma_f32_16x16x32_bf16 v[32:35], v[190:193], v[206:209], v[32:35]
	v_mfma_f32_16x16x32_bf16 v[40:43], v[180:183], v[206:209], v[40:43]
	v_mfma_f32_16x16x32_bf16 v[40:43], v[176:179], v[202:205], v[40:43]
	v_mfma_f32_16x16x32_bf16 v[24:27], v[176:179], v[210:213], v[24:27]
	v_mfma_f32_16x16x32_bf16 v[24:27], v[180:183], v[214:217], v[24:27]
	v_mfma_f32_16x16x32_bf16 v[16:19], v[190:193], v[214:217], v[16:19]
	v_mfma_f32_16x16x32_bf16 v[16:19], v[186:189], v[210:213], v[16:19]
	v_mfma_f32_16x16x32_bf16 v[0:3], v[186:189], v[218:221], v[0:3]
	v_mfma_f32_16x16x32_bf16 v[0:3], v[190:193], v[222:225], v[0:3]
	v_mfma_f32_16x16x32_bf16 v[8:11], v[180:183], v[222:225], v[8:11]
	v_mfma_f32_16x16x32_bf16 v[8:11], v[176:179], v[218:221], v[8:11]
	s_barrier
	s_setprio 0
	s_add_i32 s75, s75, 2
	s_add_u32 s71, s71, 0x100
	s_addc_u32 s74, s74, 0
	s_add_u32 s44, s44, 0x100
	s_addc_u32 s45, s45, 0
	s_cmp_gt_u32 s75, 13
	s_cbranch_scc1 .LBB0_78

.Llast_0:
	v_add_u32_e32 v153, s64, v147
	ds_read_b128 v[160:163], v153
	v_xor_b32_e32 v253, 64, v153
	ds_read_b128 v[164:167], v253
	ds_read_b128 v[168:171], v153 offset:2048
	ds_read_b128 v[172:175], v253 offset:2048
	v_add_u32_e32 v153, s65, v147
	ds_read_b128 v[176:179], v153
	v_xor_b32_e32 v253, 64, v153
	ds_read_b128 v[180:183], v253
	ds_read_b128 v[186:189], v153 offset:2048
	ds_read_b128 v[190:193], v253 offset:2048
	s_add_u32 s48, s44, 0xfffc0080
	s_addc_u32 s49, s45, -1
	s_and_b64 s[46:47], s[46:47], exec
	s_cselect_b32 s49, s27, s49
	s_cselect_b32 s48, s68, s48
	s_cselect_b32 s47, s69, s74
	s_cselect_b32 s46, s70, s71
	v_lshl_add_u64 v[154:155], s[44:45], 0, v[138:139]
	s_add_i32 m0, s55, 0xc000
	ds_read_b128 v[194:197], v150
	v_xor_b32_e32 v253, 64, v150
	ds_read_b128 v[198:201], v253
	ds_read_b128 v[202:205], v150 offset:2048
	ds_read_b128 v[206:209], v253 offset:2048
	ds_read_b128 v[210:213], v150 offset:4096
	ds_read_b128 v[214:217], v253 offset:4096
	ds_read_b128 v[218:221], v150 offset:6144
	ds_read_b128 v[222:225], v253 offset:6144
	global_load_lds_dwordx4 v[154:155], off
	v_lshl_add_u64 v[154:155], s[44:45], 0, v[136:137]
	s_add_i32 m0, s55, 0xe000
	s_nop 0
	global_load_lds_dwordx4 v[154:155], off
	s_waitcnt vmcnt(8)
	s_waitcnt lgkmcnt(0)
	s_setprio 1
	s_barrier
	v_mfma_f32_16x16x32_bf16 v[124:127], v[160:163], v[194:197], v[124:127]
	v_mfma_f32_16x16x32_bf16 v[124:127], v[164:167], v[198:201], v[124:127]
	v_mfma_f32_16x16x32_bf16 v[116:119], v[172:175], v[198:201], v[116:119]
	v_mfma_f32_16x16x32_bf16 v[116:119], v[168:171], v[194:197], v[116:119]
	v_mfma_f32_16x16x32_bf16 v[100:103], v[168:171], v[202:205], v[100:103]
	v_mfma_f32_16x16x32_bf16 v[100:103], v[172:175], v[206:209], v[100:103]
	v_mfma_f32_16x16x32_bf16 v[108:111], v[164:167], v[206:209], v[108:111]
	v_mfma_f32_16x16x32_bf16 v[108:111], v[160:163], v[202:205], v[108:111]
	v_mfma_f32_16x16x32_bf16 v[92:95], v[160:163], v[210:213], v[92:95]
	v_mfma_f32_16x16x32_bf16 v[92:95], v[164:167], v[214:217], v[92:95]
	v_mfma_f32_16x16x32_bf16 v[84:87], v[172:175], v[214:217], v[84:87]
	v_mfma_f32_16x16x32_bf16 v[84:87], v[168:171], v[210:213], v[84:87]
	v_mfma_f32_16x16x32_bf16 v[68:71], v[168:171], v[218:221], v[68:71]
	v_mfma_f32_16x16x32_bf16 v[68:71], v[172:175], v[222:225], v[68:71]
	v_mfma_f32_16x16x32_bf16 v[76:79], v[164:167], v[222:225], v[76:79]
	v_mfma_f32_16x16x32_bf16 v[76:79], v[160:163], v[218:221], v[76:79]
	v_mfma_f32_16x16x32_bf16 v[120:123], v[176:179], v[194:197], v[120:123]
	v_mfma_f32_16x16x32_bf16 v[120:123], v[180:183], v[198:201], v[120:123]
	v_mfma_f32_16x16x32_bf16 v[112:115], v[190:193], v[198:201], v[112:115]
	v_mfma_f32_16x16x32_bf16 v[112:115], v[186:189], v[194:197], v[112:115]
	v_mfma_f32_16x16x32_bf16 v[96:99], v[186:189], v[202:205], v[96:99]
	v_mfma_f32_16x16x32_bf16 v[96:99], v[190:193], v[206:209], v[96:99]
	v_mfma_f32_16x16x32_bf16 v[104:107], v[180:183], v[206:209], v[104:107]
	v_mfma_f32_16x16x32_bf16 v[104:107], v[176:179], v[202:205], v[104:107]
	v_mfma_f32_16x16x32_bf16 v[88:91], v[176:179], v[210:213], v[88:91]
	v_mfma_f32_16x16x32_bf16 v[88:91], v[180:183], v[214:217], v[88:91]
	v_mfma_f32_16x16x32_bf16 v[80:83], v[190:193], v[214:217], v[80:83]
	v_mfma_f32_16x16x32_bf16 v[80:83], v[186:189], v[210:213], v[80:83]
	v_mfma_f32_16x16x32_bf16 v[64:67], v[186:189], v[218:221], v[64:67]
	v_mfma_f32_16x16x32_bf16 v[64:67], v[190:193], v[222:225], v[64:67]
	v_mfma_f32_16x16x32_bf16 v[72:75], v[180:183], v[222:225], v[72:75]
	v_mfma_f32_16x16x32_bf16 v[72:75], v[176:179], v[218:221], v[72:75]
	s_barrier
	s_setprio 0
	s_add_i32 s76, s64, s52
	v_lshl_add_u64 v[154:155], s[46:47], 0, v[132:133]
	s_mov_b32 m0, s76
	ds_read_b128 v[194:197], v150 offset:16384
	v_xor_b32_e32 v253, 64, v150
	ds_read_b128 v[198:201], v253 offset:16384
	ds_read_b128 v[202:205], v150 offset:18432
	ds_read_b128 v[206:209], v253 offset:18432
	ds_read_b128 v[210:213], v150 offset:20480
	ds_read_b128 v[214:217], v253 offset:20480
	ds_read_b128 v[218:221], v150 offset:22528
	ds_read_b128 v[222:225], v253 offset:22528
	global_load_lds_dwordx4 v[154:155], off
	s_add_i32 m0, s76, 0x2000
	s_add_u32 s76, s46, 0x40000
	v_lshl_add_u64 v[226:227], s[46:47], 0, v[128:129]
	s_addc_u32 s77, s47, 0
	s_add_i32 s78, s65, s52
	global_load_lds_dwordx4 v[226:227], off
	v_lshl_add_u64 v[228:229], s[76:77], 0, v[132:133]
	s_mov_b32 m0, s78
	v_lshl_add_u64 v[230:231], s[48:49], 0, v[130:131]
	global_load_lds_dwordx4 v[228:229], off
	v_lshl_add_u64 v[228:229], s[76:77], 0, v[128:129]
	s_add_i32 m0, s78, 0x2000
	s_nop 0
	global_load_lds_dwordx4 v[228:229], off
	v_lshl_add_u64 v[228:229], s[48:49], 0, v[134:135]
	s_mov_b32 m0, s55
	s_nop 0
	global_load_lds_dwordx4 v[228:229], off
	s_mov_b32 m0, s56
	s_nop 0
	global_load_lds_dwordx4 v[230:231], off
	s_waitcnt vmcnt(8)
	s_waitcnt lgkmcnt(0)
	s_setprio 1
	s_barrier
	v_mfma_f32_16x16x32_bf16 v[60:63], v[160:163], v[194:197], v[60:63]
	v_mfma_f32_16x16x32_bf16 v[60:63], v[164:167], v[198:201], v[60:63]
	v_mfma_f32_16x16x32_bf16 v[52:55], v[172:175], v[198:201], v[52:55]
	v_mfma_f32_16x16x32_bf16 v[52:55], v[168:171], v[194:197], v[52:55]
	v_mfma_f32_16x16x32_bf16 v[36:39], v[168:171], v[202:205], v[36:39]
	v_mfma_f32_16x16x32_bf16 v[36:39], v[172:175], v[206:209], v[36:39]
	v_mfma_f32_16x16x32_bf16 v[44:47], v[164:167], v[206:209], v[44:47]
	v_mfma_f32_16x16x32_bf16 v[44:47], v[160:163], v[202:205], v[44:47]
	v_mfma_f32_16x16x32_bf16 v[28:31], v[160:163], v[210:213], v[28:31]
	v_mfma_f32_16x16x32_bf16 v[28:31], v[164:167], v[214:217], v[28:31]
	v_mfma_f32_16x16x32_bf16 v[20:23], v[172:175], v[214:217], v[20:23]
	v_mfma_f32_16x16x32_bf16 v[20:23], v[168:171], v[210:213], v[20:23]
	v_mfma_f32_16x16x32_bf16 v[4:7], v[168:171], v[218:221], v[4:7]
	v_mfma_f32_16x16x32_bf16 v[4:7], v[172:175], v[222:225], v[4:7]
	v_mfma_f32_16x16x32_bf16 v[12:15], v[164:167], v[222:225], v[12:15]
	v_mfma_f32_16x16x32_bf16 v[12:15], v[160:163], v[218:221], v[12:15]
	v_mfma_f32_16x16x32_bf16 v[56:59], v[176:179], v[194:197], v[56:59]
	v_mfma_f32_16x16x32_bf16 v[56:59], v[180:183], v[198:201], v[56:59]
	v_mfma_f32_16x16x32_bf16 v[48:51], v[190:193], v[198:201], v[48:51]
	v_mfma_f32_16x16x32_bf16 v[48:51], v[186:189], v[194:197], v[48:51]
	v_mfma_f32_16x16x32_bf16 v[32:35], v[186:189], v[202:205], v[32:35]
	v_mfma_f32_16x16x32_bf16 v[32:35], v[190:193], v[206:209], v[32:35]
	v_mfma_f32_16x16x32_bf16 v[40:43], v[180:183], v[206:209], v[40:43]
	v_mfma_f32_16x16x32_bf16 v[40:43], v[176:179], v[202:205], v[40:43]
	v_mfma_f32_16x16x32_bf16 v[24:27], v[176:179], v[210:213], v[24:27]
	v_mfma_f32_16x16x32_bf16 v[24:27], v[180:183], v[214:217], v[24:27]
	v_mfma_f32_16x16x32_bf16 v[16:19], v[190:193], v[214:217], v[16:19]
	v_mfma_f32_16x16x32_bf16 v[16:19], v[186:189], v[210:213], v[16:19]
	v_mfma_f32_16x16x32_bf16 v[0:3], v[186:189], v[218:221], v[0:3]
	v_mfma_f32_16x16x32_bf16 v[0:3], v[190:193], v[222:225], v[0:3]
	v_mfma_f32_16x16x32_bf16 v[8:11], v[180:183], v[222:225], v[8:11]
	v_mfma_f32_16x16x32_bf16 v[8:11], v[176:179], v[218:221], v[8:11]
	s_barrier
	s_setprio 0
	s_add_i32 s76, 0, 0x18000
	v_add_u32_e32 v153, s76, v147
	s_add_i32 s77, 0, 0x1c000
	ds_read_b128 v[160:163], v153
	v_xor_b32_e32 v253, 64, v153
	ds_read_b128 v[164:167], v253
	ds_read_b128 v[168:171], v153 offset:2048
	ds_read_b128 v[172:175], v253 offset:2048
	v_add_u32_e32 v153, s77, v147
	ds_read_b128 v[176:179], v153
	v_xor_b32_e32 v253, 64, v153
	ds_read_b128 v[180:183], v253
	ds_read_b128 v[186:189], v153 offset:2048
	ds_read_b128 v[190:193], v253 offset:2048
	s_add_u32 s48, s48, 0x40000
	s_addc_u32 s49, s49, 0
	s_mov_b32 m0, s57
	v_lshl_add_u64 v[232:233], s[48:49], 0, v[134:135]
	ds_read_b128 v[194:197], v150 offset:32768
	v_xor_b32_e32 v253, 64, v150
	ds_read_b128 v[198:201], v253 offset:32768
	ds_read_b128 v[202:205], v150 offset:34816
	ds_read_b128 v[206:209], v253 offset:34816
	ds_read_b128 v[210:213], v150 offset:36864
	ds_read_b128 v[214:217], v253 offset:36864
	ds_read_b128 v[218:221], v150 offset:38912
	ds_read_b128 v[222:225], v253 offset:38912
	global_load_lds_dwordx4 v[232:233], off
	v_lshl_add_u64 v[232:233], s[48:49], 0, v[130:131]
	s_mov_b32 m0, s58
	s_nop 0
	global_load_lds_dwordx4 v[232:233], off
	s_waitcnt vmcnt(8)
	s_waitcnt lgkmcnt(0)
	s_setprio 1
	s_barrier
	v_mfma_f32_16x16x32_bf16 v[124:127], v[160:163], v[194:197], v[124:127]
	v_mfma_f32_16x16x32_bf16 v[124:127], v[164:167], v[198:201], v[124:127]
	v_mfma_f32_16x16x32_bf16 v[116:119], v[172:175], v[198:201], v[116:119]
	v_mfma_f32_16x16x32_bf16 v[116:119], v[168:171], v[194:197], v[116:119]
	v_mfma_f32_16x16x32_bf16 v[100:103], v[168:171], v[202:205], v[100:103]
	v_mfma_f32_16x16x32_bf16 v[100:103], v[172:175], v[206:209], v[100:103]
	v_mfma_f32_16x16x32_bf16 v[108:111], v[164:167], v[206:209], v[108:111]
	v_mfma_f32_16x16x32_bf16 v[108:111], v[160:163], v[202:205], v[108:111]
	v_mfma_f32_16x16x32_bf16 v[92:95], v[160:163], v[210:213], v[92:95]
	v_mfma_f32_16x16x32_bf16 v[92:95], v[164:167], v[214:217], v[92:95]
	v_mfma_f32_16x16x32_bf16 v[84:87], v[172:175], v[214:217], v[84:87]
	v_mfma_f32_16x16x32_bf16 v[84:87], v[168:171], v[210:213], v[84:87]
	v_mfma_f32_16x16x32_bf16 v[68:71], v[168:171], v[218:221], v[68:71]
	v_mfma_f32_16x16x32_bf16 v[68:71], v[172:175], v[222:225], v[68:71]
	v_mfma_f32_16x16x32_bf16 v[76:79], v[164:167], v[222:225], v[76:79]
	v_mfma_f32_16x16x32_bf16 v[76:79], v[160:163], v[218:221], v[76:79]
	v_mfma_f32_16x16x32_bf16 v[120:123], v[176:179], v[194:197], v[120:123]
	v_mfma_f32_16x16x32_bf16 v[120:123], v[180:183], v[198:201], v[120:123]
	v_mfma_f32_16x16x32_bf16 v[112:115], v[190:193], v[198:201], v[112:115]
	v_mfma_f32_16x16x32_bf16 v[112:115], v[186:189], v[194:197], v[112:115]
	v_mfma_f32_16x16x32_bf16 v[96:99], v[186:189], v[202:205], v[96:99]
	v_mfma_f32_16x16x32_bf16 v[96:99], v[190:193], v[206:209], v[96:99]
	v_mfma_f32_16x16x32_bf16 v[104:107], v[180:183], v[206:209], v[104:107]
	v_mfma_f32_16x16x32_bf16 v[104:107], v[176:179], v[202:205], v[104:107]
	v_mfma_f32_16x16x32_bf16 v[88:91], v[176:179], v[210:213], v[88:91]
	v_mfma_f32_16x16x32_bf16 v[88:91], v[180:183], v[214:217], v[88:91]
	v_mfma_f32_16x16x32_bf16 v[80:83], v[190:193], v[214:217], v[80:83]
	v_mfma_f32_16x16x32_bf16 v[80:83], v[186:189], v[210:213], v[80:83]
	v_mfma_f32_16x16x32_bf16 v[64:67], v[186:189], v[218:221], v[64:67]
	v_mfma_f32_16x16x32_bf16 v[64:67], v[190:193], v[222:225], v[64:67]
	v_mfma_f32_16x16x32_bf16 v[72:75], v[180:183], v[222:225], v[72:75]
	v_mfma_f32_16x16x32_bf16 v[72:75], v[176:179], v[218:221], v[72:75]
	s_barrier
	s_setprio 0
	v_add_u32_e32 v234, 0x21000, v151
	ds_read_b128 v[236:239], v234
	ds_read_b128 v[240:243], v234 offset:256
	ds_read_b128 v[244:247], v234 offset:512
	ds_read_b128 v[248:251], v234 offset:768
	v_add_u32_e32 v235, s23, v146
	v_mul_u32_u24_e32 v235, 0x1600, v235
	v_lshl_or_b32 v234, s67, 7, v149
	v_lshl_add_u32 v235, v234, 1, v235
	s_add_i32 s48, s76, s52
	v_lshl_add_u64 v[154:155], v[154:155], 0, s[14:15]
	s_mov_b32 m0, s48
	ds_read_b128 v[194:197], v150 offset:49152
	v_xor_b32_e32 v253, 64, v150
	ds_read_b128 v[198:201], v253 offset:49152
	ds_read_b128 v[202:205], v150 offset:51200
	ds_read_b128 v[206:209], v253 offset:51200
	ds_read_b128 v[210:213], v150 offset:53248
	ds_read_b128 v[214:217], v253 offset:53248
	ds_read_b128 v[218:221], v150 offset:55296
	ds_read_b128 v[222:225], v253 offset:55296
	global_load_lds_dwordx4 v[154:155], off
	s_add_i32 m0, s48, 0x2000
	s_add_u32 s46, s46, 0x40080
	v_lshl_add_u64 v[154:155], v[226:227], 0, s[14:15]
	s_addc_u32 s47, s47, 0
	s_add_i32 s48, s77, s52
	global_load_lds_dwordx4 v[154:155], off
	v_lshl_add_u64 v[154:155], s[46:47], 0, v[132:133]
	s_mov_b32 m0, s48
	s_nop 0
	global_load_lds_dwordx4 v[154:155], off
	v_lshl_add_u64 v[154:155], s[46:47], 0, v[128:129]
	s_add_i32 m0, s48, 0x2000
	s_nop 0
	global_load_lds_dwordx4 v[154:155], off
	v_lshl_add_u64 v[154:155], v[228:229], 0, s[14:15]
	s_mov_b32 m0, s60
	s_nop 0
	global_load_lds_dwordx4 v[154:155], off
	v_lshl_add_u64 v[154:155], v[230:231], 0, s[14:15]
	s_mov_b32 m0, s61
	s_nop 0
	global_load_lds_dwordx4 v[154:155], off
	s_waitcnt lgkmcnt(8)
	v_add_f32_e32 v236, v236, v237
	v_add_f32_e32 v238, v238, v239
	v_add_f32_e32 v240, v240, v241
	v_add_f32_e32 v242, v242, v243
	v_add_f32_e32 v244, v244, v245
	v_add_f32_e32 v246, v246, v247
	v_add_f32_e32 v248, v248, v249
	v_add_f32_e32 v250, v250, v251
	v_add_f32_e32 v236, v236, v238
	v_add_f32_e32 v240, v240, v242
	v_add_f32_e32 v244, v244, v246
	v_add_f32_e32 v248, v248, v250
	v_fmamk_f32 v236, v236, 0x3a800000, v152
	v_fmamk_f32 v240, v240, 0x3a800000, v152
	v_fmamk_f32 v244, v244, 0x3a800000, v152
	v_fmamk_f32 v248, v248, 0x3a800000, v152
	v_rsq_f32_e32 v236, v236
	v_rsq_f32_e32 v240, v240
	v_rsq_f32_e32 v244, v244
	v_rsq_f32_e32 v248, v248
	v_mul_f32_e32 v252, 0xbfb8aa3b, v236
	v_mul_f32_e32 v254, v236, v236
	v_rcp_f32_e32 v254, v254
	v_pk_mul_f32 v[120:121], v[124:125], v[120:121]
	v_pk_mul_f32 v[122:123], v[126:127], v[122:123]
	v_pk_mul_f32 v[112:113], v[116:117], v[112:113]
	v_pk_mul_f32 v[114:115], v[118:119], v[114:115]
	v_pk_mul_f32 v[124:125], v[124:125], v[252:253] op_sel_hi:[1,0]
	v_pk_mul_f32 v[126:127], v[126:127], v[252:253] op_sel_hi:[1,0]
	v_pk_mul_f32 v[116:117], v[116:117], v[252:253] op_sel_hi:[1,0]
	v_pk_mul_f32 v[118:119], v[118:119], v[252:253] op_sel_hi:[1,0]
	v_exp_f32_e32 v124, v124
	v_exp_f32_e32 v125, v125
	v_exp_f32_e32 v126, v126
	v_exp_f32_e32 v127, v127
	v_exp_f32_e32 v116, v116
	v_exp_f32_e32 v117, v117
	v_exp_f32_e32 v118, v118
	v_exp_f32_e32 v119, v119
	v_pk_fma_f32 v[124:125], v[124:125], v[254:255], v[254:255] op_sel_hi:[1,0,0]
	v_pk_fma_f32 v[126:127], v[126:127], v[254:255], v[254:255] op_sel_hi:[1,0,0]
	v_pk_fma_f32 v[116:117], v[116:117], v[254:255], v[254:255] op_sel_hi:[1,0,0]
	v_pk_fma_f32 v[118:119], v[118:119], v[254:255], v[254:255] op_sel_hi:[1,0,0]
	v_rcp_f32_e32 v124, v124
	v_rcp_f32_e32 v125, v125
	v_rcp_f32_e32 v126, v126
	v_rcp_f32_e32 v127, v127
	v_rcp_f32_e32 v116, v116
	v_rcp_f32_e32 v117, v117
	v_rcp_f32_e32 v118, v118
	v_rcp_f32_e32 v119, v119
	v_pk_mul_f32 v[120:121], v[120:121], v[124:125]
	v_pk_mul_f32 v[122:123], v[122:123], v[126:127]
	v_pk_mul_f32 v[112:113], v[112:113], v[116:117]
	v_pk_mul_f32 v[114:115], v[114:115], v[118:119]
	v_cvt_pk_bf16_f32 v120, v120, v121
	v_cvt_pk_bf16_f32 v121, v122, v123
	v_cvt_pk_bf16_f32 v122, v112, v113
	v_cvt_pk_bf16_f32 v123, v114, v115
	global_store_dwordx4 v235, v[120:123], s[10:11]
	v_add_u32_e32 v234, 0x16000, v235
	v_mul_f32_e32 v252, 0xbfb8aa3b, v240
	v_mul_f32_e32 v254, v240, v240
	v_rcp_f32_e32 v254, v254
	v_pk_mul_f32 v[104:105], v[108:109], v[104:105]
	v_pk_mul_f32 v[106:107], v[110:111], v[106:107]
	v_pk_mul_f32 v[96:97], v[100:101], v[96:97]
	v_pk_mul_f32 v[98:99], v[102:103], v[98:99]
	v_pk_mul_f32 v[108:109], v[108:109], v[252:253] op_sel_hi:[1,0]
	v_pk_mul_f32 v[110:111], v[110:111], v[252:253] op_sel_hi:[1,0]
	v_pk_mul_f32 v[100:101], v[100:101], v[252:253] op_sel_hi:[1,0]
	v_pk_mul_f32 v[102:103], v[102:103], v[252:253] op_sel_hi:[1,0]
	v_exp_f32_e32 v108, v108
	v_exp_f32_e32 v109, v109
	v_exp_f32_e32 v110, v110
	v_exp_f32_e32 v111, v111
	v_exp_f32_e32 v100, v100
	v_exp_f32_e32 v101, v101
	v_exp_f32_e32 v102, v102
	v_exp_f32_e32 v103, v103
	v_pk_fma_f32 v[108:109], v[108:109], v[254:255], v[254:255] op_sel_hi:[1,0,0]
	v_pk_fma_f32 v[110:111], v[110:111], v[254:255], v[254:255] op_sel_hi:[1,0,0]
	v_pk_fma_f32 v[100:101], v[100:101], v[254:255], v[254:255] op_sel_hi:[1,0,0]
	v_pk_fma_f32 v[102:103], v[102:103], v[254:255], v[254:255] op_sel_hi:[1,0,0]
	v_rcp_f32_e32 v108, v108
	v_rcp_f32_e32 v109, v109
	v_rcp_f32_e32 v110, v110
	v_rcp_f32_e32 v111, v111
	v_rcp_f32_e32 v100, v100
	v_rcp_f32_e32 v101, v101
	v_rcp_f32_e32 v102, v102
	v_rcp_f32_e32 v103, v103
	v_pk_mul_f32 v[104:105], v[104:105], v[108:109]
	v_pk_mul_f32 v[106:107], v[106:107], v[110:111]
	v_pk_mul_f32 v[96:97], v[96:97], v[100:101]
	v_pk_mul_f32 v[98:99], v[98:99], v[102:103]
	v_cvt_pk_bf16_f32 v104, v104, v105
	v_cvt_pk_bf16_f32 v105, v106, v107
	v_cvt_pk_bf16_f32 v106, v96, v97
	v_cvt_pk_bf16_f32 v107, v98, v99
	global_store_dwordx4 v234, v[104:107], s[10:11]
	v_add_u32_e32 v235, 0x16000, v234
	v_mul_f32_e32 v252, 0xbfb8aa3b, v244
	v_mul_f32_e32 v254, v244, v244
	v_rcp_f32_e32 v254, v254
	v_pk_mul_f32 v[88:89], v[92:93], v[88:89]
	v_pk_mul_f32 v[90:91], v[94:95], v[90:91]
	v_pk_mul_f32 v[80:81], v[84:85], v[80:81]
	v_pk_mul_f32 v[82:83], v[86:87], v[82:83]
	v_pk_mul_f32 v[92:93], v[92:93], v[252:253] op_sel_hi:[1,0]
	v_pk_mul_f32 v[94:95], v[94:95], v[252:253] op_sel_hi:[1,0]
	v_pk_mul_f32 v[84:85], v[84:85], v[252:253] op_sel_hi:[1,0]
	v_pk_mul_f32 v[86:87], v[86:87], v[252:253] op_sel_hi:[1,0]
	v_exp_f32_e32 v92, v92
	v_exp_f32_e32 v93, v93
	v_exp_f32_e32 v94, v94
	v_exp_f32_e32 v95, v95
	v_exp_f32_e32 v84, v84
	v_exp_f32_e32 v85, v85
	v_exp_f32_e32 v86, v86
	v_exp_f32_e32 v87, v87
	v_pk_fma_f32 v[92:93], v[92:93], v[254:255], v[254:255] op_sel_hi:[1,0,0]
	v_pk_fma_f32 v[94:95], v[94:95], v[254:255], v[254:255] op_sel_hi:[1,0,0]
	v_pk_fma_f32 v[84:85], v[84:85], v[254:255], v[254:255] op_sel_hi:[1,0,0]
	v_pk_fma_f32 v[86:87], v[86:87], v[254:255], v[254:255] op_sel_hi:[1,0,0]
	v_rcp_f32_e32 v92, v92
	v_rcp_f32_e32 v93, v93
	v_rcp_f32_e32 v94, v94
	v_rcp_f32_e32 v95, v95
	v_rcp_f32_e32 v84, v84
	v_rcp_f32_e32 v85, v85
	v_rcp_f32_e32 v86, v86
	v_rcp_f32_e32 v87, v87
	v_pk_mul_f32 v[88:89], v[88:89], v[92:93]
	v_pk_mul_f32 v[90:91], v[90:91], v[94:95]
	v_pk_mul_f32 v[80:81], v[80:81], v[84:85]
	v_pk_mul_f32 v[82:83], v[82:83], v[86:87]
	v_cvt_pk_bf16_f32 v88, v88, v89
	v_cvt_pk_bf16_f32 v89, v90, v91
	v_cvt_pk_bf16_f32 v90, v80, v81
	v_cvt_pk_bf16_f32 v91, v82, v83
	global_store_dwordx4 v235, v[88:91], s[10:11]
	v_add_u32_e32 v234, 0x16000, v235
	v_mul_f32_e32 v252, 0xbfb8aa3b, v248
	v_mul_f32_e32 v254, v248, v248
	v_rcp_f32_e32 v254, v254
	v_pk_mul_f32 v[72:73], v[76:77], v[72:73]
	v_pk_mul_f32 v[74:75], v[78:79], v[74:75]
	v_pk_mul_f32 v[64:65], v[68:69], v[64:65]
	v_pk_mul_f32 v[66:67], v[70:71], v[66:67]
	v_pk_mul_f32 v[76:77], v[76:77], v[252:253] op_sel_hi:[1,0]
	v_pk_mul_f32 v[78:79], v[78:79], v[252:253] op_sel_hi:[1,0]
	v_pk_mul_f32 v[68:69], v[68:69], v[252:253] op_sel_hi:[1,0]
	v_pk_mul_f32 v[70:71], v[70:71], v[252:253] op_sel_hi:[1,0]
	v_exp_f32_e32 v76, v76
	v_exp_f32_e32 v77, v77
	v_exp_f32_e32 v78, v78
	v_exp_f32_e32 v79, v79
	v_exp_f32_e32 v68, v68
	v_exp_f32_e32 v69, v69
	v_exp_f32_e32 v70, v70
	v_exp_f32_e32 v71, v71
	v_pk_fma_f32 v[76:77], v[76:77], v[254:255], v[254:255] op_sel_hi:[1,0,0]
	v_pk_fma_f32 v[78:79], v[78:79], v[254:255], v[254:255] op_sel_hi:[1,0,0]
	v_pk_fma_f32 v[68:69], v[68:69], v[254:255], v[254:255] op_sel_hi:[1,0,0]
	v_pk_fma_f32 v[70:71], v[70:71], v[254:255], v[254:255] op_sel_hi:[1,0,0]
	v_rcp_f32_e32 v76, v76
	v_rcp_f32_e32 v77, v77
	v_rcp_f32_e32 v78, v78
	v_rcp_f32_e32 v79, v79
	v_rcp_f32_e32 v68, v68
	v_rcp_f32_e32 v69, v69
	v_rcp_f32_e32 v70, v70
	v_rcp_f32_e32 v71, v71
	v_pk_mul_f32 v[72:73], v[72:73], v[76:77]
	v_pk_mul_f32 v[74:75], v[74:75], v[78:79]
	v_pk_mul_f32 v[64:65], v[64:65], v[68:69]
	v_pk_mul_f32 v[66:67], v[66:67], v[70:71]
	v_cvt_pk_bf16_f32 v72, v72, v73
	v_cvt_pk_bf16_f32 v73, v74, v75
	v_cvt_pk_bf16_f32 v74, v64, v65
	v_cvt_pk_bf16_f32 v75, v66, v67
	global_store_dwordx4 v234, v[72:75], s[10:11]
	s_waitcnt vmcnt(12)
	s_waitcnt lgkmcnt(0)
	s_setprio 1
	s_barrier
	v_mfma_f32_16x16x32_bf16 v[60:63], v[160:163], v[194:197], v[60:63]
	v_mfma_f32_16x16x32_bf16 v[60:63], v[164:167], v[198:201], v[60:63]
	v_mfma_f32_16x16x32_bf16 v[52:55], v[172:175], v[198:201], v[52:55]
	v_mfma_f32_16x16x32_bf16 v[52:55], v[168:171], v[194:197], v[52:55]
	v_mfma_f32_16x16x32_bf16 v[36:39], v[168:171], v[202:205], v[36:39]
	v_mfma_f32_16x16x32_bf16 v[36:39], v[172:175], v[206:209], v[36:39]
	v_mfma_f32_16x16x32_bf16 v[44:47], v[164:167], v[206:209], v[44:47]
	v_mfma_f32_16x16x32_bf16 v[44:47], v[160:163], v[202:205], v[44:47]
	v_mfma_f32_16x16x32_bf16 v[28:31], v[160:163], v[210:213], v[28:31]
	v_mfma_f32_16x16x32_bf16 v[28:31], v[164:167], v[214:217], v[28:31]
	v_mfma_f32_16x16x32_bf16 v[20:23], v[172:175], v[214:217], v[20:23]
	v_mfma_f32_16x16x32_bf16 v[20:23], v[168:171], v[210:213], v[20:23]
	v_mfma_f32_16x16x32_bf16 v[4:7], v[168:171], v[218:221], v[4:7]
	v_mfma_f32_16x16x32_bf16 v[4:7], v[172:175], v[222:225], v[4:7]
	v_mfma_f32_16x16x32_bf16 v[12:15], v[164:167], v[222:225], v[12:15]
	v_mfma_f32_16x16x32_bf16 v[12:15], v[160:163], v[218:221], v[12:15]
	v_mfma_f32_16x16x32_bf16 v[56:59], v[176:179], v[194:197], v[56:59]
	v_mfma_f32_16x16x32_bf16 v[56:59], v[180:183], v[198:201], v[56:59]
	v_mfma_f32_16x16x32_bf16 v[48:51], v[190:193], v[198:201], v[48:51]
	v_mfma_f32_16x16x32_bf16 v[48:51], v[186:189], v[194:197], v[48:51]
	v_mfma_f32_16x16x32_bf16 v[32:35], v[186:189], v[202:205], v[32:35]
	v_mfma_f32_16x16x32_bf16 v[32:35], v[190:193], v[206:209], v[32:35]
	v_mfma_f32_16x16x32_bf16 v[40:43], v[180:183], v[206:209], v[40:43]
	v_mfma_f32_16x16x32_bf16 v[40:43], v[176:179], v[202:205], v[40:43]
	v_mfma_f32_16x16x32_bf16 v[24:27], v[176:179], v[210:213], v[24:27]
	v_mfma_f32_16x16x32_bf16 v[24:27], v[180:183], v[214:217], v[24:27]
	v_mfma_f32_16x16x32_bf16 v[16:19], v[190:193], v[214:217], v[16:19]
	v_mfma_f32_16x16x32_bf16 v[16:19], v[186:189], v[210:213], v[16:19]
	v_mfma_f32_16x16x32_bf16 v[0:3], v[186:189], v[218:221], v[0:3]
	v_mfma_f32_16x16x32_bf16 v[0:3], v[190:193], v[222:225], v[0:3]
	v_mfma_f32_16x16x32_bf16 v[8:11], v[180:183], v[222:225], v[8:11]
	v_mfma_f32_16x16x32_bf16 v[8:11], v[176:179], v[218:221], v[8:11]
	s_barrier
	s_setprio 0
	s_add_i32 s75, s75, 2
	s_add_u32 s71, s71, 0x100
	s_addc_u32 s74, s74, 0
	s_add_u32 s44, s44, 0x100
	s_addc_u32 s45, s45, 0

.LBB0_158:
	s_add_u32 s81, s56, 0x100
	s_addc_u32 s82, s57, 0
	s_mov_b32 s83, -2
	s_waitcnt lgkmcnt(0)
	s_cmp_eq_u32 s70, 1
	s_cbranch_scc1 .Lfa_1
	ds_read_b128 v[128:131], v189
	v_xor_b32_e32 v253, 64, v189
	ds_read_b128 v[132:135], v253
	ds_read_b128 v[136:139], v189 offset:2048
	ds_read_b128 v[140:143], v253 offset:2048
	ds_read_b128 v[144:147], v190
	v_xor_b32_e32 v253, 64, v190
	ds_read_b128 v[148:151], v253
	ds_read_b128 v[172:175], v190 offset:2048
	ds_read_b128 v[176:179], v253 offset:2048
	s_add_u32 s56, s54, 0x100
	s_addc_u32 s57, s55, 0
	s_cmp_eq_u32 s83, 40
	s_cselect_b32 s61, s15, s57
	s_cselect_b32 s60, s14, s56
	s_cselect_b32 s59, s53, s82
	s_cselect_b32 s58, s52, s81
	v_lshl_add_u64 v[222:223], s[54:55], 0, v[166:167]
	s_add_i32 m0, s66, 0xc000
	ds_read_b128 v[180:183], v191
	v_xor_b32_e32 v253, 64, v191
	ds_read_b128 v[194:197], v253
	ds_read_b128 v[198:201], v191 offset:2048
	ds_read_b128 v[202:205], v253 offset:2048
	ds_read_b128 v[206:209], v191 offset:4096
	ds_read_b128 v[210:213], v253 offset:4096
	ds_read_b128 v[214:217], v191 offset:6144
	ds_read_b128 v[218:221], v253 offset:6144
	global_load_lds_dwordx4 v[222:223], off
	v_lshl_add_u64 v[222:223], s[54:55], 0, v[164:165]
	s_add_i32 m0, s66, 0xe000
	s_nop 0
	global_load_lds_dwordx4 v[222:223], off
	s_waitcnt vmcnt(24)
	s_waitcnt lgkmcnt(0)
	s_setprio 1
	s_barrier
	v_mfma_f32_16x16x32_bf16 v[124:127], v[128:131], v[180:183], 0
	v_mfma_f32_16x16x32_bf16 v[120:123], v[136:139], v[180:183], 0
	v_mfma_f32_16x16x32_bf16 v[108:111], v[128:131], v[198:201], 0
	v_mfma_f32_16x16x32_bf16 v[104:107], v[136:139], v[198:201], 0
	v_mfma_f32_16x16x32_bf16 v[92:95], v[128:131], v[206:209], 0
	v_mfma_f32_16x16x32_bf16 v[88:91], v[136:139], v[206:209], 0
	v_mfma_f32_16x16x32_bf16 v[76:79], v[128:131], v[214:217], 0
	v_mfma_f32_16x16x32_bf16 v[72:75], v[136:139], v[214:217], 0
	v_mfma_f32_16x16x32_bf16 v[124:127], v[132:135], v[194:197], v[124:127]
	v_mfma_f32_16x16x32_bf16 v[120:123], v[140:143], v[194:197], v[120:123]
	v_mfma_f32_16x16x32_bf16 v[108:111], v[132:135], v[202:205], v[108:111]
	v_mfma_f32_16x16x32_bf16 v[104:107], v[140:143], v[202:205], v[104:107]
	v_mfma_f32_16x16x32_bf16 v[92:95], v[132:135], v[210:213], v[92:95]
	v_mfma_f32_16x16x32_bf16 v[88:91], v[140:143], v[210:213], v[88:91]
	v_mfma_f32_16x16x32_bf16 v[76:79], v[132:135], v[218:221], v[76:79]
	v_mfma_f32_16x16x32_bf16 v[72:75], v[140:143], v[218:221], v[72:75]
	v_mfma_f32_16x16x32_bf16 v[116:119], v[144:147], v[180:183], 0
	v_mfma_f32_16x16x32_bf16 v[112:115], v[172:175], v[180:183], 0
	v_mfma_f32_16x16x32_bf16 v[100:103], v[144:147], v[198:201], 0
	v_mfma_f32_16x16x32_bf16 v[96:99], v[172:175], v[198:201], 0
	v_mfma_f32_16x16x32_bf16 v[84:87], v[144:147], v[206:209], 0
	v_mfma_f32_16x16x32_bf16 v[80:83], v[172:175], v[206:209], 0
	v_mfma_f32_16x16x32_bf16 v[68:71], v[144:147], v[214:217], 0
	v_mfma_f32_16x16x32_bf16 v[64:67], v[172:175], v[214:217], 0
	v_mfma_f32_16x16x32_bf16 v[116:119], v[148:151], v[194:197], v[116:119]
	v_mfma_f32_16x16x32_bf16 v[112:115], v[176:179], v[194:197], v[112:115]
	v_mfma_f32_16x16x32_bf16 v[100:103], v[148:151], v[202:205], v[100:103]
	v_mfma_f32_16x16x32_bf16 v[96:99], v[176:179], v[202:205], v[96:99]
	v_mfma_f32_16x16x32_bf16 v[84:87], v[148:151], v[210:213], v[84:87]
	v_mfma_f32_16x16x32_bf16 v[80:83], v[176:179], v[210:213], v[80:83]
	v_mfma_f32_16x16x32_bf16 v[68:71], v[148:151], v[218:221], v[68:71]
	v_mfma_f32_16x16x32_bf16 v[64:67], v[176:179], v[218:221], v[64:67]
	s_barrier
	s_setprio 0
	s_add_i32 s54, s77, s65
	v_lshl_add_u64 v[222:223], s[58:59], 0, v[154:155]
	s_mov_b32 m0, s54
	ds_read_b128 v[180:183], v191 offset:16384
	v_xor_b32_e32 v253, 64, v191
	ds_read_b128 v[194:197], v253 offset:16384
	ds_read_b128 v[198:201], v191 offset:18432
	ds_read_b128 v[202:205], v253 offset:18432
	ds_read_b128 v[206:209], v191 offset:20480
	ds_read_b128 v[210:213], v253 offset:20480
	ds_read_b128 v[214:217], v191 offset:22528
	ds_read_b128 v[218:221], v253 offset:22528
	global_load_lds_dwordx4 v[222:223], off
	s_add_i32 m0, s54, 0x2000
	s_add_u32 s54, s58, 0xb0000
	v_lshl_add_u64 v[224:225], s[58:59], 0, v[162:163]
	s_addc_u32 s55, s59, 0
	s_add_i32 s84, s78, s65
	global_load_lds_dwordx4 v[224:225], off
	v_lshl_add_u64 v[226:227], s[54:55], 0, v[154:155]
	s_mov_b32 m0, s84
	v_lshl_add_u64 v[228:229], s[60:61], 0, v[160:161]
	global_load_lds_dwordx4 v[226:227], off
	v_lshl_add_u64 v[226:227], s[54:55], 0, v[162:163]
	s_add_i32 m0, s84, 0x2000
	s_nop 0
	global_load_lds_dwordx4 v[226:227], off
	v_lshl_add_u64 v[226:227], s[60:61], 0, v[152:153]
	s_mov_b32 m0, s66
	s_nop 0
	global_load_lds_dwordx4 v[226:227], off
	s_mov_b32 m0, s67
	s_nop 0
	global_load_lds_dwordx4 v[228:229], off
	s_waitcnt vmcnt(24)
	s_waitcnt lgkmcnt(0)
	s_setprio 1
	s_barrier
	v_mfma_f32_16x16x32_bf16 v[60:63], v[128:131], v[180:183], 0
	v_mfma_f32_16x16x32_bf16 v[56:59], v[136:139], v[180:183], 0
	v_mfma_f32_16x16x32_bf16 v[44:47], v[128:131], v[198:201], 0
	v_mfma_f32_16x16x32_bf16 v[40:43], v[136:139], v[198:201], 0
	v_mfma_f32_16x16x32_bf16 v[28:31], v[128:131], v[206:209], 0
	v_mfma_f32_16x16x32_bf16 v[24:27], v[136:139], v[206:209], 0
	v_mfma_f32_16x16x32_bf16 v[12:15], v[128:131], v[214:217], 0
	v_mfma_f32_16x16x32_bf16 v[8:11], v[136:139], v[214:217], 0
	v_mfma_f32_16x16x32_bf16 v[60:63], v[132:135], v[194:197], v[60:63]
	v_mfma_f32_16x16x32_bf16 v[56:59], v[140:143], v[194:197], v[56:59]
	v_mfma_f32_16x16x32_bf16 v[44:47], v[132:135], v[202:205], v[44:47]
	v_mfma_f32_16x16x32_bf16 v[40:43], v[140:143], v[202:205], v[40:43]
	v_mfma_f32_16x16x32_bf16 v[28:31], v[132:135], v[210:213], v[28:31]
	v_mfma_f32_16x16x32_bf16 v[24:27], v[140:143], v[210:213], v[24:27]
	v_mfma_f32_16x16x32_bf16 v[12:15], v[132:135], v[218:221], v[12:15]
	v_mfma_f32_16x16x32_bf16 v[8:11], v[140:143], v[218:221], v[8:11]
	v_mfma_f32_16x16x32_bf16 v[52:55], v[144:147], v[180:183], 0
	v_mfma_f32_16x16x32_bf16 v[48:51], v[172:175], v[180:183], 0
	v_mfma_f32_16x16x32_bf16 v[36:39], v[144:147], v[198:201], 0
	v_mfma_f32_16x16x32_bf16 v[32:35], v[172:175], v[198:201], 0
	v_mfma_f32_16x16x32_bf16 v[20:23], v[144:147], v[206:209], 0
	v_mfma_f32_16x16x32_bf16 v[16:19], v[172:175], v[206:209], 0
	v_mfma_f32_16x16x32_bf16 v[4:7], v[144:147], v[214:217], 0
	v_mfma_f32_16x16x32_bf16 v[0:3], v[172:175], v[214:217], 0
	v_mfma_f32_16x16x32_bf16 v[52:55], v[148:151], v[194:197], v[52:55]
	v_mfma_f32_16x16x32_bf16 v[48:51], v[176:179], v[194:197], v[48:51]
	v_mfma_f32_16x16x32_bf16 v[36:39], v[148:151], v[202:205], v[36:39]
	v_mfma_f32_16x16x32_bf16 v[32:35], v[176:179], v[202:205], v[32:35]
	v_mfma_f32_16x16x32_bf16 v[20:23], v[148:151], v[210:213], v[20:23]
	v_mfma_f32_16x16x32_bf16 v[16:19], v[176:179], v[210:213], v[16:19]
	v_mfma_f32_16x16x32_bf16 v[4:7], v[148:151], v[218:221], v[4:7]
	v_mfma_f32_16x16x32_bf16 v[0:3], v[176:179], v[218:221], v[0:3]
	s_barrier
	s_setprio 0
	s_add_i32 s84, 0, 0x18000
	s_add_i32 s85, 0, 0x1c000
	v_add_u32_e32 v140, s84, v186
	v_add_u32_e32 v176, s85, v186
	ds_read_b128 v[128:131], v140
	v_xor_b32_e32 v253, 64, v140
	ds_read_b128 v[132:135], v253
	ds_read_b128 v[136:139], v140 offset:2048
	ds_read_b128 v[140:143], v253 offset:2048
	ds_read_b128 v[144:147], v176
	v_xor_b32_e32 v253, 64, v176
	ds_read_b128 v[148:151], v253
	ds_read_b128 v[172:175], v176 offset:2048
	ds_read_b128 v[176:179], v253 offset:2048
	s_add_u32 s54, s60, 0xb0000
	s_addc_u32 s55, s61, 0
	s_mov_b32 m0, s68
	v_lshl_add_u64 v[230:231], s[54:55], 0, v[152:153]
	ds_read_b128 v[180:183], v191 offset:32768
	v_xor_b32_e32 v253, 64, v191
	ds_read_b128 v[194:197], v253 offset:32768
	ds_read_b128 v[198:201], v191 offset:34816
	ds_read_b128 v[202:205], v253 offset:34816
	ds_read_b128 v[206:209], v191 offset:36864
	ds_read_b128 v[210:213], v253 offset:36864
	ds_read_b128 v[214:217], v191 offset:38912
	ds_read_b128 v[218:221], v253 offset:38912
	global_load_lds_dwordx4 v[230:231], off
	v_lshl_add_u64 v[230:231], s[54:55], 0, v[160:161]
	s_mov_b32 m0, s69
	s_nop 0
	global_load_lds_dwordx4 v[230:231], off
	s_waitcnt vmcnt(8)
	s_waitcnt lgkmcnt(0)
	s_setprio 1
	s_barrier
	v_mfma_f32_16x16x32_bf16 v[124:127], v[128:131], v[180:183], v[124:127]
	v_mfma_f32_16x16x32_bf16 v[124:127], v[132:135], v[194:197], v[124:127]
	v_mfma_f32_16x16x32_bf16 v[120:123], v[140:143], v[194:197], v[120:123]
	v_mfma_f32_16x16x32_bf16 v[120:123], v[136:139], v[180:183], v[120:123]
	v_mfma_f32_16x16x32_bf16 v[104:107], v[136:139], v[198:201], v[104:107]
	v_mfma_f32_16x16x32_bf16 v[104:107], v[140:143], v[202:205], v[104:107]
	v_mfma_f32_16x16x32_bf16 v[108:111], v[132:135], v[202:205], v[108:111]
	v_mfma_f32_16x16x32_bf16 v[108:111], v[128:131], v[198:201], v[108:111]
	v_mfma_f32_16x16x32_bf16 v[92:95], v[128:131], v[206:209], v[92:95]
	v_mfma_f32_16x16x32_bf16 v[92:95], v[132:135], v[210:213], v[92:95]
	v_mfma_f32_16x16x32_bf16 v[88:91], v[140:143], v[210:213], v[88:91]
	v_mfma_f32_16x16x32_bf16 v[88:91], v[136:139], v[206:209], v[88:91]
	v_mfma_f32_16x16x32_bf16 v[72:75], v[136:139], v[214:217], v[72:75]
	v_mfma_f32_16x16x32_bf16 v[72:75], v[140:143], v[218:221], v[72:75]
	v_mfma_f32_16x16x32_bf16 v[76:79], v[132:135], v[218:221], v[76:79]
	v_mfma_f32_16x16x32_bf16 v[76:79], v[128:131], v[214:217], v[76:79]
	v_mfma_f32_16x16x32_bf16 v[116:119], v[144:147], v[180:183], v[116:119]
	v_mfma_f32_16x16x32_bf16 v[116:119], v[148:151], v[194:197], v[116:119]
	v_mfma_f32_16x16x32_bf16 v[112:115], v[176:179], v[194:197], v[112:115]
	v_mfma_f32_16x16x32_bf16 v[112:115], v[172:175], v[180:183], v[112:115]
	v_mfma_f32_16x16x32_bf16 v[96:99], v[172:175], v[198:201], v[96:99]
	v_mfma_f32_16x16x32_bf16 v[96:99], v[176:179], v[202:205], v[96:99]
	v_mfma_f32_16x16x32_bf16 v[100:103], v[148:151], v[202:205], v[100:103]
	v_mfma_f32_16x16x32_bf16 v[100:103], v[144:147], v[198:201], v[100:103]
	v_mfma_f32_16x16x32_bf16 v[84:87], v[144:147], v[206:209], v[84:87]
	v_mfma_f32_16x16x32_bf16 v[84:87], v[148:151], v[210:213], v[84:87]
	v_mfma_f32_16x16x32_bf16 v[80:83], v[176:179], v[210:213], v[80:83]
	v_mfma_f32_16x16x32_bf16 v[80:83], v[172:175], v[206:209], v[80:83]
	v_mfma_f32_16x16x32_bf16 v[64:67], v[172:175], v[214:217], v[64:67]
	v_mfma_f32_16x16x32_bf16 v[64:67], v[176:179], v[218:221], v[64:67]
	v_mfma_f32_16x16x32_bf16 v[68:71], v[148:151], v[218:221], v[68:71]
	v_mfma_f32_16x16x32_bf16 v[68:71], v[144:147], v[214:217], v[68:71]
	s_barrier
	s_setprio 0
	s_add_i32 s54, s84, s65
	v_lshl_add_u64 v[222:223], v[222:223], 0, s[28:29]
	s_mov_b32 m0, s54
	ds_read_b128 v[180:183], v191 offset:49152
	v_xor_b32_e32 v253, 64, v191
	ds_read_b128 v[194:197], v253 offset:49152
	ds_read_b128 v[198:201], v191 offset:51200
	ds_read_b128 v[202:205], v253 offset:51200
	ds_read_b128 v[206:209], v191 offset:53248
	ds_read_b128 v[210:213], v253 offset:53248
	ds_read_b128 v[214:217], v191 offset:55296
	ds_read_b128 v[218:221], v253 offset:55296
	global_load_lds_dwordx4 v[222:223], off
	s_add_i32 m0, s54, 0x2000
	s_add_u32 s54, s58, 0xb0080
	v_lshl_add_u64 v[222:223], v[224:225], 0, s[28:29]
	s_addc_u32 s55, s59, 0
	s_add_i32 s58, s85, s65
	global_load_lds_dwordx4 v[222:223], off
	v_lshl_add_u64 v[222:223], s[54:55], 0, v[154:155]
	s_mov_b32 m0, s58
	s_nop 0
	global_load_lds_dwordx4 v[222:223], off
	v_lshl_add_u64 v[222:223], s[54:55], 0, v[162:163]
	s_add_i32 m0, s58, 0x2000
	s_nop 0
	global_load_lds_dwordx4 v[222:223], off
	v_lshl_add_u64 v[222:223], v[226:227], 0, s[28:29]
	s_mov_b32 m0, s3
	s_nop 0
	global_load_lds_dwordx4 v[222:223], off
	v_lshl_add_u64 v[222:223], v[228:229], 0, s[28:29]
	s_mov_b32 m0, s71
	s_nop 0
	global_load_lds_dwordx4 v[222:223], off
	s_waitcnt vmcnt(8)
	s_waitcnt lgkmcnt(0)
	s_setprio 1
	s_barrier
	v_mfma_f32_16x16x32_bf16 v[60:63], v[128:131], v[180:183], v[60:63]
	v_mfma_f32_16x16x32_bf16 v[60:63], v[132:135], v[194:197], v[60:63]
	v_mfma_f32_16x16x32_bf16 v[56:59], v[140:143], v[194:197], v[56:59]
	v_mfma_f32_16x16x32_bf16 v[56:59], v[136:139], v[180:183], v[56:59]
	v_mfma_f32_16x16x32_bf16 v[40:43], v[136:139], v[198:201], v[40:43]
	v_mfma_f32_16x16x32_bf16 v[40:43], v[140:143], v[202:205], v[40:43]
	v_mfma_f32_16x16x32_bf16 v[44:47], v[132:135], v[202:205], v[44:47]
	v_mfma_f32_16x16x32_bf16 v[44:47], v[128:131], v[198:201], v[44:47]
	v_mfma_f32_16x16x32_bf16 v[28:31], v[128:131], v[206:209], v[28:31]
	v_mfma_f32_16x16x32_bf16 v[28:31], v[132:135], v[210:213], v[28:31]
	v_mfma_f32_16x16x32_bf16 v[24:27], v[140:143], v[210:213], v[24:27]
	v_mfma_f32_16x16x32_bf16 v[24:27], v[136:139], v[206:209], v[24:27]
	v_mfma_f32_16x16x32_bf16 v[8:11], v[136:139], v[214:217], v[8:11]
	v_mfma_f32_16x16x32_bf16 v[8:11], v[140:143], v[218:221], v[8:11]
	v_mfma_f32_16x16x32_bf16 v[12:15], v[132:135], v[218:221], v[12:15]
	v_mfma_f32_16x16x32_bf16 v[12:15], v[128:131], v[214:217], v[12:15]
	v_mfma_f32_16x16x32_bf16 v[52:55], v[144:147], v[180:183], v[52:55]
	v_mfma_f32_16x16x32_bf16 v[52:55], v[148:151], v[194:197], v[52:55]
	v_mfma_f32_16x16x32_bf16 v[48:51], v[176:179], v[194:197], v[48:51]
	v_mfma_f32_16x16x32_bf16 v[48:51], v[172:175], v[180:183], v[48:51]
	v_mfma_f32_16x16x32_bf16 v[32:35], v[172:175], v[198:201], v[32:35]
	v_mfma_f32_16x16x32_bf16 v[32:35], v[176:179], v[202:205], v[32:35]
	v_mfma_f32_16x16x32_bf16 v[36:39], v[148:151], v[202:205], v[36:39]
	v_mfma_f32_16x16x32_bf16 v[36:39], v[144:147], v[198:201], v[36:39]
	v_mfma_f32_16x16x32_bf16 v[20:23], v[144:147], v[206:209], v[20:23]
	v_mfma_f32_16x16x32_bf16 v[20:23], v[148:151], v[210:213], v[20:23]
	v_mfma_f32_16x16x32_bf16 v[16:19], v[176:179], v[210:213], v[16:19]
	v_mfma_f32_16x16x32_bf16 v[16:19], v[172:175], v[206:209], v[16:19]
	v_mfma_f32_16x16x32_bf16 v[0:3], v[172:175], v[214:217], v[0:3]
	v_mfma_f32_16x16x32_bf16 v[0:3], v[176:179], v[218:221], v[0:3]
	v_mfma_f32_16x16x32_bf16 v[4:7], v[148:151], v[218:221], v[4:7]
	v_mfma_f32_16x16x32_bf16 v[4:7], v[144:147], v[214:217], v[4:7]
	s_barrier
	s_setprio 0
	s_add_i32 s83, s83, 2
	s_add_u32 s81, s81, 0x100
	s_addc_u32 s82, s82, 0
	s_cmp_gt_u32 s83, 41
	s_mov_b64 s[54:55], s[56:57]
	s_branch .LBB0_159
.Lfa_1:
	ds_read_b128 v[128:131], v189
	v_xor_b32_e32 v253, 64, v189
	ds_read_b128 v[132:135], v253
	ds_read_b128 v[136:139], v189 offset:2048
	ds_read_b128 v[140:143], v253 offset:2048
	ds_read_b128 v[144:147], v190
	v_xor_b32_e32 v253, 64, v190
	ds_read_b128 v[148:151], v253
	ds_read_b128 v[172:175], v190 offset:2048
	ds_read_b128 v[176:179], v253 offset:2048
	s_add_u32 s56, s54, 0x100
	s_addc_u32 s57, s55, 0
	s_cmp_eq_u32 s83, 40
	s_cselect_b32 s61, s15, s57
	s_cselect_b32 s60, s14, s56
	s_cselect_b32 s59, s53, s82
	s_cselect_b32 s58, s52, s81
	v_lshl_add_u64 v[222:223], s[54:55], 0, v[166:167]
	s_add_i32 m0, s66, 0xc000
	ds_read_b128 v[180:183], v191
	v_xor_b32_e32 v253, 64, v191
	ds_read_b128 v[194:197], v253
	ds_read_b128 v[198:201], v191 offset:2048
	ds_read_b128 v[202:205], v253 offset:2048
	ds_read_b128 v[206:209], v191 offset:4096
	ds_read_b128 v[210:213], v253 offset:4096
	ds_read_b128 v[214:217], v191 offset:6144
	ds_read_b128 v[218:221], v253 offset:6144
	global_load_lds_dwordx4 v[222:223], off
	v_lshl_add_u64 v[222:223], s[54:55], 0, v[164:165]
	s_add_i32 m0, s66, 0xe000
	s_nop 0
	global_load_lds_dwordx4 v[222:223], off
	s_waitcnt vmcnt(8)
	s_waitcnt lgkmcnt(0)
	s_setprio 1
	s_barrier
	v_mfma_f32_16x16x32_bf16 v[124:127], v[128:131], v[180:183], 0
	v_mfma_f32_16x16x32_bf16 v[120:123], v[136:139], v[180:183], 0
	v_mfma_f32_16x16x32_bf16 v[108:111], v[128:131], v[198:201], 0
	v_mfma_f32_16x16x32_bf16 v[104:107], v[136:139], v[198:201], 0
	v_mfma_f32_16x16x32_bf16 v[92:95], v[128:131], v[206:209], 0
	v_mfma_f32_16x16x32_bf16 v[88:91], v[136:139], v[206:209], 0
	v_mfma_f32_16x16x32_bf16 v[76:79], v[128:131], v[214:217], 0
	v_mfma_f32_16x16x32_bf16 v[72:75], v[136:139], v[214:217], 0
	v_mfma_f32_16x16x32_bf16 v[124:127], v[132:135], v[194:197], v[124:127]
	v_mfma_f32_16x16x32_bf16 v[120:123], v[140:143], v[194:197], v[120:123]
	v_mfma_f32_16x16x32_bf16 v[108:111], v[132:135], v[202:205], v[108:111]
	v_mfma_f32_16x16x32_bf16 v[104:107], v[140:143], v[202:205], v[104:107]
	v_mfma_f32_16x16x32_bf16 v[92:95], v[132:135], v[210:213], v[92:95]
	v_mfma_f32_16x16x32_bf16 v[88:91], v[140:143], v[210:213], v[88:91]
	v_mfma_f32_16x16x32_bf16 v[76:79], v[132:135], v[218:221], v[76:79]
	v_mfma_f32_16x16x32_bf16 v[72:75], v[140:143], v[218:221], v[72:75]
	v_mfma_f32_16x16x32_bf16 v[116:119], v[144:147], v[180:183], 0
	v_mfma_f32_16x16x32_bf16 v[112:115], v[172:175], v[180:183], 0
	v_mfma_f32_16x16x32_bf16 v[100:103], v[144:147], v[198:201], 0
	v_mfma_f32_16x16x32_bf16 v[96:99], v[172:175], v[198:201], 0
	v_mfma_f32_16x16x32_bf16 v[84:87], v[144:147], v[206:209], 0
	v_mfma_f32_16x16x32_bf16 v[80:83], v[172:175], v[206:209], 0
	v_mfma_f32_16x16x32_bf16 v[68:71], v[144:147], v[214:217], 0
	v_mfma_f32_16x16x32_bf16 v[64:67], v[172:175], v[214:217], 0
	v_mfma_f32_16x16x32_bf16 v[116:119], v[148:151], v[194:197], v[116:119]
	v_mfma_f32_16x16x32_bf16 v[112:115], v[176:179], v[194:197], v[112:115]
	v_mfma_f32_16x16x32_bf16 v[100:103], v[148:151], v[202:205], v[100:103]
	v_mfma_f32_16x16x32_bf16 v[96:99], v[176:179], v[202:205], v[96:99]
	v_mfma_f32_16x16x32_bf16 v[84:87], v[148:151], v[210:213], v[84:87]
	v_mfma_f32_16x16x32_bf16 v[80:83], v[176:179], v[210:213], v[80:83]
	v_mfma_f32_16x16x32_bf16 v[68:71], v[148:151], v[218:221], v[68:71]
	v_mfma_f32_16x16x32_bf16 v[64:67], v[176:179], v[218:221], v[64:67]
	s_barrier
	s_setprio 0
	s_add_i32 s54, s77, s65
	v_lshl_add_u64 v[222:223], s[58:59], 0, v[154:155]
	s_mov_b32 m0, s54
	ds_read_b128 v[180:183], v191 offset:16384
	v_xor_b32_e32 v253, 64, v191
	ds_read_b128 v[194:197], v253 offset:16384
	ds_read_b128 v[198:201], v191 offset:18432
	ds_read_b128 v[202:205], v253 offset:18432
	ds_read_b128 v[206:209], v191 offset:20480
	ds_read_b128 v[210:213], v253 offset:20480
	ds_read_b128 v[214:217], v191 offset:22528
	ds_read_b128 v[218:221], v253 offset:22528
	global_load_lds_dwordx4 v[222:223], off
	s_add_i32 m0, s54, 0x2000
	s_add_u32 s54, s58, 0xb0000
	v_lshl_add_u64 v[224:225], s[58:59], 0, v[162:163]
	s_addc_u32 s55, s59, 0
	s_add_i32 s84, s78, s65
	global_load_lds_dwordx4 v[224:225], off
	v_lshl_add_u64 v[226:227], s[54:55], 0, v[154:155]
	s_mov_b32 m0, s84
	v_lshl_add_u64 v[228:229], s[60:61], 0, v[160:161]
	global_load_lds_dwordx4 v[226:227], off
	v_lshl_add_u64 v[226:227], s[54:55], 0, v[162:163]
	s_add_i32 m0, s84, 0x2000
	s_nop 0
	global_load_lds_dwordx4 v[226:227], off
	v_lshl_add_u64 v[226:227], s[60:61], 0, v[152:153]
	s_mov_b32 m0, s66
	s_nop 0
	global_load_lds_dwordx4 v[226:227], off
	s_mov_b32 m0, s67
	s_nop 0
	global_load_lds_dwordx4 v[228:229], off
	s_waitcnt vmcnt(8)
	s_waitcnt lgkmcnt(0)
	s_setprio 1
	s_barrier
	v_mfma_f32_16x16x32_bf16 v[60:63], v[128:131], v[180:183], 0
	v_mfma_f32_16x16x32_bf16 v[56:59], v[136:139], v[180:183], 0
	v_mfma_f32_16x16x32_bf16 v[44:47], v[128:131], v[198:201], 0
	v_mfma_f32_16x16x32_bf16 v[40:43], v[136:139], v[198:201], 0
	v_mfma_f32_16x16x32_bf16 v[28:31], v[128:131], v[206:209], 0
	v_mfma_f32_16x16x32_bf16 v[24:27], v[136:139], v[206:209], 0
	v_mfma_f32_16x16x32_bf16 v[12:15], v[128:131], v[214:217], 0
	v_mfma_f32_16x16x32_bf16 v[8:11], v[136:139], v[214:217], 0
	v_mfma_f32_16x16x32_bf16 v[60:63], v[132:135], v[194:197], v[60:63]
	v_mfma_f32_16x16x32_bf16 v[56:59], v[140:143], v[194:197], v[56:59]
	v_mfma_f32_16x16x32_bf16 v[44:47], v[132:135], v[202:205], v[44:47]
	v_mfma_f32_16x16x32_bf16 v[40:43], v[140:143], v[202:205], v[40:43]
	v_mfma_f32_16x16x32_bf16 v[28:31], v[132:135], v[210:213], v[28:31]
	v_mfma_f32_16x16x32_bf16 v[24:27], v[140:143], v[210:213], v[24:27]
	v_mfma_f32_16x16x32_bf16 v[12:15], v[132:135], v[218:221], v[12:15]
	v_mfma_f32_16x16x32_bf16 v[8:11], v[140:143], v[218:221], v[8:11]
	v_mfma_f32_16x16x32_bf16 v[52:55], v[144:147], v[180:183], 0
	v_mfma_f32_16x16x32_bf16 v[48:51], v[172:175], v[180:183], 0
	v_mfma_f32_16x16x32_bf16 v[36:39], v[144:147], v[198:201], 0
	v_mfma_f32_16x16x32_bf16 v[32:35], v[172:175], v[198:201], 0
	v_mfma_f32_16x16x32_bf16 v[20:23], v[144:147], v[206:209], 0
	v_mfma_f32_16x16x32_bf16 v[16:19], v[172:175], v[206:209], 0
	v_mfma_f32_16x16x32_bf16 v[4:7], v[144:147], v[214:217], 0
	v_mfma_f32_16x16x32_bf16 v[0:3], v[172:175], v[214:217], 0
	v_mfma_f32_16x16x32_bf16 v[52:55], v[148:151], v[194:197], v[52:55]
	v_mfma_f32_16x16x32_bf16 v[48:51], v[176:179], v[194:197], v[48:51]
	v_mfma_f32_16x16x32_bf16 v[36:39], v[148:151], v[202:205], v[36:39]
	v_mfma_f32_16x16x32_bf16 v[32:35], v[176:179], v[202:205], v[32:35]
	v_mfma_f32_16x16x32_bf16 v[20:23], v[148:151], v[210:213], v[20:23]
	v_mfma_f32_16x16x32_bf16 v[16:19], v[176:179], v[210:213], v[16:19]
	v_mfma_f32_16x16x32_bf16 v[4:7], v[148:151], v[218:221], v[4:7]
	v_mfma_f32_16x16x32_bf16 v[0:3], v[176:179], v[218:221], v[0:3]
	s_barrier
	s_setprio 0
	s_add_i32 s84, 0, 0x18000
	s_add_i32 s85, 0, 0x1c000
	v_add_u32_e32 v140, s84, v186
	v_add_u32_e32 v176, s85, v186
	ds_read_b128 v[128:131], v140
	v_xor_b32_e32 v253, 64, v140
	ds_read_b128 v[132:135], v253
	ds_read_b128 v[136:139], v140 offset:2048
	ds_read_b128 v[140:143], v253 offset:2048
	ds_read_b128 v[144:147], v176
	v_xor_b32_e32 v253, 64, v176
	ds_read_b128 v[148:151], v253
	ds_read_b128 v[172:175], v176 offset:2048
	ds_read_b128 v[176:179], v253 offset:2048
	s_add_u32 s54, s60, 0xb0000
	s_addc_u32 s55, s61, 0
	s_mov_b32 m0, s68
	v_lshl_add_u64 v[230:231], s[54:55], 0, v[152:153]
	ds_read_b128 v[180:183], v191 offset:32768
	v_xor_b32_e32 v253, 64, v191
	ds_read_b128 v[194:197], v253 offset:32768
	ds_read_b128 v[198:201], v191 offset:34816
	ds_read_b128 v[202:205], v253 offset:34816
	ds_read_b128 v[206:209], v191 offset:36864
	ds_read_b128 v[210:213], v253 offset:36864
	ds_read_b128 v[214:217], v191 offset:38912
	ds_read_b128 v[218:221], v253 offset:38912
	global_load_lds_dwordx4 v[230:231], off
	v_lshl_add_u64 v[230:231], s[54:55], 0, v[160:161]
	s_mov_b32 m0, s69
	s_nop 0
	global_load_lds_dwordx4 v[230:231], off
	s_waitcnt vmcnt(8)
	s_waitcnt lgkmcnt(0)
	s_setprio 1
	s_barrier
	v_mfma_f32_16x16x32_bf16 v[124:127], v[128:131], v[180:183], v[124:127]
	v_mfma_f32_16x16x32_bf16 v[124:127], v[132:135], v[194:197], v[124:127]
	v_mfma_f32_16x16x32_bf16 v[120:123], v[140:143], v[194:197], v[120:123]
	v_mfma_f32_16x16x32_bf16 v[120:123], v[136:139], v[180:183], v[120:123]
	v_mfma_f32_16x16x32_bf16 v[104:107], v[136:139], v[198:201], v[104:107]
	v_mfma_f32_16x16x32_bf16 v[104:107], v[140:143], v[202:205], v[104:107]
	v_mfma_f32_16x16x32_bf16 v[108:111], v[132:135], v[202:205], v[108:111]
	v_mfma_f32_16x16x32_bf16 v[108:111], v[128:131], v[198:201], v[108:111]
	v_mfma_f32_16x16x32_bf16 v[92:95], v[128:131], v[206:209], v[92:95]
	v_mfma_f32_16x16x32_bf16 v[92:95], v[132:135], v[210:213], v[92:95]
	v_mfma_f32_16x16x32_bf16 v[88:91], v[140:143], v[210:213], v[88:91]
	v_mfma_f32_16x16x32_bf16 v[88:91], v[136:139], v[206:209], v[88:91]
	v_mfma_f32_16x16x32_bf16 v[72:75], v[136:139], v[214:217], v[72:75]
	v_mfma_f32_16x16x32_bf16 v[72:75], v[140:143], v[218:221], v[72:75]
	v_mfma_f32_16x16x32_bf16 v[76:79], v[132:135], v[218:221], v[76:79]
	v_mfma_f32_16x16x32_bf16 v[76:79], v[128:131], v[214:217], v[76:79]
	v_mfma_f32_16x16x32_bf16 v[116:119], v[144:147], v[180:183], v[116:119]
	v_mfma_f32_16x16x32_bf16 v[116:119], v[148:151], v[194:197], v[116:119]
	v_mfma_f32_16x16x32_bf16 v[112:115], v[176:179], v[194:197], v[112:115]
	v_mfma_f32_16x16x32_bf16 v[112:115], v[172:175], v[180:183], v[112:115]
	v_mfma_f32_16x16x32_bf16 v[96:99], v[172:175], v[198:201], v[96:99]
	v_mfma_f32_16x16x32_bf16 v[96:99], v[176:179], v[202:205], v[96:99]
	v_mfma_f32_16x16x32_bf16 v[100:103], v[148:151], v[202:205], v[100:103]
	v_mfma_f32_16x16x32_bf16 v[100:103], v[144:147], v[198:201], v[100:103]
	v_mfma_f32_16x16x32_bf16 v[84:87], v[144:147], v[206:209], v[84:87]
	v_mfma_f32_16x16x32_bf16 v[84:87], v[148:151], v[210:213], v[84:87]
	v_mfma_f32_16x16x32_bf16 v[80:83], v[176:179], v[210:213], v[80:83]
	v_mfma_f32_16x16x32_bf16 v[80:83], v[172:175], v[206:209], v[80:83]
	v_mfma_f32_16x16x32_bf16 v[64:67], v[172:175], v[214:217], v[64:67]
	v_mfma_f32_16x16x32_bf16 v[64:67], v[176:179], v[218:221], v[64:67]
	v_mfma_f32_16x16x32_bf16 v[68:71], v[148:151], v[218:221], v[68:71]
	v_mfma_f32_16x16x32_bf16 v[68:71], v[144:147], v[214:217], v[68:71]
	s_barrier
	s_setprio 0
	s_add_i32 s54, s84, s65
	v_lshl_add_u64 v[222:223], v[222:223], 0, s[28:29]
	s_mov_b32 m0, s54
	ds_read_b128 v[180:183], v191 offset:49152
	v_xor_b32_e32 v253, 64, v191
	ds_read_b128 v[194:197], v253 offset:49152
	ds_read_b128 v[198:201], v191 offset:51200
	ds_read_b128 v[202:205], v253 offset:51200
	ds_read_b128 v[206:209], v191 offset:53248
	ds_read_b128 v[210:213], v253 offset:53248
	ds_read_b128 v[214:217], v191 offset:55296
	ds_read_b128 v[218:221], v253 offset:55296
	global_load_lds_dwordx4 v[222:223], off
	s_add_i32 m0, s54, 0x2000
	s_add_u32 s54, s58, 0xb0080
	v_lshl_add_u64 v[222:223], v[224:225], 0, s[28:29]
	s_addc_u32 s55, s59, 0
	s_add_i32 s58, s85, s65
	global_load_lds_dwordx4 v[222:223], off
	v_lshl_add_u64 v[222:223], s[54:55], 0, v[154:155]
	s_mov_b32 m0, s58
	s_nop 0
	global_load_lds_dwordx4 v[222:223], off
	v_lshl_add_u64 v[222:223], s[54:55], 0, v[162:163]
	s_add_i32 m0, s58, 0x2000
	s_nop 0
	global_load_lds_dwordx4 v[222:223], off
	v_lshl_add_u64 v[222:223], v[226:227], 0, s[28:29]
	s_mov_b32 m0, s3
	s_nop 0
	global_load_lds_dwordx4 v[222:223], off
	v_lshl_add_u64 v[222:223], v[228:229], 0, s[28:29]
	s_mov_b32 m0, s71
	s_nop 0
	global_load_lds_dwordx4 v[222:223], off
	s_waitcnt vmcnt(8)
	s_waitcnt lgkmcnt(0)
	s_setprio 1
	s_barrier
	v_mfma_f32_16x16x32_bf16 v[60:63], v[128:131], v[180:183], v[60:63]
	v_mfma_f32_16x16x32_bf16 v[60:63], v[132:135], v[194:197], v[60:63]
	v_mfma_f32_16x16x32_bf16 v[56:59], v[140:143], v[194:197], v[56:59]
	v_mfma_f32_16x16x32_bf16 v[56:59], v[136:139], v[180:183], v[56:59]
	v_mfma_f32_16x16x32_bf16 v[40:43], v[136:139], v[198:201], v[40:43]
	v_mfma_f32_16x16x32_bf16 v[40:43], v[140:143], v[202:205], v[40:43]
	v_mfma_f32_16x16x32_bf16 v[44:47], v[132:135], v[202:205], v[44:47]
	v_mfma_f32_16x16x32_bf16 v[44:47], v[128:131], v[198:201], v[44:47]
	v_mfma_f32_16x16x32_bf16 v[28:31], v[128:131], v[206:209], v[28:31]
	v_mfma_f32_16x16x32_bf16 v[28:31], v[132:135], v[210:213], v[28:31]
	v_mfma_f32_16x16x32_bf16 v[24:27], v[140:143], v[210:213], v[24:27]
	v_mfma_f32_16x16x32_bf16 v[24:27], v[136:139], v[206:209], v[24:27]
	v_mfma_f32_16x16x32_bf16 v[8:11], v[136:139], v[214:217], v[8:11]
	v_mfma_f32_16x16x32_bf16 v[8:11], v[140:143], v[218:221], v[8:11]
	v_mfma_f32_16x16x32_bf16 v[12:15], v[132:135], v[218:221], v[12:15]
	v_mfma_f32_16x16x32_bf16 v[12:15], v[128:131], v[214:217], v[12:15]
	v_mfma_f32_16x16x32_bf16 v[52:55], v[144:147], v[180:183], v[52:55]
	v_mfma_f32_16x16x32_bf16 v[52:55], v[148:151], v[194:197], v[52:55]
	v_mfma_f32_16x16x32_bf16 v[48:51], v[176:179], v[194:197], v[48:51]
	v_mfma_f32_16x16x32_bf16 v[48:51], v[172:175], v[180:183], v[48:51]
	v_mfma_f32_16x16x32_bf16 v[32:35], v[172:175], v[198:201], v[32:35]
	v_mfma_f32_16x16x32_bf16 v[32:35], v[176:179], v[202:205], v[32:35]
	v_mfma_f32_16x16x32_bf16 v[36:39], v[148:151], v[202:205], v[36:39]
	v_mfma_f32_16x16x32_bf16 v[36:39], v[144:147], v[198:201], v[36:39]
	v_mfma_f32_16x16x32_bf16 v[20:23], v[144:147], v[206:209], v[20:23]
	v_mfma_f32_16x16x32_bf16 v[20:23], v[148:151], v[210:213], v[20:23]
	v_mfma_f32_16x16x32_bf16 v[16:19], v[176:179], v[210:213], v[16:19]
	v_mfma_f32_16x16x32_bf16 v[16:19], v[172:175], v[206:209], v[16:19]
	v_mfma_f32_16x16x32_bf16 v[0:3], v[172:175], v[214:217], v[0:3]
	v_mfma_f32_16x16x32_bf16 v[0:3], v[176:179], v[218:221], v[0:3]
	v_mfma_f32_16x16x32_bf16 v[4:7], v[148:151], v[218:221], v[4:7]
	v_mfma_f32_16x16x32_bf16 v[4:7], v[144:147], v[214:217], v[4:7]
	s_barrier
	s_setprio 0
	s_add_i32 s83, s83, 2
	s_add_u32 s81, s81, 0x100
	s_addc_u32 s82, s82, 0
	s_cmp_gt_u32 s83, 41
	s_mov_b64 s[54:55], s[56:57]
.LBB0_159:
	ds_read_b128 v[128:131], v189
	v_xor_b32_e32 v253, 64, v189
	ds_read_b128 v[132:135], v253
	ds_read_b128 v[136:139], v189 offset:2048
	ds_read_b128 v[140:143], v253 offset:2048
	ds_read_b128 v[144:147], v190
	v_xor_b32_e32 v253, 64, v190
	ds_read_b128 v[148:151], v253
	ds_read_b128 v[172:175], v190 offset:2048
	ds_read_b128 v[176:179], v253 offset:2048
	s_add_u32 s56, s54, 0x100
	s_addc_u32 s57, s55, 0
	s_cmp_eq_u32 s83, 40
	s_cselect_b32 s61, s15, s57
	s_cselect_b32 s60, s14, s56
	s_cselect_b32 s59, s53, s82
	s_cselect_b32 s58, s52, s81
	v_lshl_add_u64 v[222:223], s[54:55], 0, v[166:167]
	s_add_i32 m0, s66, 0xc000
	ds_read_b128 v[180:183], v191
	v_xor_b32_e32 v253, 64, v191
	ds_read_b128 v[194:197], v253
	ds_read_b128 v[198:201], v191 offset:2048
	ds_read_b128 v[202:205], v253 offset:2048
	ds_read_b128 v[206:209], v191 offset:4096
	ds_read_b128 v[210:213], v253 offset:4096
	ds_read_b128 v[214:217], v191 offset:6144
	ds_read_b128 v[218:221], v253 offset:6144
	global_load_lds_dwordx4 v[222:223], off
	v_lshl_add_u64 v[222:223], s[54:55], 0, v[164:165]
	s_add_i32 m0, s66, 0xe000
	s_nop 0
	global_load_lds_dwordx4 v[222:223], off
	s_waitcnt vmcnt(8)
	s_waitcnt lgkmcnt(0)
	s_setprio 1
	s_barrier
	v_mfma_f32_16x16x32_bf16 v[124:127], v[128:131], v[180:183], v[124:127]
	v_mfma_f32_16x16x32_bf16 v[124:127], v[132:135], v[194:197], v[124:127]
	v_mfma_f32_16x16x32_bf16 v[120:123], v[140:143], v[194:197], v[120:123]
	v_mfma_f32_16x16x32_bf16 v[120:123], v[136:139], v[180:183], v[120:123]
	v_mfma_f32_16x16x32_bf16 v[104:107], v[136:139], v[198:201], v[104:107]
	v_mfma_f32_16x16x32_bf16 v[104:107], v[140:143], v[202:205], v[104:107]
	v_mfma_f32_16x16x32_bf16 v[108:111], v[132:135], v[202:205], v[108:111]
	v_mfma_f32_16x16x32_bf16 v[108:111], v[128:131], v[198:201], v[108:111]
	v_mfma_f32_16x16x32_bf16 v[92:95], v[128:131], v[206:209], v[92:95]
	v_mfma_f32_16x16x32_bf16 v[92:95], v[132:135], v[210:213], v[92:95]
	v_mfma_f32_16x16x32_bf16 v[88:91], v[140:143], v[210:213], v[88:91]
	v_mfma_f32_16x16x32_bf16 v[88:91], v[136:139], v[206:209], v[88:91]
	v_mfma_f32_16x16x32_bf16 v[72:75], v[136:139], v[214:217], v[72:75]
	v_mfma_f32_16x16x32_bf16 v[72:75], v[140:143], v[218:221], v[72:75]
	v_mfma_f32_16x16x32_bf16 v[76:79], v[132:135], v[218:221], v[76:79]
	v_mfma_f32_16x16x32_bf16 v[76:79], v[128:131], v[214:217], v[76:79]
	v_mfma_f32_16x16x32_bf16 v[116:119], v[144:147], v[180:183], v[116:119]
	v_mfma_f32_16x16x32_bf16 v[116:119], v[148:151], v[194:197], v[116:119]
	v_mfma_f32_16x16x32_bf16 v[112:115], v[176:179], v[194:197], v[112:115]
	v_mfma_f32_16x16x32_bf16 v[112:115], v[172:175], v[180:183], v[112:115]
	v_mfma_f32_16x16x32_bf16 v[96:99], v[172:175], v[198:201], v[96:99]
	v_mfma_f32_16x16x32_bf16 v[96:99], v[176:179], v[202:205], v[96:99]
	v_mfma_f32_16x16x32_bf16 v[100:103], v[148:151], v[202:205], v[100:103]
	v_mfma_f32_16x16x32_bf16 v[100:103], v[144:147], v[198:201], v[100:103]
	v_mfma_f32_16x16x32_bf16 v[84:87], v[144:147], v[206:209], v[84:87]
	v_mfma_f32_16x16x32_bf16 v[84:87], v[148:151], v[210:213], v[84:87]
	v_mfma_f32_16x16x32_bf16 v[80:83], v[176:179], v[210:213], v[80:83]
	v_mfma_f32_16x16x32_bf16 v[80:83], v[172:175], v[206:209], v[80:83]
	v_mfma_f32_16x16x32_bf16 v[64:67], v[172:175], v[214:217], v[64:67]
	v_mfma_f32_16x16x32_bf16 v[64:67], v[176:179], v[218:221], v[64:67]
	v_mfma_f32_16x16x32_bf16 v[68:71], v[148:151], v[218:221], v[68:71]
	v_mfma_f32_16x16x32_bf16 v[68:71], v[144:147], v[214:217], v[68:71]
	s_barrier
	s_setprio 0
	s_add_i32 s54, s77, s65
	v_lshl_add_u64 v[222:223], s[58:59], 0, v[154:155]
	s_mov_b32 m0, s54
	ds_read_b128 v[180:183], v191 offset:16384
	v_xor_b32_e32 v253, 64, v191
	ds_read_b128 v[194:197], v253 offset:16384
	ds_read_b128 v[198:201], v191 offset:18432
	ds_read_b128 v[202:205], v253 offset:18432
	ds_read_b128 v[206:209], v191 offset:20480
	ds_read_b128 v[210:213], v253 offset:20480
	ds_read_b128 v[214:217], v191 offset:22528
	ds_read_b128 v[218:221], v253 offset:22528
	global_load_lds_dwordx4 v[222:223], off
	s_add_i32 m0, s54, 0x2000
	s_add_u32 s54, s58, 0xb0000
	v_lshl_add_u64 v[224:225], s[58:59], 0, v[162:163]
	s_addc_u32 s55, s59, 0
	s_add_i32 s84, s78, s65
	global_load_lds_dwordx4 v[224:225], off
	v_lshl_add_u64 v[226:227], s[54:55], 0, v[154:155]
	s_mov_b32 m0, s84
	v_lshl_add_u64 v[228:229], s[60:61], 0, v[160:161]
	global_load_lds_dwordx4 v[226:227], off
	v_lshl_add_u64 v[226:227], s[54:55], 0, v[162:163]
	s_add_i32 m0, s84, 0x2000
	s_nop 0
	global_load_lds_dwordx4 v[226:227], off
	v_lshl_add_u64 v[226:227], s[60:61], 0, v[152:153]
	s_mov_b32 m0, s66
	s_nop 0
	global_load_lds_dwordx4 v[226:227], off
	s_mov_b32 m0, s67
	s_nop 0
	global_load_lds_dwordx4 v[228:229], off
	s_waitcnt vmcnt(8)
	s_waitcnt lgkmcnt(0)
	s_setprio 1
	s_barrier
	v_mfma_f32_16x16x32_bf16 v[60:63], v[128:131], v[180:183], v[60:63]
	v_mfma_f32_16x16x32_bf16 v[60:63], v[132:135], v[194:197], v[60:63]
	v_mfma_f32_16x16x32_bf16 v[56:59], v[140:143], v[194:197], v[56:59]
	v_mfma_f32_16x16x32_bf16 v[56:59], v[136:139], v[180:183], v[56:59]
	v_mfma_f32_16x16x32_bf16 v[40:43], v[136:139], v[198:201], v[40:43]
	v_mfma_f32_16x16x32_bf16 v[40:43], v[140:143], v[202:205], v[40:43]
	v_mfma_f32_16x16x32_bf16 v[44:47], v[132:135], v[202:205], v[44:47]
	v_mfma_f32_16x16x32_bf16 v[44:47], v[128:131], v[198:201], v[44:47]
	v_mfma_f32_16x16x32_bf16 v[28:31], v[128:131], v[206:209], v[28:31]
	v_mfma_f32_16x16x32_bf16 v[28:31], v[132:135], v[210:213], v[28:31]
	v_mfma_f32_16x16x32_bf16 v[24:27], v[140:143], v[210:213], v[24:27]
	v_mfma_f32_16x16x32_bf16 v[24:27], v[136:139], v[206:209], v[24:27]
	v_mfma_f32_16x16x32_bf16 v[8:11], v[136:139], v[214:217], v[8:11]
	v_mfma_f32_16x16x32_bf16 v[8:11], v[140:143], v[218:221], v[8:11]
	v_mfma_f32_16x16x32_bf16 v[12:15], v[132:135], v[218:221], v[12:15]
	v_mfma_f32_16x16x32_bf16 v[12:15], v[128:131], v[214:217], v[12:15]
	v_mfma_f32_16x16x32_bf16 v[52:55], v[144:147], v[180:183], v[52:55]
	v_mfma_f32_16x16x32_bf16 v[52:55], v[148:151], v[194:197], v[52:55]
	v_mfma_f32_16x16x32_bf16 v[48:51], v[176:179], v[194:197], v[48:51]
	v_mfma_f32_16x16x32_bf16 v[48:51], v[172:175], v[180:183], v[48:51]
	v_mfma_f32_16x16x32_bf16 v[32:35], v[172:175], v[198:201], v[32:35]
	v_mfma_f32_16x16x32_bf16 v[32:35], v[176:179], v[202:205], v[32:35]
	v_mfma_f32_16x16x32_bf16 v[36:39], v[148:151], v[202:205], v[36:39]
	v_mfma_f32_16x16x32_bf16 v[36:39], v[144:147], v[198:201], v[36:39]
	v_mfma_f32_16x16x32_bf16 v[20:23], v[144:147], v[206:209], v[20:23]
	v_mfma_f32_16x16x32_bf16 v[20:23], v[148:151], v[210:213], v[20:23]
	v_mfma_f32_16x16x32_bf16 v[16:19], v[176:179], v[210:213], v[16:19]
	v_mfma_f32_16x16x32_bf16 v[16:19], v[172:175], v[206:209], v[16:19]
	v_mfma_f32_16x16x32_bf16 v[0:3], v[172:175], v[214:217], v[0:3]
	v_mfma_f32_16x16x32_bf16 v[0:3], v[176:179], v[218:221], v[0:3]
	v_mfma_f32_16x16x32_bf16 v[4:7], v[148:151], v[218:221], v[4:7]
	v_mfma_f32_16x16x32_bf16 v[4:7], v[144:147], v[214:217], v[4:7]
	s_barrier
	s_setprio 0
	s_add_i32 s84, 0, 0x18000
	s_add_i32 s85, 0, 0x1c000
	v_add_u32_e32 v140, s84, v186
	v_add_u32_e32 v176, s85, v186
	ds_read_b128 v[128:131], v140
	v_xor_b32_e32 v253, 64, v140
	ds_read_b128 v[132:135], v253
	ds_read_b128 v[136:139], v140 offset:2048
	ds_read_b128 v[140:143], v253 offset:2048
	ds_read_b128 v[144:147], v176
	v_xor_b32_e32 v253, 64, v176
	ds_read_b128 v[148:151], v253
	ds_read_b128 v[172:175], v176 offset:2048
	ds_read_b128 v[176:179], v253 offset:2048
	s_add_u32 s54, s60, 0xb0000
	s_addc_u32 s55, s61, 0
	s_mov_b32 m0, s68
	v_lshl_add_u64 v[230:231], s[54:55], 0, v[152:153]
	ds_read_b128 v[180:183], v191 offset:32768
	v_xor_b32_e32 v253, 64, v191
	ds_read_b128 v[194:197], v253 offset:32768
	ds_read_b128 v[198:201], v191 offset:34816
	ds_read_b128 v[202:205], v253 offset:34816
	ds_read_b128 v[206:209], v191 offset:36864
	ds_read_b128 v[210:213], v253 offset:36864
	ds_read_b128 v[214:217], v191 offset:38912
	ds_read_b128 v[218:221], v253 offset:38912
	global_load_lds_dwordx4 v[230:231], off
	v_lshl_add_u64 v[230:231], s[54:55], 0, v[160:161]
	s_mov_b32 m0, s69
	s_nop 0
	global_load_lds_dwordx4 v[230:231], off
	s_waitcnt vmcnt(8)
	s_waitcnt lgkmcnt(0)
	s_setprio 1
	s_barrier
	v_mfma_f32_16x16x32_bf16 v[124:127], v[128:131], v[180:183], v[124:127]
	v_mfma_f32_16x16x32_bf16 v[124:127], v[132:135], v[194:197], v[124:127]
	v_mfma_f32_16x16x32_bf16 v[120:123], v[140:143], v[194:197], v[120:123]
	v_mfma_f32_16x16x32_bf16 v[120:123], v[136:139], v[180:183], v[120:123]
	v_mfma_f32_16x16x32_bf16 v[104:107], v[136:139], v[198:201], v[104:107]
	v_mfma_f32_16x16x32_bf16 v[104:107], v[140:143], v[202:205], v[104:107]
	v_mfma_f32_16x16x32_bf16 v[108:111], v[132:135], v[202:205], v[108:111]
	v_mfma_f32_16x16x32_bf16 v[108:111], v[128:131], v[198:201], v[108:111]
	v_mfma_f32_16x16x32_bf16 v[92:95], v[128:131], v[206:209], v[92:95]
	v_mfma_f32_16x16x32_bf16 v[92:95], v[132:135], v[210:213], v[92:95]
	v_mfma_f32_16x16x32_bf16 v[88:91], v[140:143], v[210:213], v[88:91]
	v_mfma_f32_16x16x32_bf16 v[88:91], v[136:139], v[206:209], v[88:91]
	v_mfma_f32_16x16x32_bf16 v[72:75], v[136:139], v[214:217], v[72:75]
	v_mfma_f32_16x16x32_bf16 v[72:75], v[140:143], v[218:221], v[72:75]
	v_mfma_f32_16x16x32_bf16 v[76:79], v[132:135], v[218:221], v[76:79]
	v_mfma_f32_16x16x32_bf16 v[76:79], v[128:131], v[214:217], v[76:79]
	v_mfma_f32_16x16x32_bf16 v[116:119], v[144:147], v[180:183], v[116:119]
	v_mfma_f32_16x16x32_bf16 v[116:119], v[148:151], v[194:197], v[116:119]
	v_mfma_f32_16x16x32_bf16 v[112:115], v[176:179], v[194:197], v[112:115]
	v_mfma_f32_16x16x32_bf16 v[112:115], v[172:175], v[180:183], v[112:115]
	v_mfma_f32_16x16x32_bf16 v[96:99], v[172:175], v[198:201], v[96:99]
	v_mfma_f32_16x16x32_bf16 v[96:99], v[176:179], v[202:205], v[96:99]
	v_mfma_f32_16x16x32_bf16 v[100:103], v[148:151], v[202:205], v[100:103]
	v_mfma_f32_16x16x32_bf16 v[100:103], v[144:147], v[198:201], v[100:103]
	v_mfma_f32_16x16x32_bf16 v[84:87], v[144:147], v[206:209], v[84:87]
	v_mfma_f32_16x16x32_bf16 v[84:87], v[148:151], v[210:213], v[84:87]
	v_mfma_f32_16x16x32_bf16 v[80:83], v[176:179], v[210:213], v[80:83]
	v_mfma_f32_16x16x32_bf16 v[80:83], v[172:175], v[206:209], v[80:83]
	v_mfma_f32_16x16x32_bf16 v[64:67], v[172:175], v[214:217], v[64:67]
	v_mfma_f32_16x16x32_bf16 v[64:67], v[176:179], v[218:221], v[64:67]
	v_mfma_f32_16x16x32_bf16 v[68:71], v[148:151], v[218:221], v[68:71]
	v_mfma_f32_16x16x32_bf16 v[68:71], v[144:147], v[214:217], v[68:71]
	s_barrier
	s_setprio 0
	s_add_i32 s54, s84, s65
	v_lshl_add_u64 v[222:223], v[222:223], 0, s[28:29]
	s_mov_b32 m0, s54
	ds_read_b128 v[180:183], v191 offset:49152
	v_xor_b32_e32 v253, 64, v191
	ds_read_b128 v[194:197], v253 offset:49152
	ds_read_b128 v[198:201], v191 offset:51200
	ds_read_b128 v[202:205], v253 offset:51200
	ds_read_b128 v[206:209], v191 offset:53248
	ds_read_b128 v[210:213], v253 offset:53248
	ds_read_b128 v[214:217], v191 offset:55296
	ds_read_b128 v[218:221], v253 offset:55296
	global_load_lds_dwordx4 v[222:223], off
	s_add_i32 m0, s54, 0x2000
	s_add_u32 s54, s58, 0xb0080
	v_lshl_add_u64 v[222:223], v[224:225], 0, s[28:29]
	s_addc_u32 s55, s59, 0
	s_add_i32 s58, s85, s65
	global_load_lds_dwordx4 v[222:223], off
	v_lshl_add_u64 v[222:223], s[54:55], 0, v[154:155]
	s_mov_b32 m0, s58
	s_nop 0
	global_load_lds_dwordx4 v[222:223], off
	v_lshl_add_u64 v[222:223], s[54:55], 0, v[162:163]
	s_add_i32 m0, s58, 0x2000
	s_nop 0
	global_load_lds_dwordx4 v[222:223], off
	v_lshl_add_u64 v[222:223], v[226:227], 0, s[28:29]
	s_mov_b32 m0, s3
	s_nop 0
	global_load_lds_dwordx4 v[222:223], off
	v_lshl_add_u64 v[222:223], v[228:229], 0, s[28:29]
	s_mov_b32 m0, s71
	s_nop 0
	global_load_lds_dwordx4 v[222:223], off
	s_waitcnt vmcnt(8)
	s_waitcnt lgkmcnt(0)
	s_setprio 1
	s_barrier
	v_mfma_f32_16x16x32_bf16 v[60:63], v[128:131], v[180:183], v[60:63]
	v_mfma_f32_16x16x32_bf16 v[60:63], v[132:135], v[194:197], v[60:63]
	v_mfma_f32_16x16x32_bf16 v[56:59], v[140:143], v[194:197], v[56:59]
	v_mfma_f32_16x16x32_bf16 v[56:59], v[136:139], v[180:183], v[56:59]
	v_mfma_f32_16x16x32_bf16 v[40:43], v[136:139], v[198:201], v[40:43]
	v_mfma_f32_16x16x32_bf16 v[40:43], v[140:143], v[202:205], v[40:43]
	v_mfma_f32_16x16x32_bf16 v[44:47], v[132:135], v[202:205], v[44:47]
	v_mfma_f32_16x16x32_bf16 v[44:47], v[128:131], v[198:201], v[44:47]
	v_mfma_f32_16x16x32_bf16 v[28:31], v[128:131], v[206:209], v[28:31]
	v_mfma_f32_16x16x32_bf16 v[28:31], v[132:135], v[210:213], v[28:31]
	v_mfma_f32_16x16x32_bf16 v[24:27], v[140:143], v[210:213], v[24:27]
	v_mfma_f32_16x16x32_bf16 v[24:27], v[136:139], v[206:209], v[24:27]
	v_mfma_f32_16x16x32_bf16 v[8:11], v[136:139], v[214:217], v[8:11]
	v_mfma_f32_16x16x32_bf16 v[8:11], v[140:143], v[218:221], v[8:11]
	v_mfma_f32_16x16x32_bf16 v[12:15], v[132:135], v[218:221], v[12:15]
	v_mfma_f32_16x16x32_bf16 v[12:15], v[128:131], v[214:217], v[12:15]
	v_mfma_f32_16x16x32_bf16 v[52:55], v[144:147], v[180:183], v[52:55]
	v_mfma_f32_16x16x32_bf16 v[52:55], v[148:151], v[194:197], v[52:55]
	v_mfma_f32_16x16x32_bf16 v[48:51], v[176:179], v[194:197], v[48:51]
	v_mfma_f32_16x16x32_bf16 v[48:51], v[172:175], v[180:183], v[48:51]
	v_mfma_f32_16x16x32_bf16 v[32:35], v[172:175], v[198:201], v[32:35]
	v_mfma_f32_16x16x32_bf16 v[32:35], v[176:179], v[202:205], v[32:35]
	v_mfma_f32_16x16x32_bf16 v[36:39], v[148:151], v[202:205], v[36:39]
	v_mfma_f32_16x16x32_bf16 v[36:39], v[144:147], v[198:201], v[36:39]
	v_mfma_f32_16x16x32_bf16 v[20:23], v[144:147], v[206:209], v[20:23]
	v_mfma_f32_16x16x32_bf16 v[20:23], v[148:151], v[210:213], v[20:23]
	v_mfma_f32_16x16x32_bf16 v[16:19], v[176:179], v[210:213], v[16:19]
	v_mfma_f32_16x16x32_bf16 v[16:19], v[172:175], v[206:209], v[16:19]
	v_mfma_f32_16x16x32_bf16 v[0:3], v[172:175], v[214:217], v[0:3]
	v_mfma_f32_16x16x32_bf16 v[0:3], v[176:179], v[218:221], v[0:3]
	v_mfma_f32_16x16x32_bf16 v[4:7], v[148:151], v[218:221], v[4:7]
	v_mfma_f32_16x16x32_bf16 v[4:7], v[144:147], v[214:217], v[4:7]
	s_barrier
	s_setprio 0
	s_add_i32 s83, s83, 2
	s_add_u32 s81, s81, 0x100
	s_addc_u32 s82, s82, 0
	s_cmp_gt_u32 s83, 41
	s_mov_b64 s[54:55], s[56:57]
	s_cbranch_scc0 .LBB0_159
	s_and_b64 vcc, exec, s[30:31]
	s_cbranch_vccz .LBB0_162
	s_barrier

.LBB0_254:
	s_ashr_i32 s61, s60, 31
	s_lshl_b64 s[62:63], s[60:61], 19
	s_add_u32 s62, s35, s62
	s_addc_u32 s63, s47, s63
	s_and_b64 s[64:65], s[12:13], exec
	s_cselect_b32 s3, s63, s69
	s_cselect_b32 s61, s62, s68
	s_ashr_i32 s59, s58, 31
	s_lshl_b64 s[64:65], s[58:59], 19
	s_add_u32 s64, s49, s64
	s_addc_u32 s65, s70, s65
	s_and_b64 s[92:93], s[12:13], exec
	s_cselect_b32 s91, s65, s67
	s_cselect_b32 s92, s64, s66
	s_lshl_b32 s59, s14, 8
	v_add_u32_e32 v0, s59, v182
	s_add_u32 s93, s66, 0x100
	s_waitcnt lgkmcnt(0)
	v_ashrrev_i32_e32 v1, 31, v0
	s_addc_u32 s94, s67, 0
	v_lshl_add_u64 v[72:73], v[0:1], 4, s[26:27]
	s_add_u32 s14, s68, 0x40080
	s_addc_u32 s15, s69, 0
	s_mov_b32 s95, -2
	s_mov_b64 s[66:67], 0
	s_cmp_eq_u32 s90, 1
	s_cbranch_scc1 .Lfa_2
	v_add_u32_e32 v74, s83, v181
	ds_read_b128 v[88:91], v74
	v_xor_b32_e32 v253, 64, v74
	ds_read_b128 v[108:111], v253
	ds_read_b128 v[128:131], v74 offset:2048
	ds_read_b128 v[144:147], v253 offset:2048
	v_add_u32_e32 v74, s84, v181
	ds_read_b128 v[148:151], v74
	v_xor_b32_e32 v253, 64, v74
	ds_read_b128 v[152:155], v253
	ds_read_b128 v[176:179], v74 offset:2048
	ds_read_b128 v[190:193], v253 offset:2048
	s_add_u32 s68, s14, 0xfffc0080
	s_addc_u32 s69, s15, -1
	s_and_b64 s[66:67], s[66:67], exec
	s_cselect_b32 s69, s3, s69
	s_cselect_b32 s68, s61, s68
	s_cselect_b32 s67, s91, s94
	s_cselect_b32 s66, s92, s93
	v_lshl_add_u64 v[74:75], s[14:15], 0, v[170:171]
	s_add_i32 m0, s74, 0xc000
	ds_read_b128 v[194:197], v187
	v_xor_b32_e32 v253, 64, v187
	ds_read_b128 v[198:201], v253
	ds_read_b128 v[202:205], v187 offset:2048
	ds_read_b128 v[206:209], v253 offset:2048
	ds_read_b128 v[210:213], v187 offset:4096
	ds_read_b128 v[214:217], v253 offset:4096
	ds_read_b128 v[218:221], v187 offset:6144
	ds_read_b128 v[222:225], v253 offset:6144
	global_load_lds_dwordx4 v[74:75], off
	v_lshl_add_u64 v[74:75], s[14:15], 0, v[168:169]
	s_add_i32 m0, s74, 0xe000
	s_nop 0
	global_load_lds_dwordx4 v[74:75], off
	s_waitcnt vmcnt(24)
	s_waitcnt lgkmcnt(0)
	s_setprio 1
	s_barrier
	v_mfma_f32_16x16x32_bf16 v[140:143], v[88:91], v[194:197], 0
	v_mfma_f32_16x16x32_bf16 v[136:139], v[128:131], v[194:197], 0
	v_mfma_f32_16x16x32_bf16 v[120:123], v[88:91], v[202:205], 0
	v_mfma_f32_16x16x32_bf16 v[116:119], v[128:131], v[202:205], 0
	v_mfma_f32_16x16x32_bf16 v[100:103], v[88:91], v[210:213], 0
	v_mfma_f32_16x16x32_bf16 v[96:99], v[128:131], v[210:213], 0
	v_mfma_f32_16x16x32_bf16 v[80:83], v[88:91], v[218:221], 0
	v_mfma_f32_16x16x32_bf16 v[74:77], v[128:131], v[218:221], 0
	v_mfma_f32_16x16x32_bf16 v[140:143], v[108:111], v[198:201], v[140:143]
	v_mfma_f32_16x16x32_bf16 v[136:139], v[144:147], v[198:201], v[136:139]
	v_mfma_f32_16x16x32_bf16 v[120:123], v[108:111], v[206:209], v[120:123]
	v_mfma_f32_16x16x32_bf16 v[116:119], v[144:147], v[206:209], v[116:119]
	v_mfma_f32_16x16x32_bf16 v[100:103], v[108:111], v[214:217], v[100:103]
	v_mfma_f32_16x16x32_bf16 v[96:99], v[144:147], v[214:217], v[96:99]
	v_mfma_f32_16x16x32_bf16 v[80:83], v[108:111], v[222:225], v[80:83]
	v_mfma_f32_16x16x32_bf16 v[74:77], v[144:147], v[222:225], v[74:77]
	v_mfma_f32_16x16x32_bf16 v[132:135], v[148:151], v[194:197], 0
	v_mfma_f32_16x16x32_bf16 v[124:127], v[176:179], v[194:197], 0
	v_mfma_f32_16x16x32_bf16 v[112:115], v[148:151], v[202:205], 0
	v_mfma_f32_16x16x32_bf16 v[104:107], v[176:179], v[202:205], 0
	v_mfma_f32_16x16x32_bf16 v[92:95], v[148:151], v[210:213], 0
	v_mfma_f32_16x16x32_bf16 v[84:87], v[176:179], v[210:213], 0
	v_mfma_f32_16x16x32_bf16 v[68:71], v[148:151], v[218:221], 0
	v_mfma_f32_16x16x32_bf16 v[64:67], v[176:179], v[218:221], 0
	v_mfma_f32_16x16x32_bf16 v[132:135], v[152:155], v[198:201], v[132:135]
	v_mfma_f32_16x16x32_bf16 v[124:127], v[190:193], v[198:201], v[124:127]
	v_mfma_f32_16x16x32_bf16 v[112:115], v[152:155], v[206:209], v[112:115]
	v_mfma_f32_16x16x32_bf16 v[104:107], v[190:193], v[206:209], v[104:107]
	v_mfma_f32_16x16x32_bf16 v[92:95], v[152:155], v[214:217], v[92:95]
	v_mfma_f32_16x16x32_bf16 v[84:87], v[190:193], v[214:217], v[84:87]
	v_mfma_f32_16x16x32_bf16 v[68:71], v[152:155], v[222:225], v[68:71]
	v_mfma_f32_16x16x32_bf16 v[64:67], v[190:193], v[222:225], v[64:67]
	s_barrier
	s_setprio 0
	s_add_i32 s96, s83, s71
	v_lshl_add_u64 v[226:227], s[66:67], 0, v[162:163]
	s_mov_b32 m0, s96
	ds_read_b128 v[194:197], v187 offset:16384
	v_xor_b32_e32 v253, 64, v187
	ds_read_b128 v[198:201], v253 offset:16384
	ds_read_b128 v[202:205], v187 offset:18432
	ds_read_b128 v[206:209], v253 offset:18432
	ds_read_b128 v[210:213], v187 offset:20480
	ds_read_b128 v[214:217], v253 offset:20480
	ds_read_b128 v[218:221], v187 offset:22528
	ds_read_b128 v[222:225], v253 offset:22528
	global_load_lds_dwordx4 v[226:227], off
	s_add_i32 m0, s96, 0x2000
	s_add_u32 s96, s66, 0x40000
	v_lshl_add_u64 v[228:229], s[66:67], 0, v[166:167]
	s_addc_u32 s97, s67, 0
	s_add_i32 vcc_lo, s84, s71
	global_load_lds_dwordx4 v[228:229], off
	v_lshl_add_u64 v[78:79], s[96:97], 0, v[162:163]
	s_mov_b32 m0, vcc_lo
	v_lshl_add_u64 v[230:231], s[68:69], 0, v[160:161]
	global_load_lds_dwordx4 v[78:79], off
	v_lshl_add_u64 v[78:79], s[96:97], 0, v[166:167]
	s_add_i32 m0, vcc_lo, 0x2000
	v_lshl_add_u64 v[232:233], s[68:69], 0, v[164:165]
	global_load_lds_dwordx4 v[78:79], off
	s_mov_b32 m0, s74
	s_nop 0
	global_load_lds_dwordx4 v[230:231], off
	s_mov_b32 m0, s75
	s_nop 0
	global_load_lds_dwordx4 v[232:233], off
	s_waitcnt vmcnt(24)
	s_waitcnt lgkmcnt(0)
	s_setprio 1
	s_barrier
	v_mfma_f32_16x16x32_bf16 v[60:63], v[88:91], v[194:197], 0
	v_mfma_f32_16x16x32_bf16 v[56:59], v[128:131], v[194:197], 0
	v_mfma_f32_16x16x32_bf16 v[44:47], v[88:91], v[202:205], 0
	v_mfma_f32_16x16x32_bf16 v[40:43], v[128:131], v[202:205], 0
	v_mfma_f32_16x16x32_bf16 v[28:31], v[88:91], v[210:213], 0
	v_mfma_f32_16x16x32_bf16 v[24:27], v[128:131], v[210:213], 0
	v_mfma_f32_16x16x32_bf16 v[12:15], v[88:91], v[218:221], 0
	v_mfma_f32_16x16x32_bf16 v[8:11], v[128:131], v[218:221], 0
	v_mfma_f32_16x16x32_bf16 v[60:63], v[108:111], v[198:201], v[60:63]
	v_mfma_f32_16x16x32_bf16 v[56:59], v[144:147], v[198:201], v[56:59]
	v_mfma_f32_16x16x32_bf16 v[44:47], v[108:111], v[206:209], v[44:47]
	v_mfma_f32_16x16x32_bf16 v[40:43], v[144:147], v[206:209], v[40:43]
	v_mfma_f32_16x16x32_bf16 v[28:31], v[108:111], v[214:217], v[28:31]
	v_mfma_f32_16x16x32_bf16 v[24:27], v[144:147], v[214:217], v[24:27]
	v_mfma_f32_16x16x32_bf16 v[12:15], v[108:111], v[222:225], v[12:15]
	v_mfma_f32_16x16x32_bf16 v[8:11], v[144:147], v[222:225], v[8:11]
	v_mfma_f32_16x16x32_bf16 v[52:55], v[148:151], v[194:197], 0
	v_mfma_f32_16x16x32_bf16 v[48:51], v[176:179], v[194:197], 0
	v_mfma_f32_16x16x32_bf16 v[36:39], v[148:151], v[202:205], 0
	v_mfma_f32_16x16x32_bf16 v[32:35], v[176:179], v[202:205], 0
	v_mfma_f32_16x16x32_bf16 v[20:23], v[148:151], v[210:213], 0
	v_mfma_f32_16x16x32_bf16 v[16:19], v[176:179], v[210:213], 0
	v_mfma_f32_16x16x32_bf16 v[4:7], v[148:151], v[218:221], 0
	v_mfma_f32_16x16x32_bf16 v[0:3], v[176:179], v[218:221], 0
	v_mfma_f32_16x16x32_bf16 v[52:55], v[152:155], v[198:201], v[52:55]
	v_mfma_f32_16x16x32_bf16 v[48:51], v[190:193], v[198:201], v[48:51]
	v_mfma_f32_16x16x32_bf16 v[36:39], v[152:155], v[206:209], v[36:39]
	v_mfma_f32_16x16x32_bf16 v[32:35], v[190:193], v[206:209], v[32:35]
	v_mfma_f32_16x16x32_bf16 v[20:23], v[152:155], v[214:217], v[20:23]
	v_mfma_f32_16x16x32_bf16 v[16:19], v[190:193], v[214:217], v[16:19]
	v_mfma_f32_16x16x32_bf16 v[4:7], v[152:155], v[222:225], v[4:7]
	v_mfma_f32_16x16x32_bf16 v[0:3], v[190:193], v[222:225], v[0:3]
	s_barrier
	s_setprio 0
	s_add_i32 s96, 0, 0x18000
	v_add_u32_e32 v78, s96, v181
	s_add_i32 s97, 0, 0x1c000
	ds_read_b128 v[88:91], v78
	v_xor_b32_e32 v253, 64, v78
	ds_read_b128 v[108:111], v253
	ds_read_b128 v[128:131], v78 offset:2048
	ds_read_b128 v[144:147], v253 offset:2048
	v_add_u32_e32 v78, s97, v181
	ds_read_b128 v[148:151], v78
	v_xor_b32_e32 v253, 64, v78
	ds_read_b128 v[152:155], v253
	ds_read_b128 v[176:179], v78 offset:2048
	ds_read_b128 v[190:193], v253 offset:2048
	s_add_u32 s68, s68, 0x40000
	s_addc_u32 s69, s69, 0
	s_mov_b32 m0, s76
	v_lshl_add_u64 v[78:79], s[68:69], 0, v[160:161]
	ds_read_b128 v[194:197], v187 offset:32768
	v_xor_b32_e32 v253, 64, v187
	ds_read_b128 v[198:201], v253 offset:32768
	ds_read_b128 v[202:205], v187 offset:34816
	ds_read_b128 v[206:209], v253 offset:34816
	ds_read_b128 v[210:213], v187 offset:36864
	ds_read_b128 v[214:217], v253 offset:36864
	ds_read_b128 v[218:221], v187 offset:38912
	ds_read_b128 v[222:225], v253 offset:38912
	global_load_lds_dwordx4 v[78:79], off
	v_lshl_add_u64 v[78:79], s[68:69], 0, v[164:165]
	s_mov_b32 m0, s77
	s_nop 0
	global_load_lds_dwordx4 v[78:79], off
	s_waitcnt vmcnt(8)
	s_waitcnt lgkmcnt(0)
	s_setprio 1
	s_barrier
	v_mfma_f32_16x16x32_bf16 v[140:143], v[88:91], v[194:197], v[140:143]
	v_mfma_f32_16x16x32_bf16 v[136:139], v[128:131], v[194:197], v[136:139]
	v_mfma_f32_16x16x32_bf16 v[120:123], v[88:91], v[202:205], v[120:123]
	v_mfma_f32_16x16x32_bf16 v[116:119], v[128:131], v[202:205], v[116:119]
	v_mfma_f32_16x16x32_bf16 v[100:103], v[88:91], v[210:213], v[100:103]
	v_mfma_f32_16x16x32_bf16 v[96:99], v[128:131], v[210:213], v[96:99]
	v_mfma_f32_16x16x32_bf16 v[78:81], v[88:91], v[218:221], v[80:83]
	v_mfma_f32_16x16x32_bf16 v[74:77], v[128:131], v[218:221], v[74:77]
	v_mfma_f32_16x16x32_bf16 v[140:143], v[108:111], v[198:201], v[140:143]
	v_mfma_f32_16x16x32_bf16 v[136:139], v[144:147], v[198:201], v[136:139]
	v_mfma_f32_16x16x32_bf16 v[120:123], v[108:111], v[206:209], v[120:123]
	v_mfma_f32_16x16x32_bf16 v[116:119], v[144:147], v[206:209], v[116:119]
	v_mfma_f32_16x16x32_bf16 v[100:103], v[108:111], v[214:217], v[100:103]
	v_mfma_f32_16x16x32_bf16 v[96:99], v[144:147], v[214:217], v[96:99]
	v_mfma_f32_16x16x32_bf16 v[80:83], v[108:111], v[222:225], v[78:81]
	v_mfma_f32_16x16x32_bf16 v[76:79], v[144:147], v[222:225], v[74:77]
	v_mfma_f32_16x16x32_bf16 v[132:135], v[148:151], v[194:197], v[132:135]
	v_mfma_f32_16x16x32_bf16 v[132:135], v[152:155], v[198:201], v[132:135]
	v_mfma_f32_16x16x32_bf16 v[124:127], v[190:193], v[198:201], v[124:127]
	v_mfma_f32_16x16x32_bf16 v[124:127], v[176:179], v[194:197], v[124:127]
	v_mfma_f32_16x16x32_bf16 v[104:107], v[176:179], v[202:205], v[104:107]
	v_mfma_f32_16x16x32_bf16 v[104:107], v[190:193], v[206:209], v[104:107]
	v_mfma_f32_16x16x32_bf16 v[112:115], v[152:155], v[206:209], v[112:115]
	v_mfma_f32_16x16x32_bf16 v[112:115], v[148:151], v[202:205], v[112:115]
	v_mfma_f32_16x16x32_bf16 v[92:95], v[148:151], v[210:213], v[92:95]
	v_mfma_f32_16x16x32_bf16 v[92:95], v[152:155], v[214:217], v[92:95]
	v_mfma_f32_16x16x32_bf16 v[84:87], v[190:193], v[214:217], v[84:87]
	v_mfma_f32_16x16x32_bf16 v[84:87], v[176:179], v[210:213], v[84:87]
	v_mfma_f32_16x16x32_bf16 v[64:67], v[176:179], v[218:221], v[64:67]
	v_mfma_f32_16x16x32_bf16 v[64:67], v[190:193], v[222:225], v[64:67]
	v_mfma_f32_16x16x32_bf16 v[68:71], v[152:155], v[222:225], v[68:71]
	v_mfma_f32_16x16x32_bf16 v[68:71], v[148:151], v[218:221], v[68:71]
	s_barrier
	s_setprio 0
	s_add_i32 s68, s96, s71
	v_lshl_add_u64 v[74:75], v[226:227], 0, s[28:29]
	s_mov_b32 m0, s68
	ds_read_b128 v[194:197], v187 offset:49152
	v_xor_b32_e32 v253, 64, v187
	ds_read_b128 v[198:201], v253 offset:49152
	ds_read_b128 v[202:205], v187 offset:51200
	ds_read_b128 v[206:209], v253 offset:51200
	ds_read_b128 v[210:213], v187 offset:53248
	ds_read_b128 v[214:217], v253 offset:53248
	ds_read_b128 v[218:221], v187 offset:55296
	ds_read_b128 v[222:225], v253 offset:55296
	global_load_lds_dwordx4 v[74:75], off
	s_add_i32 m0, s68, 0x2000
	s_add_u32 s66, s66, 0x40080
	v_lshl_add_u64 v[74:75], v[228:229], 0, s[28:29]
	s_addc_u32 s67, s67, 0
	s_add_i32 s68, s97, s71
	global_load_lds_dwordx4 v[74:75], off
	v_lshl_add_u64 v[74:75], s[66:67], 0, v[162:163]
	s_mov_b32 m0, s68
	s_nop 0
	global_load_lds_dwordx4 v[74:75], off
	v_lshl_add_u64 v[74:75], s[66:67], 0, v[166:167]
	s_add_i32 m0, s68, 0x2000
	s_nop 0
	global_load_lds_dwordx4 v[74:75], off
	v_lshl_add_u64 v[74:75], v[230:231], 0, s[28:29]
	s_mov_b32 m0, s78
	s_nop 0
	global_load_lds_dwordx4 v[74:75], off
	v_lshl_add_u64 v[74:75], v[232:233], 0, s[28:29]
	s_mov_b32 m0, s79
	s_nop 0
	global_load_lds_dwordx4 v[74:75], off
	s_waitcnt vmcnt(8)
	s_waitcnt lgkmcnt(0)
	s_setprio 1
	s_barrier
	v_mfma_f32_16x16x32_bf16 v[60:63], v[88:91], v[194:197], v[60:63]
	v_mfma_f32_16x16x32_bf16 v[60:63], v[108:111], v[198:201], v[60:63]
	v_mfma_f32_16x16x32_bf16 v[56:59], v[144:147], v[198:201], v[56:59]
	v_mfma_f32_16x16x32_bf16 v[56:59], v[128:131], v[194:197], v[56:59]
	v_mfma_f32_16x16x32_bf16 v[40:43], v[128:131], v[202:205], v[40:43]
	v_mfma_f32_16x16x32_bf16 v[40:43], v[144:147], v[206:209], v[40:43]
	v_mfma_f32_16x16x32_bf16 v[44:47], v[108:111], v[206:209], v[44:47]
	v_mfma_f32_16x16x32_bf16 v[44:47], v[88:91], v[202:205], v[44:47]
	v_mfma_f32_16x16x32_bf16 v[28:31], v[88:91], v[210:213], v[28:31]
	v_mfma_f32_16x16x32_bf16 v[28:31], v[108:111], v[214:217], v[28:31]
	v_mfma_f32_16x16x32_bf16 v[24:27], v[144:147], v[214:217], v[24:27]
	v_mfma_f32_16x16x32_bf16 v[24:27], v[128:131], v[210:213], v[24:27]
	v_mfma_f32_16x16x32_bf16 v[8:11], v[128:131], v[218:221], v[8:11]
	v_mfma_f32_16x16x32_bf16 v[8:11], v[144:147], v[222:225], v[8:11]
	v_mfma_f32_16x16x32_bf16 v[12:15], v[108:111], v[222:225], v[12:15]
	v_mfma_f32_16x16x32_bf16 v[12:15], v[88:91], v[218:221], v[12:15]
	v_mfma_f32_16x16x32_bf16 v[52:55], v[148:151], v[194:197], v[52:55]
	v_mfma_f32_16x16x32_bf16 v[52:55], v[152:155], v[198:201], v[52:55]
	v_mfma_f32_16x16x32_bf16 v[48:51], v[190:193], v[198:201], v[48:51]
	v_mfma_f32_16x16x32_bf16 v[48:51], v[176:179], v[194:197], v[48:51]
	v_mfma_f32_16x16x32_bf16 v[32:35], v[176:179], v[202:205], v[32:35]
	v_mfma_f32_16x16x32_bf16 v[32:35], v[190:193], v[206:209], v[32:35]
	v_mfma_f32_16x16x32_bf16 v[36:39], v[152:155], v[206:209], v[36:39]
	v_mfma_f32_16x16x32_bf16 v[36:39], v[148:151], v[202:205], v[36:39]
	v_mfma_f32_16x16x32_bf16 v[20:23], v[148:151], v[210:213], v[20:23]
	v_mfma_f32_16x16x32_bf16 v[20:23], v[152:155], v[214:217], v[20:23]
	v_mfma_f32_16x16x32_bf16 v[16:19], v[190:193], v[214:217], v[16:19]
	v_mfma_f32_16x16x32_bf16 v[16:19], v[176:179], v[210:213], v[16:19]
	v_mfma_f32_16x16x32_bf16 v[0:3], v[176:179], v[218:221], v[0:3]
	v_mfma_f32_16x16x32_bf16 v[0:3], v[190:193], v[222:225], v[0:3]
	v_mfma_f32_16x16x32_bf16 v[4:7], v[152:155], v[222:225], v[4:7]
	v_mfma_f32_16x16x32_bf16 v[4:7], v[148:151], v[218:221], v[4:7]
	s_barrier
	s_setprio 0
	s_add_i32 s95, s95, 2
	s_add_u32 s93, s93, 0x100
	s_addc_u32 s94, s94, 0
	s_add_u32 s14, s14, 0x100
	s_addc_u32 s15, s15, 0
	s_branch .LBB0_256
.Lfa_2:
	v_add_u32_e32 v74, s83, v181
	ds_read_b128 v[88:91], v74
	v_xor_b32_e32 v253, 64, v74
	ds_read_b128 v[108:111], v253
	ds_read_b128 v[128:131], v74 offset:2048
	ds_read_b128 v[144:147], v253 offset:2048
	v_add_u32_e32 v74, s84, v181
	ds_read_b128 v[148:151], v74
	v_xor_b32_e32 v253, 64, v74
	ds_read_b128 v[152:155], v253
	ds_read_b128 v[176:179], v74 offset:2048
	ds_read_b128 v[190:193], v253 offset:2048
	s_add_u32 s68, s14, 0xfffc0080
	s_addc_u32 s69, s15, -1
	s_and_b64 s[66:67], s[66:67], exec
	s_cselect_b32 s69, s3, s69
	s_cselect_b32 s68, s61, s68
	s_cselect_b32 s67, s91, s94
	s_cselect_b32 s66, s92, s93
	v_lshl_add_u64 v[74:75], s[14:15], 0, v[170:171]
	s_add_i32 m0, s74, 0xc000
	ds_read_b128 v[194:197], v187
	v_xor_b32_e32 v253, 64, v187
	ds_read_b128 v[198:201], v253
	ds_read_b128 v[202:205], v187 offset:2048
	ds_read_b128 v[206:209], v253 offset:2048
	ds_read_b128 v[210:213], v187 offset:4096
	ds_read_b128 v[214:217], v253 offset:4096
	ds_read_b128 v[218:221], v187 offset:6144
	ds_read_b128 v[222:225], v253 offset:6144
	global_load_lds_dwordx4 v[74:75], off
	v_lshl_add_u64 v[74:75], s[14:15], 0, v[168:169]
	s_add_i32 m0, s74, 0xe000
	s_nop 0
	global_load_lds_dwordx4 v[74:75], off
	s_waitcnt vmcnt(8)
	s_waitcnt lgkmcnt(0)
	s_setprio 1
	s_barrier
	v_mfma_f32_16x16x32_bf16 v[140:143], v[88:91], v[194:197], 0
	v_mfma_f32_16x16x32_bf16 v[136:139], v[128:131], v[194:197], 0
	v_mfma_f32_16x16x32_bf16 v[120:123], v[88:91], v[202:205], 0
	v_mfma_f32_16x16x32_bf16 v[116:119], v[128:131], v[202:205], 0
	v_mfma_f32_16x16x32_bf16 v[100:103], v[88:91], v[210:213], 0
	v_mfma_f32_16x16x32_bf16 v[96:99], v[128:131], v[210:213], 0
	v_mfma_f32_16x16x32_bf16 v[80:83], v[88:91], v[218:221], 0
	v_mfma_f32_16x16x32_bf16 v[74:77], v[128:131], v[218:221], 0
	v_mfma_f32_16x16x32_bf16 v[140:143], v[108:111], v[198:201], v[140:143]
	v_mfma_f32_16x16x32_bf16 v[136:139], v[144:147], v[198:201], v[136:139]
	v_mfma_f32_16x16x32_bf16 v[120:123], v[108:111], v[206:209], v[120:123]
	v_mfma_f32_16x16x32_bf16 v[116:119], v[144:147], v[206:209], v[116:119]
	v_mfma_f32_16x16x32_bf16 v[100:103], v[108:111], v[214:217], v[100:103]
	v_mfma_f32_16x16x32_bf16 v[96:99], v[144:147], v[214:217], v[96:99]
	v_mfma_f32_16x16x32_bf16 v[80:83], v[108:111], v[222:225], v[80:83]
	v_mfma_f32_16x16x32_bf16 v[74:77], v[144:147], v[222:225], v[74:77]
	v_mfma_f32_16x16x32_bf16 v[132:135], v[148:151], v[194:197], 0
	v_mfma_f32_16x16x32_bf16 v[124:127], v[176:179], v[194:197], 0
	v_mfma_f32_16x16x32_bf16 v[112:115], v[148:151], v[202:205], 0
	v_mfma_f32_16x16x32_bf16 v[104:107], v[176:179], v[202:205], 0
	v_mfma_f32_16x16x32_bf16 v[92:95], v[148:151], v[210:213], 0
	v_mfma_f32_16x16x32_bf16 v[84:87], v[176:179], v[210:213], 0
	v_mfma_f32_16x16x32_bf16 v[68:71], v[148:151], v[218:221], 0
	v_mfma_f32_16x16x32_bf16 v[64:67], v[176:179], v[218:221], 0
	v_mfma_f32_16x16x32_bf16 v[132:135], v[152:155], v[198:201], v[132:135]
	v_mfma_f32_16x16x32_bf16 v[124:127], v[190:193], v[198:201], v[124:127]
	v_mfma_f32_16x16x32_bf16 v[112:115], v[152:155], v[206:209], v[112:115]
	v_mfma_f32_16x16x32_bf16 v[104:107], v[190:193], v[206:209], v[104:107]
	v_mfma_f32_16x16x32_bf16 v[92:95], v[152:155], v[214:217], v[92:95]
	v_mfma_f32_16x16x32_bf16 v[84:87], v[190:193], v[214:217], v[84:87]
	v_mfma_f32_16x16x32_bf16 v[68:71], v[152:155], v[222:225], v[68:71]
	v_mfma_f32_16x16x32_bf16 v[64:67], v[190:193], v[222:225], v[64:67]
	s_barrier
	s_setprio 0
	s_add_i32 s96, s83, s71
	v_lshl_add_u64 v[226:227], s[66:67], 0, v[162:163]
	s_mov_b32 m0, s96
	ds_read_b128 v[194:197], v187 offset:16384
	v_xor_b32_e32 v253, 64, v187
	ds_read_b128 v[198:201], v253 offset:16384
	ds_read_b128 v[202:205], v187 offset:18432
	ds_read_b128 v[206:209], v253 offset:18432
	ds_read_b128 v[210:213], v187 offset:20480
	ds_read_b128 v[214:217], v253 offset:20480
	ds_read_b128 v[218:221], v187 offset:22528
	ds_read_b128 v[222:225], v253 offset:22528
	global_load_lds_dwordx4 v[226:227], off
	s_add_i32 m0, s96, 0x2000
	s_add_u32 s96, s66, 0x40000
	v_lshl_add_u64 v[228:229], s[66:67], 0, v[166:167]
	s_addc_u32 s97, s67, 0
	s_add_i32 vcc_lo, s84, s71
	global_load_lds_dwordx4 v[228:229], off
	v_lshl_add_u64 v[78:79], s[96:97], 0, v[162:163]
	s_mov_b32 m0, vcc_lo
	v_lshl_add_u64 v[230:231], s[68:69], 0, v[160:161]
	global_load_lds_dwordx4 v[78:79], off
	v_lshl_add_u64 v[78:79], s[96:97], 0, v[166:167]
	s_add_i32 m0, vcc_lo, 0x2000
	v_lshl_add_u64 v[232:233], s[68:69], 0, v[164:165]
	global_load_lds_dwordx4 v[78:79], off
	s_mov_b32 m0, s74
	s_nop 0
	global_load_lds_dwordx4 v[230:231], off
	s_mov_b32 m0, s75
	s_nop 0
	global_load_lds_dwordx4 v[232:233], off
	s_waitcnt vmcnt(8)
	s_waitcnt lgkmcnt(0)
	s_setprio 1
	s_barrier
	v_mfma_f32_16x16x32_bf16 v[60:63], v[88:91], v[194:197], 0
	v_mfma_f32_16x16x32_bf16 v[56:59], v[128:131], v[194:197], 0
	v_mfma_f32_16x16x32_bf16 v[44:47], v[88:91], v[202:205], 0
	v_mfma_f32_16x16x32_bf16 v[40:43], v[128:131], v[202:205], 0
	v_mfma_f32_16x16x32_bf16 v[28:31], v[88:91], v[210:213], 0
	v_mfma_f32_16x16x32_bf16 v[24:27], v[128:131], v[210:213], 0
	v_mfma_f32_16x16x32_bf16 v[12:15], v[88:91], v[218:221], 0
	v_mfma_f32_16x16x32_bf16 v[8:11], v[128:131], v[218:221], 0
	v_mfma_f32_16x16x32_bf16 v[60:63], v[108:111], v[198:201], v[60:63]
	v_mfma_f32_16x16x32_bf16 v[56:59], v[144:147], v[198:201], v[56:59]
	v_mfma_f32_16x16x32_bf16 v[44:47], v[108:111], v[206:209], v[44:47]
	v_mfma_f32_16x16x32_bf16 v[40:43], v[144:147], v[206:209], v[40:43]
	v_mfma_f32_16x16x32_bf16 v[28:31], v[108:111], v[214:217], v[28:31]
	v_mfma_f32_16x16x32_bf16 v[24:27], v[144:147], v[214:217], v[24:27]
	v_mfma_f32_16x16x32_bf16 v[12:15], v[108:111], v[222:225], v[12:15]
	v_mfma_f32_16x16x32_bf16 v[8:11], v[144:147], v[222:225], v[8:11]
	v_mfma_f32_16x16x32_bf16 v[52:55], v[148:151], v[194:197], 0
	v_mfma_f32_16x16x32_bf16 v[48:51], v[176:179], v[194:197], 0
	v_mfma_f32_16x16x32_bf16 v[36:39], v[148:151], v[202:205], 0
	v_mfma_f32_16x16x32_bf16 v[32:35], v[176:179], v[202:205], 0
	v_mfma_f32_16x16x32_bf16 v[20:23], v[148:151], v[210:213], 0
	v_mfma_f32_16x16x32_bf16 v[16:19], v[176:179], v[210:213], 0
	v_mfma_f32_16x16x32_bf16 v[4:7], v[148:151], v[218:221], 0
	v_mfma_f32_16x16x32_bf16 v[0:3], v[176:179], v[218:221], 0
	v_mfma_f32_16x16x32_bf16 v[52:55], v[152:155], v[198:201], v[52:55]
	v_mfma_f32_16x16x32_bf16 v[48:51], v[190:193], v[198:201], v[48:51]
	v_mfma_f32_16x16x32_bf16 v[36:39], v[152:155], v[206:209], v[36:39]
	v_mfma_f32_16x16x32_bf16 v[32:35], v[190:193], v[206:209], v[32:35]
	v_mfma_f32_16x16x32_bf16 v[20:23], v[152:155], v[214:217], v[20:23]
	v_mfma_f32_16x16x32_bf16 v[16:19], v[190:193], v[214:217], v[16:19]
	v_mfma_f32_16x16x32_bf16 v[4:7], v[152:155], v[222:225], v[4:7]
	v_mfma_f32_16x16x32_bf16 v[0:3], v[190:193], v[222:225], v[0:3]
	s_barrier
	s_setprio 0
	s_add_i32 s96, 0, 0x18000
	v_add_u32_e32 v78, s96, v181
	s_add_i32 s97, 0, 0x1c000
	ds_read_b128 v[88:91], v78
	v_xor_b32_e32 v253, 64, v78
	ds_read_b128 v[108:111], v253
	ds_read_b128 v[128:131], v78 offset:2048
	ds_read_b128 v[144:147], v253 offset:2048
	v_add_u32_e32 v78, s97, v181
	ds_read_b128 v[148:151], v78
	v_xor_b32_e32 v253, 64, v78
	ds_read_b128 v[152:155], v253
	ds_read_b128 v[176:179], v78 offset:2048
	ds_read_b128 v[190:193], v253 offset:2048
	s_add_u32 s68, s68, 0x40000
	s_addc_u32 s69, s69, 0
	s_mov_b32 m0, s76
	v_lshl_add_u64 v[78:79], s[68:69], 0, v[160:161]
	ds_read_b128 v[194:197], v187 offset:32768
	v_xor_b32_e32 v253, 64, v187
	ds_read_b128 v[198:201], v253 offset:32768
	ds_read_b128 v[202:205], v187 offset:34816
	ds_read_b128 v[206:209], v253 offset:34816
	ds_read_b128 v[210:213], v187 offset:36864
	ds_read_b128 v[214:217], v253 offset:36864
	ds_read_b128 v[218:221], v187 offset:38912
	ds_read_b128 v[222:225], v253 offset:38912
	global_load_lds_dwordx4 v[78:79], off
	v_lshl_add_u64 v[78:79], s[68:69], 0, v[164:165]
	s_mov_b32 m0, s77
	s_nop 0
	global_load_lds_dwordx4 v[78:79], off
	s_waitcnt vmcnt(8)
	s_waitcnt lgkmcnt(0)
	s_setprio 1
	s_barrier
	v_mfma_f32_16x16x32_bf16 v[140:143], v[88:91], v[194:197], v[140:143]
	v_mfma_f32_16x16x32_bf16 v[136:139], v[128:131], v[194:197], v[136:139]
	v_mfma_f32_16x16x32_bf16 v[120:123], v[88:91], v[202:205], v[120:123]
	v_mfma_f32_16x16x32_bf16 v[116:119], v[128:131], v[202:205], v[116:119]
	v_mfma_f32_16x16x32_bf16 v[100:103], v[88:91], v[210:213], v[100:103]
	v_mfma_f32_16x16x32_bf16 v[96:99], v[128:131], v[210:213], v[96:99]
	v_mfma_f32_16x16x32_bf16 v[78:81], v[88:91], v[218:221], v[80:83]
	v_mfma_f32_16x16x32_bf16 v[74:77], v[128:131], v[218:221], v[74:77]
	v_mfma_f32_16x16x32_bf16 v[140:143], v[108:111], v[198:201], v[140:143]
	v_mfma_f32_16x16x32_bf16 v[136:139], v[144:147], v[198:201], v[136:139]
	v_mfma_f32_16x16x32_bf16 v[120:123], v[108:111], v[206:209], v[120:123]
	v_mfma_f32_16x16x32_bf16 v[116:119], v[144:147], v[206:209], v[116:119]
	v_mfma_f32_16x16x32_bf16 v[100:103], v[108:111], v[214:217], v[100:103]
	v_mfma_f32_16x16x32_bf16 v[96:99], v[144:147], v[214:217], v[96:99]
	v_mfma_f32_16x16x32_bf16 v[80:83], v[108:111], v[222:225], v[78:81]
	v_mfma_f32_16x16x32_bf16 v[76:79], v[144:147], v[222:225], v[74:77]
	v_mfma_f32_16x16x32_bf16 v[132:135], v[148:151], v[194:197], v[132:135]
	v_mfma_f32_16x16x32_bf16 v[132:135], v[152:155], v[198:201], v[132:135]
	v_mfma_f32_16x16x32_bf16 v[124:127], v[190:193], v[198:201], v[124:127]
	v_mfma_f32_16x16x32_bf16 v[124:127], v[176:179], v[194:197], v[124:127]
	v_mfma_f32_16x16x32_bf16 v[104:107], v[176:179], v[202:205], v[104:107]
	v_mfma_f32_16x16x32_bf16 v[104:107], v[190:193], v[206:209], v[104:107]
	v_mfma_f32_16x16x32_bf16 v[112:115], v[152:155], v[206:209], v[112:115]
	v_mfma_f32_16x16x32_bf16 v[112:115], v[148:151], v[202:205], v[112:115]
	v_mfma_f32_16x16x32_bf16 v[92:95], v[148:151], v[210:213], v[92:95]
	v_mfma_f32_16x16x32_bf16 v[92:95], v[152:155], v[214:217], v[92:95]
	v_mfma_f32_16x16x32_bf16 v[84:87], v[190:193], v[214:217], v[84:87]
	v_mfma_f32_16x16x32_bf16 v[84:87], v[176:179], v[210:213], v[84:87]
	v_mfma_f32_16x16x32_bf16 v[64:67], v[176:179], v[218:221], v[64:67]
	v_mfma_f32_16x16x32_bf16 v[64:67], v[190:193], v[222:225], v[64:67]
	v_mfma_f32_16x16x32_bf16 v[68:71], v[152:155], v[222:225], v[68:71]
	v_mfma_f32_16x16x32_bf16 v[68:71], v[148:151], v[218:221], v[68:71]
	s_barrier
	s_setprio 0
	s_add_i32 s68, s96, s71
	v_lshl_add_u64 v[74:75], v[226:227], 0, s[28:29]
	s_mov_b32 m0, s68
	ds_read_b128 v[194:197], v187 offset:49152
	v_xor_b32_e32 v253, 64, v187
	ds_read_b128 v[198:201], v253 offset:49152
	ds_read_b128 v[202:205], v187 offset:51200
	ds_read_b128 v[206:209], v253 offset:51200
	ds_read_b128 v[210:213], v187 offset:53248
	ds_read_b128 v[214:217], v253 offset:53248
	ds_read_b128 v[218:221], v187 offset:55296
	ds_read_b128 v[222:225], v253 offset:55296
	global_load_lds_dwordx4 v[74:75], off
	s_add_i32 m0, s68, 0x2000
	s_add_u32 s66, s66, 0x40080
	v_lshl_add_u64 v[74:75], v[228:229], 0, s[28:29]
	s_addc_u32 s67, s67, 0
	s_add_i32 s68, s97, s71
	global_load_lds_dwordx4 v[74:75], off
	v_lshl_add_u64 v[74:75], s[66:67], 0, v[162:163]
	s_mov_b32 m0, s68
	s_nop 0
	global_load_lds_dwordx4 v[74:75], off
	v_lshl_add_u64 v[74:75], s[66:67], 0, v[166:167]
	s_add_i32 m0, s68, 0x2000
	s_nop 0
	global_load_lds_dwordx4 v[74:75], off
	v_lshl_add_u64 v[74:75], v[230:231], 0, s[28:29]
	s_mov_b32 m0, s78
	s_nop 0
	global_load_lds_dwordx4 v[74:75], off
	v_lshl_add_u64 v[74:75], v[232:233], 0, s[28:29]
	s_mov_b32 m0, s79
	s_nop 0
	global_load_lds_dwordx4 v[74:75], off
	s_waitcnt vmcnt(8)
	s_waitcnt lgkmcnt(0)
	s_setprio 1
	s_barrier
	v_mfma_f32_16x16x32_bf16 v[60:63], v[88:91], v[194:197], v[60:63]
	v_mfma_f32_16x16x32_bf16 v[60:63], v[108:111], v[198:201], v[60:63]
	v_mfma_f32_16x16x32_bf16 v[56:59], v[144:147], v[198:201], v[56:59]
	v_mfma_f32_16x16x32_bf16 v[56:59], v[128:131], v[194:197], v[56:59]
	v_mfma_f32_16x16x32_bf16 v[40:43], v[128:131], v[202:205], v[40:43]
	v_mfma_f32_16x16x32_bf16 v[40:43], v[144:147], v[206:209], v[40:43]
	v_mfma_f32_16x16x32_bf16 v[44:47], v[108:111], v[206:209], v[44:47]
	v_mfma_f32_16x16x32_bf16 v[44:47], v[88:91], v[202:205], v[44:47]
	v_mfma_f32_16x16x32_bf16 v[28:31], v[88:91], v[210:213], v[28:31]
	v_mfma_f32_16x16x32_bf16 v[28:31], v[108:111], v[214:217], v[28:31]
	v_mfma_f32_16x16x32_bf16 v[24:27], v[144:147], v[214:217], v[24:27]
	v_mfma_f32_16x16x32_bf16 v[24:27], v[128:131], v[210:213], v[24:27]
	v_mfma_f32_16x16x32_bf16 v[8:11], v[128:131], v[218:221], v[8:11]
	v_mfma_f32_16x16x32_bf16 v[8:11], v[144:147], v[222:225], v[8:11]
	v_mfma_f32_16x16x32_bf16 v[12:15], v[108:111], v[222:225], v[12:15]
	v_mfma_f32_16x16x32_bf16 v[12:15], v[88:91], v[218:221], v[12:15]
	v_mfma_f32_16x16x32_bf16 v[52:55], v[148:151], v[194:197], v[52:55]
	v_mfma_f32_16x16x32_bf16 v[52:55], v[152:155], v[198:201], v[52:55]
	v_mfma_f32_16x16x32_bf16 v[48:51], v[190:193], v[198:201], v[48:51]
	v_mfma_f32_16x16x32_bf16 v[48:51], v[176:179], v[194:197], v[48:51]
	v_mfma_f32_16x16x32_bf16 v[32:35], v[176:179], v[202:205], v[32:35]
	v_mfma_f32_16x16x32_bf16 v[32:35], v[190:193], v[206:209], v[32:35]
	v_mfma_f32_16x16x32_bf16 v[36:39], v[152:155], v[206:209], v[36:39]
	v_mfma_f32_16x16x32_bf16 v[36:39], v[148:151], v[202:205], v[36:39]
	v_mfma_f32_16x16x32_bf16 v[20:23], v[148:151], v[210:213], v[20:23]
	v_mfma_f32_16x16x32_bf16 v[20:23], v[152:155], v[214:217], v[20:23]
	v_mfma_f32_16x16x32_bf16 v[16:19], v[190:193], v[214:217], v[16:19]
	v_mfma_f32_16x16x32_bf16 v[16:19], v[176:179], v[210:213], v[16:19]
	v_mfma_f32_16x16x32_bf16 v[0:3], v[176:179], v[218:221], v[0:3]
	v_mfma_f32_16x16x32_bf16 v[0:3], v[190:193], v[222:225], v[0:3]
	v_mfma_f32_16x16x32_bf16 v[4:7], v[152:155], v[222:225], v[4:7]
	v_mfma_f32_16x16x32_bf16 v[4:7], v[148:151], v[218:221], v[4:7]
	s_barrier
	s_setprio 0
	s_add_i32 s95, s95, 2
	s_add_u32 s93, s93, 0x100
	s_addc_u32 s94, s94, 0
	s_add_u32 s14, s14, 0x100
	s_addc_u32 s15, s15, 0
	s_branch .LBB0_256
.LBB0_255:
	v_add_u32_e32 v74, s83, v181
	ds_read_b128 v[88:91], v74
	v_xor_b32_e32 v253, 64, v74
	ds_read_b128 v[108:111], v253
	ds_read_b128 v[128:131], v74 offset:2048
	ds_read_b128 v[144:147], v253 offset:2048
	v_add_u32_e32 v74, s84, v181
	ds_read_b128 v[148:151], v74
	v_xor_b32_e32 v253, 64, v74
	ds_read_b128 v[152:155], v253
	ds_read_b128 v[176:179], v74 offset:2048
	ds_read_b128 v[190:193], v253 offset:2048
	s_add_u32 s68, s14, 0xfffc0080
	s_addc_u32 s69, s15, -1
	s_and_b64 s[66:67], s[66:67], exec
	s_cselect_b32 s69, s3, s69
	s_cselect_b32 s68, s61, s68
	s_cselect_b32 s67, s91, s94
	s_cselect_b32 s66, s92, s93
	v_lshl_add_u64 v[74:75], s[14:15], 0, v[170:171]
	s_add_i32 m0, s74, 0xc000
	ds_read_b128 v[194:197], v187
	v_xor_b32_e32 v253, 64, v187
	ds_read_b128 v[198:201], v253
	ds_read_b128 v[202:205], v187 offset:2048
	ds_read_b128 v[206:209], v253 offset:2048
	ds_read_b128 v[210:213], v187 offset:4096
	ds_read_b128 v[214:217], v253 offset:4096
	ds_read_b128 v[218:221], v187 offset:6144
	ds_read_b128 v[222:225], v253 offset:6144
	global_load_lds_dwordx4 v[74:75], off
	v_lshl_add_u64 v[74:75], s[14:15], 0, v[168:169]
	s_add_i32 m0, s74, 0xe000
	s_nop 0
	global_load_lds_dwordx4 v[74:75], off
	s_waitcnt vmcnt(8)
	s_waitcnt lgkmcnt(0)
	s_setprio 1
	s_barrier
	v_mfma_f32_16x16x32_bf16 v[140:143], v[88:91], v[194:197], v[140:143]
	v_mfma_f32_16x16x32_bf16 v[136:139], v[128:131], v[194:197], v[136:139]
	v_mfma_f32_16x16x32_bf16 v[120:123], v[88:91], v[202:205], v[120:123]
	v_mfma_f32_16x16x32_bf16 v[116:119], v[128:131], v[202:205], v[116:119]
	v_mfma_f32_16x16x32_bf16 v[100:103], v[88:91], v[210:213], v[100:103]
	v_mfma_f32_16x16x32_bf16 v[96:99], v[128:131], v[210:213], v[96:99]
	v_mfma_f32_16x16x32_bf16 v[80:83], v[88:91], v[218:221], v[80:83]
	v_mfma_f32_16x16x32_bf16 v[74:77], v[128:131], v[218:221], v[76:79]
	v_mfma_f32_16x16x32_bf16 v[140:143], v[108:111], v[198:201], v[140:143]
	v_mfma_f32_16x16x32_bf16 v[136:139], v[144:147], v[198:201], v[136:139]
	v_mfma_f32_16x16x32_bf16 v[120:123], v[108:111], v[206:209], v[120:123]
	v_mfma_f32_16x16x32_bf16 v[116:119], v[144:147], v[206:209], v[116:119]
	v_mfma_f32_16x16x32_bf16 v[100:103], v[108:111], v[214:217], v[100:103]
	v_mfma_f32_16x16x32_bf16 v[96:99], v[144:147], v[214:217], v[96:99]
	v_mfma_f32_16x16x32_bf16 v[80:83], v[108:111], v[222:225], v[80:83]
	v_mfma_f32_16x16x32_bf16 v[74:77], v[144:147], v[222:225], v[74:77]
	v_mfma_f32_16x16x32_bf16 v[132:135], v[148:151], v[194:197], v[132:135]
	v_mfma_f32_16x16x32_bf16 v[132:135], v[152:155], v[198:201], v[132:135]
	v_mfma_f32_16x16x32_bf16 v[124:127], v[190:193], v[198:201], v[124:127]
	v_mfma_f32_16x16x32_bf16 v[124:127], v[176:179], v[194:197], v[124:127]
	v_mfma_f32_16x16x32_bf16 v[104:107], v[176:179], v[202:205], v[104:107]
	v_mfma_f32_16x16x32_bf16 v[104:107], v[190:193], v[206:209], v[104:107]
	v_mfma_f32_16x16x32_bf16 v[112:115], v[152:155], v[206:209], v[112:115]
	v_mfma_f32_16x16x32_bf16 v[112:115], v[148:151], v[202:205], v[112:115]
	v_mfma_f32_16x16x32_bf16 v[92:95], v[148:151], v[210:213], v[92:95]
	v_mfma_f32_16x16x32_bf16 v[92:95], v[152:155], v[214:217], v[92:95]
	v_mfma_f32_16x16x32_bf16 v[84:87], v[190:193], v[214:217], v[84:87]
	v_mfma_f32_16x16x32_bf16 v[84:87], v[176:179], v[210:213], v[84:87]
	v_mfma_f32_16x16x32_bf16 v[64:67], v[176:179], v[218:221], v[64:67]
	v_mfma_f32_16x16x32_bf16 v[64:67], v[190:193], v[222:225], v[64:67]
	v_mfma_f32_16x16x32_bf16 v[68:71], v[152:155], v[222:225], v[68:71]
	v_mfma_f32_16x16x32_bf16 v[68:71], v[148:151], v[218:221], v[68:71]
	s_barrier
	s_setprio 0
	s_add_i32 s96, s83, s71
	v_lshl_add_u64 v[226:227], s[66:67], 0, v[162:163]
	s_mov_b32 m0, s96
	ds_read_b128 v[194:197], v187 offset:16384
	v_xor_b32_e32 v253, 64, v187
	ds_read_b128 v[198:201], v253 offset:16384
	ds_read_b128 v[202:205], v187 offset:18432
	ds_read_b128 v[206:209], v253 offset:18432
	ds_read_b128 v[210:213], v187 offset:20480
	ds_read_b128 v[214:217], v253 offset:20480
	ds_read_b128 v[218:221], v187 offset:22528
	ds_read_b128 v[222:225], v253 offset:22528
	global_load_lds_dwordx4 v[226:227], off
	s_add_i32 m0, s96, 0x2000
	s_add_u32 s96, s66, 0x40000
	v_lshl_add_u64 v[228:229], s[66:67], 0, v[166:167]
	s_addc_u32 s97, s67, 0
	s_add_i32 vcc_lo, s84, s71
	global_load_lds_dwordx4 v[228:229], off
	v_lshl_add_u64 v[78:79], s[96:97], 0, v[162:163]
	s_mov_b32 m0, vcc_lo
	v_lshl_add_u64 v[230:231], s[68:69], 0, v[160:161]
	global_load_lds_dwordx4 v[78:79], off
	v_lshl_add_u64 v[78:79], s[96:97], 0, v[166:167]
	s_add_i32 m0, vcc_lo, 0x2000
	v_lshl_add_u64 v[232:233], s[68:69], 0, v[164:165]
	global_load_lds_dwordx4 v[78:79], off
	s_mov_b32 m0, s74
	s_nop 0
	global_load_lds_dwordx4 v[230:231], off
	s_mov_b32 m0, s75
	s_nop 0
	global_load_lds_dwordx4 v[232:233], off
	s_waitcnt vmcnt(8)
	s_waitcnt lgkmcnt(0)
	s_setprio 1
	s_barrier
	v_mfma_f32_16x16x32_bf16 v[60:63], v[88:91], v[194:197], v[60:63]
	v_mfma_f32_16x16x32_bf16 v[60:63], v[108:111], v[198:201], v[60:63]
	v_mfma_f32_16x16x32_bf16 v[56:59], v[144:147], v[198:201], v[56:59]
	v_mfma_f32_16x16x32_bf16 v[56:59], v[128:131], v[194:197], v[56:59]
	v_mfma_f32_16x16x32_bf16 v[40:43], v[128:131], v[202:205], v[40:43]
	v_mfma_f32_16x16x32_bf16 v[40:43], v[144:147], v[206:209], v[40:43]
	v_mfma_f32_16x16x32_bf16 v[44:47], v[108:111], v[206:209], v[44:47]
	v_mfma_f32_16x16x32_bf16 v[44:47], v[88:91], v[202:205], v[44:47]
	v_mfma_f32_16x16x32_bf16 v[28:31], v[88:91], v[210:213], v[28:31]
	v_mfma_f32_16x16x32_bf16 v[28:31], v[108:111], v[214:217], v[28:31]
	v_mfma_f32_16x16x32_bf16 v[24:27], v[144:147], v[214:217], v[24:27]
	v_mfma_f32_16x16x32_bf16 v[24:27], v[128:131], v[210:213], v[24:27]
	v_mfma_f32_16x16x32_bf16 v[8:11], v[128:131], v[218:221], v[8:11]
	v_mfma_f32_16x16x32_bf16 v[8:11], v[144:147], v[222:225], v[8:11]
	v_mfma_f32_16x16x32_bf16 v[12:15], v[108:111], v[222:225], v[12:15]
	v_mfma_f32_16x16x32_bf16 v[12:15], v[88:91], v[218:221], v[12:15]
	v_mfma_f32_16x16x32_bf16 v[52:55], v[148:151], v[194:197], v[52:55]
	v_mfma_f32_16x16x32_bf16 v[52:55], v[152:155], v[198:201], v[52:55]
	v_mfma_f32_16x16x32_bf16 v[48:51], v[190:193], v[198:201], v[48:51]
	v_mfma_f32_16x16x32_bf16 v[48:51], v[176:179], v[194:197], v[48:51]
	v_mfma_f32_16x16x32_bf16 v[32:35], v[176:179], v[202:205], v[32:35]
	v_mfma_f32_16x16x32_bf16 v[32:35], v[190:193], v[206:209], v[32:35]
	v_mfma_f32_16x16x32_bf16 v[36:39], v[152:155], v[206:209], v[36:39]
	v_mfma_f32_16x16x32_bf16 v[36:39], v[148:151], v[202:205], v[36:39]
	v_mfma_f32_16x16x32_bf16 v[20:23], v[148:151], v[210:213], v[20:23]
	v_mfma_f32_16x16x32_bf16 v[20:23], v[152:155], v[214:217], v[20:23]
	v_mfma_f32_16x16x32_bf16 v[16:19], v[190:193], v[214:217], v[16:19]
	v_mfma_f32_16x16x32_bf16 v[16:19], v[176:179], v[210:213], v[16:19]
	v_mfma_f32_16x16x32_bf16 v[0:3], v[176:179], v[218:221], v[0:3]
	v_mfma_f32_16x16x32_bf16 v[0:3], v[190:193], v[222:225], v[0:3]
	v_mfma_f32_16x16x32_bf16 v[4:7], v[152:155], v[222:225], v[4:7]
	v_mfma_f32_16x16x32_bf16 v[4:7], v[148:151], v[218:221], v[4:7]
	s_barrier
	s_setprio 0
	s_add_i32 s96, 0, 0x18000
	v_add_u32_e32 v78, s96, v181
	s_add_i32 s97, 0, 0x1c000
	ds_read_b128 v[88:91], v78
	v_xor_b32_e32 v253, 64, v78
	ds_read_b128 v[108:111], v253
	ds_read_b128 v[128:131], v78 offset:2048
	ds_read_b128 v[144:147], v253 offset:2048
	v_add_u32_e32 v78, s97, v181
	ds_read_b128 v[148:151], v78
	v_xor_b32_e32 v253, 64, v78
	ds_read_b128 v[152:155], v253
	ds_read_b128 v[176:179], v78 offset:2048
	ds_read_b128 v[190:193], v253 offset:2048
	s_add_u32 s68, s68, 0x40000
	s_addc_u32 s69, s69, 0
	s_mov_b32 m0, s76
	v_lshl_add_u64 v[78:79], s[68:69], 0, v[160:161]
	ds_read_b128 v[194:197], v187 offset:32768
	v_xor_b32_e32 v253, 64, v187
	ds_read_b128 v[198:201], v253 offset:32768
	ds_read_b128 v[202:205], v187 offset:34816
	ds_read_b128 v[206:209], v253 offset:34816
	ds_read_b128 v[210:213], v187 offset:36864
	ds_read_b128 v[214:217], v253 offset:36864
	ds_read_b128 v[218:221], v187 offset:38912
	ds_read_b128 v[222:225], v253 offset:38912
	global_load_lds_dwordx4 v[78:79], off
	v_lshl_add_u64 v[78:79], s[68:69], 0, v[164:165]
	s_mov_b32 m0, s77
	s_nop 0
	global_load_lds_dwordx4 v[78:79], off
	s_waitcnt vmcnt(8)
	s_waitcnt lgkmcnt(0)
	s_setprio 1
	s_barrier
	v_mfma_f32_16x16x32_bf16 v[140:143], v[88:91], v[194:197], v[140:143]
	v_mfma_f32_16x16x32_bf16 v[136:139], v[128:131], v[194:197], v[136:139]
	v_mfma_f32_16x16x32_bf16 v[120:123], v[88:91], v[202:205], v[120:123]
	v_mfma_f32_16x16x32_bf16 v[116:119], v[128:131], v[202:205], v[116:119]
	v_mfma_f32_16x16x32_bf16 v[100:103], v[88:91], v[210:213], v[100:103]
	v_mfma_f32_16x16x32_bf16 v[96:99], v[128:131], v[210:213], v[96:99]
	v_mfma_f32_16x16x32_bf16 v[78:81], v[88:91], v[218:221], v[80:83]
	v_mfma_f32_16x16x32_bf16 v[74:77], v[128:131], v[218:221], v[74:77]
	v_mfma_f32_16x16x32_bf16 v[140:143], v[108:111], v[198:201], v[140:143]
	v_mfma_f32_16x16x32_bf16 v[136:139], v[144:147], v[198:201], v[136:139]
	v_mfma_f32_16x16x32_bf16 v[120:123], v[108:111], v[206:209], v[120:123]
	v_mfma_f32_16x16x32_bf16 v[116:119], v[144:147], v[206:209], v[116:119]
	v_mfma_f32_16x16x32_bf16 v[100:103], v[108:111], v[214:217], v[100:103]
	v_mfma_f32_16x16x32_bf16 v[96:99], v[144:147], v[214:217], v[96:99]
	v_mfma_f32_16x16x32_bf16 v[80:83], v[108:111], v[222:225], v[78:81]
	v_mfma_f32_16x16x32_bf16 v[76:79], v[144:147], v[222:225], v[74:77]
	v_mfma_f32_16x16x32_bf16 v[132:135], v[148:151], v[194:197], v[132:135]
	v_mfma_f32_16x16x32_bf16 v[132:135], v[152:155], v[198:201], v[132:135]
	v_mfma_f32_16x16x32_bf16 v[124:127], v[190:193], v[198:201], v[124:127]
	v_mfma_f32_16x16x32_bf16 v[124:127], v[176:179], v[194:197], v[124:127]
	v_mfma_f32_16x16x32_bf16 v[104:107], v[176:179], v[202:205], v[104:107]
	v_mfma_f32_16x16x32_bf16 v[104:107], v[190:193], v[206:209], v[104:107]
	v_mfma_f32_16x16x32_bf16 v[112:115], v[152:155], v[206:209], v[112:115]
	v_mfma_f32_16x16x32_bf16 v[112:115], v[148:151], v[202:205], v[112:115]
	v_mfma_f32_16x16x32_bf16 v[92:95], v[148:151], v[210:213], v[92:95]
	v_mfma_f32_16x16x32_bf16 v[92:95], v[152:155], v[214:217], v[92:95]
	v_mfma_f32_16x16x32_bf16 v[84:87], v[190:193], v[214:217], v[84:87]
	v_mfma_f32_16x16x32_bf16 v[84:87], v[176:179], v[210:213], v[84:87]
	v_mfma_f32_16x16x32_bf16 v[64:67], v[176:179], v[218:221], v[64:67]
	v_mfma_f32_16x16x32_bf16 v[64:67], v[190:193], v[222:225], v[64:67]
	v_mfma_f32_16x16x32_bf16 v[68:71], v[152:155], v[222:225], v[68:71]
	v_mfma_f32_16x16x32_bf16 v[68:71], v[148:151], v[218:221], v[68:71]
	s_barrier
	s_setprio 0
	s_add_i32 s68, s96, s71
	v_lshl_add_u64 v[74:75], v[226:227], 0, s[28:29]
	s_mov_b32 m0, s68
	ds_read_b128 v[194:197], v187 offset:49152
	v_xor_b32_e32 v253, 64, v187
	ds_read_b128 v[198:201], v253 offset:49152
	ds_read_b128 v[202:205], v187 offset:51200
	ds_read_b128 v[206:209], v253 offset:51200
	ds_read_b128 v[210:213], v187 offset:53248
	ds_read_b128 v[214:217], v253 offset:53248
	ds_read_b128 v[218:221], v187 offset:55296
	ds_read_b128 v[222:225], v253 offset:55296
	global_load_lds_dwordx4 v[74:75], off
	s_add_i32 m0, s68, 0x2000
	s_add_u32 s66, s66, 0x40080
	v_lshl_add_u64 v[74:75], v[228:229], 0, s[28:29]
	s_addc_u32 s67, s67, 0
	s_add_i32 s68, s97, s71
	global_load_lds_dwordx4 v[74:75], off
	v_lshl_add_u64 v[74:75], s[66:67], 0, v[162:163]
	s_mov_b32 m0, s68
	s_nop 0
	global_load_lds_dwordx4 v[74:75], off
	v_lshl_add_u64 v[74:75], s[66:67], 0, v[166:167]
	s_add_i32 m0, s68, 0x2000
	s_nop 0
	global_load_lds_dwordx4 v[74:75], off
	v_lshl_add_u64 v[74:75], v[230:231], 0, s[28:29]
	s_mov_b32 m0, s78
	s_nop 0
	global_load_lds_dwordx4 v[74:75], off
	v_lshl_add_u64 v[74:75], v[232:233], 0, s[28:29]
	s_mov_b32 m0, s79
	s_nop 0
	global_load_lds_dwordx4 v[74:75], off
	s_waitcnt vmcnt(8)
	s_waitcnt lgkmcnt(0)
	s_setprio 1
	s_barrier
	v_mfma_f32_16x16x32_bf16 v[60:63], v[88:91], v[194:197], v[60:63]
	v_mfma_f32_16x16x32_bf16 v[60:63], v[108:111], v[198:201], v[60:63]
	v_mfma_f32_16x16x32_bf16 v[56:59], v[144:147], v[198:201], v[56:59]
	v_mfma_f32_16x16x32_bf16 v[56:59], v[128:131], v[194:197], v[56:59]
	v_mfma_f32_16x16x32_bf16 v[40:43], v[128:131], v[202:205], v[40:43]
	v_mfma_f32_16x16x32_bf16 v[40:43], v[144:147], v[206:209], v[40:43]
	v_mfma_f32_16x16x32_bf16 v[44:47], v[108:111], v[206:209], v[44:47]
	v_mfma_f32_16x16x32_bf16 v[44:47], v[88:91], v[202:205], v[44:47]
	v_mfma_f32_16x16x32_bf16 v[28:31], v[88:91], v[210:213], v[28:31]
	v_mfma_f32_16x16x32_bf16 v[28:31], v[108:111], v[214:217], v[28:31]
	v_mfma_f32_16x16x32_bf16 v[24:27], v[144:147], v[214:217], v[24:27]
	v_mfma_f32_16x16x32_bf16 v[24:27], v[128:131], v[210:213], v[24:27]
	v_mfma_f32_16x16x32_bf16 v[8:11], v[128:131], v[218:221], v[8:11]
	v_mfma_f32_16x16x32_bf16 v[8:11], v[144:147], v[222:225], v[8:11]
	v_mfma_f32_16x16x32_bf16 v[12:15], v[108:111], v[222:225], v[12:15]
	v_mfma_f32_16x16x32_bf16 v[12:15], v[88:91], v[218:221], v[12:15]
	v_mfma_f32_16x16x32_bf16 v[52:55], v[148:151], v[194:197], v[52:55]
	v_mfma_f32_16x16x32_bf16 v[52:55], v[152:155], v[198:201], v[52:55]
	v_mfma_f32_16x16x32_bf16 v[48:51], v[190:193], v[198:201], v[48:51]
	v_mfma_f32_16x16x32_bf16 v[48:51], v[176:179], v[194:197], v[48:51]
	v_mfma_f32_16x16x32_bf16 v[32:35], v[176:179], v[202:205], v[32:35]
	v_mfma_f32_16x16x32_bf16 v[32:35], v[190:193], v[206:209], v[32:35]
	v_mfma_f32_16x16x32_bf16 v[36:39], v[152:155], v[206:209], v[36:39]
	v_mfma_f32_16x16x32_bf16 v[36:39], v[148:151], v[202:205], v[36:39]
	v_mfma_f32_16x16x32_bf16 v[20:23], v[148:151], v[210:213], v[20:23]
	v_mfma_f32_16x16x32_bf16 v[20:23], v[152:155], v[214:217], v[20:23]
	v_mfma_f32_16x16x32_bf16 v[16:19], v[190:193], v[214:217], v[16:19]
	v_mfma_f32_16x16x32_bf16 v[16:19], v[176:179], v[210:213], v[16:19]
	v_mfma_f32_16x16x32_bf16 v[0:3], v[176:179], v[218:221], v[0:3]
	v_mfma_f32_16x16x32_bf16 v[0:3], v[190:193], v[222:225], v[0:3]
	v_mfma_f32_16x16x32_bf16 v[4:7], v[152:155], v[222:225], v[4:7]
	v_mfma_f32_16x16x32_bf16 v[4:7], v[148:151], v[218:221], v[4:7]
	s_barrier
	s_setprio 0
	s_add_i32 s95, s95, 2
	s_add_u32 s93, s93, 0x100
	s_addc_u32 s94, s94, 0
	s_add_u32 s14, s14, 0x100
	s_addc_u32 s15, s15, 0
	s_cmp_gt_u32 s95, 13
	s_cbranch_scc1 .LBB0_258

.LBB0_439:
	s_ashr_i32 s53, s52, 31
	s_lshl_b64 s[54:55], s[52:53], 20
	s_add_u32 s54, s35, s54
	s_addc_u32 s55, s66, s55
	s_and_b64 s[56:57], s[12:13], exec
	s_cselect_b32 s15, s55, s63
	s_cselect_b32 s53, s54, s62
	s_ashr_i32 s51, s50, 31
	s_lshl_b64 s[56:57], s[50:51], 20
	s_add_u32 s56, s67, s56
	s_addc_u32 s57, s68, s57
	s_and_b64 s[64:65], s[12:13], exec
	s_cselect_b32 s51, s57, s61
	s_cselect_b32 s59, s56, s60
	s_add_u32 s81, s60, 0x100
	s_addc_u32 s82, s61, 0
	s_add_u32 s60, s62, 0x80080
	s_addc_u32 s61, s63, 0
	s_mov_b32 s83, -2
	s_waitcnt lgkmcnt(0)
	s_cmp_eq_u32 s74, 1
	s_cbranch_scc1 .Lfa_3
	ds_read_b128 v[128:131], v189
	v_xor_b32_e32 v253, 64, v189
	ds_read_b128 v[132:135], v253
	ds_read_b128 v[136:139], v189 offset:2048
	ds_read_b128 v[140:143], v253 offset:2048
	ds_read_b128 v[144:147], v190
	v_xor_b32_e32 v253, 64, v190
	ds_read_b128 v[148:151], v253
	ds_read_b128 v[172:175], v190 offset:2048
	ds_read_b128 v[176:179], v253 offset:2048
	s_add_u32 s62, s60, 0xfff80080
	s_addc_u32 s63, s61, -1
	s_cmp_eq_u32 s83, 28
	s_cselect_b32 s65, s15, s63
	s_cselect_b32 s64, s53, s62
	s_cselect_b32 s63, s51, s82
	s_cselect_b32 s62, s59, s81
	v_lshl_add_u64 v[222:223], s[60:61], 0, v[166:167]
	s_add_i32 m0, s70, 0xc000
	ds_read_b128 v[180:183], v191
	v_xor_b32_e32 v253, 64, v191
	ds_read_b128 v[194:197], v253
	ds_read_b128 v[198:201], v191 offset:2048
	ds_read_b128 v[202:205], v253 offset:2048
	ds_read_b128 v[206:209], v191 offset:4096
	ds_read_b128 v[210:213], v253 offset:4096
	ds_read_b128 v[214:217], v191 offset:6144
	ds_read_b128 v[218:221], v253 offset:6144
	global_load_lds_dwordx4 v[222:223], off
	v_lshl_add_u64 v[222:223], s[60:61], 0, v[164:165]
	s_add_i32 m0, s70, 0xe000
	s_nop 0
	global_load_lds_dwordx4 v[222:223], off
	s_waitcnt vmcnt(24)
	s_waitcnt lgkmcnt(0)
	s_setprio 1
	s_barrier
	v_mfma_f32_16x16x32_bf16 v[124:127], v[128:131], v[180:183], 0
	v_mfma_f32_16x16x32_bf16 v[120:123], v[136:139], v[180:183], 0
	v_mfma_f32_16x16x32_bf16 v[108:111], v[128:131], v[198:201], 0
	v_mfma_f32_16x16x32_bf16 v[104:107], v[136:139], v[198:201], 0
	v_mfma_f32_16x16x32_bf16 v[92:95], v[128:131], v[206:209], 0
	v_mfma_f32_16x16x32_bf16 v[88:91], v[136:139], v[206:209], 0
	v_mfma_f32_16x16x32_bf16 v[76:79], v[128:131], v[214:217], 0
	v_mfma_f32_16x16x32_bf16 v[72:75], v[136:139], v[214:217], 0
	v_mfma_f32_16x16x32_bf16 v[124:127], v[132:135], v[194:197], v[124:127]
	v_mfma_f32_16x16x32_bf16 v[120:123], v[140:143], v[194:197], v[120:123]
	v_mfma_f32_16x16x32_bf16 v[108:111], v[132:135], v[202:205], v[108:111]
	v_mfma_f32_16x16x32_bf16 v[104:107], v[140:143], v[202:205], v[104:107]
	v_mfma_f32_16x16x32_bf16 v[92:95], v[132:135], v[210:213], v[92:95]
	v_mfma_f32_16x16x32_bf16 v[88:91], v[140:143], v[210:213], v[88:91]
	v_mfma_f32_16x16x32_bf16 v[76:79], v[132:135], v[218:221], v[76:79]
	v_mfma_f32_16x16x32_bf16 v[72:75], v[140:143], v[218:221], v[72:75]
	v_mfma_f32_16x16x32_bf16 v[116:119], v[144:147], v[180:183], 0
	v_mfma_f32_16x16x32_bf16 v[112:115], v[172:175], v[180:183], 0
	v_mfma_f32_16x16x32_bf16 v[100:103], v[144:147], v[198:201], 0
	v_mfma_f32_16x16x32_bf16 v[96:99], v[172:175], v[198:201], 0
	v_mfma_f32_16x16x32_bf16 v[84:87], v[144:147], v[206:209], 0
	v_mfma_f32_16x16x32_bf16 v[80:83], v[172:175], v[206:209], 0
	v_mfma_f32_16x16x32_bf16 v[68:71], v[144:147], v[214:217], 0
	v_mfma_f32_16x16x32_bf16 v[64:67], v[172:175], v[214:217], 0
	v_mfma_f32_16x16x32_bf16 v[116:119], v[148:151], v[194:197], v[116:119]
	v_mfma_f32_16x16x32_bf16 v[112:115], v[176:179], v[194:197], v[112:115]
	v_mfma_f32_16x16x32_bf16 v[100:103], v[148:151], v[202:205], v[100:103]
	v_mfma_f32_16x16x32_bf16 v[96:99], v[176:179], v[202:205], v[96:99]
	v_mfma_f32_16x16x32_bf16 v[84:87], v[148:151], v[210:213], v[84:87]
	v_mfma_f32_16x16x32_bf16 v[80:83], v[176:179], v[210:213], v[80:83]
	v_mfma_f32_16x16x32_bf16 v[68:71], v[148:151], v[218:221], v[68:71]
	v_mfma_f32_16x16x32_bf16 v[64:67], v[176:179], v[218:221], v[64:67]
	s_barrier
	s_setprio 0
	s_add_i32 s84, s79, s69
	v_lshl_add_u64 v[222:223], s[62:63], 0, v[154:155]
	s_mov_b32 m0, s84
	ds_read_b128 v[180:183], v191 offset:16384
	v_xor_b32_e32 v253, 64, v191
	ds_read_b128 v[194:197], v253 offset:16384
	ds_read_b128 v[198:201], v191 offset:18432
	ds_read_b128 v[202:205], v253 offset:18432
	ds_read_b128 v[206:209], v191 offset:20480
	ds_read_b128 v[210:213], v253 offset:20480
	ds_read_b128 v[214:217], v191 offset:22528
	ds_read_b128 v[218:221], v253 offset:22528
	global_load_lds_dwordx4 v[222:223], off
	s_add_i32 m0, s84, 0x2000
	s_add_u32 s84, s62, 0x80000
	v_lshl_add_u64 v[224:225], s[62:63], 0, v[162:163]
	s_addc_u32 s85, s63, 0
	s_add_i32 s86, s80, s69
	global_load_lds_dwordx4 v[224:225], off
	v_lshl_add_u64 v[226:227], s[84:85], 0, v[154:155]
	s_mov_b32 m0, s86
	v_lshl_add_u64 v[228:229], s[64:65], 0, v[160:161]
	global_load_lds_dwordx4 v[226:227], off
	v_lshl_add_u64 v[226:227], s[84:85], 0, v[162:163]
	s_add_i32 m0, s86, 0x2000
	s_nop 0
	global_load_lds_dwordx4 v[226:227], off
	v_lshl_add_u64 v[226:227], s[64:65], 0, v[152:153]
	s_mov_b32 m0, s70
	s_nop 0
	global_load_lds_dwordx4 v[226:227], off
	s_mov_b32 m0, s71
	s_nop 0
	global_load_lds_dwordx4 v[228:229], off
	s_waitcnt vmcnt(24)
	s_waitcnt lgkmcnt(0)
	s_setprio 1
	s_barrier
	v_mfma_f32_16x16x32_bf16 v[60:63], v[128:131], v[180:183], 0
	v_mfma_f32_16x16x32_bf16 v[56:59], v[136:139], v[180:183], 0
	v_mfma_f32_16x16x32_bf16 v[44:47], v[128:131], v[198:201], 0
	v_mfma_f32_16x16x32_bf16 v[40:43], v[136:139], v[198:201], 0
	v_mfma_f32_16x16x32_bf16 v[28:31], v[128:131], v[206:209], 0
	v_mfma_f32_16x16x32_bf16 v[24:27], v[136:139], v[206:209], 0
	v_mfma_f32_16x16x32_bf16 v[12:15], v[128:131], v[214:217], 0
	v_mfma_f32_16x16x32_bf16 v[8:11], v[136:139], v[214:217], 0
	v_mfma_f32_16x16x32_bf16 v[60:63], v[132:135], v[194:197], v[60:63]
	v_mfma_f32_16x16x32_bf16 v[56:59], v[140:143], v[194:197], v[56:59]
	v_mfma_f32_16x16x32_bf16 v[44:47], v[132:135], v[202:205], v[44:47]
	v_mfma_f32_16x16x32_bf16 v[40:43], v[140:143], v[202:205], v[40:43]
	v_mfma_f32_16x16x32_bf16 v[28:31], v[132:135], v[210:213], v[28:31]
	v_mfma_f32_16x16x32_bf16 v[24:27], v[140:143], v[210:213], v[24:27]
	v_mfma_f32_16x16x32_bf16 v[12:15], v[132:135], v[218:221], v[12:15]
	v_mfma_f32_16x16x32_bf16 v[8:11], v[140:143], v[218:221], v[8:11]
	v_mfma_f32_16x16x32_bf16 v[52:55], v[144:147], v[180:183], 0
	v_mfma_f32_16x16x32_bf16 v[48:51], v[172:175], v[180:183], 0
	v_mfma_f32_16x16x32_bf16 v[36:39], v[144:147], v[198:201], 0
	v_mfma_f32_16x16x32_bf16 v[32:35], v[172:175], v[198:201], 0
	v_mfma_f32_16x16x32_bf16 v[20:23], v[144:147], v[206:209], 0
	v_mfma_f32_16x16x32_bf16 v[16:19], v[172:175], v[206:209], 0
	v_mfma_f32_16x16x32_bf16 v[4:7], v[144:147], v[214:217], 0
	v_mfma_f32_16x16x32_bf16 v[0:3], v[172:175], v[214:217], 0
	v_mfma_f32_16x16x32_bf16 v[52:55], v[148:151], v[194:197], v[52:55]
	v_mfma_f32_16x16x32_bf16 v[48:51], v[176:179], v[194:197], v[48:51]
	v_mfma_f32_16x16x32_bf16 v[36:39], v[148:151], v[202:205], v[36:39]
	v_mfma_f32_16x16x32_bf16 v[32:35], v[176:179], v[202:205], v[32:35]
	v_mfma_f32_16x16x32_bf16 v[20:23], v[148:151], v[210:213], v[20:23]
	v_mfma_f32_16x16x32_bf16 v[16:19], v[176:179], v[210:213], v[16:19]
	v_mfma_f32_16x16x32_bf16 v[4:7], v[148:151], v[218:221], v[4:7]
	v_mfma_f32_16x16x32_bf16 v[0:3], v[176:179], v[218:221], v[0:3]
	s_barrier
	s_setprio 0
	s_add_i32 s84, 0, 0x18000
	s_add_i32 s85, 0, 0x1c000
	v_add_u32_e32 v140, s84, v186
	v_add_u32_e32 v176, s85, v186
	ds_read_b128 v[128:131], v140
	v_xor_b32_e32 v253, 64, v140
	ds_read_b128 v[132:135], v253
	ds_read_b128 v[136:139], v140 offset:2048
	ds_read_b128 v[140:143], v253 offset:2048
	ds_read_b128 v[144:147], v176
	v_xor_b32_e32 v253, 64, v176
	ds_read_b128 v[148:151], v253
	ds_read_b128 v[172:175], v176 offset:2048
	ds_read_b128 v[176:179], v253 offset:2048
	s_add_u32 s64, s64, 0x80000
	s_addc_u32 s65, s65, 0
	s_mov_b32 m0, s72
	v_lshl_add_u64 v[230:231], s[64:65], 0, v[152:153]
	ds_read_b128 v[180:183], v191 offset:32768
	v_xor_b32_e32 v253, 64, v191
	ds_read_b128 v[194:197], v253 offset:32768
	ds_read_b128 v[198:201], v191 offset:34816
	ds_read_b128 v[202:205], v253 offset:34816
	ds_read_b128 v[206:209], v191 offset:36864
	ds_read_b128 v[210:213], v253 offset:36864
	ds_read_b128 v[214:217], v191 offset:38912
	ds_read_b128 v[218:221], v253 offset:38912
	global_load_lds_dwordx4 v[230:231], off
	v_lshl_add_u64 v[230:231], s[64:65], 0, v[160:161]
	s_mov_b32 m0, s73
	s_nop 0
	global_load_lds_dwordx4 v[230:231], off
	s_waitcnt vmcnt(8)
	s_waitcnt lgkmcnt(0)
	s_setprio 1
	s_barrier
	v_mfma_f32_16x16x32_bf16 v[124:127], v[128:131], v[180:183], v[124:127]
	v_mfma_f32_16x16x32_bf16 v[124:127], v[132:135], v[194:197], v[124:127]
	v_mfma_f32_16x16x32_bf16 v[120:123], v[140:143], v[194:197], v[120:123]
	v_mfma_f32_16x16x32_bf16 v[120:123], v[136:139], v[180:183], v[120:123]
	v_mfma_f32_16x16x32_bf16 v[104:107], v[136:139], v[198:201], v[104:107]
	v_mfma_f32_16x16x32_bf16 v[104:107], v[140:143], v[202:205], v[104:107]
	v_mfma_f32_16x16x32_bf16 v[108:111], v[132:135], v[202:205], v[108:111]
	v_mfma_f32_16x16x32_bf16 v[108:111], v[128:131], v[198:201], v[108:111]
	v_mfma_f32_16x16x32_bf16 v[92:95], v[128:131], v[206:209], v[92:95]
	v_mfma_f32_16x16x32_bf16 v[92:95], v[132:135], v[210:213], v[92:95]
	v_mfma_f32_16x16x32_bf16 v[88:91], v[140:143], v[210:213], v[88:91]
	v_mfma_f32_16x16x32_bf16 v[88:91], v[136:139], v[206:209], v[88:91]
	v_mfma_f32_16x16x32_bf16 v[72:75], v[136:139], v[214:217], v[72:75]
	v_mfma_f32_16x16x32_bf16 v[72:75], v[140:143], v[218:221], v[72:75]
	v_mfma_f32_16x16x32_bf16 v[76:79], v[132:135], v[218:221], v[76:79]
	v_mfma_f32_16x16x32_bf16 v[76:79], v[128:131], v[214:217], v[76:79]
	v_mfma_f32_16x16x32_bf16 v[116:119], v[144:147], v[180:183], v[116:119]
	v_mfma_f32_16x16x32_bf16 v[116:119], v[148:151], v[194:197], v[116:119]
	v_mfma_f32_16x16x32_bf16 v[112:115], v[176:179], v[194:197], v[112:115]
	v_mfma_f32_16x16x32_bf16 v[112:115], v[172:175], v[180:183], v[112:115]
	v_mfma_f32_16x16x32_bf16 v[96:99], v[172:175], v[198:201], v[96:99]
	v_mfma_f32_16x16x32_bf16 v[96:99], v[176:179], v[202:205], v[96:99]
	v_mfma_f32_16x16x32_bf16 v[100:103], v[148:151], v[202:205], v[100:103]
	v_mfma_f32_16x16x32_bf16 v[100:103], v[144:147], v[198:201], v[100:103]
	v_mfma_f32_16x16x32_bf16 v[84:87], v[144:147], v[206:209], v[84:87]
	v_mfma_f32_16x16x32_bf16 v[84:87], v[148:151], v[210:213], v[84:87]
	v_mfma_f32_16x16x32_bf16 v[80:83], v[176:179], v[210:213], v[80:83]
	v_mfma_f32_16x16x32_bf16 v[80:83], v[172:175], v[206:209], v[80:83]
	v_mfma_f32_16x16x32_bf16 v[64:67], v[172:175], v[214:217], v[64:67]
	v_mfma_f32_16x16x32_bf16 v[64:67], v[176:179], v[218:221], v[64:67]
	v_mfma_f32_16x16x32_bf16 v[68:71], v[148:151], v[218:221], v[68:71]
	v_mfma_f32_16x16x32_bf16 v[68:71], v[144:147], v[214:217], v[68:71]
	s_barrier
	s_setprio 0
	s_add_i32 s64, s84, s69
	v_lshl_add_u64 v[222:223], v[222:223], 0, s[26:27]
	s_mov_b32 m0, s64
	ds_read_b128 v[180:183], v191 offset:49152
	v_xor_b32_e32 v253, 64, v191
	ds_read_b128 v[194:197], v253 offset:49152
	ds_read_b128 v[198:201], v191 offset:51200
	ds_read_b128 v[202:205], v253 offset:51200
	ds_read_b128 v[206:209], v191 offset:53248
	ds_read_b128 v[210:213], v253 offset:53248
	ds_read_b128 v[214:217], v191 offset:55296
	ds_read_b128 v[218:221], v253 offset:55296
	global_load_lds_dwordx4 v[222:223], off
	s_add_i32 m0, s64, 0x2000
	s_add_u32 s62, s62, 0x80080
	v_lshl_add_u64 v[222:223], v[224:225], 0, s[26:27]
	s_addc_u32 s63, s63, 0
	s_add_i32 s64, s85, s69
	global_load_lds_dwordx4 v[222:223], off
	v_lshl_add_u64 v[222:223], s[62:63], 0, v[154:155]
	s_mov_b32 m0, s64
	s_nop 0
	global_load_lds_dwordx4 v[222:223], off
	v_lshl_add_u64 v[222:223], s[62:63], 0, v[162:163]
	s_add_i32 m0, s64, 0x2000
	s_nop 0
	global_load_lds_dwordx4 v[222:223], off
	v_lshl_add_u64 v[222:223], v[226:227], 0, s[26:27]
	s_mov_b32 m0, s3
	s_nop 0
	global_load_lds_dwordx4 v[222:223], off
	v_lshl_add_u64 v[222:223], v[228:229], 0, s[26:27]
	s_mov_b32 m0, s75
	s_nop 0
	global_load_lds_dwordx4 v[222:223], off
	s_waitcnt vmcnt(8)
	s_waitcnt lgkmcnt(0)
	s_setprio 1
	s_barrier
	v_mfma_f32_16x16x32_bf16 v[60:63], v[128:131], v[180:183], v[60:63]
	v_mfma_f32_16x16x32_bf16 v[60:63], v[132:135], v[194:197], v[60:63]
	v_mfma_f32_16x16x32_bf16 v[56:59], v[140:143], v[194:197], v[56:59]
	v_mfma_f32_16x16x32_bf16 v[56:59], v[136:139], v[180:183], v[56:59]
	v_mfma_f32_16x16x32_bf16 v[40:43], v[136:139], v[198:201], v[40:43]
	v_mfma_f32_16x16x32_bf16 v[40:43], v[140:143], v[202:205], v[40:43]
	v_mfma_f32_16x16x32_bf16 v[44:47], v[132:135], v[202:205], v[44:47]
	v_mfma_f32_16x16x32_bf16 v[44:47], v[128:131], v[198:201], v[44:47]
	v_mfma_f32_16x16x32_bf16 v[28:31], v[128:131], v[206:209], v[28:31]
	v_mfma_f32_16x16x32_bf16 v[28:31], v[132:135], v[210:213], v[28:31]
	v_mfma_f32_16x16x32_bf16 v[24:27], v[140:143], v[210:213], v[24:27]
	v_mfma_f32_16x16x32_bf16 v[24:27], v[136:139], v[206:209], v[24:27]
	v_mfma_f32_16x16x32_bf16 v[8:11], v[136:139], v[214:217], v[8:11]
	v_mfma_f32_16x16x32_bf16 v[8:11], v[140:143], v[218:221], v[8:11]
	v_mfma_f32_16x16x32_bf16 v[12:15], v[132:135], v[218:221], v[12:15]
	v_mfma_f32_16x16x32_bf16 v[12:15], v[128:131], v[214:217], v[12:15]
	v_mfma_f32_16x16x32_bf16 v[52:55], v[144:147], v[180:183], v[52:55]
	v_mfma_f32_16x16x32_bf16 v[52:55], v[148:151], v[194:197], v[52:55]
	v_mfma_f32_16x16x32_bf16 v[48:51], v[176:179], v[194:197], v[48:51]
	v_mfma_f32_16x16x32_bf16 v[48:51], v[172:175], v[180:183], v[48:51]
	v_mfma_f32_16x16x32_bf16 v[32:35], v[172:175], v[198:201], v[32:35]
	v_mfma_f32_16x16x32_bf16 v[32:35], v[176:179], v[202:205], v[32:35]
	v_mfma_f32_16x16x32_bf16 v[36:39], v[148:151], v[202:205], v[36:39]
	v_mfma_f32_16x16x32_bf16 v[36:39], v[144:147], v[198:201], v[36:39]
	v_mfma_f32_16x16x32_bf16 v[20:23], v[144:147], v[206:209], v[20:23]
	v_mfma_f32_16x16x32_bf16 v[20:23], v[148:151], v[210:213], v[20:23]
	v_mfma_f32_16x16x32_bf16 v[16:19], v[176:179], v[210:213], v[16:19]
	v_mfma_f32_16x16x32_bf16 v[16:19], v[172:175], v[206:209], v[16:19]
	v_mfma_f32_16x16x32_bf16 v[0:3], v[172:175], v[214:217], v[0:3]
	v_mfma_f32_16x16x32_bf16 v[0:3], v[176:179], v[218:221], v[0:3]
	v_mfma_f32_16x16x32_bf16 v[4:7], v[148:151], v[218:221], v[4:7]
	v_mfma_f32_16x16x32_bf16 v[4:7], v[144:147], v[214:217], v[4:7]
	s_barrier
	s_setprio 0
	s_add_i32 s83, s83, 2
	s_add_u32 s81, s81, 0x100
	s_addc_u32 s82, s82, 0
	s_add_u32 s60, s60, 0x100
	s_addc_u32 s61, s61, 0
	s_cmp_gt_u32 s83, 29
	s_branch .LBB0_440
.Lfa_3:
	ds_read_b128 v[128:131], v189
	v_xor_b32_e32 v253, 64, v189
	ds_read_b128 v[132:135], v253
	ds_read_b128 v[136:139], v189 offset:2048
	ds_read_b128 v[140:143], v253 offset:2048
	ds_read_b128 v[144:147], v190
	v_xor_b32_e32 v253, 64, v190
	ds_read_b128 v[148:151], v253
	ds_read_b128 v[172:175], v190 offset:2048
	ds_read_b128 v[176:179], v253 offset:2048
	s_add_u32 s62, s60, 0xfff80080
	s_addc_u32 s63, s61, -1
	s_cmp_eq_u32 s83, 28
	s_cselect_b32 s65, s15, s63
	s_cselect_b32 s64, s53, s62
	s_cselect_b32 s63, s51, s82
	s_cselect_b32 s62, s59, s81
	v_lshl_add_u64 v[222:223], s[60:61], 0, v[166:167]
	s_add_i32 m0, s70, 0xc000
	ds_read_b128 v[180:183], v191
	v_xor_b32_e32 v253, 64, v191
	ds_read_b128 v[194:197], v253
	ds_read_b128 v[198:201], v191 offset:2048
	ds_read_b128 v[202:205], v253 offset:2048
	ds_read_b128 v[206:209], v191 offset:4096
	ds_read_b128 v[210:213], v253 offset:4096
	ds_read_b128 v[214:217], v191 offset:6144
	ds_read_b128 v[218:221], v253 offset:6144
	global_load_lds_dwordx4 v[222:223], off
	v_lshl_add_u64 v[222:223], s[60:61], 0, v[164:165]
	s_add_i32 m0, s70, 0xe000
	s_nop 0
	global_load_lds_dwordx4 v[222:223], off
	s_waitcnt vmcnt(8)
	s_waitcnt lgkmcnt(0)
	s_setprio 1
	s_barrier
	v_mfma_f32_16x16x32_bf16 v[124:127], v[128:131], v[180:183], 0
	v_mfma_f32_16x16x32_bf16 v[120:123], v[136:139], v[180:183], 0
	v_mfma_f32_16x16x32_bf16 v[108:111], v[128:131], v[198:201], 0
	v_mfma_f32_16x16x32_bf16 v[104:107], v[136:139], v[198:201], 0
	v_mfma_f32_16x16x32_bf16 v[92:95], v[128:131], v[206:209], 0
	v_mfma_f32_16x16x32_bf16 v[88:91], v[136:139], v[206:209], 0
	v_mfma_f32_16x16x32_bf16 v[76:79], v[128:131], v[214:217], 0
	v_mfma_f32_16x16x32_bf16 v[72:75], v[136:139], v[214:217], 0
	v_mfma_f32_16x16x32_bf16 v[124:127], v[132:135], v[194:197], v[124:127]
	v_mfma_f32_16x16x32_bf16 v[120:123], v[140:143], v[194:197], v[120:123]
	v_mfma_f32_16x16x32_bf16 v[108:111], v[132:135], v[202:205], v[108:111]
	v_mfma_f32_16x16x32_bf16 v[104:107], v[140:143], v[202:205], v[104:107]
	v_mfma_f32_16x16x32_bf16 v[92:95], v[132:135], v[210:213], v[92:95]
	v_mfma_f32_16x16x32_bf16 v[88:91], v[140:143], v[210:213], v[88:91]
	v_mfma_f32_16x16x32_bf16 v[76:79], v[132:135], v[218:221], v[76:79]
	v_mfma_f32_16x16x32_bf16 v[72:75], v[140:143], v[218:221], v[72:75]
	v_mfma_f32_16x16x32_bf16 v[116:119], v[144:147], v[180:183], 0
	v_mfma_f32_16x16x32_bf16 v[112:115], v[172:175], v[180:183], 0
	v_mfma_f32_16x16x32_bf16 v[100:103], v[144:147], v[198:201], 0
	v_mfma_f32_16x16x32_bf16 v[96:99], v[172:175], v[198:201], 0
	v_mfma_f32_16x16x32_bf16 v[84:87], v[144:147], v[206:209], 0
	v_mfma_f32_16x16x32_bf16 v[80:83], v[172:175], v[206:209], 0
	v_mfma_f32_16x16x32_bf16 v[68:71], v[144:147], v[214:217], 0
	v_mfma_f32_16x16x32_bf16 v[64:67], v[172:175], v[214:217], 0
	v_mfma_f32_16x16x32_bf16 v[116:119], v[148:151], v[194:197], v[116:119]
	v_mfma_f32_16x16x32_bf16 v[112:115], v[176:179], v[194:197], v[112:115]
	v_mfma_f32_16x16x32_bf16 v[100:103], v[148:151], v[202:205], v[100:103]
	v_mfma_f32_16x16x32_bf16 v[96:99], v[176:179], v[202:205], v[96:99]
	v_mfma_f32_16x16x32_bf16 v[84:87], v[148:151], v[210:213], v[84:87]
	v_mfma_f32_16x16x32_bf16 v[80:83], v[176:179], v[210:213], v[80:83]
	v_mfma_f32_16x16x32_bf16 v[68:71], v[148:151], v[218:221], v[68:71]
	v_mfma_f32_16x16x32_bf16 v[64:67], v[176:179], v[218:221], v[64:67]
	s_barrier
	s_setprio 0
	s_add_i32 s84, s79, s69
	v_lshl_add_u64 v[222:223], s[62:63], 0, v[154:155]
	s_mov_b32 m0, s84
	ds_read_b128 v[180:183], v191 offset:16384
	v_xor_b32_e32 v253, 64, v191
	ds_read_b128 v[194:197], v253 offset:16384
	ds_read_b128 v[198:201], v191 offset:18432
	ds_read_b128 v[202:205], v253 offset:18432
	ds_read_b128 v[206:209], v191 offset:20480
	ds_read_b128 v[210:213], v253 offset:20480
	ds_read_b128 v[214:217], v191 offset:22528
	ds_read_b128 v[218:221], v253 offset:22528
	global_load_lds_dwordx4 v[222:223], off
	s_add_i32 m0, s84, 0x2000
	s_add_u32 s84, s62, 0x80000
	v_lshl_add_u64 v[224:225], s[62:63], 0, v[162:163]
	s_addc_u32 s85, s63, 0
	s_add_i32 s86, s80, s69
	global_load_lds_dwordx4 v[224:225], off
	v_lshl_add_u64 v[226:227], s[84:85], 0, v[154:155]
	s_mov_b32 m0, s86
	v_lshl_add_u64 v[228:229], s[64:65], 0, v[160:161]
	global_load_lds_dwordx4 v[226:227], off
	v_lshl_add_u64 v[226:227], s[84:85], 0, v[162:163]
	s_add_i32 m0, s86, 0x2000
	s_nop 0
	global_load_lds_dwordx4 v[226:227], off
	v_lshl_add_u64 v[226:227], s[64:65], 0, v[152:153]
	s_mov_b32 m0, s70
	s_nop 0
	global_load_lds_dwordx4 v[226:227], off
	s_mov_b32 m0, s71
	s_nop 0
	global_load_lds_dwordx4 v[228:229], off
	s_waitcnt vmcnt(8)
	s_waitcnt lgkmcnt(0)
	s_setprio 1
	s_barrier
	v_mfma_f32_16x16x32_bf16 v[60:63], v[128:131], v[180:183], 0
	v_mfma_f32_16x16x32_bf16 v[56:59], v[136:139], v[180:183], 0
	v_mfma_f32_16x16x32_bf16 v[44:47], v[128:131], v[198:201], 0
	v_mfma_f32_16x16x32_bf16 v[40:43], v[136:139], v[198:201], 0
	v_mfma_f32_16x16x32_bf16 v[28:31], v[128:131], v[206:209], 0
	v_mfma_f32_16x16x32_bf16 v[24:27], v[136:139], v[206:209], 0
	v_mfma_f32_16x16x32_bf16 v[12:15], v[128:131], v[214:217], 0
	v_mfma_f32_16x16x32_bf16 v[8:11], v[136:139], v[214:217], 0
	v_mfma_f32_16x16x32_bf16 v[60:63], v[132:135], v[194:197], v[60:63]
	v_mfma_f32_16x16x32_bf16 v[56:59], v[140:143], v[194:197], v[56:59]
	v_mfma_f32_16x16x32_bf16 v[44:47], v[132:135], v[202:205], v[44:47]
	v_mfma_f32_16x16x32_bf16 v[40:43], v[140:143], v[202:205], v[40:43]
	v_mfma_f32_16x16x32_bf16 v[28:31], v[132:135], v[210:213], v[28:31]
	v_mfma_f32_16x16x32_bf16 v[24:27], v[140:143], v[210:213], v[24:27]
	v_mfma_f32_16x16x32_bf16 v[12:15], v[132:135], v[218:221], v[12:15]
	v_mfma_f32_16x16x32_bf16 v[8:11], v[140:143], v[218:221], v[8:11]
	v_mfma_f32_16x16x32_bf16 v[52:55], v[144:147], v[180:183], 0
	v_mfma_f32_16x16x32_bf16 v[48:51], v[172:175], v[180:183], 0
	v_mfma_f32_16x16x32_bf16 v[36:39], v[144:147], v[198:201], 0
	v_mfma_f32_16x16x32_bf16 v[32:35], v[172:175], v[198:201], 0
	v_mfma_f32_16x16x32_bf16 v[20:23], v[144:147], v[206:209], 0
	v_mfma_f32_16x16x32_bf16 v[16:19], v[172:175], v[206:209], 0
	v_mfma_f32_16x16x32_bf16 v[4:7], v[144:147], v[214:217], 0
	v_mfma_f32_16x16x32_bf16 v[0:3], v[172:175], v[214:217], 0
	v_mfma_f32_16x16x32_bf16 v[52:55], v[148:151], v[194:197], v[52:55]
	v_mfma_f32_16x16x32_bf16 v[48:51], v[176:179], v[194:197], v[48:51]
	v_mfma_f32_16x16x32_bf16 v[36:39], v[148:151], v[202:205], v[36:39]
	v_mfma_f32_16x16x32_bf16 v[32:35], v[176:179], v[202:205], v[32:35]
	v_mfma_f32_16x16x32_bf16 v[20:23], v[148:151], v[210:213], v[20:23]
	v_mfma_f32_16x16x32_bf16 v[16:19], v[176:179], v[210:213], v[16:19]
	v_mfma_f32_16x16x32_bf16 v[4:7], v[148:151], v[218:221], v[4:7]
	v_mfma_f32_16x16x32_bf16 v[0:3], v[176:179], v[218:221], v[0:3]
	s_barrier
	s_setprio 0
	s_add_i32 s84, 0, 0x18000
	s_add_i32 s85, 0, 0x1c000
	v_add_u32_e32 v140, s84, v186
	v_add_u32_e32 v176, s85, v186
	ds_read_b128 v[128:131], v140
	v_xor_b32_e32 v253, 64, v140
	ds_read_b128 v[132:135], v253
	ds_read_b128 v[136:139], v140 offset:2048
	ds_read_b128 v[140:143], v253 offset:2048
	ds_read_b128 v[144:147], v176
	v_xor_b32_e32 v253, 64, v176
	ds_read_b128 v[148:151], v253
	ds_read_b128 v[172:175], v176 offset:2048
	ds_read_b128 v[176:179], v253 offset:2048
	s_add_u32 s64, s64, 0x80000
	s_addc_u32 s65, s65, 0
	s_mov_b32 m0, s72
	v_lshl_add_u64 v[230:231], s[64:65], 0, v[152:153]
	ds_read_b128 v[180:183], v191 offset:32768
	v_xor_b32_e32 v253, 64, v191
	ds_read_b128 v[194:197], v253 offset:32768
	ds_read_b128 v[198:201], v191 offset:34816
	ds_read_b128 v[202:205], v253 offset:34816
	ds_read_b128 v[206:209], v191 offset:36864
	ds_read_b128 v[210:213], v253 offset:36864
	ds_read_b128 v[214:217], v191 offset:38912
	ds_read_b128 v[218:221], v253 offset:38912
	global_load_lds_dwordx4 v[230:231], off
	v_lshl_add_u64 v[230:231], s[64:65], 0, v[160:161]
	s_mov_b32 m0, s73
	s_nop 0
	global_load_lds_dwordx4 v[230:231], off
	s_waitcnt vmcnt(8)
	s_waitcnt lgkmcnt(0)
	s_setprio 1
	s_barrier
	v_mfma_f32_16x16x32_bf16 v[124:127], v[128:131], v[180:183], v[124:127]
	v_mfma_f32_16x16x32_bf16 v[124:127], v[132:135], v[194:197], v[124:127]
	v_mfma_f32_16x16x32_bf16 v[120:123], v[140:143], v[194:197], v[120:123]
	v_mfma_f32_16x16x32_bf16 v[120:123], v[136:139], v[180:183], v[120:123]
	v_mfma_f32_16x16x32_bf16 v[104:107], v[136:139], v[198:201], v[104:107]
	v_mfma_f32_16x16x32_bf16 v[104:107], v[140:143], v[202:205], v[104:107]
	v_mfma_f32_16x16x32_bf16 v[108:111], v[132:135], v[202:205], v[108:111]
	v_mfma_f32_16x16x32_bf16 v[108:111], v[128:131], v[198:201], v[108:111]
	v_mfma_f32_16x16x32_bf16 v[92:95], v[128:131], v[206:209], v[92:95]
	v_mfma_f32_16x16x32_bf16 v[92:95], v[132:135], v[210:213], v[92:95]
	v_mfma_f32_16x16x32_bf16 v[88:91], v[140:143], v[210:213], v[88:91]
	v_mfma_f32_16x16x32_bf16 v[88:91], v[136:139], v[206:209], v[88:91]
	v_mfma_f32_16x16x32_bf16 v[72:75], v[136:139], v[214:217], v[72:75]
	v_mfma_f32_16x16x32_bf16 v[72:75], v[140:143], v[218:221], v[72:75]
	v_mfma_f32_16x16x32_bf16 v[76:79], v[132:135], v[218:221], v[76:79]
	v_mfma_f32_16x16x32_bf16 v[76:79], v[128:131], v[214:217], v[76:79]
	v_mfma_f32_16x16x32_bf16 v[116:119], v[144:147], v[180:183], v[116:119]
	v_mfma_f32_16x16x32_bf16 v[116:119], v[148:151], v[194:197], v[116:119]
	v_mfma_f32_16x16x32_bf16 v[112:115], v[176:179], v[194:197], v[112:115]
	v_mfma_f32_16x16x32_bf16 v[112:115], v[172:175], v[180:183], v[112:115]
	v_mfma_f32_16x16x32_bf16 v[96:99], v[172:175], v[198:201], v[96:99]
	v_mfma_f32_16x16x32_bf16 v[96:99], v[176:179], v[202:205], v[96:99]
	v_mfma_f32_16x16x32_bf16 v[100:103], v[148:151], v[202:205], v[100:103]
	v_mfma_f32_16x16x32_bf16 v[100:103], v[144:147], v[198:201], v[100:103]
	v_mfma_f32_16x16x32_bf16 v[84:87], v[144:147], v[206:209], v[84:87]
	v_mfma_f32_16x16x32_bf16 v[84:87], v[148:151], v[210:213], v[84:87]
	v_mfma_f32_16x16x32_bf16 v[80:83], v[176:179], v[210:213], v[80:83]
	v_mfma_f32_16x16x32_bf16 v[80:83], v[172:175], v[206:209], v[80:83]
	v_mfma_f32_16x16x32_bf16 v[64:67], v[172:175], v[214:217], v[64:67]
	v_mfma_f32_16x16x32_bf16 v[64:67], v[176:179], v[218:221], v[64:67]
	v_mfma_f32_16x16x32_bf16 v[68:71], v[148:151], v[218:221], v[68:71]
	v_mfma_f32_16x16x32_bf16 v[68:71], v[144:147], v[214:217], v[68:71]
	s_barrier
	s_setprio 0
	s_add_i32 s64, s84, s69
	v_lshl_add_u64 v[222:223], v[222:223], 0, s[26:27]
	s_mov_b32 m0, s64
	ds_read_b128 v[180:183], v191 offset:49152
	v_xor_b32_e32 v253, 64, v191
	ds_read_b128 v[194:197], v253 offset:49152
	ds_read_b128 v[198:201], v191 offset:51200
	ds_read_b128 v[202:205], v253 offset:51200
	ds_read_b128 v[206:209], v191 offset:53248
	ds_read_b128 v[210:213], v253 offset:53248
	ds_read_b128 v[214:217], v191 offset:55296
	ds_read_b128 v[218:221], v253 offset:55296
	global_load_lds_dwordx4 v[222:223], off
	s_add_i32 m0, s64, 0x2000
	s_add_u32 s62, s62, 0x80080
	v_lshl_add_u64 v[222:223], v[224:225], 0, s[26:27]
	s_addc_u32 s63, s63, 0
	s_add_i32 s64, s85, s69
	global_load_lds_dwordx4 v[222:223], off
	v_lshl_add_u64 v[222:223], s[62:63], 0, v[154:155]
	s_mov_b32 m0, s64
	s_nop 0
	global_load_lds_dwordx4 v[222:223], off
	v_lshl_add_u64 v[222:223], s[62:63], 0, v[162:163]
	s_add_i32 m0, s64, 0x2000
	s_nop 0
	global_load_lds_dwordx4 v[222:223], off
	v_lshl_add_u64 v[222:223], v[226:227], 0, s[26:27]
	s_mov_b32 m0, s3
	s_nop 0
	global_load_lds_dwordx4 v[222:223], off
	v_lshl_add_u64 v[222:223], v[228:229], 0, s[26:27]
	s_mov_b32 m0, s75
	s_nop 0
	global_load_lds_dwordx4 v[222:223], off
	s_waitcnt vmcnt(8)
	s_waitcnt lgkmcnt(0)
	s_setprio 1
	s_barrier
	v_mfma_f32_16x16x32_bf16 v[60:63], v[128:131], v[180:183], v[60:63]
	v_mfma_f32_16x16x32_bf16 v[60:63], v[132:135], v[194:197], v[60:63]
	v_mfma_f32_16x16x32_bf16 v[56:59], v[140:143], v[194:197], v[56:59]
	v_mfma_f32_16x16x32_bf16 v[56:59], v[136:139], v[180:183], v[56:59]
	v_mfma_f32_16x16x32_bf16 v[40:43], v[136:139], v[198:201], v[40:43]
	v_mfma_f32_16x16x32_bf16 v[40:43], v[140:143], v[202:205], v[40:43]
	v_mfma_f32_16x16x32_bf16 v[44:47], v[132:135], v[202:205], v[44:47]
	v_mfma_f32_16x16x32_bf16 v[44:47], v[128:131], v[198:201], v[44:47]
	v_mfma_f32_16x16x32_bf16 v[28:31], v[128:131], v[206:209], v[28:31]
	v_mfma_f32_16x16x32_bf16 v[28:31], v[132:135], v[210:213], v[28:31]
	v_mfma_f32_16x16x32_bf16 v[24:27], v[140:143], v[210:213], v[24:27]
	v_mfma_f32_16x16x32_bf16 v[24:27], v[136:139], v[206:209], v[24:27]
	v_mfma_f32_16x16x32_bf16 v[8:11], v[136:139], v[214:217], v[8:11]
	v_mfma_f32_16x16x32_bf16 v[8:11], v[140:143], v[218:221], v[8:11]
	v_mfma_f32_16x16x32_bf16 v[12:15], v[132:135], v[218:221], v[12:15]
	v_mfma_f32_16x16x32_bf16 v[12:15], v[128:131], v[214:217], v[12:15]
	v_mfma_f32_16x16x32_bf16 v[52:55], v[144:147], v[180:183], v[52:55]
	v_mfma_f32_16x16x32_bf16 v[52:55], v[148:151], v[194:197], v[52:55]
	v_mfma_f32_16x16x32_bf16 v[48:51], v[176:179], v[194:197], v[48:51]
	v_mfma_f32_16x16x32_bf16 v[48:51], v[172:175], v[180:183], v[48:51]
	v_mfma_f32_16x16x32_bf16 v[32:35], v[172:175], v[198:201], v[32:35]
	v_mfma_f32_16x16x32_bf16 v[32:35], v[176:179], v[202:205], v[32:35]
	v_mfma_f32_16x16x32_bf16 v[36:39], v[148:151], v[202:205], v[36:39]
	v_mfma_f32_16x16x32_bf16 v[36:39], v[144:147], v[198:201], v[36:39]
	v_mfma_f32_16x16x32_bf16 v[20:23], v[144:147], v[206:209], v[20:23]
	v_mfma_f32_16x16x32_bf16 v[20:23], v[148:151], v[210:213], v[20:23]
	v_mfma_f32_16x16x32_bf16 v[16:19], v[176:179], v[210:213], v[16:19]
	v_mfma_f32_16x16x32_bf16 v[16:19], v[172:175], v[206:209], v[16:19]
	v_mfma_f32_16x16x32_bf16 v[0:3], v[172:175], v[214:217], v[0:3]
	v_mfma_f32_16x16x32_bf16 v[0:3], v[176:179], v[218:221], v[0:3]
	v_mfma_f32_16x16x32_bf16 v[4:7], v[148:151], v[218:221], v[4:7]
	v_mfma_f32_16x16x32_bf16 v[4:7], v[144:147], v[214:217], v[4:7]
	s_barrier
	s_setprio 0
	s_add_i32 s83, s83, 2
	s_add_u32 s81, s81, 0x100
	s_addc_u32 s82, s82, 0
	s_add_u32 s60, s60, 0x100
	s_addc_u32 s61, s61, 0
	s_cmp_gt_u32 s83, 29
.LBB0_440:
	ds_read_b128 v[128:131], v189
	v_xor_b32_e32 v253, 64, v189
	ds_read_b128 v[132:135], v253
	ds_read_b128 v[136:139], v189 offset:2048
	ds_read_b128 v[140:143], v253 offset:2048
	ds_read_b128 v[144:147], v190
	v_xor_b32_e32 v253, 64, v190
	ds_read_b128 v[148:151], v253
	ds_read_b128 v[172:175], v190 offset:2048
	ds_read_b128 v[176:179], v253 offset:2048
	s_add_u32 s62, s60, 0xfff80080
	s_addc_u32 s63, s61, -1
	s_cmp_eq_u32 s83, 28
	s_cselect_b32 s65, s15, s63
	s_cselect_b32 s64, s53, s62
	s_cselect_b32 s63, s51, s82
	s_cselect_b32 s62, s59, s81
	v_lshl_add_u64 v[222:223], s[60:61], 0, v[166:167]
	s_add_i32 m0, s70, 0xc000
	ds_read_b128 v[180:183], v191
	v_xor_b32_e32 v253, 64, v191
	ds_read_b128 v[194:197], v253
	ds_read_b128 v[198:201], v191 offset:2048
	ds_read_b128 v[202:205], v253 offset:2048
	ds_read_b128 v[206:209], v191 offset:4096
	ds_read_b128 v[210:213], v253 offset:4096
	ds_read_b128 v[214:217], v191 offset:6144
	ds_read_b128 v[218:221], v253 offset:6144
	global_load_lds_dwordx4 v[222:223], off
	v_lshl_add_u64 v[222:223], s[60:61], 0, v[164:165]
	s_add_i32 m0, s70, 0xe000
	s_nop 0
	global_load_lds_dwordx4 v[222:223], off
	s_waitcnt vmcnt(8)
	s_waitcnt lgkmcnt(0)
	s_setprio 1
	s_barrier
	v_mfma_f32_16x16x32_bf16 v[124:127], v[128:131], v[180:183], v[124:127]
	v_mfma_f32_16x16x32_bf16 v[124:127], v[132:135], v[194:197], v[124:127]
	v_mfma_f32_16x16x32_bf16 v[120:123], v[140:143], v[194:197], v[120:123]
	v_mfma_f32_16x16x32_bf16 v[120:123], v[136:139], v[180:183], v[120:123]
	v_mfma_f32_16x16x32_bf16 v[104:107], v[136:139], v[198:201], v[104:107]
	v_mfma_f32_16x16x32_bf16 v[104:107], v[140:143], v[202:205], v[104:107]
	v_mfma_f32_16x16x32_bf16 v[108:111], v[132:135], v[202:205], v[108:111]
	v_mfma_f32_16x16x32_bf16 v[108:111], v[128:131], v[198:201], v[108:111]
	v_mfma_f32_16x16x32_bf16 v[92:95], v[128:131], v[206:209], v[92:95]
	v_mfma_f32_16x16x32_bf16 v[92:95], v[132:135], v[210:213], v[92:95]
	v_mfma_f32_16x16x32_bf16 v[88:91], v[140:143], v[210:213], v[88:91]
	v_mfma_f32_16x16x32_bf16 v[88:91], v[136:139], v[206:209], v[88:91]
	v_mfma_f32_16x16x32_bf16 v[72:75], v[136:139], v[214:217], v[72:75]
	v_mfma_f32_16x16x32_bf16 v[72:75], v[140:143], v[218:221], v[72:75]
	v_mfma_f32_16x16x32_bf16 v[76:79], v[132:135], v[218:221], v[76:79]
	v_mfma_f32_16x16x32_bf16 v[76:79], v[128:131], v[214:217], v[76:79]
	v_mfma_f32_16x16x32_bf16 v[116:119], v[144:147], v[180:183], v[116:119]
	v_mfma_f32_16x16x32_bf16 v[116:119], v[148:151], v[194:197], v[116:119]
	v_mfma_f32_16x16x32_bf16 v[112:115], v[176:179], v[194:197], v[112:115]
	v_mfma_f32_16x16x32_bf16 v[112:115], v[172:175], v[180:183], v[112:115]
	v_mfma_f32_16x16x32_bf16 v[96:99], v[172:175], v[198:201], v[96:99]
	v_mfma_f32_16x16x32_bf16 v[96:99], v[176:179], v[202:205], v[96:99]
	v_mfma_f32_16x16x32_bf16 v[100:103], v[148:151], v[202:205], v[100:103]
	v_mfma_f32_16x16x32_bf16 v[100:103], v[144:147], v[198:201], v[100:103]
	v_mfma_f32_16x16x32_bf16 v[84:87], v[144:147], v[206:209], v[84:87]
	v_mfma_f32_16x16x32_bf16 v[84:87], v[148:151], v[210:213], v[84:87]
	v_mfma_f32_16x16x32_bf16 v[80:83], v[176:179], v[210:213], v[80:83]
	v_mfma_f32_16x16x32_bf16 v[80:83], v[172:175], v[206:209], v[80:83]
	v_mfma_f32_16x16x32_bf16 v[64:67], v[172:175], v[214:217], v[64:67]
	v_mfma_f32_16x16x32_bf16 v[64:67], v[176:179], v[218:221], v[64:67]
	v_mfma_f32_16x16x32_bf16 v[68:71], v[148:151], v[218:221], v[68:71]
	v_mfma_f32_16x16x32_bf16 v[68:71], v[144:147], v[214:217], v[68:71]
	s_barrier
	s_setprio 0
	s_add_i32 s84, s79, s69
	v_lshl_add_u64 v[222:223], s[62:63], 0, v[154:155]
	s_mov_b32 m0, s84
	ds_read_b128 v[180:183], v191 offset:16384
	v_xor_b32_e32 v253, 64, v191
	ds_read_b128 v[194:197], v253 offset:16384
	ds_read_b128 v[198:201], v191 offset:18432
	ds_read_b128 v[202:205], v253 offset:18432
	ds_read_b128 v[206:209], v191 offset:20480
	ds_read_b128 v[210:213], v253 offset:20480
	ds_read_b128 v[214:217], v191 offset:22528
	ds_read_b128 v[218:221], v253 offset:22528
	global_load_lds_dwordx4 v[222:223], off
	s_add_i32 m0, s84, 0x2000
	s_add_u32 s84, s62, 0x80000
	v_lshl_add_u64 v[224:225], s[62:63], 0, v[162:163]
	s_addc_u32 s85, s63, 0
	s_add_i32 s86, s80, s69
	global_load_lds_dwordx4 v[224:225], off
	v_lshl_add_u64 v[226:227], s[84:85], 0, v[154:155]
	s_mov_b32 m0, s86
	v_lshl_add_u64 v[228:229], s[64:65], 0, v[160:161]
	global_load_lds_dwordx4 v[226:227], off
	v_lshl_add_u64 v[226:227], s[84:85], 0, v[162:163]
	s_add_i32 m0, s86, 0x2000
	s_nop 0
	global_load_lds_dwordx4 v[226:227], off
	v_lshl_add_u64 v[226:227], s[64:65], 0, v[152:153]
	s_mov_b32 m0, s70
	s_nop 0
	global_load_lds_dwordx4 v[226:227], off
	s_mov_b32 m0, s71
	s_nop 0
	global_load_lds_dwordx4 v[228:229], off
	s_waitcnt vmcnt(8)
	s_waitcnt lgkmcnt(0)
	s_setprio 1
	s_barrier
	v_mfma_f32_16x16x32_bf16 v[60:63], v[128:131], v[180:183], v[60:63]
	v_mfma_f32_16x16x32_bf16 v[60:63], v[132:135], v[194:197], v[60:63]
	v_mfma_f32_16x16x32_bf16 v[56:59], v[140:143], v[194:197], v[56:59]
	v_mfma_f32_16x16x32_bf16 v[56:59], v[136:139], v[180:183], v[56:59]
	v_mfma_f32_16x16x32_bf16 v[40:43], v[136:139], v[198:201], v[40:43]
	v_mfma_f32_16x16x32_bf16 v[40:43], v[140:143], v[202:205], v[40:43]
	v_mfma_f32_16x16x32_bf16 v[44:47], v[132:135], v[202:205], v[44:47]
	v_mfma_f32_16x16x32_bf16 v[44:47], v[128:131], v[198:201], v[44:47]
	v_mfma_f32_16x16x32_bf16 v[28:31], v[128:131], v[206:209], v[28:31]
	v_mfma_f32_16x16x32_bf16 v[28:31], v[132:135], v[210:213], v[28:31]
	v_mfma_f32_16x16x32_bf16 v[24:27], v[140:143], v[210:213], v[24:27]
	v_mfma_f32_16x16x32_bf16 v[24:27], v[136:139], v[206:209], v[24:27]
	v_mfma_f32_16x16x32_bf16 v[8:11], v[136:139], v[214:217], v[8:11]
	v_mfma_f32_16x16x32_bf16 v[8:11], v[140:143], v[218:221], v[8:11]
	v_mfma_f32_16x16x32_bf16 v[12:15], v[132:135], v[218:221], v[12:15]
	v_mfma_f32_16x16x32_bf16 v[12:15], v[128:131], v[214:217], v[12:15]
	v_mfma_f32_16x16x32_bf16 v[52:55], v[144:147], v[180:183], v[52:55]
	v_mfma_f32_16x16x32_bf16 v[52:55], v[148:151], v[194:197], v[52:55]
	v_mfma_f32_16x16x32_bf16 v[48:51], v[176:179], v[194:197], v[48:51]
	v_mfma_f32_16x16x32_bf16 v[48:51], v[172:175], v[180:183], v[48:51]
	v_mfma_f32_16x16x32_bf16 v[32:35], v[172:175], v[198:201], v[32:35]
	v_mfma_f32_16x16x32_bf16 v[32:35], v[176:179], v[202:205], v[32:35]
	v_mfma_f32_16x16x32_bf16 v[36:39], v[148:151], v[202:205], v[36:39]
	v_mfma_f32_16x16x32_bf16 v[36:39], v[144:147], v[198:201], v[36:39]
	v_mfma_f32_16x16x32_bf16 v[20:23], v[144:147], v[206:209], v[20:23]
	v_mfma_f32_16x16x32_bf16 v[20:23], v[148:151], v[210:213], v[20:23]
	v_mfma_f32_16x16x32_bf16 v[16:19], v[176:179], v[210:213], v[16:19]
	v_mfma_f32_16x16x32_bf16 v[16:19], v[172:175], v[206:209], v[16:19]
	v_mfma_f32_16x16x32_bf16 v[0:3], v[172:175], v[214:217], v[0:3]
	v_mfma_f32_16x16x32_bf16 v[0:3], v[176:179], v[218:221], v[0:3]
	v_mfma_f32_16x16x32_bf16 v[4:7], v[148:151], v[218:221], v[4:7]
	v_mfma_f32_16x16x32_bf16 v[4:7], v[144:147], v[214:217], v[4:7]
	s_barrier
	s_setprio 0
	s_add_i32 s84, 0, 0x18000
	s_add_i32 s85, 0, 0x1c000
	v_add_u32_e32 v140, s84, v186
	v_add_u32_e32 v176, s85, v186
	ds_read_b128 v[128:131], v140
	v_xor_b32_e32 v253, 64, v140
	ds_read_b128 v[132:135], v253
	ds_read_b128 v[136:139], v140 offset:2048
	ds_read_b128 v[140:143], v253 offset:2048
	ds_read_b128 v[144:147], v176
	v_xor_b32_e32 v253, 64, v176
	ds_read_b128 v[148:151], v253
	ds_read_b128 v[172:175], v176 offset:2048
	ds_read_b128 v[176:179], v253 offset:2048
	s_add_u32 s64, s64, 0x80000
	s_addc_u32 s65, s65, 0
	s_mov_b32 m0, s72
	v_lshl_add_u64 v[230:231], s[64:65], 0, v[152:153]
	ds_read_b128 v[180:183], v191 offset:32768
	v_xor_b32_e32 v253, 64, v191
	ds_read_b128 v[194:197], v253 offset:32768
	ds_read_b128 v[198:201], v191 offset:34816
	ds_read_b128 v[202:205], v253 offset:34816
	ds_read_b128 v[206:209], v191 offset:36864
	ds_read_b128 v[210:213], v253 offset:36864
	ds_read_b128 v[214:217], v191 offset:38912
	ds_read_b128 v[218:221], v253 offset:38912
	global_load_lds_dwordx4 v[230:231], off
	v_lshl_add_u64 v[230:231], s[64:65], 0, v[160:161]
	s_mov_b32 m0, s73
	s_nop 0
	global_load_lds_dwordx4 v[230:231], off
	s_waitcnt vmcnt(8)
	s_waitcnt lgkmcnt(0)
	s_setprio 1
	s_barrier
	v_mfma_f32_16x16x32_bf16 v[124:127], v[128:131], v[180:183], v[124:127]
	v_mfma_f32_16x16x32_bf16 v[124:127], v[132:135], v[194:197], v[124:127]
	v_mfma_f32_16x16x32_bf16 v[120:123], v[140:143], v[194:197], v[120:123]
	v_mfma_f32_16x16x32_bf16 v[120:123], v[136:139], v[180:183], v[120:123]
	v_mfma_f32_16x16x32_bf16 v[104:107], v[136:139], v[198:201], v[104:107]
	v_mfma_f32_16x16x32_bf16 v[104:107], v[140:143], v[202:205], v[104:107]
	v_mfma_f32_16x16x32_bf16 v[108:111], v[132:135], v[202:205], v[108:111]
	v_mfma_f32_16x16x32_bf16 v[108:111], v[128:131], v[198:201], v[108:111]
	v_mfma_f32_16x16x32_bf16 v[92:95], v[128:131], v[206:209], v[92:95]
	v_mfma_f32_16x16x32_bf16 v[92:95], v[132:135], v[210:213], v[92:95]
	v_mfma_f32_16x16x32_bf16 v[88:91], v[140:143], v[210:213], v[88:91]
	v_mfma_f32_16x16x32_bf16 v[88:91], v[136:139], v[206:209], v[88:91]
	v_mfma_f32_16x16x32_bf16 v[72:75], v[136:139], v[214:217], v[72:75]
	v_mfma_f32_16x16x32_bf16 v[72:75], v[140:143], v[218:221], v[72:75]
	v_mfma_f32_16x16x32_bf16 v[76:79], v[132:135], v[218:221], v[76:79]
	v_mfma_f32_16x16x32_bf16 v[76:79], v[128:131], v[214:217], v[76:79]
	v_mfma_f32_16x16x32_bf16 v[116:119], v[144:147], v[180:183], v[116:119]
	v_mfma_f32_16x16x32_bf16 v[116:119], v[148:151], v[194:197], v[116:119]
	v_mfma_f32_16x16x32_bf16 v[112:115], v[176:179], v[194:197], v[112:115]
	v_mfma_f32_16x16x32_bf16 v[112:115], v[172:175], v[180:183], v[112:115]
	v_mfma_f32_16x16x32_bf16 v[96:99], v[172:175], v[198:201], v[96:99]
	v_mfma_f32_16x16x32_bf16 v[96:99], v[176:179], v[202:205], v[96:99]
	v_mfma_f32_16x16x32_bf16 v[100:103], v[148:151], v[202:205], v[100:103]
	v_mfma_f32_16x16x32_bf16 v[100:103], v[144:147], v[198:201], v[100:103]
	v_mfma_f32_16x16x32_bf16 v[84:87], v[144:147], v[206:209], v[84:87]
	v_mfma_f32_16x16x32_bf16 v[84:87], v[148:151], v[210:213], v[84:87]
	v_mfma_f32_16x16x32_bf16 v[80:83], v[176:179], v[210:213], v[80:83]
	v_mfma_f32_16x16x32_bf16 v[80:83], v[172:175], v[206:209], v[80:83]
	v_mfma_f32_16x16x32_bf16 v[64:67], v[172:175], v[214:217], v[64:67]
	v_mfma_f32_16x16x32_bf16 v[64:67], v[176:179], v[218:221], v[64:67]
	v_mfma_f32_16x16x32_bf16 v[68:71], v[148:151], v[218:221], v[68:71]
	v_mfma_f32_16x16x32_bf16 v[68:71], v[144:147], v[214:217], v[68:71]
	s_barrier
	s_setprio 0
	s_add_i32 s64, s84, s69
	v_lshl_add_u64 v[222:223], v[222:223], 0, s[26:27]
	s_mov_b32 m0, s64
	ds_read_b128 v[180:183], v191 offset:49152
	v_xor_b32_e32 v253, 64, v191
	ds_read_b128 v[194:197], v253 offset:49152
	ds_read_b128 v[198:201], v191 offset:51200
	ds_read_b128 v[202:205], v253 offset:51200
	ds_read_b128 v[206:209], v191 offset:53248
	ds_read_b128 v[210:213], v253 offset:53248
	ds_read_b128 v[214:217], v191 offset:55296
	ds_read_b128 v[218:221], v253 offset:55296
	global_load_lds_dwordx4 v[222:223], off
	s_add_i32 m0, s64, 0x2000
	s_add_u32 s62, s62, 0x80080
	v_lshl_add_u64 v[222:223], v[224:225], 0, s[26:27]
	s_addc_u32 s63, s63, 0
	s_add_i32 s64, s85, s69
	global_load_lds_dwordx4 v[222:223], off
	v_lshl_add_u64 v[222:223], s[62:63], 0, v[154:155]
	s_mov_b32 m0, s64
	s_nop 0
	global_load_lds_dwordx4 v[222:223], off
	v_lshl_add_u64 v[222:223], s[62:63], 0, v[162:163]
	s_add_i32 m0, s64, 0x2000
	s_nop 0
	global_load_lds_dwordx4 v[222:223], off
	v_lshl_add_u64 v[222:223], v[226:227], 0, s[26:27]
	s_mov_b32 m0, s3
	s_nop 0
	global_load_lds_dwordx4 v[222:223], off
	v_lshl_add_u64 v[222:223], v[228:229], 0, s[26:27]
	s_mov_b32 m0, s75
	s_nop 0
	global_load_lds_dwordx4 v[222:223], off
	s_waitcnt vmcnt(8)
	s_waitcnt lgkmcnt(0)
	s_setprio 1
	s_barrier
	v_mfma_f32_16x16x32_bf16 v[60:63], v[128:131], v[180:183], v[60:63]
	v_mfma_f32_16x16x32_bf16 v[60:63], v[132:135], v[194:197], v[60:63]
	v_mfma_f32_16x16x32_bf16 v[56:59], v[140:143], v[194:197], v[56:59]
	v_mfma_f32_16x16x32_bf16 v[56:59], v[136:139], v[180:183], v[56:59]
	v_mfma_f32_16x16x32_bf16 v[40:43], v[136:139], v[198:201], v[40:43]
	v_mfma_f32_16x16x32_bf16 v[40:43], v[140:143], v[202:205], v[40:43]
	v_mfma_f32_16x16x32_bf16 v[44:47], v[132:135], v[202:205], v[44:47]
	v_mfma_f32_16x16x32_bf16 v[44:47], v[128:131], v[198:201], v[44:47]
	v_mfma_f32_16x16x32_bf16 v[28:31], v[128:131], v[206:209], v[28:31]
	v_mfma_f32_16x16x32_bf16 v[28:31], v[132:135], v[210:213], v[28:31]
	v_mfma_f32_16x16x32_bf16 v[24:27], v[140:143], v[210:213], v[24:27]
	v_mfma_f32_16x16x32_bf16 v[24:27], v[136:139], v[206:209], v[24:27]
	v_mfma_f32_16x16x32_bf16 v[8:11], v[136:139], v[214:217], v[8:11]
	v_mfma_f32_16x16x32_bf16 v[8:11], v[140:143], v[218:221], v[8:11]
	v_mfma_f32_16x16x32_bf16 v[12:15], v[132:135], v[218:221], v[12:15]
	v_mfma_f32_16x16x32_bf16 v[12:15], v[128:131], v[214:217], v[12:15]
	v_mfma_f32_16x16x32_bf16 v[52:55], v[144:147], v[180:183], v[52:55]
	v_mfma_f32_16x16x32_bf16 v[52:55], v[148:151], v[194:197], v[52:55]
	v_mfma_f32_16x16x32_bf16 v[48:51], v[176:179], v[194:197], v[48:51]
	v_mfma_f32_16x16x32_bf16 v[48:51], v[172:175], v[180:183], v[48:51]
	v_mfma_f32_16x16x32_bf16 v[32:35], v[172:175], v[198:201], v[32:35]
	v_mfma_f32_16x16x32_bf16 v[32:35], v[176:179], v[202:205], v[32:35]
	v_mfma_f32_16x16x32_bf16 v[36:39], v[148:151], v[202:205], v[36:39]
	v_mfma_f32_16x16x32_bf16 v[36:39], v[144:147], v[198:201], v[36:39]
	v_mfma_f32_16x16x32_bf16 v[20:23], v[144:147], v[206:209], v[20:23]
	v_mfma_f32_16x16x32_bf16 v[20:23], v[148:151], v[210:213], v[20:23]
	v_mfma_f32_16x16x32_bf16 v[16:19], v[176:179], v[210:213], v[16:19]
	v_mfma_f32_16x16x32_bf16 v[16:19], v[172:175], v[206:209], v[16:19]
	v_mfma_f32_16x16x32_bf16 v[0:3], v[172:175], v[214:217], v[0:3]
	v_mfma_f32_16x16x32_bf16 v[0:3], v[176:179], v[218:221], v[0:3]
	v_mfma_f32_16x16x32_bf16 v[4:7], v[148:151], v[218:221], v[4:7]
	v_mfma_f32_16x16x32_bf16 v[4:7], v[144:147], v[214:217], v[4:7]
	s_barrier
	s_setprio 0
	s_add_i32 s83, s83, 2
	s_add_u32 s81, s81, 0x100
	s_addc_u32 s82, s82, 0
	s_add_u32 s60, s60, 0x100
	s_addc_u32 s61, s61, 0
	s_cmp_gt_u32 s83, 29
	s_cbranch_scc0 .LBB0_440
	s_and_b64 vcc, exec, s[28:29]
	s_cbranch_vccz .LBB0_443
	s_barrier

.LBB0_525:
	s_ashr_i32 s29, s28, 31
	s_lshl_b64 s[30:31], s[28:29], 19
	s_add_u32 s30, s3, s30
	s_addc_u32 s31, s35, s31
	s_and_b64 s[44:45], s[10:11], exec
	s_cselect_b32 s29, s31, s51
	s_cselect_b32 s70, s30, s50
	s_ashr_i32 s27, s26, 31
	s_lshl_b64 s[44:45], s[26:27], 19
	s_add_u32 s44, s52, s44
	s_addc_u32 s45, s53, s45
	s_and_b64 s[72:73], s[10:11], exec
	s_cselect_b32 s71, s45, s49
	s_cselect_b32 s72, s44, s48
	s_lshl_b32 s27, s46, 8
	v_add_u32_e32 v0, s27, v148
	s_add_u32 s73, s48, 0x100
	v_ashrrev_i32_e32 v1, 31, v0
	s_addc_u32 s74, s49, 0
	v_lshl_add_u64 v[144:145], v[0:1], 4, s[16:17]
	s_add_u32 s46, s50, 0x40080
	s_addc_u32 s47, s51, 0
	s_mov_b32 s75, -2
	s_mov_b64 s[48:49], 0
	s_cmp_eq_u32 s61, 1
	s_cbranch_scc1 .Lfa_4
	v_add_u32_e32 v153, s66, v147
	ds_read_b128 v[160:163], v153
	v_xor_b32_e32 v253, 64, v153
	ds_read_b128 v[164:167], v253
	ds_read_b128 v[168:171], v153 offset:2048
	ds_read_b128 v[172:175], v253 offset:2048
	v_add_u32_e32 v153, s67, v147
	ds_read_b128 v[176:179], v153
	v_xor_b32_e32 v253, 64, v153
	ds_read_b128 v[180:183], v253
	ds_read_b128 v[186:189], v153 offset:2048
	ds_read_b128 v[190:193], v253 offset:2048
	s_add_u32 s50, s46, 0xfffc0080
	s_addc_u32 s51, s47, -1
	s_and_b64 s[48:49], s[48:49], exec
	s_cselect_b32 s51, s29, s51
	s_cselect_b32 s50, s70, s50
	s_cselect_b32 s49, s71, s74
	s_cselect_b32 s48, s72, s73
	v_lshl_add_u64 v[154:155], s[46:47], 0, v[138:139]
	s_add_i32 m0, s57, 0xc000
	ds_read_b128 v[194:197], v150
	v_xor_b32_e32 v253, 64, v150
	ds_read_b128 v[198:201], v253
	ds_read_b128 v[202:205], v150 offset:2048
	ds_read_b128 v[206:209], v253 offset:2048
	ds_read_b128 v[210:213], v150 offset:4096
	ds_read_b128 v[214:217], v253 offset:4096
	ds_read_b128 v[218:221], v150 offset:6144
	ds_read_b128 v[222:225], v253 offset:6144
	global_load_lds_dwordx4 v[154:155], off
	v_lshl_add_u64 v[154:155], s[46:47], 0, v[136:137]
	s_add_i32 m0, s57, 0xe000
	s_nop 0
	global_load_lds_dwordx4 v[154:155], off
	s_waitcnt vmcnt(16)
	s_waitcnt lgkmcnt(0)
	s_setprio 1
	s_barrier
	v_mfma_f32_16x16x32_bf16 v[124:127], v[160:163], v[194:197], 0
	v_mfma_f32_16x16x32_bf16 v[116:119], v[168:171], v[194:197], 0
	v_mfma_f32_16x16x32_bf16 v[108:111], v[160:163], v[202:205], 0
	v_mfma_f32_16x16x32_bf16 v[100:103], v[168:171], v[202:205], 0
	v_mfma_f32_16x16x32_bf16 v[92:95], v[160:163], v[210:213], 0
	v_mfma_f32_16x16x32_bf16 v[84:87], v[168:171], v[210:213], 0
	v_mfma_f32_16x16x32_bf16 v[76:79], v[160:163], v[218:221], 0
	v_mfma_f32_16x16x32_bf16 v[68:71], v[168:171], v[218:221], 0
	v_mfma_f32_16x16x32_bf16 v[124:127], v[164:167], v[198:201], v[124:127]
	v_mfma_f32_16x16x32_bf16 v[116:119], v[172:175], v[198:201], v[116:119]
	v_mfma_f32_16x16x32_bf16 v[108:111], v[164:167], v[206:209], v[108:111]
	v_mfma_f32_16x16x32_bf16 v[100:103], v[172:175], v[206:209], v[100:103]
	v_mfma_f32_16x16x32_bf16 v[92:95], v[164:167], v[214:217], v[92:95]
	v_mfma_f32_16x16x32_bf16 v[84:87], v[172:175], v[214:217], v[84:87]
	v_mfma_f32_16x16x32_bf16 v[76:79], v[164:167], v[222:225], v[76:79]
	v_mfma_f32_16x16x32_bf16 v[68:71], v[172:175], v[222:225], v[68:71]
	v_mfma_f32_16x16x32_bf16 v[120:123], v[176:179], v[194:197], 0
	v_mfma_f32_16x16x32_bf16 v[112:115], v[186:189], v[194:197], 0
	v_mfma_f32_16x16x32_bf16 v[104:107], v[176:179], v[202:205], 0
	v_mfma_f32_16x16x32_bf16 v[96:99], v[186:189], v[202:205], 0
	v_mfma_f32_16x16x32_bf16 v[88:91], v[176:179], v[210:213], 0
	v_mfma_f32_16x16x32_bf16 v[80:83], v[186:189], v[210:213], 0
	v_mfma_f32_16x16x32_bf16 v[72:75], v[176:179], v[218:221], 0
	v_mfma_f32_16x16x32_bf16 v[64:67], v[186:189], v[218:221], 0
	v_mfma_f32_16x16x32_bf16 v[120:123], v[180:183], v[198:201], v[120:123]
	v_mfma_f32_16x16x32_bf16 v[112:115], v[190:193], v[198:201], v[112:115]
	v_mfma_f32_16x16x32_bf16 v[104:107], v[180:183], v[206:209], v[104:107]
	v_mfma_f32_16x16x32_bf16 v[96:99], v[190:193], v[206:209], v[96:99]
	v_mfma_f32_16x16x32_bf16 v[88:91], v[180:183], v[214:217], v[88:91]
	v_mfma_f32_16x16x32_bf16 v[80:83], v[190:193], v[214:217], v[80:83]
	v_mfma_f32_16x16x32_bf16 v[72:75], v[180:183], v[222:225], v[72:75]
	v_mfma_f32_16x16x32_bf16 v[64:67], v[190:193], v[222:225], v[64:67]
	s_barrier
	s_setprio 0
	s_add_i32 s76, s66, s54
	v_lshl_add_u64 v[154:155], s[48:49], 0, v[132:133]
	s_mov_b32 m0, s76
	ds_read_b128 v[194:197], v150 offset:16384
	v_xor_b32_e32 v253, 64, v150
	ds_read_b128 v[198:201], v253 offset:16384
	ds_read_b128 v[202:205], v150 offset:18432
	ds_read_b128 v[206:209], v253 offset:18432
	ds_read_b128 v[210:213], v150 offset:20480
	ds_read_b128 v[214:217], v253 offset:20480
	ds_read_b128 v[218:221], v150 offset:22528
	ds_read_b128 v[222:225], v253 offset:22528
	global_load_lds_dwordx4 v[154:155], off
	s_add_i32 m0, s76, 0x2000
	s_add_u32 s76, s48, 0x40000
	v_lshl_add_u64 v[226:227], s[48:49], 0, v[128:129]
	s_addc_u32 s77, s49, 0
	s_add_i32 s78, s67, s54
	global_load_lds_dwordx4 v[226:227], off
	v_lshl_add_u64 v[228:229], s[76:77], 0, v[132:133]
	s_mov_b32 m0, s78
	v_lshl_add_u64 v[230:231], s[50:51], 0, v[130:131]
	global_load_lds_dwordx4 v[228:229], off
	v_lshl_add_u64 v[228:229], s[76:77], 0, v[128:129]
	s_add_i32 m0, s78, 0x2000
	s_nop 0
	global_load_lds_dwordx4 v[228:229], off
	v_lshl_add_u64 v[228:229], s[50:51], 0, v[134:135]
	s_mov_b32 m0, s57
	s_nop 0
	global_load_lds_dwordx4 v[228:229], off
	s_mov_b32 m0, s58
	s_nop 0
	global_load_lds_dwordx4 v[230:231], off
	s_waitcnt vmcnt(16)
	s_waitcnt lgkmcnt(0)
	s_setprio 1
	s_barrier
	v_mfma_f32_16x16x32_bf16 v[60:63], v[160:163], v[194:197], 0
	v_mfma_f32_16x16x32_bf16 v[52:55], v[168:171], v[194:197], 0
	v_mfma_f32_16x16x32_bf16 v[44:47], v[160:163], v[202:205], 0
	v_mfma_f32_16x16x32_bf16 v[36:39], v[168:171], v[202:205], 0
	v_mfma_f32_16x16x32_bf16 v[28:31], v[160:163], v[210:213], 0
	v_mfma_f32_16x16x32_bf16 v[20:23], v[168:171], v[210:213], 0
	v_mfma_f32_16x16x32_bf16 v[12:15], v[160:163], v[218:221], 0
	v_mfma_f32_16x16x32_bf16 v[4:7], v[168:171], v[218:221], 0
	v_mfma_f32_16x16x32_bf16 v[60:63], v[164:167], v[198:201], v[60:63]
	v_mfma_f32_16x16x32_bf16 v[52:55], v[172:175], v[198:201], v[52:55]
	v_mfma_f32_16x16x32_bf16 v[44:47], v[164:167], v[206:209], v[44:47]
	v_mfma_f32_16x16x32_bf16 v[36:39], v[172:175], v[206:209], v[36:39]
	v_mfma_f32_16x16x32_bf16 v[28:31], v[164:167], v[214:217], v[28:31]
	v_mfma_f32_16x16x32_bf16 v[20:23], v[172:175], v[214:217], v[20:23]
	v_mfma_f32_16x16x32_bf16 v[12:15], v[164:167], v[222:225], v[12:15]
	v_mfma_f32_16x16x32_bf16 v[4:7], v[172:175], v[222:225], v[4:7]
	v_mfma_f32_16x16x32_bf16 v[56:59], v[176:179], v[194:197], 0
	v_mfma_f32_16x16x32_bf16 v[48:51], v[186:189], v[194:197], 0
	v_mfma_f32_16x16x32_bf16 v[40:43], v[176:179], v[202:205], 0
	v_mfma_f32_16x16x32_bf16 v[32:35], v[186:189], v[202:205], 0
	v_mfma_f32_16x16x32_bf16 v[24:27], v[176:179], v[210:213], 0
	v_mfma_f32_16x16x32_bf16 v[16:19], v[186:189], v[210:213], 0
	v_mfma_f32_16x16x32_bf16 v[8:11], v[176:179], v[218:221], 0
	v_mfma_f32_16x16x32_bf16 v[0:3], v[186:189], v[218:221], 0
	v_mfma_f32_16x16x32_bf16 v[56:59], v[180:183], v[198:201], v[56:59]
	v_mfma_f32_16x16x32_bf16 v[48:51], v[190:193], v[198:201], v[48:51]
	v_mfma_f32_16x16x32_bf16 v[40:43], v[180:183], v[206:209], v[40:43]
	v_mfma_f32_16x16x32_bf16 v[32:35], v[190:193], v[206:209], v[32:35]
	v_mfma_f32_16x16x32_bf16 v[24:27], v[180:183], v[214:217], v[24:27]
	v_mfma_f32_16x16x32_bf16 v[16:19], v[190:193], v[214:217], v[16:19]
	v_mfma_f32_16x16x32_bf16 v[8:11], v[180:183], v[222:225], v[8:11]
	v_mfma_f32_16x16x32_bf16 v[0:3], v[190:193], v[222:225], v[0:3]
	s_barrier
	s_setprio 0
	s_add_i32 s76, 0, 0x18000
	v_add_u32_e32 v153, s76, v147
	s_add_i32 s77, 0, 0x1c000
	ds_read_b128 v[160:163], v153
	v_xor_b32_e32 v253, 64, v153
	ds_read_b128 v[164:167], v253
	ds_read_b128 v[168:171], v153 offset:2048
	ds_read_b128 v[172:175], v253 offset:2048
	v_add_u32_e32 v153, s77, v147
	ds_read_b128 v[176:179], v153
	v_xor_b32_e32 v253, 64, v153
	ds_read_b128 v[180:183], v253
	ds_read_b128 v[186:189], v153 offset:2048
	ds_read_b128 v[190:193], v253 offset:2048
	s_add_u32 s50, s50, 0x40000
	s_addc_u32 s51, s51, 0
	s_mov_b32 m0, s59
	v_lshl_add_u64 v[232:233], s[50:51], 0, v[134:135]
	ds_read_b128 v[194:197], v150 offset:32768
	v_xor_b32_e32 v253, 64, v150
	ds_read_b128 v[198:201], v253 offset:32768
	ds_read_b128 v[202:205], v150 offset:34816
	ds_read_b128 v[206:209], v253 offset:34816
	ds_read_b128 v[210:213], v150 offset:36864
	ds_read_b128 v[214:217], v253 offset:36864
	ds_read_b128 v[218:221], v150 offset:38912
	ds_read_b128 v[222:225], v253 offset:38912
	global_load_lds_dwordx4 v[232:233], off
	v_lshl_add_u64 v[232:233], s[50:51], 0, v[130:131]
	s_mov_b32 m0, s60
	s_nop 0
	global_load_lds_dwordx4 v[232:233], off
	s_waitcnt vmcnt(8)
	s_waitcnt lgkmcnt(0)
	s_setprio 1
	s_barrier
	v_mfma_f32_16x16x32_bf16 v[124:127], v[160:163], v[194:197], v[124:127]
	v_mfma_f32_16x16x32_bf16 v[124:127], v[164:167], v[198:201], v[124:127]
	v_mfma_f32_16x16x32_bf16 v[116:119], v[172:175], v[198:201], v[116:119]
	v_mfma_f32_16x16x32_bf16 v[116:119], v[168:171], v[194:197], v[116:119]
	v_mfma_f32_16x16x32_bf16 v[100:103], v[168:171], v[202:205], v[100:103]
	v_mfma_f32_16x16x32_bf16 v[100:103], v[172:175], v[206:209], v[100:103]
	v_mfma_f32_16x16x32_bf16 v[108:111], v[164:167], v[206:209], v[108:111]
	v_mfma_f32_16x16x32_bf16 v[108:111], v[160:163], v[202:205], v[108:111]
	v_mfma_f32_16x16x32_bf16 v[92:95], v[160:163], v[210:213], v[92:95]
	v_mfma_f32_16x16x32_bf16 v[92:95], v[164:167], v[214:217], v[92:95]
	v_mfma_f32_16x16x32_bf16 v[84:87], v[172:175], v[214:217], v[84:87]
	v_mfma_f32_16x16x32_bf16 v[84:87], v[168:171], v[210:213], v[84:87]
	v_mfma_f32_16x16x32_bf16 v[68:71], v[168:171], v[218:221], v[68:71]
	v_mfma_f32_16x16x32_bf16 v[68:71], v[172:175], v[222:225], v[68:71]
	v_mfma_f32_16x16x32_bf16 v[76:79], v[164:167], v[222:225], v[76:79]
	v_mfma_f32_16x16x32_bf16 v[76:79], v[160:163], v[218:221], v[76:79]
	v_mfma_f32_16x16x32_bf16 v[120:123], v[176:179], v[194:197], v[120:123]
	v_mfma_f32_16x16x32_bf16 v[120:123], v[180:183], v[198:201], v[120:123]
	v_mfma_f32_16x16x32_bf16 v[112:115], v[190:193], v[198:201], v[112:115]
	v_mfma_f32_16x16x32_bf16 v[112:115], v[186:189], v[194:197], v[112:115]
	v_mfma_f32_16x16x32_bf16 v[96:99], v[186:189], v[202:205], v[96:99]
	v_mfma_f32_16x16x32_bf16 v[96:99], v[190:193], v[206:209], v[96:99]
	v_mfma_f32_16x16x32_bf16 v[104:107], v[180:183], v[206:209], v[104:107]
	v_mfma_f32_16x16x32_bf16 v[104:107], v[176:179], v[202:205], v[104:107]
	v_mfma_f32_16x16x32_bf16 v[88:91], v[176:179], v[210:213], v[88:91]
	v_mfma_f32_16x16x32_bf16 v[88:91], v[180:183], v[214:217], v[88:91]
	v_mfma_f32_16x16x32_bf16 v[80:83], v[190:193], v[214:217], v[80:83]
	v_mfma_f32_16x16x32_bf16 v[80:83], v[186:189], v[210:213], v[80:83]
	v_mfma_f32_16x16x32_bf16 v[64:67], v[186:189], v[218:221], v[64:67]
	v_mfma_f32_16x16x32_bf16 v[64:67], v[190:193], v[222:225], v[64:67]
	v_mfma_f32_16x16x32_bf16 v[72:75], v[180:183], v[222:225], v[72:75]
	v_mfma_f32_16x16x32_bf16 v[72:75], v[176:179], v[218:221], v[72:75]
	s_barrier
	s_setprio 0
	s_add_i32 s50, s76, s54
	v_lshl_add_u64 v[154:155], v[154:155], 0, s[20:21]
	s_mov_b32 m0, s50
	ds_read_b128 v[194:197], v150 offset:49152
	v_xor_b32_e32 v253, 64, v150
	ds_read_b128 v[198:201], v253 offset:49152
	ds_read_b128 v[202:205], v150 offset:51200
	ds_read_b128 v[206:209], v253 offset:51200
	ds_read_b128 v[210:213], v150 offset:53248
	ds_read_b128 v[214:217], v253 offset:53248
	ds_read_b128 v[218:221], v150 offset:55296
	ds_read_b128 v[222:225], v253 offset:55296
	global_load_lds_dwordx4 v[154:155], off
	s_add_i32 m0, s50, 0x2000
	s_add_u32 s48, s48, 0x40080
	v_lshl_add_u64 v[154:155], v[226:227], 0, s[20:21]
	s_addc_u32 s49, s49, 0
	s_add_i32 s50, s77, s54
	global_load_lds_dwordx4 v[154:155], off
	v_lshl_add_u64 v[154:155], s[48:49], 0, v[132:133]
	s_mov_b32 m0, s50
	s_nop 0
	global_load_lds_dwordx4 v[154:155], off
	v_lshl_add_u64 v[154:155], s[48:49], 0, v[128:129]
	s_add_i32 m0, s50, 0x2000
	s_nop 0
	global_load_lds_dwordx4 v[154:155], off
	v_lshl_add_u64 v[154:155], v[228:229], 0, s[20:21]
	s_mov_b32 m0, s62
	s_nop 0
	global_load_lds_dwordx4 v[154:155], off
	v_lshl_add_u64 v[154:155], v[230:231], 0, s[20:21]
	s_mov_b32 m0, s63
	s_nop 0
	global_load_lds_dwordx4 v[154:155], off
	s_waitcnt vmcnt(8)
	s_waitcnt lgkmcnt(0)
	s_setprio 1
	s_barrier
	v_mfma_f32_16x16x32_bf16 v[60:63], v[160:163], v[194:197], v[60:63]
	v_mfma_f32_16x16x32_bf16 v[60:63], v[164:167], v[198:201], v[60:63]
	v_mfma_f32_16x16x32_bf16 v[52:55], v[172:175], v[198:201], v[52:55]
	v_mfma_f32_16x16x32_bf16 v[52:55], v[168:171], v[194:197], v[52:55]
	v_mfma_f32_16x16x32_bf16 v[36:39], v[168:171], v[202:205], v[36:39]
	v_mfma_f32_16x16x32_bf16 v[36:39], v[172:175], v[206:209], v[36:39]
	v_mfma_f32_16x16x32_bf16 v[44:47], v[164:167], v[206:209], v[44:47]
	v_mfma_f32_16x16x32_bf16 v[44:47], v[160:163], v[202:205], v[44:47]
	v_mfma_f32_16x16x32_bf16 v[28:31], v[160:163], v[210:213], v[28:31]
	v_mfma_f32_16x16x32_bf16 v[28:31], v[164:167], v[214:217], v[28:31]
	v_mfma_f32_16x16x32_bf16 v[20:23], v[172:175], v[214:217], v[20:23]
	v_mfma_f32_16x16x32_bf16 v[20:23], v[168:171], v[210:213], v[20:23]
	v_mfma_f32_16x16x32_bf16 v[4:7], v[168:171], v[218:221], v[4:7]
	v_mfma_f32_16x16x32_bf16 v[4:7], v[172:175], v[222:225], v[4:7]
	v_mfma_f32_16x16x32_bf16 v[12:15], v[164:167], v[222:225], v[12:15]
	v_mfma_f32_16x16x32_bf16 v[12:15], v[160:163], v[218:221], v[12:15]
	v_mfma_f32_16x16x32_bf16 v[56:59], v[176:179], v[194:197], v[56:59]
	v_mfma_f32_16x16x32_bf16 v[56:59], v[180:183], v[198:201], v[56:59]
	v_mfma_f32_16x16x32_bf16 v[48:51], v[190:193], v[198:201], v[48:51]
	v_mfma_f32_16x16x32_bf16 v[48:51], v[186:189], v[194:197], v[48:51]
	v_mfma_f32_16x16x32_bf16 v[32:35], v[186:189], v[202:205], v[32:35]
	v_mfma_f32_16x16x32_bf16 v[32:35], v[190:193], v[206:209], v[32:35]
	v_mfma_f32_16x16x32_bf16 v[40:43], v[180:183], v[206:209], v[40:43]
	v_mfma_f32_16x16x32_bf16 v[40:43], v[176:179], v[202:205], v[40:43]
	v_mfma_f32_16x16x32_bf16 v[24:27], v[176:179], v[210:213], v[24:27]
	v_mfma_f32_16x16x32_bf16 v[24:27], v[180:183], v[214:217], v[24:27]
	v_mfma_f32_16x16x32_bf16 v[16:19], v[190:193], v[214:217], v[16:19]
	v_mfma_f32_16x16x32_bf16 v[16:19], v[186:189], v[210:213], v[16:19]
	v_mfma_f32_16x16x32_bf16 v[0:3], v[186:189], v[218:221], v[0:3]
	v_mfma_f32_16x16x32_bf16 v[0:3], v[190:193], v[222:225], v[0:3]
	v_mfma_f32_16x16x32_bf16 v[8:11], v[180:183], v[222:225], v[8:11]
	v_mfma_f32_16x16x32_bf16 v[8:11], v[176:179], v[218:221], v[8:11]
	s_barrier
	s_setprio 0
	s_add_i32 s75, s75, 2
	s_add_u32 s73, s73, 0x100
	s_addc_u32 s74, s74, 0
	s_add_u32 s46, s46, 0x100
	s_addc_u32 s47, s47, 0
	s_branch .LBB0_527
.Lfa_4:
	v_add_u32_e32 v153, s66, v147
	ds_read_b128 v[160:163], v153
	v_xor_b32_e32 v253, 64, v153
	ds_read_b128 v[164:167], v253
	ds_read_b128 v[168:171], v153 offset:2048
	ds_read_b128 v[172:175], v253 offset:2048
	v_add_u32_e32 v153, s67, v147
	ds_read_b128 v[176:179], v153
	v_xor_b32_e32 v253, 64, v153
	ds_read_b128 v[180:183], v253
	ds_read_b128 v[186:189], v153 offset:2048
	ds_read_b128 v[190:193], v253 offset:2048
	s_add_u32 s50, s46, 0xfffc0080
	s_addc_u32 s51, s47, -1
	s_and_b64 s[48:49], s[48:49], exec
	s_cselect_b32 s51, s29, s51
	s_cselect_b32 s50, s70, s50
	s_cselect_b32 s49, s71, s74
	s_cselect_b32 s48, s72, s73
	v_lshl_add_u64 v[154:155], s[46:47], 0, v[138:139]
	s_add_i32 m0, s57, 0xc000
	ds_read_b128 v[194:197], v150
	v_xor_b32_e32 v253, 64, v150
	ds_read_b128 v[198:201], v253
	ds_read_b128 v[202:205], v150 offset:2048
	ds_read_b128 v[206:209], v253 offset:2048
	ds_read_b128 v[210:213], v150 offset:4096
	ds_read_b128 v[214:217], v253 offset:4096
	ds_read_b128 v[218:221], v150 offset:6144
	ds_read_b128 v[222:225], v253 offset:6144
	global_load_lds_dwordx4 v[154:155], off
	v_lshl_add_u64 v[154:155], s[46:47], 0, v[136:137]
	s_add_i32 m0, s57, 0xe000
	s_nop 0
	global_load_lds_dwordx4 v[154:155], off
	s_waitcnt vmcnt(8)
	s_waitcnt lgkmcnt(0)
	s_setprio 1
	s_barrier
	v_mfma_f32_16x16x32_bf16 v[124:127], v[160:163], v[194:197], 0
	v_mfma_f32_16x16x32_bf16 v[116:119], v[168:171], v[194:197], 0
	v_mfma_f32_16x16x32_bf16 v[108:111], v[160:163], v[202:205], 0
	v_mfma_f32_16x16x32_bf16 v[100:103], v[168:171], v[202:205], 0
	v_mfma_f32_16x16x32_bf16 v[92:95], v[160:163], v[210:213], 0
	v_mfma_f32_16x16x32_bf16 v[84:87], v[168:171], v[210:213], 0
	v_mfma_f32_16x16x32_bf16 v[76:79], v[160:163], v[218:221], 0
	v_mfma_f32_16x16x32_bf16 v[68:71], v[168:171], v[218:221], 0
	v_mfma_f32_16x16x32_bf16 v[124:127], v[164:167], v[198:201], v[124:127]
	v_mfma_f32_16x16x32_bf16 v[116:119], v[172:175], v[198:201], v[116:119]
	v_mfma_f32_16x16x32_bf16 v[108:111], v[164:167], v[206:209], v[108:111]
	v_mfma_f32_16x16x32_bf16 v[100:103], v[172:175], v[206:209], v[100:103]
	v_mfma_f32_16x16x32_bf16 v[92:95], v[164:167], v[214:217], v[92:95]
	v_mfma_f32_16x16x32_bf16 v[84:87], v[172:175], v[214:217], v[84:87]
	v_mfma_f32_16x16x32_bf16 v[76:79], v[164:167], v[222:225], v[76:79]
	v_mfma_f32_16x16x32_bf16 v[68:71], v[172:175], v[222:225], v[68:71]
	v_mfma_f32_16x16x32_bf16 v[120:123], v[176:179], v[194:197], 0
	v_mfma_f32_16x16x32_bf16 v[112:115], v[186:189], v[194:197], 0
	v_mfma_f32_16x16x32_bf16 v[104:107], v[176:179], v[202:205], 0
	v_mfma_f32_16x16x32_bf16 v[96:99], v[186:189], v[202:205], 0
	v_mfma_f32_16x16x32_bf16 v[88:91], v[176:179], v[210:213], 0
	v_mfma_f32_16x16x32_bf16 v[80:83], v[186:189], v[210:213], 0
	v_mfma_f32_16x16x32_bf16 v[72:75], v[176:179], v[218:221], 0
	v_mfma_f32_16x16x32_bf16 v[64:67], v[186:189], v[218:221], 0
	v_mfma_f32_16x16x32_bf16 v[120:123], v[180:183], v[198:201], v[120:123]
	v_mfma_f32_16x16x32_bf16 v[112:115], v[190:193], v[198:201], v[112:115]
	v_mfma_f32_16x16x32_bf16 v[104:107], v[180:183], v[206:209], v[104:107]
	v_mfma_f32_16x16x32_bf16 v[96:99], v[190:193], v[206:209], v[96:99]
	v_mfma_f32_16x16x32_bf16 v[88:91], v[180:183], v[214:217], v[88:91]
	v_mfma_f32_16x16x32_bf16 v[80:83], v[190:193], v[214:217], v[80:83]
	v_mfma_f32_16x16x32_bf16 v[72:75], v[180:183], v[222:225], v[72:75]
	v_mfma_f32_16x16x32_bf16 v[64:67], v[190:193], v[222:225], v[64:67]
	s_barrier
	s_setprio 0
	s_add_i32 s76, s66, s54
	v_lshl_add_u64 v[154:155], s[48:49], 0, v[132:133]
	s_mov_b32 m0, s76
	ds_read_b128 v[194:197], v150 offset:16384
	v_xor_b32_e32 v253, 64, v150
	ds_read_b128 v[198:201], v253 offset:16384
	ds_read_b128 v[202:205], v150 offset:18432
	ds_read_b128 v[206:209], v253 offset:18432
	ds_read_b128 v[210:213], v150 offset:20480
	ds_read_b128 v[214:217], v253 offset:20480
	ds_read_b128 v[218:221], v150 offset:22528
	ds_read_b128 v[222:225], v253 offset:22528
	global_load_lds_dwordx4 v[154:155], off
	s_add_i32 m0, s76, 0x2000
	s_add_u32 s76, s48, 0x40000
	v_lshl_add_u64 v[226:227], s[48:49], 0, v[128:129]
	s_addc_u32 s77, s49, 0
	s_add_i32 s78, s67, s54
	global_load_lds_dwordx4 v[226:227], off
	v_lshl_add_u64 v[228:229], s[76:77], 0, v[132:133]
	s_mov_b32 m0, s78
	v_lshl_add_u64 v[230:231], s[50:51], 0, v[130:131]
	global_load_lds_dwordx4 v[228:229], off
	v_lshl_add_u64 v[228:229], s[76:77], 0, v[128:129]
	s_add_i32 m0, s78, 0x2000
	s_nop 0
	global_load_lds_dwordx4 v[228:229], off
	v_lshl_add_u64 v[228:229], s[50:51], 0, v[134:135]
	s_mov_b32 m0, s57
	s_nop 0
	global_load_lds_dwordx4 v[228:229], off
	s_mov_b32 m0, s58
	s_nop 0
	global_load_lds_dwordx4 v[230:231], off
	s_waitcnt vmcnt(8)
	s_waitcnt lgkmcnt(0)
	s_setprio 1
	s_barrier
	v_mfma_f32_16x16x32_bf16 v[60:63], v[160:163], v[194:197], 0
	v_mfma_f32_16x16x32_bf16 v[52:55], v[168:171], v[194:197], 0
	v_mfma_f32_16x16x32_bf16 v[44:47], v[160:163], v[202:205], 0
	v_mfma_f32_16x16x32_bf16 v[36:39], v[168:171], v[202:205], 0
	v_mfma_f32_16x16x32_bf16 v[28:31], v[160:163], v[210:213], 0
	v_mfma_f32_16x16x32_bf16 v[20:23], v[168:171], v[210:213], 0
	v_mfma_f32_16x16x32_bf16 v[12:15], v[160:163], v[218:221], 0
	v_mfma_f32_16x16x32_bf16 v[4:7], v[168:171], v[218:221], 0
	v_mfma_f32_16x16x32_bf16 v[60:63], v[164:167], v[198:201], v[60:63]
	v_mfma_f32_16x16x32_bf16 v[52:55], v[172:175], v[198:201], v[52:55]
	v_mfma_f32_16x16x32_bf16 v[44:47], v[164:167], v[206:209], v[44:47]
	v_mfma_f32_16x16x32_bf16 v[36:39], v[172:175], v[206:209], v[36:39]
	v_mfma_f32_16x16x32_bf16 v[28:31], v[164:167], v[214:217], v[28:31]
	v_mfma_f32_16x16x32_bf16 v[20:23], v[172:175], v[214:217], v[20:23]
	v_mfma_f32_16x16x32_bf16 v[12:15], v[164:167], v[222:225], v[12:15]
	v_mfma_f32_16x16x32_bf16 v[4:7], v[172:175], v[222:225], v[4:7]
	v_mfma_f32_16x16x32_bf16 v[56:59], v[176:179], v[194:197], 0
	v_mfma_f32_16x16x32_bf16 v[48:51], v[186:189], v[194:197], 0
	v_mfma_f32_16x16x32_bf16 v[40:43], v[176:179], v[202:205], 0
	v_mfma_f32_16x16x32_bf16 v[32:35], v[186:189], v[202:205], 0
	v_mfma_f32_16x16x32_bf16 v[24:27], v[176:179], v[210:213], 0
	v_mfma_f32_16x16x32_bf16 v[16:19], v[186:189], v[210:213], 0
	v_mfma_f32_16x16x32_bf16 v[8:11], v[176:179], v[218:221], 0
	v_mfma_f32_16x16x32_bf16 v[0:3], v[186:189], v[218:221], 0
	v_mfma_f32_16x16x32_bf16 v[56:59], v[180:183], v[198:201], v[56:59]
	v_mfma_f32_16x16x32_bf16 v[48:51], v[190:193], v[198:201], v[48:51]
	v_mfma_f32_16x16x32_bf16 v[40:43], v[180:183], v[206:209], v[40:43]
	v_mfma_f32_16x16x32_bf16 v[32:35], v[190:193], v[206:209], v[32:35]
	v_mfma_f32_16x16x32_bf16 v[24:27], v[180:183], v[214:217], v[24:27]
	v_mfma_f32_16x16x32_bf16 v[16:19], v[190:193], v[214:217], v[16:19]
	v_mfma_f32_16x16x32_bf16 v[8:11], v[180:183], v[222:225], v[8:11]
	v_mfma_f32_16x16x32_bf16 v[0:3], v[190:193], v[222:225], v[0:3]
	s_barrier
	s_setprio 0
	s_add_i32 s76, 0, 0x18000
	v_add_u32_e32 v153, s76, v147
	s_add_i32 s77, 0, 0x1c000
	ds_read_b128 v[160:163], v153
	v_xor_b32_e32 v253, 64, v153
	ds_read_b128 v[164:167], v253
	ds_read_b128 v[168:171], v153 offset:2048
	ds_read_b128 v[172:175], v253 offset:2048
	v_add_u32_e32 v153, s77, v147
	ds_read_b128 v[176:179], v153
	v_xor_b32_e32 v253, 64, v153
	ds_read_b128 v[180:183], v253
	ds_read_b128 v[186:189], v153 offset:2048
	ds_read_b128 v[190:193], v253 offset:2048
	s_add_u32 s50, s50, 0x40000
	s_addc_u32 s51, s51, 0
	s_mov_b32 m0, s59
	v_lshl_add_u64 v[232:233], s[50:51], 0, v[134:135]
	ds_read_b128 v[194:197], v150 offset:32768
	v_xor_b32_e32 v253, 64, v150
	ds_read_b128 v[198:201], v253 offset:32768
	ds_read_b128 v[202:205], v150 offset:34816
	ds_read_b128 v[206:209], v253 offset:34816
	ds_read_b128 v[210:213], v150 offset:36864
	ds_read_b128 v[214:217], v253 offset:36864
	ds_read_b128 v[218:221], v150 offset:38912
	ds_read_b128 v[222:225], v253 offset:38912
	global_load_lds_dwordx4 v[232:233], off
	v_lshl_add_u64 v[232:233], s[50:51], 0, v[130:131]
	s_mov_b32 m0, s60
	s_nop 0
	global_load_lds_dwordx4 v[232:233], off
	s_waitcnt vmcnt(8)
	s_waitcnt lgkmcnt(0)
	s_setprio 1
	s_barrier
	v_mfma_f32_16x16x32_bf16 v[124:127], v[160:163], v[194:197], v[124:127]
	v_mfma_f32_16x16x32_bf16 v[124:127], v[164:167], v[198:201], v[124:127]
	v_mfma_f32_16x16x32_bf16 v[116:119], v[172:175], v[198:201], v[116:119]
	v_mfma_f32_16x16x32_bf16 v[116:119], v[168:171], v[194:197], v[116:119]
	v_mfma_f32_16x16x32_bf16 v[100:103], v[168:171], v[202:205], v[100:103]
	v_mfma_f32_16x16x32_bf16 v[100:103], v[172:175], v[206:209], v[100:103]
	v_mfma_f32_16x16x32_bf16 v[108:111], v[164:167], v[206:209], v[108:111]
	v_mfma_f32_16x16x32_bf16 v[108:111], v[160:163], v[202:205], v[108:111]
	v_mfma_f32_16x16x32_bf16 v[92:95], v[160:163], v[210:213], v[92:95]
	v_mfma_f32_16x16x32_bf16 v[92:95], v[164:167], v[214:217], v[92:95]
	v_mfma_f32_16x16x32_bf16 v[84:87], v[172:175], v[214:217], v[84:87]
	v_mfma_f32_16x16x32_bf16 v[84:87], v[168:171], v[210:213], v[84:87]
	v_mfma_f32_16x16x32_bf16 v[68:71], v[168:171], v[218:221], v[68:71]
	v_mfma_f32_16x16x32_bf16 v[68:71], v[172:175], v[222:225], v[68:71]
	v_mfma_f32_16x16x32_bf16 v[76:79], v[164:167], v[222:225], v[76:79]
	v_mfma_f32_16x16x32_bf16 v[76:79], v[160:163], v[218:221], v[76:79]
	v_mfma_f32_16x16x32_bf16 v[120:123], v[176:179], v[194:197], v[120:123]
	v_mfma_f32_16x16x32_bf16 v[120:123], v[180:183], v[198:201], v[120:123]
	v_mfma_f32_16x16x32_bf16 v[112:115], v[190:193], v[198:201], v[112:115]
	v_mfma_f32_16x16x32_bf16 v[112:115], v[186:189], v[194:197], v[112:115]
	v_mfma_f32_16x16x32_bf16 v[96:99], v[186:189], v[202:205], v[96:99]
	v_mfma_f32_16x16x32_bf16 v[96:99], v[190:193], v[206:209], v[96:99]
	v_mfma_f32_16x16x32_bf16 v[104:107], v[180:183], v[206:209], v[104:107]
	v_mfma_f32_16x16x32_bf16 v[104:107], v[176:179], v[202:205], v[104:107]
	v_mfma_f32_16x16x32_bf16 v[88:91], v[176:179], v[210:213], v[88:91]
	v_mfma_f32_16x16x32_bf16 v[88:91], v[180:183], v[214:217], v[88:91]
	v_mfma_f32_16x16x32_bf16 v[80:83], v[190:193], v[214:217], v[80:83]
	v_mfma_f32_16x16x32_bf16 v[80:83], v[186:189], v[210:213], v[80:83]
	v_mfma_f32_16x16x32_bf16 v[64:67], v[186:189], v[218:221], v[64:67]
	v_mfma_f32_16x16x32_bf16 v[64:67], v[190:193], v[222:225], v[64:67]
	v_mfma_f32_16x16x32_bf16 v[72:75], v[180:183], v[222:225], v[72:75]
	v_mfma_f32_16x16x32_bf16 v[72:75], v[176:179], v[218:221], v[72:75]
	s_barrier
	s_setprio 0
	s_add_i32 s50, s76, s54
	v_lshl_add_u64 v[154:155], v[154:155], 0, s[20:21]
	s_mov_b32 m0, s50
	ds_read_b128 v[194:197], v150 offset:49152
	v_xor_b32_e32 v253, 64, v150
	ds_read_b128 v[198:201], v253 offset:49152
	ds_read_b128 v[202:205], v150 offset:51200
	ds_read_b128 v[206:209], v253 offset:51200
	ds_read_b128 v[210:213], v150 offset:53248
	ds_read_b128 v[214:217], v253 offset:53248
	ds_read_b128 v[218:221], v150 offset:55296
	ds_read_b128 v[222:225], v253 offset:55296
	global_load_lds_dwordx4 v[154:155], off
	s_add_i32 m0, s50, 0x2000
	s_add_u32 s48, s48, 0x40080
	v_lshl_add_u64 v[154:155], v[226:227], 0, s[20:21]
	s_addc_u32 s49, s49, 0
	s_add_i32 s50, s77, s54
	global_load_lds_dwordx4 v[154:155], off
	v_lshl_add_u64 v[154:155], s[48:49], 0, v[132:133]
	s_mov_b32 m0, s50
	s_nop 0
	global_load_lds_dwordx4 v[154:155], off
	v_lshl_add_u64 v[154:155], s[48:49], 0, v[128:129]
	s_add_i32 m0, s50, 0x2000
	s_nop 0
	global_load_lds_dwordx4 v[154:155], off
	v_lshl_add_u64 v[154:155], v[228:229], 0, s[20:21]
	s_mov_b32 m0, s62
	s_nop 0
	global_load_lds_dwordx4 v[154:155], off
	v_lshl_add_u64 v[154:155], v[230:231], 0, s[20:21]
	s_mov_b32 m0, s63
	s_nop 0
	global_load_lds_dwordx4 v[154:155], off
	s_waitcnt vmcnt(8)
	s_waitcnt lgkmcnt(0)
	s_setprio 1
	s_barrier
	v_mfma_f32_16x16x32_bf16 v[60:63], v[160:163], v[194:197], v[60:63]
	v_mfma_f32_16x16x32_bf16 v[60:63], v[164:167], v[198:201], v[60:63]
	v_mfma_f32_16x16x32_bf16 v[52:55], v[172:175], v[198:201], v[52:55]
	v_mfma_f32_16x16x32_bf16 v[52:55], v[168:171], v[194:197], v[52:55]
	v_mfma_f32_16x16x32_bf16 v[36:39], v[168:171], v[202:205], v[36:39]
	v_mfma_f32_16x16x32_bf16 v[36:39], v[172:175], v[206:209], v[36:39]
	v_mfma_f32_16x16x32_bf16 v[44:47], v[164:167], v[206:209], v[44:47]
	v_mfma_f32_16x16x32_bf16 v[44:47], v[160:163], v[202:205], v[44:47]
	v_mfma_f32_16x16x32_bf16 v[28:31], v[160:163], v[210:213], v[28:31]
	v_mfma_f32_16x16x32_bf16 v[28:31], v[164:167], v[214:217], v[28:31]
	v_mfma_f32_16x16x32_bf16 v[20:23], v[172:175], v[214:217], v[20:23]
	v_mfma_f32_16x16x32_bf16 v[20:23], v[168:171], v[210:213], v[20:23]
	v_mfma_f32_16x16x32_bf16 v[4:7], v[168:171], v[218:221], v[4:7]
	v_mfma_f32_16x16x32_bf16 v[4:7], v[172:175], v[222:225], v[4:7]
	v_mfma_f32_16x16x32_bf16 v[12:15], v[164:167], v[222:225], v[12:15]
	v_mfma_f32_16x16x32_bf16 v[12:15], v[160:163], v[218:221], v[12:15]
	v_mfma_f32_16x16x32_bf16 v[56:59], v[176:179], v[194:197], v[56:59]
	v_mfma_f32_16x16x32_bf16 v[56:59], v[180:183], v[198:201], v[56:59]
	v_mfma_f32_16x16x32_bf16 v[48:51], v[190:193], v[198:201], v[48:51]
	v_mfma_f32_16x16x32_bf16 v[48:51], v[186:189], v[194:197], v[48:51]
	v_mfma_f32_16x16x32_bf16 v[32:35], v[186:189], v[202:205], v[32:35]
	v_mfma_f32_16x16x32_bf16 v[32:35], v[190:193], v[206:209], v[32:35]
	v_mfma_f32_16x16x32_bf16 v[40:43], v[180:183], v[206:209], v[40:43]
	v_mfma_f32_16x16x32_bf16 v[40:43], v[176:179], v[202:205], v[40:43]
	v_mfma_f32_16x16x32_bf16 v[24:27], v[176:179], v[210:213], v[24:27]
	v_mfma_f32_16x16x32_bf16 v[24:27], v[180:183], v[214:217], v[24:27]
	v_mfma_f32_16x16x32_bf16 v[16:19], v[190:193], v[214:217], v[16:19]
	v_mfma_f32_16x16x32_bf16 v[16:19], v[186:189], v[210:213], v[16:19]
	v_mfma_f32_16x16x32_bf16 v[0:3], v[186:189], v[218:221], v[0:3]
	v_mfma_f32_16x16x32_bf16 v[0:3], v[190:193], v[222:225], v[0:3]
	v_mfma_f32_16x16x32_bf16 v[8:11], v[180:183], v[222:225], v[8:11]
	v_mfma_f32_16x16x32_bf16 v[8:11], v[176:179], v[218:221], v[8:11]
	s_barrier
	s_setprio 0
	s_add_i32 s75, s75, 2
	s_add_u32 s73, s73, 0x100
	s_addc_u32 s74, s74, 0
	s_add_u32 s46, s46, 0x100
	s_addc_u32 s47, s47, 0
	s_branch .LBB0_527
.LBB0_526:
	v_add_u32_e32 v153, s66, v147
	ds_read_b128 v[160:163], v153
	v_xor_b32_e32 v253, 64, v153
	ds_read_b128 v[164:167], v253
	ds_read_b128 v[168:171], v153 offset:2048
	ds_read_b128 v[172:175], v253 offset:2048
	v_add_u32_e32 v153, s67, v147
	ds_read_b128 v[176:179], v153
	v_xor_b32_e32 v253, 64, v153
	ds_read_b128 v[180:183], v253
	ds_read_b128 v[186:189], v153 offset:2048
	ds_read_b128 v[190:193], v253 offset:2048
	s_add_u32 s50, s46, 0xfffc0080
	s_addc_u32 s51, s47, -1
	s_and_b64 s[48:49], s[48:49], exec
	s_cselect_b32 s51, s29, s51
	s_cselect_b32 s50, s70, s50
	s_cselect_b32 s49, s71, s74
	s_cselect_b32 s48, s72, s73
	v_lshl_add_u64 v[154:155], s[46:47], 0, v[138:139]
	s_add_i32 m0, s57, 0xc000
	ds_read_b128 v[194:197], v150
	v_xor_b32_e32 v253, 64, v150
	ds_read_b128 v[198:201], v253
	ds_read_b128 v[202:205], v150 offset:2048
	ds_read_b128 v[206:209], v253 offset:2048
	ds_read_b128 v[210:213], v150 offset:4096
	ds_read_b128 v[214:217], v253 offset:4096
	ds_read_b128 v[218:221], v150 offset:6144
	ds_read_b128 v[222:225], v253 offset:6144
	global_load_lds_dwordx4 v[154:155], off
	v_lshl_add_u64 v[154:155], s[46:47], 0, v[136:137]
	s_add_i32 m0, s57, 0xe000
	s_nop 0
	global_load_lds_dwordx4 v[154:155], off
	s_waitcnt vmcnt(8)
	s_waitcnt lgkmcnt(0)
	s_setprio 1
	s_barrier
	v_mfma_f32_16x16x32_bf16 v[124:127], v[160:163], v[194:197], v[124:127]
	v_mfma_f32_16x16x32_bf16 v[124:127], v[164:167], v[198:201], v[124:127]
	v_mfma_f32_16x16x32_bf16 v[116:119], v[172:175], v[198:201], v[116:119]
	v_mfma_f32_16x16x32_bf16 v[116:119], v[168:171], v[194:197], v[116:119]
	v_mfma_f32_16x16x32_bf16 v[100:103], v[168:171], v[202:205], v[100:103]
	v_mfma_f32_16x16x32_bf16 v[100:103], v[172:175], v[206:209], v[100:103]
	v_mfma_f32_16x16x32_bf16 v[108:111], v[164:167], v[206:209], v[108:111]
	v_mfma_f32_16x16x32_bf16 v[108:111], v[160:163], v[202:205], v[108:111]
	v_mfma_f32_16x16x32_bf16 v[92:95], v[160:163], v[210:213], v[92:95]
	v_mfma_f32_16x16x32_bf16 v[92:95], v[164:167], v[214:217], v[92:95]
	v_mfma_f32_16x16x32_bf16 v[84:87], v[172:175], v[214:217], v[84:87]
	v_mfma_f32_16x16x32_bf16 v[84:87], v[168:171], v[210:213], v[84:87]
	v_mfma_f32_16x16x32_bf16 v[68:71], v[168:171], v[218:221], v[68:71]
	v_mfma_f32_16x16x32_bf16 v[68:71], v[172:175], v[222:225], v[68:71]
	v_mfma_f32_16x16x32_bf16 v[76:79], v[164:167], v[222:225], v[76:79]
	v_mfma_f32_16x16x32_bf16 v[76:79], v[160:163], v[218:221], v[76:79]
	v_mfma_f32_16x16x32_bf16 v[120:123], v[176:179], v[194:197], v[120:123]
	v_mfma_f32_16x16x32_bf16 v[120:123], v[180:183], v[198:201], v[120:123]
	v_mfma_f32_16x16x32_bf16 v[112:115], v[190:193], v[198:201], v[112:115]
	v_mfma_f32_16x16x32_bf16 v[112:115], v[186:189], v[194:197], v[112:115]
	v_mfma_f32_16x16x32_bf16 v[96:99], v[186:189], v[202:205], v[96:99]
	v_mfma_f32_16x16x32_bf16 v[96:99], v[190:193], v[206:209], v[96:99]
	v_mfma_f32_16x16x32_bf16 v[104:107], v[180:183], v[206:209], v[104:107]
	v_mfma_f32_16x16x32_bf16 v[104:107], v[176:179], v[202:205], v[104:107]
	v_mfma_f32_16x16x32_bf16 v[88:91], v[176:179], v[210:213], v[88:91]
	v_mfma_f32_16x16x32_bf16 v[88:91], v[180:183], v[214:217], v[88:91]
	v_mfma_f32_16x16x32_bf16 v[80:83], v[190:193], v[214:217], v[80:83]
	v_mfma_f32_16x16x32_bf16 v[80:83], v[186:189], v[210:213], v[80:83]
	v_mfma_f32_16x16x32_bf16 v[64:67], v[186:189], v[218:221], v[64:67]
	v_mfma_f32_16x16x32_bf16 v[64:67], v[190:193], v[222:225], v[64:67]
	v_mfma_f32_16x16x32_bf16 v[72:75], v[180:183], v[222:225], v[72:75]
	v_mfma_f32_16x16x32_bf16 v[72:75], v[176:179], v[218:221], v[72:75]
	s_barrier
	s_setprio 0
	s_add_i32 s76, s66, s54
	v_lshl_add_u64 v[154:155], s[48:49], 0, v[132:133]
	s_mov_b32 m0, s76
	ds_read_b128 v[194:197], v150 offset:16384
	v_xor_b32_e32 v253, 64, v150
	ds_read_b128 v[198:201], v253 offset:16384
	ds_read_b128 v[202:205], v150 offset:18432
	ds_read_b128 v[206:209], v253 offset:18432
	ds_read_b128 v[210:213], v150 offset:20480
	ds_read_b128 v[214:217], v253 offset:20480
	ds_read_b128 v[218:221], v150 offset:22528
	ds_read_b128 v[222:225], v253 offset:22528
	global_load_lds_dwordx4 v[154:155], off
	s_add_i32 m0, s76, 0x2000
	s_add_u32 s76, s48, 0x40000
	v_lshl_add_u64 v[226:227], s[48:49], 0, v[128:129]
	s_addc_u32 s77, s49, 0
	s_add_i32 s78, s67, s54
	global_load_lds_dwordx4 v[226:227], off
	v_lshl_add_u64 v[228:229], s[76:77], 0, v[132:133]
	s_mov_b32 m0, s78
	v_lshl_add_u64 v[230:231], s[50:51], 0, v[130:131]
	global_load_lds_dwordx4 v[228:229], off
	v_lshl_add_u64 v[228:229], s[76:77], 0, v[128:129]
	s_add_i32 m0, s78, 0x2000
	s_nop 0
	global_load_lds_dwordx4 v[228:229], off
	v_lshl_add_u64 v[228:229], s[50:51], 0, v[134:135]
	s_mov_b32 m0, s57
	s_nop 0
	global_load_lds_dwordx4 v[228:229], off
	s_mov_b32 m0, s58
	s_nop 0
	global_load_lds_dwordx4 v[230:231], off
	s_waitcnt vmcnt(8)
	s_waitcnt lgkmcnt(0)
	s_setprio 1
	s_barrier
	v_mfma_f32_16x16x32_bf16 v[60:63], v[160:163], v[194:197], v[60:63]
	v_mfma_f32_16x16x32_bf16 v[60:63], v[164:167], v[198:201], v[60:63]
	v_mfma_f32_16x16x32_bf16 v[52:55], v[172:175], v[198:201], v[52:55]
	v_mfma_f32_16x16x32_bf16 v[52:55], v[168:171], v[194:197], v[52:55]
	v_mfma_f32_16x16x32_bf16 v[36:39], v[168:171], v[202:205], v[36:39]
	v_mfma_f32_16x16x32_bf16 v[36:39], v[172:175], v[206:209], v[36:39]
	v_mfma_f32_16x16x32_bf16 v[44:47], v[164:167], v[206:209], v[44:47]
	v_mfma_f32_16x16x32_bf16 v[44:47], v[160:163], v[202:205], v[44:47]
	v_mfma_f32_16x16x32_bf16 v[28:31], v[160:163], v[210:213], v[28:31]
	v_mfma_f32_16x16x32_bf16 v[28:31], v[164:167], v[214:217], v[28:31]
	v_mfma_f32_16x16x32_bf16 v[20:23], v[172:175], v[214:217], v[20:23]
	v_mfma_f32_16x16x32_bf16 v[20:23], v[168:171], v[210:213], v[20:23]
	v_mfma_f32_16x16x32_bf16 v[4:7], v[168:171], v[218:221], v[4:7]
	v_mfma_f32_16x16x32_bf16 v[4:7], v[172:175], v[222:225], v[4:7]
	v_mfma_f32_16x16x32_bf16 v[12:15], v[164:167], v[222:225], v[12:15]
	v_mfma_f32_16x16x32_bf16 v[12:15], v[160:163], v[218:221], v[12:15]
	v_mfma_f32_16x16x32_bf16 v[56:59], v[176:179], v[194:197], v[56:59]
	v_mfma_f32_16x16x32_bf16 v[56:59], v[180:183], v[198:201], v[56:59]
	v_mfma_f32_16x16x32_bf16 v[48:51], v[190:193], v[198:201], v[48:51]
	v_mfma_f32_16x16x32_bf16 v[48:51], v[186:189], v[194:197], v[48:51]
	v_mfma_f32_16x16x32_bf16 v[32:35], v[186:189], v[202:205], v[32:35]
	v_mfma_f32_16x16x32_bf16 v[32:35], v[190:193], v[206:209], v[32:35]
	v_mfma_f32_16x16x32_bf16 v[40:43], v[180:183], v[206:209], v[40:43]
	v_mfma_f32_16x16x32_bf16 v[40:43], v[176:179], v[202:205], v[40:43]
	v_mfma_f32_16x16x32_bf16 v[24:27], v[176:179], v[210:213], v[24:27]
	v_mfma_f32_16x16x32_bf16 v[24:27], v[180:183], v[214:217], v[24:27]
	v_mfma_f32_16x16x32_bf16 v[16:19], v[190:193], v[214:217], v[16:19]
	v_mfma_f32_16x16x32_bf16 v[16:19], v[186:189], v[210:213], v[16:19]
	v_mfma_f32_16x16x32_bf16 v[0:3], v[186:189], v[218:221], v[0:3]
	v_mfma_f32_16x16x32_bf16 v[0:3], v[190:193], v[222:225], v[0:3]
	v_mfma_f32_16x16x32_bf16 v[8:11], v[180:183], v[222:225], v[8:11]
	v_mfma_f32_16x16x32_bf16 v[8:11], v[176:179], v[218:221], v[8:11]
	s_barrier
	s_setprio 0
	s_add_i32 s76, 0, 0x18000
	v_add_u32_e32 v153, s76, v147
	s_add_i32 s77, 0, 0x1c000
	ds_read_b128 v[160:163], v153
	v_xor_b32_e32 v253, 64, v153
	ds_read_b128 v[164:167], v253
	ds_read_b128 v[168:171], v153 offset:2048
	ds_read_b128 v[172:175], v253 offset:2048
	v_add_u32_e32 v153, s77, v147
	ds_read_b128 v[176:179], v153
	v_xor_b32_e32 v253, 64, v153
	ds_read_b128 v[180:183], v253
	ds_read_b128 v[186:189], v153 offset:2048
	ds_read_b128 v[190:193], v253 offset:2048
	s_add_u32 s50, s50, 0x40000
	s_addc_u32 s51, s51, 0
	s_mov_b32 m0, s59
	v_lshl_add_u64 v[232:233], s[50:51], 0, v[134:135]
	ds_read_b128 v[194:197], v150 offset:32768
	v_xor_b32_e32 v253, 64, v150
	ds_read_b128 v[198:201], v253 offset:32768
	ds_read_b128 v[202:205], v150 offset:34816
	ds_read_b128 v[206:209], v253 offset:34816
	ds_read_b128 v[210:213], v150 offset:36864
	ds_read_b128 v[214:217], v253 offset:36864
	ds_read_b128 v[218:221], v150 offset:38912
	ds_read_b128 v[222:225], v253 offset:38912
	global_load_lds_dwordx4 v[232:233], off
	v_lshl_add_u64 v[232:233], s[50:51], 0, v[130:131]
	s_mov_b32 m0, s60
	s_nop 0
	global_load_lds_dwordx4 v[232:233], off
	s_waitcnt vmcnt(8)
	s_waitcnt lgkmcnt(0)
	s_setprio 1
	s_barrier
	v_mfma_f32_16x16x32_bf16 v[124:127], v[160:163], v[194:197], v[124:127]
	v_mfma_f32_16x16x32_bf16 v[124:127], v[164:167], v[198:201], v[124:127]
	v_mfma_f32_16x16x32_bf16 v[116:119], v[172:175], v[198:201], v[116:119]
	v_mfma_f32_16x16x32_bf16 v[116:119], v[168:171], v[194:197], v[116:119]
	v_mfma_f32_16x16x32_bf16 v[100:103], v[168:171], v[202:205], v[100:103]
	v_mfma_f32_16x16x32_bf16 v[100:103], v[172:175], v[206:209], v[100:103]
	v_mfma_f32_16x16x32_bf16 v[108:111], v[164:167], v[206:209], v[108:111]
	v_mfma_f32_16x16x32_bf16 v[108:111], v[160:163], v[202:205], v[108:111]
	v_mfma_f32_16x16x32_bf16 v[92:95], v[160:163], v[210:213], v[92:95]
	v_mfma_f32_16x16x32_bf16 v[92:95], v[164:167], v[214:217], v[92:95]
	v_mfma_f32_16x16x32_bf16 v[84:87], v[172:175], v[214:217], v[84:87]
	v_mfma_f32_16x16x32_bf16 v[84:87], v[168:171], v[210:213], v[84:87]
	v_mfma_f32_16x16x32_bf16 v[68:71], v[168:171], v[218:221], v[68:71]
	v_mfma_f32_16x16x32_bf16 v[68:71], v[172:175], v[222:225], v[68:71]
	v_mfma_f32_16x16x32_bf16 v[76:79], v[164:167], v[222:225], v[76:79]
	v_mfma_f32_16x16x32_bf16 v[76:79], v[160:163], v[218:221], v[76:79]
	v_mfma_f32_16x16x32_bf16 v[120:123], v[176:179], v[194:197], v[120:123]
	v_mfma_f32_16x16x32_bf16 v[120:123], v[180:183], v[198:201], v[120:123]
	v_mfma_f32_16x16x32_bf16 v[112:115], v[190:193], v[198:201], v[112:115]
	v_mfma_f32_16x16x32_bf16 v[112:115], v[186:189], v[194:197], v[112:115]
	v_mfma_f32_16x16x32_bf16 v[96:99], v[186:189], v[202:205], v[96:99]
	v_mfma_f32_16x16x32_bf16 v[96:99], v[190:193], v[206:209], v[96:99]
	v_mfma_f32_16x16x32_bf16 v[104:107], v[180:183], v[206:209], v[104:107]
	v_mfma_f32_16x16x32_bf16 v[104:107], v[176:179], v[202:205], v[104:107]
	v_mfma_f32_16x16x32_bf16 v[88:91], v[176:179], v[210:213], v[88:91]
	v_mfma_f32_16x16x32_bf16 v[88:91], v[180:183], v[214:217], v[88:91]
	v_mfma_f32_16x16x32_bf16 v[80:83], v[190:193], v[214:217], v[80:83]
	v_mfma_f32_16x16x32_bf16 v[80:83], v[186:189], v[210:213], v[80:83]
	v_mfma_f32_16x16x32_bf16 v[64:67], v[186:189], v[218:221], v[64:67]
	v_mfma_f32_16x16x32_bf16 v[64:67], v[190:193], v[222:225], v[64:67]
	v_mfma_f32_16x16x32_bf16 v[72:75], v[180:183], v[222:225], v[72:75]
	v_mfma_f32_16x16x32_bf16 v[72:75], v[176:179], v[218:221], v[72:75]
	s_barrier
	s_setprio 0
	s_add_i32 s50, s76, s54
	v_lshl_add_u64 v[154:155], v[154:155], 0, s[20:21]
	s_mov_b32 m0, s50
	ds_read_b128 v[194:197], v150 offset:49152
	v_xor_b32_e32 v253, 64, v150
	ds_read_b128 v[198:201], v253 offset:49152
	ds_read_b128 v[202:205], v150 offset:51200
	ds_read_b128 v[206:209], v253 offset:51200
	ds_read_b128 v[210:213], v150 offset:53248
	ds_read_b128 v[214:217], v253 offset:53248
	ds_read_b128 v[218:221], v150 offset:55296
	ds_read_b128 v[222:225], v253 offset:55296
	global_load_lds_dwordx4 v[154:155], off
	s_add_i32 m0, s50, 0x2000
	s_add_u32 s48, s48, 0x40080
	v_lshl_add_u64 v[154:155], v[226:227], 0, s[20:21]
	s_addc_u32 s49, s49, 0
	s_add_i32 s50, s77, s54
	global_load_lds_dwordx4 v[154:155], off
	v_lshl_add_u64 v[154:155], s[48:49], 0, v[132:133]
	s_mov_b32 m0, s50
	s_nop 0
	global_load_lds_dwordx4 v[154:155], off
	v_lshl_add_u64 v[154:155], s[48:49], 0, v[128:129]
	s_add_i32 m0, s50, 0x2000
	s_nop 0
	global_load_lds_dwordx4 v[154:155], off
	v_lshl_add_u64 v[154:155], v[228:229], 0, s[20:21]
	s_mov_b32 m0, s62
	s_nop 0
	global_load_lds_dwordx4 v[154:155], off
	v_lshl_add_u64 v[154:155], v[230:231], 0, s[20:21]
	s_mov_b32 m0, s63
	s_nop 0
	global_load_lds_dwordx4 v[154:155], off
	s_waitcnt vmcnt(8)
	s_waitcnt lgkmcnt(0)
	s_setprio 1
	s_barrier
	v_mfma_f32_16x16x32_bf16 v[60:63], v[160:163], v[194:197], v[60:63]
	v_mfma_f32_16x16x32_bf16 v[60:63], v[164:167], v[198:201], v[60:63]
	v_mfma_f32_16x16x32_bf16 v[52:55], v[172:175], v[198:201], v[52:55]
	v_mfma_f32_16x16x32_bf16 v[52:55], v[168:171], v[194:197], v[52:55]
	v_mfma_f32_16x16x32_bf16 v[36:39], v[168:171], v[202:205], v[36:39]
	v_mfma_f32_16x16x32_bf16 v[36:39], v[172:175], v[206:209], v[36:39]
	v_mfma_f32_16x16x32_bf16 v[44:47], v[164:167], v[206:209], v[44:47]
	v_mfma_f32_16x16x32_bf16 v[44:47], v[160:163], v[202:205], v[44:47]
	v_mfma_f32_16x16x32_bf16 v[28:31], v[160:163], v[210:213], v[28:31]
	v_mfma_f32_16x16x32_bf16 v[28:31], v[164:167], v[214:217], v[28:31]
	v_mfma_f32_16x16x32_bf16 v[20:23], v[172:175], v[214:217], v[20:23]
	v_mfma_f32_16x16x32_bf16 v[20:23], v[168:171], v[210:213], v[20:23]
	v_mfma_f32_16x16x32_bf16 v[4:7], v[168:171], v[218:221], v[4:7]
	v_mfma_f32_16x16x32_bf16 v[4:7], v[172:175], v[222:225], v[4:7]
	v_mfma_f32_16x16x32_bf16 v[12:15], v[164:167], v[222:225], v[12:15]
	v_mfma_f32_16x16x32_bf16 v[12:15], v[160:163], v[218:221], v[12:15]
	v_mfma_f32_16x16x32_bf16 v[56:59], v[176:179], v[194:197], v[56:59]
	v_mfma_f32_16x16x32_bf16 v[56:59], v[180:183], v[198:201], v[56:59]
	v_mfma_f32_16x16x32_bf16 v[48:51], v[190:193], v[198:201], v[48:51]
	v_mfma_f32_16x16x32_bf16 v[48:51], v[186:189], v[194:197], v[48:51]
	v_mfma_f32_16x16x32_bf16 v[32:35], v[186:189], v[202:205], v[32:35]
	v_mfma_f32_16x16x32_bf16 v[32:35], v[190:193], v[206:209], v[32:35]
	v_mfma_f32_16x16x32_bf16 v[40:43], v[180:183], v[206:209], v[40:43]
	v_mfma_f32_16x16x32_bf16 v[40:43], v[176:179], v[202:205], v[40:43]
	v_mfma_f32_16x16x32_bf16 v[24:27], v[176:179], v[210:213], v[24:27]
	v_mfma_f32_16x16x32_bf16 v[24:27], v[180:183], v[214:217], v[24:27]
	v_mfma_f32_16x16x32_bf16 v[16:19], v[190:193], v[214:217], v[16:19]
	v_mfma_f32_16x16x32_bf16 v[16:19], v[186:189], v[210:213], v[16:19]
	v_mfma_f32_16x16x32_bf16 v[0:3], v[186:189], v[218:221], v[0:3]
	v_mfma_f32_16x16x32_bf16 v[0:3], v[190:193], v[222:225], v[0:3]
	v_mfma_f32_16x16x32_bf16 v[8:11], v[180:183], v[222:225], v[8:11]
	v_mfma_f32_16x16x32_bf16 v[8:11], v[176:179], v[218:221], v[8:11]
	s_barrier
	s_setprio 0
	s_add_i32 s75, s75, 2
	s_add_u32 s73, s73, 0x100
	s_addc_u32 s74, s74, 0
	s_add_u32 s46, s46, 0x100
	s_addc_u32 s47, s47, 0
	s_cmp_gt_u32 s75, 13
	s_cbranch_scc1 .LBB0_529

.Llast_4:
	v_add_u32_e32 v153, s66, v147
	ds_read_b128 v[160:163], v153
	v_xor_b32_e32 v253, 64, v153
	ds_read_b128 v[164:167], v253
	ds_read_b128 v[168:171], v153 offset:2048
	ds_read_b128 v[172:175], v253 offset:2048
	v_add_u32_e32 v153, s67, v147
	ds_read_b128 v[176:179], v153
	v_xor_b32_e32 v253, 64, v153
	ds_read_b128 v[180:183], v253
	ds_read_b128 v[186:189], v153 offset:2048
	ds_read_b128 v[190:193], v253 offset:2048
	s_add_u32 s50, s46, 0xfffc0080
	s_addc_u32 s51, s47, -1
	s_and_b64 s[48:49], s[48:49], exec
	s_cselect_b32 s51, s29, s51
	s_cselect_b32 s50, s70, s50
	s_cselect_b32 s49, s71, s74
	s_cselect_b32 s48, s72, s73
	v_lshl_add_u64 v[154:155], s[46:47], 0, v[138:139]
	s_add_i32 m0, s57, 0xc000
	ds_read_b128 v[194:197], v150
	v_xor_b32_e32 v253, 64, v150
	ds_read_b128 v[198:201], v253
	ds_read_b128 v[202:205], v150 offset:2048
	ds_read_b128 v[206:209], v253 offset:2048
	ds_read_b128 v[210:213], v150 offset:4096
	ds_read_b128 v[214:217], v253 offset:4096
	ds_read_b128 v[218:221], v150 offset:6144
	ds_read_b128 v[222:225], v253 offset:6144
	global_load_lds_dwordx4 v[154:155], off
	v_lshl_add_u64 v[154:155], s[46:47], 0, v[136:137]
	s_add_i32 m0, s57, 0xe000
	s_nop 0
	global_load_lds_dwordx4 v[154:155], off
	s_waitcnt vmcnt(8)
	s_waitcnt lgkmcnt(0)
	s_setprio 1
	s_barrier
	v_mfma_f32_16x16x32_bf16 v[124:127], v[160:163], v[194:197], v[124:127]
	v_mfma_f32_16x16x32_bf16 v[124:127], v[164:167], v[198:201], v[124:127]
	v_mfma_f32_16x16x32_bf16 v[116:119], v[172:175], v[198:201], v[116:119]
	v_mfma_f32_16x16x32_bf16 v[116:119], v[168:171], v[194:197], v[116:119]
	v_mfma_f32_16x16x32_bf16 v[100:103], v[168:171], v[202:205], v[100:103]
	v_mfma_f32_16x16x32_bf16 v[100:103], v[172:175], v[206:209], v[100:103]
	v_mfma_f32_16x16x32_bf16 v[108:111], v[164:167], v[206:209], v[108:111]
	v_mfma_f32_16x16x32_bf16 v[108:111], v[160:163], v[202:205], v[108:111]
	v_mfma_f32_16x16x32_bf16 v[92:95], v[160:163], v[210:213], v[92:95]
	v_mfma_f32_16x16x32_bf16 v[92:95], v[164:167], v[214:217], v[92:95]
	v_mfma_f32_16x16x32_bf16 v[84:87], v[172:175], v[214:217], v[84:87]
	v_mfma_f32_16x16x32_bf16 v[84:87], v[168:171], v[210:213], v[84:87]
	v_mfma_f32_16x16x32_bf16 v[68:71], v[168:171], v[218:221], v[68:71]
	v_mfma_f32_16x16x32_bf16 v[68:71], v[172:175], v[222:225], v[68:71]
	v_mfma_f32_16x16x32_bf16 v[76:79], v[164:167], v[222:225], v[76:79]
	v_mfma_f32_16x16x32_bf16 v[76:79], v[160:163], v[218:221], v[76:79]
	v_mfma_f32_16x16x32_bf16 v[120:123], v[176:179], v[194:197], v[120:123]
	v_mfma_f32_16x16x32_bf16 v[120:123], v[180:183], v[198:201], v[120:123]
	v_mfma_f32_16x16x32_bf16 v[112:115], v[190:193], v[198:201], v[112:115]
	v_mfma_f32_16x16x32_bf16 v[112:115], v[186:189], v[194:197], v[112:115]
	v_mfma_f32_16x16x32_bf16 v[96:99], v[186:189], v[202:205], v[96:99]
	v_mfma_f32_16x16x32_bf16 v[96:99], v[190:193], v[206:209], v[96:99]
	v_mfma_f32_16x16x32_bf16 v[104:107], v[180:183], v[206:209], v[104:107]
	v_mfma_f32_16x16x32_bf16 v[104:107], v[176:179], v[202:205], v[104:107]
	v_mfma_f32_16x16x32_bf16 v[88:91], v[176:179], v[210:213], v[88:91]
	v_mfma_f32_16x16x32_bf16 v[88:91], v[180:183], v[214:217], v[88:91]
	v_mfma_f32_16x16x32_bf16 v[80:83], v[190:193], v[214:217], v[80:83]
	v_mfma_f32_16x16x32_bf16 v[80:83], v[186:189], v[210:213], v[80:83]
	v_mfma_f32_16x16x32_bf16 v[64:67], v[186:189], v[218:221], v[64:67]
	v_mfma_f32_16x16x32_bf16 v[64:67], v[190:193], v[222:225], v[64:67]
	v_mfma_f32_16x16x32_bf16 v[72:75], v[180:183], v[222:225], v[72:75]
	v_mfma_f32_16x16x32_bf16 v[72:75], v[176:179], v[218:221], v[72:75]
	s_barrier
	s_setprio 0
	s_add_i32 s76, s66, s54
	v_lshl_add_u64 v[154:155], s[48:49], 0, v[132:133]
	s_mov_b32 m0, s76
	ds_read_b128 v[194:197], v150 offset:16384
	v_xor_b32_e32 v253, 64, v150
	ds_read_b128 v[198:201], v253 offset:16384
	ds_read_b128 v[202:205], v150 offset:18432
	ds_read_b128 v[206:209], v253 offset:18432
	ds_read_b128 v[210:213], v150 offset:20480
	ds_read_b128 v[214:217], v253 offset:20480
	ds_read_b128 v[218:221], v150 offset:22528
	ds_read_b128 v[222:225], v253 offset:22528
	global_load_lds_dwordx4 v[154:155], off
	s_add_i32 m0, s76, 0x2000
	s_add_u32 s76, s48, 0x40000
	v_lshl_add_u64 v[226:227], s[48:49], 0, v[128:129]
	s_addc_u32 s77, s49, 0
	s_add_i32 s78, s67, s54
	global_load_lds_dwordx4 v[226:227], off
	v_lshl_add_u64 v[228:229], s[76:77], 0, v[132:133]
	s_mov_b32 m0, s78
	v_lshl_add_u64 v[230:231], s[50:51], 0, v[130:131]
	global_load_lds_dwordx4 v[228:229], off
	v_lshl_add_u64 v[228:229], s[76:77], 0, v[128:129]
	s_add_i32 m0, s78, 0x2000
	s_nop 0
	global_load_lds_dwordx4 v[228:229], off
	v_lshl_add_u64 v[228:229], s[50:51], 0, v[134:135]
	s_mov_b32 m0, s57
	s_nop 0
	global_load_lds_dwordx4 v[228:229], off
	s_mov_b32 m0, s58
	s_nop 0
	global_load_lds_dwordx4 v[230:231], off
	s_waitcnt vmcnt(8)
	s_waitcnt lgkmcnt(0)
	s_setprio 1
	s_barrier
	v_mfma_f32_16x16x32_bf16 v[60:63], v[160:163], v[194:197], v[60:63]
	v_mfma_f32_16x16x32_bf16 v[60:63], v[164:167], v[198:201], v[60:63]
	v_mfma_f32_16x16x32_bf16 v[52:55], v[172:175], v[198:201], v[52:55]
	v_mfma_f32_16x16x32_bf16 v[52:55], v[168:171], v[194:197], v[52:55]
	v_mfma_f32_16x16x32_bf16 v[36:39], v[168:171], v[202:205], v[36:39]
	v_mfma_f32_16x16x32_bf16 v[36:39], v[172:175], v[206:209], v[36:39]
	v_mfma_f32_16x16x32_bf16 v[44:47], v[164:167], v[206:209], v[44:47]
	v_mfma_f32_16x16x32_bf16 v[44:47], v[160:163], v[202:205], v[44:47]
	v_mfma_f32_16x16x32_bf16 v[28:31], v[160:163], v[210:213], v[28:31]
	v_mfma_f32_16x16x32_bf16 v[28:31], v[164:167], v[214:217], v[28:31]
	v_mfma_f32_16x16x32_bf16 v[20:23], v[172:175], v[214:217], v[20:23]
	v_mfma_f32_16x16x32_bf16 v[20:23], v[168:171], v[210:213], v[20:23]
	v_mfma_f32_16x16x32_bf16 v[4:7], v[168:171], v[218:221], v[4:7]
	v_mfma_f32_16x16x32_bf16 v[4:7], v[172:175], v[222:225], v[4:7]
	v_mfma_f32_16x16x32_bf16 v[12:15], v[164:167], v[222:225], v[12:15]
	v_mfma_f32_16x16x32_bf16 v[12:15], v[160:163], v[218:221], v[12:15]
	v_mfma_f32_16x16x32_bf16 v[56:59], v[176:179], v[194:197], v[56:59]
	v_mfma_f32_16x16x32_bf16 v[56:59], v[180:183], v[198:201], v[56:59]
	v_mfma_f32_16x16x32_bf16 v[48:51], v[190:193], v[198:201], v[48:51]
	v_mfma_f32_16x16x32_bf16 v[48:51], v[186:189], v[194:197], v[48:51]
	v_mfma_f32_16x16x32_bf16 v[32:35], v[186:189], v[202:205], v[32:35]
	v_mfma_f32_16x16x32_bf16 v[32:35], v[190:193], v[206:209], v[32:35]
	v_mfma_f32_16x16x32_bf16 v[40:43], v[180:183], v[206:209], v[40:43]
	v_mfma_f32_16x16x32_bf16 v[40:43], v[176:179], v[202:205], v[40:43]
	v_mfma_f32_16x16x32_bf16 v[24:27], v[176:179], v[210:213], v[24:27]
	v_mfma_f32_16x16x32_bf16 v[24:27], v[180:183], v[214:217], v[24:27]
	v_mfma_f32_16x16x32_bf16 v[16:19], v[190:193], v[214:217], v[16:19]
	v_mfma_f32_16x16x32_bf16 v[16:19], v[186:189], v[210:213], v[16:19]
	v_mfma_f32_16x16x32_bf16 v[0:3], v[186:189], v[218:221], v[0:3]
	v_mfma_f32_16x16x32_bf16 v[0:3], v[190:193], v[222:225], v[0:3]
	v_mfma_f32_16x16x32_bf16 v[8:11], v[180:183], v[222:225], v[8:11]
	v_mfma_f32_16x16x32_bf16 v[8:11], v[176:179], v[218:221], v[8:11]
	s_barrier
	s_setprio 0
	s_add_i32 s76, 0, 0x18000
	v_add_u32_e32 v153, s76, v147
	s_add_i32 s77, 0, 0x1c000
	ds_read_b128 v[160:163], v153
	v_xor_b32_e32 v253, 64, v153
	ds_read_b128 v[164:167], v253
	ds_read_b128 v[168:171], v153 offset:2048
	ds_read_b128 v[172:175], v253 offset:2048
	v_add_u32_e32 v153, s77, v147
	ds_read_b128 v[176:179], v153
	v_xor_b32_e32 v253, 64, v153
	ds_read_b128 v[180:183], v253
	ds_read_b128 v[186:189], v153 offset:2048
	ds_read_b128 v[190:193], v253 offset:2048
	s_add_u32 s50, s50, 0x40000
	s_addc_u32 s51, s51, 0
	s_mov_b32 m0, s59
	v_lshl_add_u64 v[232:233], s[50:51], 0, v[134:135]
	ds_read_b128 v[194:197], v150 offset:32768
	v_xor_b32_e32 v253, 64, v150
	ds_read_b128 v[198:201], v253 offset:32768
	ds_read_b128 v[202:205], v150 offset:34816
	ds_read_b128 v[206:209], v253 offset:34816
	ds_read_b128 v[210:213], v150 offset:36864
	ds_read_b128 v[214:217], v253 offset:36864
	ds_read_b128 v[218:221], v150 offset:38912
	ds_read_b128 v[222:225], v253 offset:38912
	global_load_lds_dwordx4 v[232:233], off
	v_lshl_add_u64 v[232:233], s[50:51], 0, v[130:131]
	s_mov_b32 m0, s60
	s_nop 0
	global_load_lds_dwordx4 v[232:233], off
	s_waitcnt vmcnt(8)
	s_waitcnt lgkmcnt(0)
	s_setprio 1
	s_barrier
	v_mfma_f32_16x16x32_bf16 v[124:127], v[160:163], v[194:197], v[124:127]
	v_mfma_f32_16x16x32_bf16 v[124:127], v[164:167], v[198:201], v[124:127]
	v_mfma_f32_16x16x32_bf16 v[116:119], v[172:175], v[198:201], v[116:119]
	v_mfma_f32_16x16x32_bf16 v[116:119], v[168:171], v[194:197], v[116:119]
	v_mfma_f32_16x16x32_bf16 v[100:103], v[168:171], v[202:205], v[100:103]
	v_mfma_f32_16x16x32_bf16 v[100:103], v[172:175], v[206:209], v[100:103]
	v_mfma_f32_16x16x32_bf16 v[108:111], v[164:167], v[206:209], v[108:111]
	v_mfma_f32_16x16x32_bf16 v[108:111], v[160:163], v[202:205], v[108:111]
	v_mfma_f32_16x16x32_bf16 v[92:95], v[160:163], v[210:213], v[92:95]
	v_mfma_f32_16x16x32_bf16 v[92:95], v[164:167], v[214:217], v[92:95]
	v_mfma_f32_16x16x32_bf16 v[84:87], v[172:175], v[214:217], v[84:87]
	v_mfma_f32_16x16x32_bf16 v[84:87], v[168:171], v[210:213], v[84:87]
	v_mfma_f32_16x16x32_bf16 v[68:71], v[168:171], v[218:221], v[68:71]
	v_mfma_f32_16x16x32_bf16 v[68:71], v[172:175], v[222:225], v[68:71]
	v_mfma_f32_16x16x32_bf16 v[76:79], v[164:167], v[222:225], v[76:79]
	v_mfma_f32_16x16x32_bf16 v[76:79], v[160:163], v[218:221], v[76:79]
	v_mfma_f32_16x16x32_bf16 v[120:123], v[176:179], v[194:197], v[120:123]
	v_mfma_f32_16x16x32_bf16 v[120:123], v[180:183], v[198:201], v[120:123]
	v_mfma_f32_16x16x32_bf16 v[112:115], v[190:193], v[198:201], v[112:115]
	v_mfma_f32_16x16x32_bf16 v[112:115], v[186:189], v[194:197], v[112:115]
	v_mfma_f32_16x16x32_bf16 v[96:99], v[186:189], v[202:205], v[96:99]
	v_mfma_f32_16x16x32_bf16 v[96:99], v[190:193], v[206:209], v[96:99]
	v_mfma_f32_16x16x32_bf16 v[104:107], v[180:183], v[206:209], v[104:107]
	v_mfma_f32_16x16x32_bf16 v[104:107], v[176:179], v[202:205], v[104:107]
	v_mfma_f32_16x16x32_bf16 v[88:91], v[176:179], v[210:213], v[88:91]
	v_mfma_f32_16x16x32_bf16 v[88:91], v[180:183], v[214:217], v[88:91]
	v_mfma_f32_16x16x32_bf16 v[80:83], v[190:193], v[214:217], v[80:83]
	v_mfma_f32_16x16x32_bf16 v[80:83], v[186:189], v[210:213], v[80:83]
	v_mfma_f32_16x16x32_bf16 v[64:67], v[186:189], v[218:221], v[64:67]
	v_mfma_f32_16x16x32_bf16 v[64:67], v[190:193], v[222:225], v[64:67]
	v_mfma_f32_16x16x32_bf16 v[72:75], v[180:183], v[222:225], v[72:75]
	v_mfma_f32_16x16x32_bf16 v[72:75], v[176:179], v[218:221], v[72:75]
	s_barrier
	s_setprio 0
	v_add_u32_e32 v234, 0x21000, v151
	ds_read_b128 v[236:239], v234
	ds_read_b128 v[240:243], v234 offset:256
	ds_read_b128 v[244:247], v234 offset:512
	ds_read_b128 v[248:251], v234 offset:768
	v_add_u32_e32 v235, s27, v146
	v_mul_u32_u24_e32 v235, 0x1600, v235
	v_lshl_or_b32 v234, s69, 7, v149
	v_lshl_add_u32 v235, v234, 1, v235
	s_add_i32 s50, s76, s54
	v_lshl_add_u64 v[154:155], v[154:155], 0, s[20:21]
	s_mov_b32 m0, s50
	ds_read_b128 v[194:197], v150 offset:49152
	v_xor_b32_e32 v253, 64, v150
	ds_read_b128 v[198:201], v253 offset:49152
	ds_read_b128 v[202:205], v150 offset:51200
	ds_read_b128 v[206:209], v253 offset:51200
	ds_read_b128 v[210:213], v150 offset:53248
	ds_read_b128 v[214:217], v253 offset:53248
	ds_read_b128 v[218:221], v150 offset:55296
	ds_read_b128 v[222:225], v253 offset:55296
	global_load_lds_dwordx4 v[154:155], off
	s_add_i32 m0, s50, 0x2000
	s_add_u32 s48, s48, 0x40080
	v_lshl_add_u64 v[154:155], v[226:227], 0, s[20:21]
	s_addc_u32 s49, s49, 0
	s_add_i32 s50, s77, s54
	global_load_lds_dwordx4 v[154:155], off
	v_lshl_add_u64 v[154:155], s[48:49], 0, v[132:133]
	s_mov_b32 m0, s50
	s_nop 0
	global_load_lds_dwordx4 v[154:155], off
	v_lshl_add_u64 v[154:155], s[48:49], 0, v[128:129]
	s_add_i32 m0, s50, 0x2000
	s_nop 0
	global_load_lds_dwordx4 v[154:155], off
	v_lshl_add_u64 v[154:155], v[228:229], 0, s[20:21]
	s_mov_b32 m0, s62
	s_nop 0
	global_load_lds_dwordx4 v[154:155], off
	v_lshl_add_u64 v[154:155], v[230:231], 0, s[20:21]
	s_mov_b32 m0, s63
	s_nop 0
	global_load_lds_dwordx4 v[154:155], off
	s_waitcnt lgkmcnt(8)
	v_add_f32_e32 v236, v236, v237
	v_add_f32_e32 v238, v238, v239
	v_add_f32_e32 v240, v240, v241
	v_add_f32_e32 v242, v242, v243
	v_add_f32_e32 v244, v244, v245
	v_add_f32_e32 v246, v246, v247
	v_add_f32_e32 v248, v248, v249
	v_add_f32_e32 v250, v250, v251
	v_add_f32_e32 v236, v236, v238
	v_add_f32_e32 v240, v240, v242
	v_add_f32_e32 v244, v244, v246
	v_add_f32_e32 v248, v248, v250
	v_fmamk_f32 v236, v236, 0x3a800000, v152
	v_fmamk_f32 v240, v240, 0x3a800000, v152
	v_fmamk_f32 v244, v244, 0x3a800000, v152
	v_fmamk_f32 v248, v248, 0x3a800000, v152
	v_rsq_f32_e32 v236, v236
	v_rsq_f32_e32 v240, v240
	v_rsq_f32_e32 v244, v244
	v_rsq_f32_e32 v248, v248
	v_mul_f32_e32 v252, 0xbfb8aa3b, v236
	v_mul_f32_e32 v254, v236, v236
	v_rcp_f32_e32 v254, v254
	v_pk_mul_f32 v[120:121], v[124:125], v[120:121]
	v_pk_mul_f32 v[122:123], v[126:127], v[122:123]
	v_pk_mul_f32 v[112:113], v[116:117], v[112:113]
	v_pk_mul_f32 v[114:115], v[118:119], v[114:115]
	v_pk_mul_f32 v[124:125], v[124:125], v[252:253] op_sel_hi:[1,0]
	v_pk_mul_f32 v[126:127], v[126:127], v[252:253] op_sel_hi:[1,0]
	v_pk_mul_f32 v[116:117], v[116:117], v[252:253] op_sel_hi:[1,0]
	v_pk_mul_f32 v[118:119], v[118:119], v[252:253] op_sel_hi:[1,0]
	v_exp_f32_e32 v124, v124
	v_exp_f32_e32 v125, v125
	v_exp_f32_e32 v126, v126
	v_exp_f32_e32 v127, v127
	v_exp_f32_e32 v116, v116
	v_exp_f32_e32 v117, v117
	v_exp_f32_e32 v118, v118
	v_exp_f32_e32 v119, v119
	v_pk_fma_f32 v[124:125], v[124:125], v[254:255], v[254:255] op_sel_hi:[1,0,0]
	v_pk_fma_f32 v[126:127], v[126:127], v[254:255], v[254:255] op_sel_hi:[1,0,0]
	v_pk_fma_f32 v[116:117], v[116:117], v[254:255], v[254:255] op_sel_hi:[1,0,0]
	v_pk_fma_f32 v[118:119], v[118:119], v[254:255], v[254:255] op_sel_hi:[1,0,0]
	v_rcp_f32_e32 v124, v124
	v_rcp_f32_e32 v125, v125
	v_rcp_f32_e32 v126, v126
	v_rcp_f32_e32 v127, v127
	v_rcp_f32_e32 v116, v116
	v_rcp_f32_e32 v117, v117
	v_rcp_f32_e32 v118, v118
	v_rcp_f32_e32 v119, v119
	v_pk_mul_f32 v[120:121], v[120:121], v[124:125]
	v_pk_mul_f32 v[122:123], v[122:123], v[126:127]
	v_pk_mul_f32 v[112:113], v[112:113], v[116:117]
	v_pk_mul_f32 v[114:115], v[114:115], v[118:119]
	v_cvt_pk_bf16_f32 v120, v120, v121
	v_cvt_pk_bf16_f32 v121, v122, v123
	v_cvt_pk_bf16_f32 v122, v112, v113
	v_cvt_pk_bf16_f32 v123, v114, v115
	global_store_dwordx4 v235, v[120:123], s[14:15]
	v_add_u32_e32 v234, 0x16000, v235
	v_mul_f32_e32 v252, 0xbfb8aa3b, v240
	v_mul_f32_e32 v254, v240, v240
	v_rcp_f32_e32 v254, v254
	v_pk_mul_f32 v[104:105], v[108:109], v[104:105]
	v_pk_mul_f32 v[106:107], v[110:111], v[106:107]
	v_pk_mul_f32 v[96:97], v[100:101], v[96:97]
	v_pk_mul_f32 v[98:99], v[102:103], v[98:99]
	v_pk_mul_f32 v[108:109], v[108:109], v[252:253] op_sel_hi:[1,0]
	v_pk_mul_f32 v[110:111], v[110:111], v[252:253] op_sel_hi:[1,0]
	v_pk_mul_f32 v[100:101], v[100:101], v[252:253] op_sel_hi:[1,0]
	v_pk_mul_f32 v[102:103], v[102:103], v[252:253] op_sel_hi:[1,0]
	v_exp_f32_e32 v108, v108
	v_exp_f32_e32 v109, v109
	v_exp_f32_e32 v110, v110
	v_exp_f32_e32 v111, v111
	v_exp_f32_e32 v100, v100
	v_exp_f32_e32 v101, v101
	v_exp_f32_e32 v102, v102
	v_exp_f32_e32 v103, v103
	v_pk_fma_f32 v[108:109], v[108:109], v[254:255], v[254:255] op_sel_hi:[1,0,0]
	v_pk_fma_f32 v[110:111], v[110:111], v[254:255], v[254:255] op_sel_hi:[1,0,0]
	v_pk_fma_f32 v[100:101], v[100:101], v[254:255], v[254:255] op_sel_hi:[1,0,0]
	v_pk_fma_f32 v[102:103], v[102:103], v[254:255], v[254:255] op_sel_hi:[1,0,0]
	v_rcp_f32_e32 v108, v108
	v_rcp_f32_e32 v109, v109
	v_rcp_f32_e32 v110, v110
	v_rcp_f32_e32 v111, v111
	v_rcp_f32_e32 v100, v100
	v_rcp_f32_e32 v101, v101
	v_rcp_f32_e32 v102, v102
	v_rcp_f32_e32 v103, v103
	v_pk_mul_f32 v[104:105], v[104:105], v[108:109]
	v_pk_mul_f32 v[106:107], v[106:107], v[110:111]
	v_pk_mul_f32 v[96:97], v[96:97], v[100:101]
	v_pk_mul_f32 v[98:99], v[98:99], v[102:103]
	v_cvt_pk_bf16_f32 v104, v104, v105
	v_cvt_pk_bf16_f32 v105, v106, v107
	v_cvt_pk_bf16_f32 v106, v96, v97
	v_cvt_pk_bf16_f32 v107, v98, v99
	global_store_dwordx4 v234, v[104:107], s[14:15]
	v_add_u32_e32 v235, 0x16000, v234
	v_mul_f32_e32 v252, 0xbfb8aa3b, v244
	v_mul_f32_e32 v254, v244, v244
	v_rcp_f32_e32 v254, v254
	v_pk_mul_f32 v[88:89], v[92:93], v[88:89]
	v_pk_mul_f32 v[90:91], v[94:95], v[90:91]
	v_pk_mul_f32 v[80:81], v[84:85], v[80:81]
	v_pk_mul_f32 v[82:83], v[86:87], v[82:83]
	v_pk_mul_f32 v[92:93], v[92:93], v[252:253] op_sel_hi:[1,0]
	v_pk_mul_f32 v[94:95], v[94:95], v[252:253] op_sel_hi:[1,0]
	v_pk_mul_f32 v[84:85], v[84:85], v[252:253] op_sel_hi:[1,0]
	v_pk_mul_f32 v[86:87], v[86:87], v[252:253] op_sel_hi:[1,0]
	v_exp_f32_e32 v92, v92
	v_exp_f32_e32 v93, v93
	v_exp_f32_e32 v94, v94
	v_exp_f32_e32 v95, v95
	v_exp_f32_e32 v84, v84
	v_exp_f32_e32 v85, v85
	v_exp_f32_e32 v86, v86
	v_exp_f32_e32 v87, v87
	v_pk_fma_f32 v[92:93], v[92:93], v[254:255], v[254:255] op_sel_hi:[1,0,0]
	v_pk_fma_f32 v[94:95], v[94:95], v[254:255], v[254:255] op_sel_hi:[1,0,0]
	v_pk_fma_f32 v[84:85], v[84:85], v[254:255], v[254:255] op_sel_hi:[1,0,0]
	v_pk_fma_f32 v[86:87], v[86:87], v[254:255], v[254:255] op_sel_hi:[1,0,0]
	v_rcp_f32_e32 v92, v92
	v_rcp_f32_e32 v93, v93
	v_rcp_f32_e32 v94, v94
	v_rcp_f32_e32 v95, v95
	v_rcp_f32_e32 v84, v84
	v_rcp_f32_e32 v85, v85
	v_rcp_f32_e32 v86, v86
	v_rcp_f32_e32 v87, v87
	v_pk_mul_f32 v[88:89], v[88:89], v[92:93]
	v_pk_mul_f32 v[90:91], v[90:91], v[94:95]
	v_pk_mul_f32 v[80:81], v[80:81], v[84:85]
	v_pk_mul_f32 v[82:83], v[82:83], v[86:87]
	v_cvt_pk_bf16_f32 v88, v88, v89
	v_cvt_pk_bf16_f32 v89, v90, v91
	v_cvt_pk_bf16_f32 v90, v80, v81
	v_cvt_pk_bf16_f32 v91, v82, v83
	global_store_dwordx4 v235, v[88:91], s[14:15]
	v_add_u32_e32 v234, 0x16000, v235
	v_mul_f32_e32 v252, 0xbfb8aa3b, v248
	v_mul_f32_e32 v254, v248, v248
	v_rcp_f32_e32 v254, v254
	v_pk_mul_f32 v[72:73], v[76:77], v[72:73]
	v_pk_mul_f32 v[74:75], v[78:79], v[74:75]
	v_pk_mul_f32 v[64:65], v[68:69], v[64:65]
	v_pk_mul_f32 v[66:67], v[70:71], v[66:67]
	v_pk_mul_f32 v[76:77], v[76:77], v[252:253] op_sel_hi:[1,0]
	v_pk_mul_f32 v[78:79], v[78:79], v[252:253] op_sel_hi:[1,0]
	v_pk_mul_f32 v[68:69], v[68:69], v[252:253] op_sel_hi:[1,0]
	v_pk_mul_f32 v[70:71], v[70:71], v[252:253] op_sel_hi:[1,0]
	v_exp_f32_e32 v76, v76
	v_exp_f32_e32 v77, v77
	v_exp_f32_e32 v78, v78
	v_exp_f32_e32 v79, v79
	v_exp_f32_e32 v68, v68
	v_exp_f32_e32 v69, v69
	v_exp_f32_e32 v70, v70
	v_exp_f32_e32 v71, v71
	v_pk_fma_f32 v[76:77], v[76:77], v[254:255], v[254:255] op_sel_hi:[1,0,0]
	v_pk_fma_f32 v[78:79], v[78:79], v[254:255], v[254:255] op_sel_hi:[1,0,0]
	v_pk_fma_f32 v[68:69], v[68:69], v[254:255], v[254:255] op_sel_hi:[1,0,0]
	v_pk_fma_f32 v[70:71], v[70:71], v[254:255], v[254:255] op_sel_hi:[1,0,0]
	v_rcp_f32_e32 v76, v76
	v_rcp_f32_e32 v77, v77
	v_rcp_f32_e32 v78, v78
	v_rcp_f32_e32 v79, v79
	v_rcp_f32_e32 v68, v68
	v_rcp_f32_e32 v69, v69
	v_rcp_f32_e32 v70, v70
	v_rcp_f32_e32 v71, v71
	v_pk_mul_f32 v[72:73], v[72:73], v[76:77]
	v_pk_mul_f32 v[74:75], v[74:75], v[78:79]
	v_pk_mul_f32 v[64:65], v[64:65], v[68:69]
	v_pk_mul_f32 v[66:67], v[66:67], v[70:71]
	v_cvt_pk_bf16_f32 v72, v72, v73
	v_cvt_pk_bf16_f32 v73, v74, v75
	v_cvt_pk_bf16_f32 v74, v64, v65
	v_cvt_pk_bf16_f32 v75, v66, v67
	global_store_dwordx4 v234, v[72:75], s[14:15]
	s_waitcnt vmcnt(12)
	s_waitcnt lgkmcnt(0)
	s_setprio 1
	s_barrier
	v_mfma_f32_16x16x32_bf16 v[60:63], v[160:163], v[194:197], v[60:63]
	v_mfma_f32_16x16x32_bf16 v[60:63], v[164:167], v[198:201], v[60:63]
	v_mfma_f32_16x16x32_bf16 v[52:55], v[172:175], v[198:201], v[52:55]
	v_mfma_f32_16x16x32_bf16 v[52:55], v[168:171], v[194:197], v[52:55]
	v_mfma_f32_16x16x32_bf16 v[36:39], v[168:171], v[202:205], v[36:39]
	v_mfma_f32_16x16x32_bf16 v[36:39], v[172:175], v[206:209], v[36:39]
	v_mfma_f32_16x16x32_bf16 v[44:47], v[164:167], v[206:209], v[44:47]
	v_mfma_f32_16x16x32_bf16 v[44:47], v[160:163], v[202:205], v[44:47]
	v_mfma_f32_16x16x32_bf16 v[28:31], v[160:163], v[210:213], v[28:31]
	v_mfma_f32_16x16x32_bf16 v[28:31], v[164:167], v[214:217], v[28:31]
	v_mfma_f32_16x16x32_bf16 v[20:23], v[172:175], v[214:217], v[20:23]
	v_mfma_f32_16x16x32_bf16 v[20:23], v[168:171], v[210:213], v[20:23]
	v_mfma_f32_16x16x32_bf16 v[4:7], v[168:171], v[218:221], v[4:7]
	v_mfma_f32_16x16x32_bf16 v[4:7], v[172:175], v[222:225], v[4:7]
	v_mfma_f32_16x16x32_bf16 v[12:15], v[164:167], v[222:225], v[12:15]
	v_mfma_f32_16x16x32_bf16 v[12:15], v[160:163], v[218:221], v[12:15]
	v_mfma_f32_16x16x32_bf16 v[56:59], v[176:179], v[194:197], v[56:59]
	v_mfma_f32_16x16x32_bf16 v[56:59], v[180:183], v[198:201], v[56:59]
	v_mfma_f32_16x16x32_bf16 v[48:51], v[190:193], v[198:201], v[48:51]
	v_mfma_f32_16x16x32_bf16 v[48:51], v[186:189], v[194:197], v[48:51]
	v_mfma_f32_16x16x32_bf16 v[32:35], v[186:189], v[202:205], v[32:35]
	v_mfma_f32_16x16x32_bf16 v[32:35], v[190:193], v[206:209], v[32:35]
	v_mfma_f32_16x16x32_bf16 v[40:43], v[180:183], v[206:209], v[40:43]
	v_mfma_f32_16x16x32_bf16 v[40:43], v[176:179], v[202:205], v[40:43]
	v_mfma_f32_16x16x32_bf16 v[24:27], v[176:179], v[210:213], v[24:27]
	v_mfma_f32_16x16x32_bf16 v[24:27], v[180:183], v[214:217], v[24:27]
	v_mfma_f32_16x16x32_bf16 v[16:19], v[190:193], v[214:217], v[16:19]
	v_mfma_f32_16x16x32_bf16 v[16:19], v[186:189], v[210:213], v[16:19]
	v_mfma_f32_16x16x32_bf16 v[0:3], v[186:189], v[218:221], v[0:3]
	v_mfma_f32_16x16x32_bf16 v[0:3], v[190:193], v[222:225], v[0:3]
	v_mfma_f32_16x16x32_bf16 v[8:11], v[180:183], v[222:225], v[8:11]
	v_mfma_f32_16x16x32_bf16 v[8:11], v[176:179], v[218:221], v[8:11]
	s_barrier
	s_setprio 0
	s_add_i32 s75, s75, 2
	s_add_u32 s73, s73, 0x100
	s_addc_u32 s74, s74, 0
	s_add_u32 s46, s46, 0x100
	s_addc_u32 s47, s47, 0

.LBB0_609:
	s_add_u32 s79, s56, 0x100
	s_addc_u32 s80, s57, 0
	s_mov_b32 s81, -2
	s_waitcnt lgkmcnt(0)
	s_cmp_eq_u32 s70, 1
	s_cbranch_scc1 .Lfa_5
	ds_read_b128 v[128:131], v189
	v_xor_b32_e32 v253, 64, v189
	ds_read_b128 v[132:135], v253
	ds_read_b128 v[136:139], v189 offset:2048
	ds_read_b128 v[140:143], v253 offset:2048
	ds_read_b128 v[144:147], v190
	v_xor_b32_e32 v253, 64, v190
	ds_read_b128 v[148:151], v253
	ds_read_b128 v[172:175], v190 offset:2048
	ds_read_b128 v[176:179], v253 offset:2048
	s_add_u32 s56, s54, 0x100
	s_addc_u32 s57, s55, 0
	s_cmp_eq_u32 s81, 40
	s_cselect_b32 s61, s17, s57
	s_cselect_b32 s60, s16, s56
	s_cselect_b32 s59, s53, s80
	s_cselect_b32 s58, s52, s79
	v_lshl_add_u64 v[222:223], s[54:55], 0, v[166:167]
	s_add_i32 m0, s66, 0xc000
	ds_read_b128 v[180:183], v191
	v_xor_b32_e32 v253, 64, v191
	ds_read_b128 v[194:197], v253
	ds_read_b128 v[198:201], v191 offset:2048
	ds_read_b128 v[202:205], v253 offset:2048
	ds_read_b128 v[206:209], v191 offset:4096
	ds_read_b128 v[210:213], v253 offset:4096
	ds_read_b128 v[214:217], v191 offset:6144
	ds_read_b128 v[218:221], v253 offset:6144
	global_load_lds_dwordx4 v[222:223], off
	v_lshl_add_u64 v[222:223], s[54:55], 0, v[164:165]
	s_add_i32 m0, s66, 0xe000
	s_nop 0
	global_load_lds_dwordx4 v[222:223], off
	s_waitcnt vmcnt(24)
	s_waitcnt lgkmcnt(0)
	s_setprio 1
	s_barrier
	v_mfma_f32_16x16x32_bf16 v[124:127], v[128:131], v[180:183], 0
	v_mfma_f32_16x16x32_bf16 v[120:123], v[136:139], v[180:183], 0
	v_mfma_f32_16x16x32_bf16 v[108:111], v[128:131], v[198:201], 0
	v_mfma_f32_16x16x32_bf16 v[104:107], v[136:139], v[198:201], 0
	v_mfma_f32_16x16x32_bf16 v[92:95], v[128:131], v[206:209], 0
	v_mfma_f32_16x16x32_bf16 v[88:91], v[136:139], v[206:209], 0
	v_mfma_f32_16x16x32_bf16 v[76:79], v[128:131], v[214:217], 0
	v_mfma_f32_16x16x32_bf16 v[72:75], v[136:139], v[214:217], 0
	v_mfma_f32_16x16x32_bf16 v[124:127], v[132:135], v[194:197], v[124:127]
	v_mfma_f32_16x16x32_bf16 v[120:123], v[140:143], v[194:197], v[120:123]
	v_mfma_f32_16x16x32_bf16 v[108:111], v[132:135], v[202:205], v[108:111]
	v_mfma_f32_16x16x32_bf16 v[104:107], v[140:143], v[202:205], v[104:107]
	v_mfma_f32_16x16x32_bf16 v[92:95], v[132:135], v[210:213], v[92:95]
	v_mfma_f32_16x16x32_bf16 v[88:91], v[140:143], v[210:213], v[88:91]
	v_mfma_f32_16x16x32_bf16 v[76:79], v[132:135], v[218:221], v[76:79]
	v_mfma_f32_16x16x32_bf16 v[72:75], v[140:143], v[218:221], v[72:75]
	v_mfma_f32_16x16x32_bf16 v[116:119], v[144:147], v[180:183], 0
	v_mfma_f32_16x16x32_bf16 v[112:115], v[172:175], v[180:183], 0
	v_mfma_f32_16x16x32_bf16 v[100:103], v[144:147], v[198:201], 0
	v_mfma_f32_16x16x32_bf16 v[96:99], v[172:175], v[198:201], 0
	v_mfma_f32_16x16x32_bf16 v[84:87], v[144:147], v[206:209], 0
	v_mfma_f32_16x16x32_bf16 v[80:83], v[172:175], v[206:209], 0
	v_mfma_f32_16x16x32_bf16 v[68:71], v[144:147], v[214:217], 0
	v_mfma_f32_16x16x32_bf16 v[64:67], v[172:175], v[214:217], 0
	v_mfma_f32_16x16x32_bf16 v[116:119], v[148:151], v[194:197], v[116:119]
	v_mfma_f32_16x16x32_bf16 v[112:115], v[176:179], v[194:197], v[112:115]
	v_mfma_f32_16x16x32_bf16 v[100:103], v[148:151], v[202:205], v[100:103]
	v_mfma_f32_16x16x32_bf16 v[96:99], v[176:179], v[202:205], v[96:99]
	v_mfma_f32_16x16x32_bf16 v[84:87], v[148:151], v[210:213], v[84:87]
	v_mfma_f32_16x16x32_bf16 v[80:83], v[176:179], v[210:213], v[80:83]
	v_mfma_f32_16x16x32_bf16 v[68:71], v[148:151], v[218:221], v[68:71]
	v_mfma_f32_16x16x32_bf16 v[64:67], v[176:179], v[218:221], v[64:67]
	s_barrier
	s_setprio 0
	s_add_i32 s54, s75, s65
	v_lshl_add_u64 v[222:223], s[58:59], 0, v[154:155]
	s_mov_b32 m0, s54
	ds_read_b128 v[180:183], v191 offset:16384
	v_xor_b32_e32 v253, 64, v191
	ds_read_b128 v[194:197], v253 offset:16384
	ds_read_b128 v[198:201], v191 offset:18432
	ds_read_b128 v[202:205], v253 offset:18432
	ds_read_b128 v[206:209], v191 offset:20480
	ds_read_b128 v[210:213], v253 offset:20480
	ds_read_b128 v[214:217], v191 offset:22528
	ds_read_b128 v[218:221], v253 offset:22528
	global_load_lds_dwordx4 v[222:223], off
	s_add_i32 m0, s54, 0x2000
	s_add_u32 s54, s58, 0xb0000
	v_lshl_add_u64 v[224:225], s[58:59], 0, v[162:163]
	s_addc_u32 s55, s59, 0
	s_add_i32 s82, s76, s65
	global_load_lds_dwordx4 v[224:225], off
	v_lshl_add_u64 v[226:227], s[54:55], 0, v[154:155]
	s_mov_b32 m0, s82
	v_lshl_add_u64 v[228:229], s[60:61], 0, v[160:161]
	global_load_lds_dwordx4 v[226:227], off
	v_lshl_add_u64 v[226:227], s[54:55], 0, v[162:163]
	s_add_i32 m0, s82, 0x2000
	s_nop 0
	global_load_lds_dwordx4 v[226:227], off
	v_lshl_add_u64 v[226:227], s[60:61], 0, v[152:153]
	s_mov_b32 m0, s66
	s_nop 0
	global_load_lds_dwordx4 v[226:227], off
	s_mov_b32 m0, s67
	s_nop 0
	global_load_lds_dwordx4 v[228:229], off
	s_waitcnt vmcnt(24)
	s_waitcnt lgkmcnt(0)
	s_setprio 1
	s_barrier
	v_mfma_f32_16x16x32_bf16 v[60:63], v[128:131], v[180:183], 0
	v_mfma_f32_16x16x32_bf16 v[56:59], v[136:139], v[180:183], 0
	v_mfma_f32_16x16x32_bf16 v[44:47], v[128:131], v[198:201], 0
	v_mfma_f32_16x16x32_bf16 v[40:43], v[136:139], v[198:201], 0
	v_mfma_f32_16x16x32_bf16 v[28:31], v[128:131], v[206:209], 0
	v_mfma_f32_16x16x32_bf16 v[24:27], v[136:139], v[206:209], 0
	v_mfma_f32_16x16x32_bf16 v[12:15], v[128:131], v[214:217], 0
	v_mfma_f32_16x16x32_bf16 v[8:11], v[136:139], v[214:217], 0
	v_mfma_f32_16x16x32_bf16 v[60:63], v[132:135], v[194:197], v[60:63]
	v_mfma_f32_16x16x32_bf16 v[56:59], v[140:143], v[194:197], v[56:59]
	v_mfma_f32_16x16x32_bf16 v[44:47], v[132:135], v[202:205], v[44:47]
	v_mfma_f32_16x16x32_bf16 v[40:43], v[140:143], v[202:205], v[40:43]
	v_mfma_f32_16x16x32_bf16 v[28:31], v[132:135], v[210:213], v[28:31]
	v_mfma_f32_16x16x32_bf16 v[24:27], v[140:143], v[210:213], v[24:27]
	v_mfma_f32_16x16x32_bf16 v[12:15], v[132:135], v[218:221], v[12:15]
	v_mfma_f32_16x16x32_bf16 v[8:11], v[140:143], v[218:221], v[8:11]
	v_mfma_f32_16x16x32_bf16 v[52:55], v[144:147], v[180:183], 0
	v_mfma_f32_16x16x32_bf16 v[48:51], v[172:175], v[180:183], 0
	v_mfma_f32_16x16x32_bf16 v[36:39], v[144:147], v[198:201], 0
	v_mfma_f32_16x16x32_bf16 v[32:35], v[172:175], v[198:201], 0
	v_mfma_f32_16x16x32_bf16 v[20:23], v[144:147], v[206:209], 0
	v_mfma_f32_16x16x32_bf16 v[16:19], v[172:175], v[206:209], 0
	v_mfma_f32_16x16x32_bf16 v[4:7], v[144:147], v[214:217], 0
	v_mfma_f32_16x16x32_bf16 v[0:3], v[172:175], v[214:217], 0
	v_mfma_f32_16x16x32_bf16 v[52:55], v[148:151], v[194:197], v[52:55]
	v_mfma_f32_16x16x32_bf16 v[48:51], v[176:179], v[194:197], v[48:51]
	v_mfma_f32_16x16x32_bf16 v[36:39], v[148:151], v[202:205], v[36:39]
	v_mfma_f32_16x16x32_bf16 v[32:35], v[176:179], v[202:205], v[32:35]
	v_mfma_f32_16x16x32_bf16 v[20:23], v[148:151], v[210:213], v[20:23]
	v_mfma_f32_16x16x32_bf16 v[16:19], v[176:179], v[210:213], v[16:19]
	v_mfma_f32_16x16x32_bf16 v[4:7], v[148:151], v[218:221], v[4:7]
	v_mfma_f32_16x16x32_bf16 v[0:3], v[176:179], v[218:221], v[0:3]
	s_barrier
	s_setprio 0
	s_add_i32 s82, 0, 0x18000
	s_add_i32 s83, 0, 0x1c000
	v_add_u32_e32 v140, s82, v186
	v_add_u32_e32 v176, s83, v186
	ds_read_b128 v[128:131], v140
	v_xor_b32_e32 v253, 64, v140
	ds_read_b128 v[132:135], v253
	ds_read_b128 v[136:139], v140 offset:2048
	ds_read_b128 v[140:143], v253 offset:2048
	ds_read_b128 v[144:147], v176
	v_xor_b32_e32 v253, 64, v176
	ds_read_b128 v[148:151], v253
	ds_read_b128 v[172:175], v176 offset:2048
	ds_read_b128 v[176:179], v253 offset:2048
	s_add_u32 s54, s60, 0xb0000
	s_addc_u32 s55, s61, 0
	s_mov_b32 m0, s68
	v_lshl_add_u64 v[230:231], s[54:55], 0, v[152:153]
	ds_read_b128 v[180:183], v191 offset:32768
	v_xor_b32_e32 v253, 64, v191
	ds_read_b128 v[194:197], v253 offset:32768
	ds_read_b128 v[198:201], v191 offset:34816
	ds_read_b128 v[202:205], v253 offset:34816
	ds_read_b128 v[206:209], v191 offset:36864
	ds_read_b128 v[210:213], v253 offset:36864
	ds_read_b128 v[214:217], v191 offset:38912
	ds_read_b128 v[218:221], v253 offset:38912
	global_load_lds_dwordx4 v[230:231], off
	v_lshl_add_u64 v[230:231], s[54:55], 0, v[160:161]
	s_mov_b32 m0, s69
	s_nop 0
	global_load_lds_dwordx4 v[230:231], off
	s_waitcnt vmcnt(8)
	s_waitcnt lgkmcnt(0)
	s_setprio 1
	s_barrier
	v_mfma_f32_16x16x32_bf16 v[124:127], v[128:131], v[180:183], v[124:127]
	v_mfma_f32_16x16x32_bf16 v[124:127], v[132:135], v[194:197], v[124:127]
	v_mfma_f32_16x16x32_bf16 v[120:123], v[140:143], v[194:197], v[120:123]
	v_mfma_f32_16x16x32_bf16 v[120:123], v[136:139], v[180:183], v[120:123]
	v_mfma_f32_16x16x32_bf16 v[104:107], v[136:139], v[198:201], v[104:107]
	v_mfma_f32_16x16x32_bf16 v[104:107], v[140:143], v[202:205], v[104:107]
	v_mfma_f32_16x16x32_bf16 v[108:111], v[132:135], v[202:205], v[108:111]
	v_mfma_f32_16x16x32_bf16 v[108:111], v[128:131], v[198:201], v[108:111]
	v_mfma_f32_16x16x32_bf16 v[92:95], v[128:131], v[206:209], v[92:95]
	v_mfma_f32_16x16x32_bf16 v[92:95], v[132:135], v[210:213], v[92:95]
	v_mfma_f32_16x16x32_bf16 v[88:91], v[140:143], v[210:213], v[88:91]
	v_mfma_f32_16x16x32_bf16 v[88:91], v[136:139], v[206:209], v[88:91]
	v_mfma_f32_16x16x32_bf16 v[72:75], v[136:139], v[214:217], v[72:75]
	v_mfma_f32_16x16x32_bf16 v[72:75], v[140:143], v[218:221], v[72:75]
	v_mfma_f32_16x16x32_bf16 v[76:79], v[132:135], v[218:221], v[76:79]
	v_mfma_f32_16x16x32_bf16 v[76:79], v[128:131], v[214:217], v[76:79]
	v_mfma_f32_16x16x32_bf16 v[116:119], v[144:147], v[180:183], v[116:119]
	v_mfma_f32_16x16x32_bf16 v[116:119], v[148:151], v[194:197], v[116:119]
	v_mfma_f32_16x16x32_bf16 v[112:115], v[176:179], v[194:197], v[112:115]
	v_mfma_f32_16x16x32_bf16 v[112:115], v[172:175], v[180:183], v[112:115]
	v_mfma_f32_16x16x32_bf16 v[96:99], v[172:175], v[198:201], v[96:99]
	v_mfma_f32_16x16x32_bf16 v[96:99], v[176:179], v[202:205], v[96:99]
	v_mfma_f32_16x16x32_bf16 v[100:103], v[148:151], v[202:205], v[100:103]
	v_mfma_f32_16x16x32_bf16 v[100:103], v[144:147], v[198:201], v[100:103]
	v_mfma_f32_16x16x32_bf16 v[84:87], v[144:147], v[206:209], v[84:87]
	v_mfma_f32_16x16x32_bf16 v[84:87], v[148:151], v[210:213], v[84:87]
	v_mfma_f32_16x16x32_bf16 v[80:83], v[176:179], v[210:213], v[80:83]
	v_mfma_f32_16x16x32_bf16 v[80:83], v[172:175], v[206:209], v[80:83]
	v_mfma_f32_16x16x32_bf16 v[64:67], v[172:175], v[214:217], v[64:67]
	v_mfma_f32_16x16x32_bf16 v[64:67], v[176:179], v[218:221], v[64:67]
	v_mfma_f32_16x16x32_bf16 v[68:71], v[148:151], v[218:221], v[68:71]
	v_mfma_f32_16x16x32_bf16 v[68:71], v[144:147], v[214:217], v[68:71]
	s_barrier
	s_setprio 0
	s_add_i32 s54, s82, s65
	v_lshl_add_u64 v[222:223], v[222:223], 0, s[28:29]
	s_mov_b32 m0, s54
	ds_read_b128 v[180:183], v191 offset:49152
	v_xor_b32_e32 v253, 64, v191
	ds_read_b128 v[194:197], v253 offset:49152
	ds_read_b128 v[198:201], v191 offset:51200
	ds_read_b128 v[202:205], v253 offset:51200
	ds_read_b128 v[206:209], v191 offset:53248
	ds_read_b128 v[210:213], v253 offset:53248
	ds_read_b128 v[214:217], v191 offset:55296
	ds_read_b128 v[218:221], v253 offset:55296
	global_load_lds_dwordx4 v[222:223], off
	s_add_i32 m0, s54, 0x2000
	s_add_u32 s54, s58, 0xb0080
	v_lshl_add_u64 v[222:223], v[224:225], 0, s[28:29]
	s_addc_u32 s55, s59, 0
	s_add_i32 s58, s83, s65
	global_load_lds_dwordx4 v[222:223], off
	v_lshl_add_u64 v[222:223], s[54:55], 0, v[154:155]
	s_mov_b32 m0, s58
	s_nop 0
	global_load_lds_dwordx4 v[222:223], off
	v_lshl_add_u64 v[222:223], s[54:55], 0, v[162:163]
	s_add_i32 m0, s58, 0x2000
	s_nop 0
	global_load_lds_dwordx4 v[222:223], off
	v_lshl_add_u64 v[222:223], v[226:227], 0, s[28:29]
	s_mov_b32 m0, s3
	s_nop 0
	global_load_lds_dwordx4 v[222:223], off
	v_lshl_add_u64 v[222:223], v[228:229], 0, s[28:29]
	s_mov_b32 m0, s71
	s_nop 0
	global_load_lds_dwordx4 v[222:223], off
	s_waitcnt vmcnt(8)
	s_waitcnt lgkmcnt(0)
	s_setprio 1
	s_barrier
	v_mfma_f32_16x16x32_bf16 v[60:63], v[128:131], v[180:183], v[60:63]
	v_mfma_f32_16x16x32_bf16 v[60:63], v[132:135], v[194:197], v[60:63]
	v_mfma_f32_16x16x32_bf16 v[56:59], v[140:143], v[194:197], v[56:59]
	v_mfma_f32_16x16x32_bf16 v[56:59], v[136:139], v[180:183], v[56:59]
	v_mfma_f32_16x16x32_bf16 v[40:43], v[136:139], v[198:201], v[40:43]
	v_mfma_f32_16x16x32_bf16 v[40:43], v[140:143], v[202:205], v[40:43]
	v_mfma_f32_16x16x32_bf16 v[44:47], v[132:135], v[202:205], v[44:47]
	v_mfma_f32_16x16x32_bf16 v[44:47], v[128:131], v[198:201], v[44:47]
	v_mfma_f32_16x16x32_bf16 v[28:31], v[128:131], v[206:209], v[28:31]
	v_mfma_f32_16x16x32_bf16 v[28:31], v[132:135], v[210:213], v[28:31]
	v_mfma_f32_16x16x32_bf16 v[24:27], v[140:143], v[210:213], v[24:27]
	v_mfma_f32_16x16x32_bf16 v[24:27], v[136:139], v[206:209], v[24:27]
	v_mfma_f32_16x16x32_bf16 v[8:11], v[136:139], v[214:217], v[8:11]
	v_mfma_f32_16x16x32_bf16 v[8:11], v[140:143], v[218:221], v[8:11]
	v_mfma_f32_16x16x32_bf16 v[12:15], v[132:135], v[218:221], v[12:15]
	v_mfma_f32_16x16x32_bf16 v[12:15], v[128:131], v[214:217], v[12:15]
	v_mfma_f32_16x16x32_bf16 v[52:55], v[144:147], v[180:183], v[52:55]
	v_mfma_f32_16x16x32_bf16 v[52:55], v[148:151], v[194:197], v[52:55]
	v_mfma_f32_16x16x32_bf16 v[48:51], v[176:179], v[194:197], v[48:51]
	v_mfma_f32_16x16x32_bf16 v[48:51], v[172:175], v[180:183], v[48:51]
	v_mfma_f32_16x16x32_bf16 v[32:35], v[172:175], v[198:201], v[32:35]
	v_mfma_f32_16x16x32_bf16 v[32:35], v[176:179], v[202:205], v[32:35]
	v_mfma_f32_16x16x32_bf16 v[36:39], v[148:151], v[202:205], v[36:39]
	v_mfma_f32_16x16x32_bf16 v[36:39], v[144:147], v[198:201], v[36:39]
	v_mfma_f32_16x16x32_bf16 v[20:23], v[144:147], v[206:209], v[20:23]
	v_mfma_f32_16x16x32_bf16 v[20:23], v[148:151], v[210:213], v[20:23]
	v_mfma_f32_16x16x32_bf16 v[16:19], v[176:179], v[210:213], v[16:19]
	v_mfma_f32_16x16x32_bf16 v[16:19], v[172:175], v[206:209], v[16:19]
	v_mfma_f32_16x16x32_bf16 v[0:3], v[172:175], v[214:217], v[0:3]
	v_mfma_f32_16x16x32_bf16 v[0:3], v[176:179], v[218:221], v[0:3]
	v_mfma_f32_16x16x32_bf16 v[4:7], v[148:151], v[218:221], v[4:7]
	v_mfma_f32_16x16x32_bf16 v[4:7], v[144:147], v[214:217], v[4:7]
	s_barrier
	s_setprio 0
	s_add_i32 s81, s81, 2
	s_add_u32 s79, s79, 0x100
	s_addc_u32 s80, s80, 0
	s_cmp_gt_u32 s81, 41
	s_mov_b64 s[54:55], s[56:57]
	s_branch .LBB0_610
.Lfa_5:
	ds_read_b128 v[128:131], v189
	v_xor_b32_e32 v253, 64, v189
	ds_read_b128 v[132:135], v253
	ds_read_b128 v[136:139], v189 offset:2048
	ds_read_b128 v[140:143], v253 offset:2048
	ds_read_b128 v[144:147], v190
	v_xor_b32_e32 v253, 64, v190
	ds_read_b128 v[148:151], v253
	ds_read_b128 v[172:175], v190 offset:2048
	ds_read_b128 v[176:179], v253 offset:2048
	s_add_u32 s56, s54, 0x100
	s_addc_u32 s57, s55, 0
	s_cmp_eq_u32 s81, 40
	s_cselect_b32 s61, s17, s57
	s_cselect_b32 s60, s16, s56
	s_cselect_b32 s59, s53, s80
	s_cselect_b32 s58, s52, s79
	v_lshl_add_u64 v[222:223], s[54:55], 0, v[166:167]
	s_add_i32 m0, s66, 0xc000
	ds_read_b128 v[180:183], v191
	v_xor_b32_e32 v253, 64, v191
	ds_read_b128 v[194:197], v253
	ds_read_b128 v[198:201], v191 offset:2048
	ds_read_b128 v[202:205], v253 offset:2048
	ds_read_b128 v[206:209], v191 offset:4096
	ds_read_b128 v[210:213], v253 offset:4096
	ds_read_b128 v[214:217], v191 offset:6144
	ds_read_b128 v[218:221], v253 offset:6144
	global_load_lds_dwordx4 v[222:223], off
	v_lshl_add_u64 v[222:223], s[54:55], 0, v[164:165]
	s_add_i32 m0, s66, 0xe000
	s_nop 0
	global_load_lds_dwordx4 v[222:223], off
	s_waitcnt vmcnt(8)
	s_waitcnt lgkmcnt(0)
	s_setprio 1
	s_barrier
	v_mfma_f32_16x16x32_bf16 v[124:127], v[128:131], v[180:183], 0
	v_mfma_f32_16x16x32_bf16 v[120:123], v[136:139], v[180:183], 0
	v_mfma_f32_16x16x32_bf16 v[108:111], v[128:131], v[198:201], 0
	v_mfma_f32_16x16x32_bf16 v[104:107], v[136:139], v[198:201], 0
	v_mfma_f32_16x16x32_bf16 v[92:95], v[128:131], v[206:209], 0
	v_mfma_f32_16x16x32_bf16 v[88:91], v[136:139], v[206:209], 0
	v_mfma_f32_16x16x32_bf16 v[76:79], v[128:131], v[214:217], 0
	v_mfma_f32_16x16x32_bf16 v[72:75], v[136:139], v[214:217], 0
	v_mfma_f32_16x16x32_bf16 v[124:127], v[132:135], v[194:197], v[124:127]
	v_mfma_f32_16x16x32_bf16 v[120:123], v[140:143], v[194:197], v[120:123]
	v_mfma_f32_16x16x32_bf16 v[108:111], v[132:135], v[202:205], v[108:111]
	v_mfma_f32_16x16x32_bf16 v[104:107], v[140:143], v[202:205], v[104:107]
	v_mfma_f32_16x16x32_bf16 v[92:95], v[132:135], v[210:213], v[92:95]
	v_mfma_f32_16x16x32_bf16 v[88:91], v[140:143], v[210:213], v[88:91]
	v_mfma_f32_16x16x32_bf16 v[76:79], v[132:135], v[218:221], v[76:79]
	v_mfma_f32_16x16x32_bf16 v[72:75], v[140:143], v[218:221], v[72:75]
	v_mfma_f32_16x16x32_bf16 v[116:119], v[144:147], v[180:183], 0
	v_mfma_f32_16x16x32_bf16 v[112:115], v[172:175], v[180:183], 0
	v_mfma_f32_16x16x32_bf16 v[100:103], v[144:147], v[198:201], 0
	v_mfma_f32_16x16x32_bf16 v[96:99], v[172:175], v[198:201], 0
	v_mfma_f32_16x16x32_bf16 v[84:87], v[144:147], v[206:209], 0
	v_mfma_f32_16x16x32_bf16 v[80:83], v[172:175], v[206:209], 0
	v_mfma_f32_16x16x32_bf16 v[68:71], v[144:147], v[214:217], 0
	v_mfma_f32_16x16x32_bf16 v[64:67], v[172:175], v[214:217], 0
	v_mfma_f32_16x16x32_bf16 v[116:119], v[148:151], v[194:197], v[116:119]
	v_mfma_f32_16x16x32_bf16 v[112:115], v[176:179], v[194:197], v[112:115]
	v_mfma_f32_16x16x32_bf16 v[100:103], v[148:151], v[202:205], v[100:103]
	v_mfma_f32_16x16x32_bf16 v[96:99], v[176:179], v[202:205], v[96:99]
	v_mfma_f32_16x16x32_bf16 v[84:87], v[148:151], v[210:213], v[84:87]
	v_mfma_f32_16x16x32_bf16 v[80:83], v[176:179], v[210:213], v[80:83]
	v_mfma_f32_16x16x32_bf16 v[68:71], v[148:151], v[218:221], v[68:71]
	v_mfma_f32_16x16x32_bf16 v[64:67], v[176:179], v[218:221], v[64:67]
	s_barrier
	s_setprio 0
	s_add_i32 s54, s75, s65
	v_lshl_add_u64 v[222:223], s[58:59], 0, v[154:155]
	s_mov_b32 m0, s54
	ds_read_b128 v[180:183], v191 offset:16384
	v_xor_b32_e32 v253, 64, v191
	ds_read_b128 v[194:197], v253 offset:16384
	ds_read_b128 v[198:201], v191 offset:18432
	ds_read_b128 v[202:205], v253 offset:18432
	ds_read_b128 v[206:209], v191 offset:20480
	ds_read_b128 v[210:213], v253 offset:20480
	ds_read_b128 v[214:217], v191 offset:22528
	ds_read_b128 v[218:221], v253 offset:22528
	global_load_lds_dwordx4 v[222:223], off
	s_add_i32 m0, s54, 0x2000
	s_add_u32 s54, s58, 0xb0000
	v_lshl_add_u64 v[224:225], s[58:59], 0, v[162:163]
	s_addc_u32 s55, s59, 0
	s_add_i32 s82, s76, s65
	global_load_lds_dwordx4 v[224:225], off
	v_lshl_add_u64 v[226:227], s[54:55], 0, v[154:155]
	s_mov_b32 m0, s82
	v_lshl_add_u64 v[228:229], s[60:61], 0, v[160:161]
	global_load_lds_dwordx4 v[226:227], off
	v_lshl_add_u64 v[226:227], s[54:55], 0, v[162:163]
	s_add_i32 m0, s82, 0x2000
	s_nop 0
	global_load_lds_dwordx4 v[226:227], off
	v_lshl_add_u64 v[226:227], s[60:61], 0, v[152:153]
	s_mov_b32 m0, s66
	s_nop 0
	global_load_lds_dwordx4 v[226:227], off
	s_mov_b32 m0, s67
	s_nop 0
	global_load_lds_dwordx4 v[228:229], off
	s_waitcnt vmcnt(8)
	s_waitcnt lgkmcnt(0)
	s_setprio 1
	s_barrier
	v_mfma_f32_16x16x32_bf16 v[60:63], v[128:131], v[180:183], 0
	v_mfma_f32_16x16x32_bf16 v[56:59], v[136:139], v[180:183], 0
	v_mfma_f32_16x16x32_bf16 v[44:47], v[128:131], v[198:201], 0
	v_mfma_f32_16x16x32_bf16 v[40:43], v[136:139], v[198:201], 0
	v_mfma_f32_16x16x32_bf16 v[28:31], v[128:131], v[206:209], 0
	v_mfma_f32_16x16x32_bf16 v[24:27], v[136:139], v[206:209], 0
	v_mfma_f32_16x16x32_bf16 v[12:15], v[128:131], v[214:217], 0
	v_mfma_f32_16x16x32_bf16 v[8:11], v[136:139], v[214:217], 0
	v_mfma_f32_16x16x32_bf16 v[60:63], v[132:135], v[194:197], v[60:63]
	v_mfma_f32_16x16x32_bf16 v[56:59], v[140:143], v[194:197], v[56:59]
	v_mfma_f32_16x16x32_bf16 v[44:47], v[132:135], v[202:205], v[44:47]
	v_mfma_f32_16x16x32_bf16 v[40:43], v[140:143], v[202:205], v[40:43]
	v_mfma_f32_16x16x32_bf16 v[28:31], v[132:135], v[210:213], v[28:31]
	v_mfma_f32_16x16x32_bf16 v[24:27], v[140:143], v[210:213], v[24:27]
	v_mfma_f32_16x16x32_bf16 v[12:15], v[132:135], v[218:221], v[12:15]
	v_mfma_f32_16x16x32_bf16 v[8:11], v[140:143], v[218:221], v[8:11]
	v_mfma_f32_16x16x32_bf16 v[52:55], v[144:147], v[180:183], 0
	v_mfma_f32_16x16x32_bf16 v[48:51], v[172:175], v[180:183], 0
	v_mfma_f32_16x16x32_bf16 v[36:39], v[144:147], v[198:201], 0
	v_mfma_f32_16x16x32_bf16 v[32:35], v[172:175], v[198:201], 0
	v_mfma_f32_16x16x32_bf16 v[20:23], v[144:147], v[206:209], 0
	v_mfma_f32_16x16x32_bf16 v[16:19], v[172:175], v[206:209], 0
	v_mfma_f32_16x16x32_bf16 v[4:7], v[144:147], v[214:217], 0
	v_mfma_f32_16x16x32_bf16 v[0:3], v[172:175], v[214:217], 0
	v_mfma_f32_16x16x32_bf16 v[52:55], v[148:151], v[194:197], v[52:55]
	v_mfma_f32_16x16x32_bf16 v[48:51], v[176:179], v[194:197], v[48:51]
	v_mfma_f32_16x16x32_bf16 v[36:39], v[148:151], v[202:205], v[36:39]
	v_mfma_f32_16x16x32_bf16 v[32:35], v[176:179], v[202:205], v[32:35]
	v_mfma_f32_16x16x32_bf16 v[20:23], v[148:151], v[210:213], v[20:23]
	v_mfma_f32_16x16x32_bf16 v[16:19], v[176:179], v[210:213], v[16:19]
	v_mfma_f32_16x16x32_bf16 v[4:7], v[148:151], v[218:221], v[4:7]
	v_mfma_f32_16x16x32_bf16 v[0:3], v[176:179], v[218:221], v[0:3]
	s_barrier
	s_setprio 0
	s_add_i32 s82, 0, 0x18000
	s_add_i32 s83, 0, 0x1c000
	v_add_u32_e32 v140, s82, v186
	v_add_u32_e32 v176, s83, v186
	ds_read_b128 v[128:131], v140
	v_xor_b32_e32 v253, 64, v140
	ds_read_b128 v[132:135], v253
	ds_read_b128 v[136:139], v140 offset:2048
	ds_read_b128 v[140:143], v253 offset:2048
	ds_read_b128 v[144:147], v176
	v_xor_b32_e32 v253, 64, v176
	ds_read_b128 v[148:151], v253
	ds_read_b128 v[172:175], v176 offset:2048
	ds_read_b128 v[176:179], v253 offset:2048
	s_add_u32 s54, s60, 0xb0000
	s_addc_u32 s55, s61, 0
	s_mov_b32 m0, s68
	v_lshl_add_u64 v[230:231], s[54:55], 0, v[152:153]
	ds_read_b128 v[180:183], v191 offset:32768
	v_xor_b32_e32 v253, 64, v191
	ds_read_b128 v[194:197], v253 offset:32768
	ds_read_b128 v[198:201], v191 offset:34816
	ds_read_b128 v[202:205], v253 offset:34816
	ds_read_b128 v[206:209], v191 offset:36864
	ds_read_b128 v[210:213], v253 offset:36864
	ds_read_b128 v[214:217], v191 offset:38912
	ds_read_b128 v[218:221], v253 offset:38912
	global_load_lds_dwordx4 v[230:231], off
	v_lshl_add_u64 v[230:231], s[54:55], 0, v[160:161]
	s_mov_b32 m0, s69
	s_nop 0
	global_load_lds_dwordx4 v[230:231], off
	s_waitcnt vmcnt(8)
	s_waitcnt lgkmcnt(0)
	s_setprio 1
	s_barrier
	v_mfma_f32_16x16x32_bf16 v[124:127], v[128:131], v[180:183], v[124:127]
	v_mfma_f32_16x16x32_bf16 v[124:127], v[132:135], v[194:197], v[124:127]
	v_mfma_f32_16x16x32_bf16 v[120:123], v[140:143], v[194:197], v[120:123]
	v_mfma_f32_16x16x32_bf16 v[120:123], v[136:139], v[180:183], v[120:123]
	v_mfma_f32_16x16x32_bf16 v[104:107], v[136:139], v[198:201], v[104:107]
	v_mfma_f32_16x16x32_bf16 v[104:107], v[140:143], v[202:205], v[104:107]
	v_mfma_f32_16x16x32_bf16 v[108:111], v[132:135], v[202:205], v[108:111]
	v_mfma_f32_16x16x32_bf16 v[108:111], v[128:131], v[198:201], v[108:111]
	v_mfma_f32_16x16x32_bf16 v[92:95], v[128:131], v[206:209], v[92:95]
	v_mfma_f32_16x16x32_bf16 v[92:95], v[132:135], v[210:213], v[92:95]
	v_mfma_f32_16x16x32_bf16 v[88:91], v[140:143], v[210:213], v[88:91]
	v_mfma_f32_16x16x32_bf16 v[88:91], v[136:139], v[206:209], v[88:91]
	v_mfma_f32_16x16x32_bf16 v[72:75], v[136:139], v[214:217], v[72:75]
	v_mfma_f32_16x16x32_bf16 v[72:75], v[140:143], v[218:221], v[72:75]
	v_mfma_f32_16x16x32_bf16 v[76:79], v[132:135], v[218:221], v[76:79]
	v_mfma_f32_16x16x32_bf16 v[76:79], v[128:131], v[214:217], v[76:79]
	v_mfma_f32_16x16x32_bf16 v[116:119], v[144:147], v[180:183], v[116:119]
	v_mfma_f32_16x16x32_bf16 v[116:119], v[148:151], v[194:197], v[116:119]
	v_mfma_f32_16x16x32_bf16 v[112:115], v[176:179], v[194:197], v[112:115]
	v_mfma_f32_16x16x32_bf16 v[112:115], v[172:175], v[180:183], v[112:115]
	v_mfma_f32_16x16x32_bf16 v[96:99], v[172:175], v[198:201], v[96:99]
	v_mfma_f32_16x16x32_bf16 v[96:99], v[176:179], v[202:205], v[96:99]
	v_mfma_f32_16x16x32_bf16 v[100:103], v[148:151], v[202:205], v[100:103]
	v_mfma_f32_16x16x32_bf16 v[100:103], v[144:147], v[198:201], v[100:103]
	v_mfma_f32_16x16x32_bf16 v[84:87], v[144:147], v[206:209], v[84:87]
	v_mfma_f32_16x16x32_bf16 v[84:87], v[148:151], v[210:213], v[84:87]
	v_mfma_f32_16x16x32_bf16 v[80:83], v[176:179], v[210:213], v[80:83]
	v_mfma_f32_16x16x32_bf16 v[80:83], v[172:175], v[206:209], v[80:83]
	v_mfma_f32_16x16x32_bf16 v[64:67], v[172:175], v[214:217], v[64:67]
	v_mfma_f32_16x16x32_bf16 v[64:67], v[176:179], v[218:221], v[64:67]
	v_mfma_f32_16x16x32_bf16 v[68:71], v[148:151], v[218:221], v[68:71]
	v_mfma_f32_16x16x32_bf16 v[68:71], v[144:147], v[214:217], v[68:71]
	s_barrier
	s_setprio 0
	s_add_i32 s54, s82, s65
	v_lshl_add_u64 v[222:223], v[222:223], 0, s[28:29]
	s_mov_b32 m0, s54
	ds_read_b128 v[180:183], v191 offset:49152
	v_xor_b32_e32 v253, 64, v191
	ds_read_b128 v[194:197], v253 offset:49152
	ds_read_b128 v[198:201], v191 offset:51200
	ds_read_b128 v[202:205], v253 offset:51200
	ds_read_b128 v[206:209], v191 offset:53248
	ds_read_b128 v[210:213], v253 offset:53248
	ds_read_b128 v[214:217], v191 offset:55296
	ds_read_b128 v[218:221], v253 offset:55296
	global_load_lds_dwordx4 v[222:223], off
	s_add_i32 m0, s54, 0x2000
	s_add_u32 s54, s58, 0xb0080
	v_lshl_add_u64 v[222:223], v[224:225], 0, s[28:29]
	s_addc_u32 s55, s59, 0
	s_add_i32 s58, s83, s65
	global_load_lds_dwordx4 v[222:223], off
	v_lshl_add_u64 v[222:223], s[54:55], 0, v[154:155]
	s_mov_b32 m0, s58
	s_nop 0
	global_load_lds_dwordx4 v[222:223], off
	v_lshl_add_u64 v[222:223], s[54:55], 0, v[162:163]
	s_add_i32 m0, s58, 0x2000
	s_nop 0
	global_load_lds_dwordx4 v[222:223], off
	v_lshl_add_u64 v[222:223], v[226:227], 0, s[28:29]
	s_mov_b32 m0, s3
	s_nop 0
	global_load_lds_dwordx4 v[222:223], off
	v_lshl_add_u64 v[222:223], v[228:229], 0, s[28:29]
	s_mov_b32 m0, s71
	s_nop 0
	global_load_lds_dwordx4 v[222:223], off
	s_waitcnt vmcnt(8)
	s_waitcnt lgkmcnt(0)
	s_setprio 1
	s_barrier
	v_mfma_f32_16x16x32_bf16 v[60:63], v[128:131], v[180:183], v[60:63]
	v_mfma_f32_16x16x32_bf16 v[60:63], v[132:135], v[194:197], v[60:63]
	v_mfma_f32_16x16x32_bf16 v[56:59], v[140:143], v[194:197], v[56:59]
	v_mfma_f32_16x16x32_bf16 v[56:59], v[136:139], v[180:183], v[56:59]
	v_mfma_f32_16x16x32_bf16 v[40:43], v[136:139], v[198:201], v[40:43]
	v_mfma_f32_16x16x32_bf16 v[40:43], v[140:143], v[202:205], v[40:43]
	v_mfma_f32_16x16x32_bf16 v[44:47], v[132:135], v[202:205], v[44:47]
	v_mfma_f32_16x16x32_bf16 v[44:47], v[128:131], v[198:201], v[44:47]
	v_mfma_f32_16x16x32_bf16 v[28:31], v[128:131], v[206:209], v[28:31]
	v_mfma_f32_16x16x32_bf16 v[28:31], v[132:135], v[210:213], v[28:31]
	v_mfma_f32_16x16x32_bf16 v[24:27], v[140:143], v[210:213], v[24:27]
	v_mfma_f32_16x16x32_bf16 v[24:27], v[136:139], v[206:209], v[24:27]
	v_mfma_f32_16x16x32_bf16 v[8:11], v[136:139], v[214:217], v[8:11]
	v_mfma_f32_16x16x32_bf16 v[8:11], v[140:143], v[218:221], v[8:11]
	v_mfma_f32_16x16x32_bf16 v[12:15], v[132:135], v[218:221], v[12:15]
	v_mfma_f32_16x16x32_bf16 v[12:15], v[128:131], v[214:217], v[12:15]
	v_mfma_f32_16x16x32_bf16 v[52:55], v[144:147], v[180:183], v[52:55]
	v_mfma_f32_16x16x32_bf16 v[52:55], v[148:151], v[194:197], v[52:55]
	v_mfma_f32_16x16x32_bf16 v[48:51], v[176:179], v[194:197], v[48:51]
	v_mfma_f32_16x16x32_bf16 v[48:51], v[172:175], v[180:183], v[48:51]
	v_mfma_f32_16x16x32_bf16 v[32:35], v[172:175], v[198:201], v[32:35]
	v_mfma_f32_16x16x32_bf16 v[32:35], v[176:179], v[202:205], v[32:35]
	v_mfma_f32_16x16x32_bf16 v[36:39], v[148:151], v[202:205], v[36:39]
	v_mfma_f32_16x16x32_bf16 v[36:39], v[144:147], v[198:201], v[36:39]
	v_mfma_f32_16x16x32_bf16 v[20:23], v[144:147], v[206:209], v[20:23]
	v_mfma_f32_16x16x32_bf16 v[20:23], v[148:151], v[210:213], v[20:23]
	v_mfma_f32_16x16x32_bf16 v[16:19], v[176:179], v[210:213], v[16:19]
	v_mfma_f32_16x16x32_bf16 v[16:19], v[172:175], v[206:209], v[16:19]
	v_mfma_f32_16x16x32_bf16 v[0:3], v[172:175], v[214:217], v[0:3]
	v_mfma_f32_16x16x32_bf16 v[0:3], v[176:179], v[218:221], v[0:3]
	v_mfma_f32_16x16x32_bf16 v[4:7], v[148:151], v[218:221], v[4:7]
	v_mfma_f32_16x16x32_bf16 v[4:7], v[144:147], v[214:217], v[4:7]
	s_barrier
	s_setprio 0
	s_add_i32 s81, s81, 2
	s_add_u32 s79, s79, 0x100
	s_addc_u32 s80, s80, 0
	s_cmp_gt_u32 s81, 41
	s_mov_b64 s[54:55], s[56:57]
.LBB0_610:
	ds_read_b128 v[128:131], v189
	v_xor_b32_e32 v253, 64, v189
	ds_read_b128 v[132:135], v253
	ds_read_b128 v[136:139], v189 offset:2048
	ds_read_b128 v[140:143], v253 offset:2048
	ds_read_b128 v[144:147], v190
	v_xor_b32_e32 v253, 64, v190
	ds_read_b128 v[148:151], v253
	ds_read_b128 v[172:175], v190 offset:2048
	ds_read_b128 v[176:179], v253 offset:2048
	s_add_u32 s56, s54, 0x100
	s_addc_u32 s57, s55, 0
	s_cmp_eq_u32 s81, 40
	s_cselect_b32 s61, s17, s57
	s_cselect_b32 s60, s16, s56
	s_cselect_b32 s59, s53, s80
	s_cselect_b32 s58, s52, s79
	v_lshl_add_u64 v[222:223], s[54:55], 0, v[166:167]
	s_add_i32 m0, s66, 0xc000
	ds_read_b128 v[180:183], v191
	v_xor_b32_e32 v253, 64, v191
	ds_read_b128 v[194:197], v253
	ds_read_b128 v[198:201], v191 offset:2048
	ds_read_b128 v[202:205], v253 offset:2048
	ds_read_b128 v[206:209], v191 offset:4096
	ds_read_b128 v[210:213], v253 offset:4096
	ds_read_b128 v[214:217], v191 offset:6144
	ds_read_b128 v[218:221], v253 offset:6144
	global_load_lds_dwordx4 v[222:223], off
	v_lshl_add_u64 v[222:223], s[54:55], 0, v[164:165]
	s_add_i32 m0, s66, 0xe000
	s_nop 0
	global_load_lds_dwordx4 v[222:223], off
	s_waitcnt vmcnt(8)
	s_waitcnt lgkmcnt(0)
	s_setprio 1
	s_barrier
	v_mfma_f32_16x16x32_bf16 v[124:127], v[128:131], v[180:183], v[124:127]
	v_mfma_f32_16x16x32_bf16 v[124:127], v[132:135], v[194:197], v[124:127]
	v_mfma_f32_16x16x32_bf16 v[120:123], v[140:143], v[194:197], v[120:123]
	v_mfma_f32_16x16x32_bf16 v[120:123], v[136:139], v[180:183], v[120:123]
	v_mfma_f32_16x16x32_bf16 v[104:107], v[136:139], v[198:201], v[104:107]
	v_mfma_f32_16x16x32_bf16 v[104:107], v[140:143], v[202:205], v[104:107]
	v_mfma_f32_16x16x32_bf16 v[108:111], v[132:135], v[202:205], v[108:111]
	v_mfma_f32_16x16x32_bf16 v[108:111], v[128:131], v[198:201], v[108:111]
	v_mfma_f32_16x16x32_bf16 v[92:95], v[128:131], v[206:209], v[92:95]
	v_mfma_f32_16x16x32_bf16 v[92:95], v[132:135], v[210:213], v[92:95]
	v_mfma_f32_16x16x32_bf16 v[88:91], v[140:143], v[210:213], v[88:91]
	v_mfma_f32_16x16x32_bf16 v[88:91], v[136:139], v[206:209], v[88:91]
	v_mfma_f32_16x16x32_bf16 v[72:75], v[136:139], v[214:217], v[72:75]
	v_mfma_f32_16x16x32_bf16 v[72:75], v[140:143], v[218:221], v[72:75]
	v_mfma_f32_16x16x32_bf16 v[76:79], v[132:135], v[218:221], v[76:79]
	v_mfma_f32_16x16x32_bf16 v[76:79], v[128:131], v[214:217], v[76:79]
	v_mfma_f32_16x16x32_bf16 v[116:119], v[144:147], v[180:183], v[116:119]
	v_mfma_f32_16x16x32_bf16 v[116:119], v[148:151], v[194:197], v[116:119]
	v_mfma_f32_16x16x32_bf16 v[112:115], v[176:179], v[194:197], v[112:115]
	v_mfma_f32_16x16x32_bf16 v[112:115], v[172:175], v[180:183], v[112:115]
	v_mfma_f32_16x16x32_bf16 v[96:99], v[172:175], v[198:201], v[96:99]
	v_mfma_f32_16x16x32_bf16 v[96:99], v[176:179], v[202:205], v[96:99]
	v_mfma_f32_16x16x32_bf16 v[100:103], v[148:151], v[202:205], v[100:103]
	v_mfma_f32_16x16x32_bf16 v[100:103], v[144:147], v[198:201], v[100:103]
	v_mfma_f32_16x16x32_bf16 v[84:87], v[144:147], v[206:209], v[84:87]
	v_mfma_f32_16x16x32_bf16 v[84:87], v[148:151], v[210:213], v[84:87]
	v_mfma_f32_16x16x32_bf16 v[80:83], v[176:179], v[210:213], v[80:83]
	v_mfma_f32_16x16x32_bf16 v[80:83], v[172:175], v[206:209], v[80:83]
	v_mfma_f32_16x16x32_bf16 v[64:67], v[172:175], v[214:217], v[64:67]
	v_mfma_f32_16x16x32_bf16 v[64:67], v[176:179], v[218:221], v[64:67]
	v_mfma_f32_16x16x32_bf16 v[68:71], v[148:151], v[218:221], v[68:71]
	v_mfma_f32_16x16x32_bf16 v[68:71], v[144:147], v[214:217], v[68:71]
	s_barrier
	s_setprio 0
	s_add_i32 s54, s75, s65
	v_lshl_add_u64 v[222:223], s[58:59], 0, v[154:155]
	s_mov_b32 m0, s54
	ds_read_b128 v[180:183], v191 offset:16384
	v_xor_b32_e32 v253, 64, v191
	ds_read_b128 v[194:197], v253 offset:16384
	ds_read_b128 v[198:201], v191 offset:18432
	ds_read_b128 v[202:205], v253 offset:18432
	ds_read_b128 v[206:209], v191 offset:20480
	ds_read_b128 v[210:213], v253 offset:20480
	ds_read_b128 v[214:217], v191 offset:22528
	ds_read_b128 v[218:221], v253 offset:22528
	global_load_lds_dwordx4 v[222:223], off
	s_add_i32 m0, s54, 0x2000
	s_add_u32 s54, s58, 0xb0000
	v_lshl_add_u64 v[224:225], s[58:59], 0, v[162:163]
	s_addc_u32 s55, s59, 0
	s_add_i32 s82, s76, s65
	global_load_lds_dwordx4 v[224:225], off
	v_lshl_add_u64 v[226:227], s[54:55], 0, v[154:155]
	s_mov_b32 m0, s82
	v_lshl_add_u64 v[228:229], s[60:61], 0, v[160:161]
	global_load_lds_dwordx4 v[226:227], off
	v_lshl_add_u64 v[226:227], s[54:55], 0, v[162:163]
	s_add_i32 m0, s82, 0x2000
	s_nop 0
	global_load_lds_dwordx4 v[226:227], off
	v_lshl_add_u64 v[226:227], s[60:61], 0, v[152:153]
	s_mov_b32 m0, s66
	s_nop 0
	global_load_lds_dwordx4 v[226:227], off
	s_mov_b32 m0, s67
	s_nop 0
	global_load_lds_dwordx4 v[228:229], off
	s_waitcnt vmcnt(8)
	s_waitcnt lgkmcnt(0)
	s_setprio 1
	s_barrier
	v_mfma_f32_16x16x32_bf16 v[60:63], v[128:131], v[180:183], v[60:63]
	v_mfma_f32_16x16x32_bf16 v[60:63], v[132:135], v[194:197], v[60:63]
	v_mfma_f32_16x16x32_bf16 v[56:59], v[140:143], v[194:197], v[56:59]
	v_mfma_f32_16x16x32_bf16 v[56:59], v[136:139], v[180:183], v[56:59]
	v_mfma_f32_16x16x32_bf16 v[40:43], v[136:139], v[198:201], v[40:43]
	v_mfma_f32_16x16x32_bf16 v[40:43], v[140:143], v[202:205], v[40:43]
	v_mfma_f32_16x16x32_bf16 v[44:47], v[132:135], v[202:205], v[44:47]
	v_mfma_f32_16x16x32_bf16 v[44:47], v[128:131], v[198:201], v[44:47]
	v_mfma_f32_16x16x32_bf16 v[28:31], v[128:131], v[206:209], v[28:31]
	v_mfma_f32_16x16x32_bf16 v[28:31], v[132:135], v[210:213], v[28:31]
	v_mfma_f32_16x16x32_bf16 v[24:27], v[140:143], v[210:213], v[24:27]
	v_mfma_f32_16x16x32_bf16 v[24:27], v[136:139], v[206:209], v[24:27]
	v_mfma_f32_16x16x32_bf16 v[8:11], v[136:139], v[214:217], v[8:11]
	v_mfma_f32_16x16x32_bf16 v[8:11], v[140:143], v[218:221], v[8:11]
	v_mfma_f32_16x16x32_bf16 v[12:15], v[132:135], v[218:221], v[12:15]
	v_mfma_f32_16x16x32_bf16 v[12:15], v[128:131], v[214:217], v[12:15]
	v_mfma_f32_16x16x32_bf16 v[52:55], v[144:147], v[180:183], v[52:55]
	v_mfma_f32_16x16x32_bf16 v[52:55], v[148:151], v[194:197], v[52:55]
	v_mfma_f32_16x16x32_bf16 v[48:51], v[176:179], v[194:197], v[48:51]
	v_mfma_f32_16x16x32_bf16 v[48:51], v[172:175], v[180:183], v[48:51]
	v_mfma_f32_16x16x32_bf16 v[32:35], v[172:175], v[198:201], v[32:35]
	v_mfma_f32_16x16x32_bf16 v[32:35], v[176:179], v[202:205], v[32:35]
	v_mfma_f32_16x16x32_bf16 v[36:39], v[148:151], v[202:205], v[36:39]
	v_mfma_f32_16x16x32_bf16 v[36:39], v[144:147], v[198:201], v[36:39]
	v_mfma_f32_16x16x32_bf16 v[20:23], v[144:147], v[206:209], v[20:23]
	v_mfma_f32_16x16x32_bf16 v[20:23], v[148:151], v[210:213], v[20:23]
	v_mfma_f32_16x16x32_bf16 v[16:19], v[176:179], v[210:213], v[16:19]
	v_mfma_f32_16x16x32_bf16 v[16:19], v[172:175], v[206:209], v[16:19]
	v_mfma_f32_16x16x32_bf16 v[0:3], v[172:175], v[214:217], v[0:3]
	v_mfma_f32_16x16x32_bf16 v[0:3], v[176:179], v[218:221], v[0:3]
	v_mfma_f32_16x16x32_bf16 v[4:7], v[148:151], v[218:221], v[4:7]
	v_mfma_f32_16x16x32_bf16 v[4:7], v[144:147], v[214:217], v[4:7]
	s_barrier
	s_setprio 0
	s_add_i32 s82, 0, 0x18000
	s_add_i32 s83, 0, 0x1c000
	v_add_u32_e32 v140, s82, v186
	v_add_u32_e32 v176, s83, v186
	ds_read_b128 v[128:131], v140
	v_xor_b32_e32 v253, 64, v140
	ds_read_b128 v[132:135], v253
	ds_read_b128 v[136:139], v140 offset:2048
	ds_read_b128 v[140:143], v253 offset:2048
	ds_read_b128 v[144:147], v176
	v_xor_b32_e32 v253, 64, v176
	ds_read_b128 v[148:151], v253
	ds_read_b128 v[172:175], v176 offset:2048
	ds_read_b128 v[176:179], v253 offset:2048
	s_add_u32 s54, s60, 0xb0000
	s_addc_u32 s55, s61, 0
	s_mov_b32 m0, s68
	v_lshl_add_u64 v[230:231], s[54:55], 0, v[152:153]
	ds_read_b128 v[180:183], v191 offset:32768
	v_xor_b32_e32 v253, 64, v191
	ds_read_b128 v[194:197], v253 offset:32768
	ds_read_b128 v[198:201], v191 offset:34816
	ds_read_b128 v[202:205], v253 offset:34816
	ds_read_b128 v[206:209], v191 offset:36864
	ds_read_b128 v[210:213], v253 offset:36864
	ds_read_b128 v[214:217], v191 offset:38912
	ds_read_b128 v[218:221], v253 offset:38912
	global_load_lds_dwordx4 v[230:231], off
	v_lshl_add_u64 v[230:231], s[54:55], 0, v[160:161]
	s_mov_b32 m0, s69
	s_nop 0
	global_load_lds_dwordx4 v[230:231], off
	s_waitcnt vmcnt(8)
	s_waitcnt lgkmcnt(0)
	s_setprio 1
	s_barrier
	v_mfma_f32_16x16x32_bf16 v[124:127], v[128:131], v[180:183], v[124:127]
	v_mfma_f32_16x16x32_bf16 v[124:127], v[132:135], v[194:197], v[124:127]
	v_mfma_f32_16x16x32_bf16 v[120:123], v[140:143], v[194:197], v[120:123]
	v_mfma_f32_16x16x32_bf16 v[120:123], v[136:139], v[180:183], v[120:123]
	v_mfma_f32_16x16x32_bf16 v[104:107], v[136:139], v[198:201], v[104:107]
	v_mfma_f32_16x16x32_bf16 v[104:107], v[140:143], v[202:205], v[104:107]
	v_mfma_f32_16x16x32_bf16 v[108:111], v[132:135], v[202:205], v[108:111]
	v_mfma_f32_16x16x32_bf16 v[108:111], v[128:131], v[198:201], v[108:111]
	v_mfma_f32_16x16x32_bf16 v[92:95], v[128:131], v[206:209], v[92:95]
	v_mfma_f32_16x16x32_bf16 v[92:95], v[132:135], v[210:213], v[92:95]
	v_mfma_f32_16x16x32_bf16 v[88:91], v[140:143], v[210:213], v[88:91]
	v_mfma_f32_16x16x32_bf16 v[88:91], v[136:139], v[206:209], v[88:91]
	v_mfma_f32_16x16x32_bf16 v[72:75], v[136:139], v[214:217], v[72:75]
	v_mfma_f32_16x16x32_bf16 v[72:75], v[140:143], v[218:221], v[72:75]
	v_mfma_f32_16x16x32_bf16 v[76:79], v[132:135], v[218:221], v[76:79]
	v_mfma_f32_16x16x32_bf16 v[76:79], v[128:131], v[214:217], v[76:79]
	v_mfma_f32_16x16x32_bf16 v[116:119], v[144:147], v[180:183], v[116:119]
	v_mfma_f32_16x16x32_bf16 v[116:119], v[148:151], v[194:197], v[116:119]
	v_mfma_f32_16x16x32_bf16 v[112:115], v[176:179], v[194:197], v[112:115]
	v_mfma_f32_16x16x32_bf16 v[112:115], v[172:175], v[180:183], v[112:115]
	v_mfma_f32_16x16x32_bf16 v[96:99], v[172:175], v[198:201], v[96:99]
	v_mfma_f32_16x16x32_bf16 v[96:99], v[176:179], v[202:205], v[96:99]
	v_mfma_f32_16x16x32_bf16 v[100:103], v[148:151], v[202:205], v[100:103]
	v_mfma_f32_16x16x32_bf16 v[100:103], v[144:147], v[198:201], v[100:103]
	v_mfma_f32_16x16x32_bf16 v[84:87], v[144:147], v[206:209], v[84:87]
	v_mfma_f32_16x16x32_bf16 v[84:87], v[148:151], v[210:213], v[84:87]
	v_mfma_f32_16x16x32_bf16 v[80:83], v[176:179], v[210:213], v[80:83]
	v_mfma_f32_16x16x32_bf16 v[80:83], v[172:175], v[206:209], v[80:83]
	v_mfma_f32_16x16x32_bf16 v[64:67], v[172:175], v[214:217], v[64:67]
	v_mfma_f32_16x16x32_bf16 v[64:67], v[176:179], v[218:221], v[64:67]
	v_mfma_f32_16x16x32_bf16 v[68:71], v[148:151], v[218:221], v[68:71]
	v_mfma_f32_16x16x32_bf16 v[68:71], v[144:147], v[214:217], v[68:71]
	s_barrier
	s_setprio 0
	s_add_i32 s54, s82, s65
	v_lshl_add_u64 v[222:223], v[222:223], 0, s[28:29]
	s_mov_b32 m0, s54
	ds_read_b128 v[180:183], v191 offset:49152
	v_xor_b32_e32 v253, 64, v191
	ds_read_b128 v[194:197], v253 offset:49152
	ds_read_b128 v[198:201], v191 offset:51200
	ds_read_b128 v[202:205], v253 offset:51200
	ds_read_b128 v[206:209], v191 offset:53248
	ds_read_b128 v[210:213], v253 offset:53248
	ds_read_b128 v[214:217], v191 offset:55296
	ds_read_b128 v[218:221], v253 offset:55296
	global_load_lds_dwordx4 v[222:223], off
	s_add_i32 m0, s54, 0x2000
	s_add_u32 s54, s58, 0xb0080
	v_lshl_add_u64 v[222:223], v[224:225], 0, s[28:29]
	s_addc_u32 s55, s59, 0
	s_add_i32 s58, s83, s65
	global_load_lds_dwordx4 v[222:223], off
	v_lshl_add_u64 v[222:223], s[54:55], 0, v[154:155]
	s_mov_b32 m0, s58
	s_nop 0
	global_load_lds_dwordx4 v[222:223], off
	v_lshl_add_u64 v[222:223], s[54:55], 0, v[162:163]
	s_add_i32 m0, s58, 0x2000
	s_nop 0
	global_load_lds_dwordx4 v[222:223], off
	v_lshl_add_u64 v[222:223], v[226:227], 0, s[28:29]
	s_mov_b32 m0, s3
	s_nop 0
	global_load_lds_dwordx4 v[222:223], off
	v_lshl_add_u64 v[222:223], v[228:229], 0, s[28:29]
	s_mov_b32 m0, s71
	s_nop 0
	global_load_lds_dwordx4 v[222:223], off
	s_waitcnt vmcnt(8)
	s_waitcnt lgkmcnt(0)
	s_setprio 1
	s_barrier
	v_mfma_f32_16x16x32_bf16 v[60:63], v[128:131], v[180:183], v[60:63]
	v_mfma_f32_16x16x32_bf16 v[60:63], v[132:135], v[194:197], v[60:63]
	v_mfma_f32_16x16x32_bf16 v[56:59], v[140:143], v[194:197], v[56:59]
	v_mfma_f32_16x16x32_bf16 v[56:59], v[136:139], v[180:183], v[56:59]
	v_mfma_f32_16x16x32_bf16 v[40:43], v[136:139], v[198:201], v[40:43]
	v_mfma_f32_16x16x32_bf16 v[40:43], v[140:143], v[202:205], v[40:43]
	v_mfma_f32_16x16x32_bf16 v[44:47], v[132:135], v[202:205], v[44:47]
	v_mfma_f32_16x16x32_bf16 v[44:47], v[128:131], v[198:201], v[44:47]
	v_mfma_f32_16x16x32_bf16 v[28:31], v[128:131], v[206:209], v[28:31]
	v_mfma_f32_16x16x32_bf16 v[28:31], v[132:135], v[210:213], v[28:31]
	v_mfma_f32_16x16x32_bf16 v[24:27], v[140:143], v[210:213], v[24:27]
	v_mfma_f32_16x16x32_bf16 v[24:27], v[136:139], v[206:209], v[24:27]
	v_mfma_f32_16x16x32_bf16 v[8:11], v[136:139], v[214:217], v[8:11]
	v_mfma_f32_16x16x32_bf16 v[8:11], v[140:143], v[218:221], v[8:11]
	v_mfma_f32_16x16x32_bf16 v[12:15], v[132:135], v[218:221], v[12:15]
	v_mfma_f32_16x16x32_bf16 v[12:15], v[128:131], v[214:217], v[12:15]
	v_mfma_f32_16x16x32_bf16 v[52:55], v[144:147], v[180:183], v[52:55]
	v_mfma_f32_16x16x32_bf16 v[52:55], v[148:151], v[194:197], v[52:55]
	v_mfma_f32_16x16x32_bf16 v[48:51], v[176:179], v[194:197], v[48:51]
	v_mfma_f32_16x16x32_bf16 v[48:51], v[172:175], v[180:183], v[48:51]
	v_mfma_f32_16x16x32_bf16 v[32:35], v[172:175], v[198:201], v[32:35]
	v_mfma_f32_16x16x32_bf16 v[32:35], v[176:179], v[202:205], v[32:35]
	v_mfma_f32_16x16x32_bf16 v[36:39], v[148:151], v[202:205], v[36:39]
	v_mfma_f32_16x16x32_bf16 v[36:39], v[144:147], v[198:201], v[36:39]
	v_mfma_f32_16x16x32_bf16 v[20:23], v[144:147], v[206:209], v[20:23]
	v_mfma_f32_16x16x32_bf16 v[20:23], v[148:151], v[210:213], v[20:23]
	v_mfma_f32_16x16x32_bf16 v[16:19], v[176:179], v[210:213], v[16:19]
	v_mfma_f32_16x16x32_bf16 v[16:19], v[172:175], v[206:209], v[16:19]
	v_mfma_f32_16x16x32_bf16 v[0:3], v[172:175], v[214:217], v[0:3]
	v_mfma_f32_16x16x32_bf16 v[0:3], v[176:179], v[218:221], v[0:3]
	v_mfma_f32_16x16x32_bf16 v[4:7], v[148:151], v[218:221], v[4:7]
	v_mfma_f32_16x16x32_bf16 v[4:7], v[144:147], v[214:217], v[4:7]
	s_barrier
	s_setprio 0
	s_add_i32 s81, s81, 2
	s_add_u32 s79, s79, 0x100
	s_addc_u32 s80, s80, 0
	s_cmp_gt_u32 s81, 41
	s_mov_b64 s[54:55], s[56:57]
	s_cbranch_scc0 .LBB0_610
	s_and_b64 vcc, exec, s[30:31]
	s_cbranch_vccz .LBB0_613
	s_barrier

.LBB0_873:
	s_ashr_i32 s49, s48, 31
	s_lshl_b64 s[50:51], s[48:49], 19
	s_add_u32 s50, s35, s50
	s_addc_u32 s51, s60, s51
	s_and_b64 s[52:53], s[10:11], exec
	s_cselect_b32 s49, s51, s59
	s_cselect_b32 s80, s50, s58
	s_ashr_i32 s47, s46, 31
	s_lshl_b64 s[52:53], s[46:47], 19
	s_add_u32 s52, s61, s52
	s_addc_u32 s53, s62, s53
	s_and_b64 s[82:83], s[10:11], exec
	s_cselect_b32 s81, s53, s57
	s_cselect_b32 s82, s52, s56
	s_lshl_b32 s47, s54, 8
	v_add_u32_e32 v0, s47, v151
	s_add_u32 s83, s56, 0x100
	v_ashrrev_i32_e32 v1, 31, v0
	s_addc_u32 s84, s57, 0
	v_lshl_add_u64 v[144:145], v[0:1], 4, s[20:21]
	s_add_u32 s54, s58, 0x40080
	s_addc_u32 s55, s59, 0
	s_mov_b32 s85, -2
	s_mov_b64 s[56:57], 0
	s_cmp_eq_u32 s68, 1
	s_cbranch_scc1 .Lfa_8
	v_add_u32_e32 v146, s73, v149
	ds_read_b128 v[162:165], v146
	v_xor_b32_e32 v253, 64, v146
	ds_read_b128 v[166:169], v253
	ds_read_b128 v[170:173], v146 offset:2048
	ds_read_b128 v[174:177], v253 offset:2048
	v_add_u32_e32 v146, s74, v149
	ds_read_b128 v[178:181], v146
	v_xor_b32_e32 v253, 64, v146
	ds_read_b128 v[186:189], v253
	ds_read_b128 v[190:193], v146 offset:2048
	ds_read_b128 v[194:197], v253 offset:2048
	s_add_u32 s58, s54, 0xfffc0080
	s_addc_u32 s59, s55, -1
	s_and_b64 s[56:57], s[56:57], exec
	s_cselect_b32 s59, s49, s59
	s_cselect_b32 s58, s80, s58
	s_cselect_b32 s57, s81, s84
	s_cselect_b32 s56, s82, s83
	v_lshl_add_u64 v[182:183], s[54:55], 0, v[138:139]
	s_add_i32 m0, s64, 0xc000
	ds_read_b128 v[198:201], v154
	v_xor_b32_e32 v253, 64, v154
	ds_read_b128 v[202:205], v253
	ds_read_b128 v[206:209], v154 offset:2048
	ds_read_b128 v[210:213], v253 offset:2048
	ds_read_b128 v[214:217], v154 offset:4096
	ds_read_b128 v[218:221], v253 offset:4096
	ds_read_b128 v[222:225], v154 offset:6144
	ds_read_b128 v[226:229], v253 offset:6144
	global_load_lds_dwordx4 v[182:183], off
	v_lshl_add_u64 v[182:183], s[54:55], 0, v[136:137]
	s_add_i32 m0, s64, 0xe000
	s_nop 0
	global_load_lds_dwordx4 v[182:183], off
	s_waitcnt vmcnt(24)
	s_waitcnt lgkmcnt(0)
	s_setprio 1
	s_barrier
	v_mfma_f32_16x16x32_bf16 v[124:127], v[162:165], v[198:201], 0
	v_mfma_f32_16x16x32_bf16 v[120:123], v[170:173], v[198:201], 0
	v_mfma_f32_16x16x32_bf16 v[112:115], v[162:165], v[206:209], 0
	v_mfma_f32_16x16x32_bf16 v[104:107], v[170:173], v[206:209], 0
	v_mfma_f32_16x16x32_bf16 v[96:99], v[162:165], v[214:217], 0
	v_mfma_f32_16x16x32_bf16 v[88:91], v[170:173], v[214:217], 0
	v_mfma_f32_16x16x32_bf16 v[80:83], v[162:165], v[222:225], 0
	v_mfma_f32_16x16x32_bf16 v[72:75], v[170:173], v[222:225], 0
	v_mfma_f32_16x16x32_bf16 v[124:127], v[166:169], v[202:205], v[124:127]
	v_mfma_f32_16x16x32_bf16 v[120:123], v[174:177], v[202:205], v[120:123]
	v_mfma_f32_16x16x32_bf16 v[112:115], v[166:169], v[210:213], v[112:115]
	v_mfma_f32_16x16x32_bf16 v[104:107], v[174:177], v[210:213], v[104:107]
	v_mfma_f32_16x16x32_bf16 v[96:99], v[166:169], v[218:221], v[96:99]
	v_mfma_f32_16x16x32_bf16 v[88:91], v[174:177], v[218:221], v[88:91]
	v_mfma_f32_16x16x32_bf16 v[80:83], v[166:169], v[226:229], v[80:83]
	v_mfma_f32_16x16x32_bf16 v[72:75], v[174:177], v[226:229], v[72:75]
	v_mfma_f32_16x16x32_bf16 v[116:119], v[178:181], v[198:201], 0
	v_mfma_f32_16x16x32_bf16 v[108:111], v[190:193], v[198:201], 0
	v_mfma_f32_16x16x32_bf16 v[100:103], v[178:181], v[206:209], 0
	v_mfma_f32_16x16x32_bf16 v[92:95], v[190:193], v[206:209], 0
	v_mfma_f32_16x16x32_bf16 v[84:87], v[178:181], v[214:217], 0
	v_mfma_f32_16x16x32_bf16 v[76:79], v[190:193], v[214:217], 0
	v_mfma_f32_16x16x32_bf16 v[68:71], v[178:181], v[222:225], 0
	v_mfma_f32_16x16x32_bf16 v[64:67], v[190:193], v[222:225], 0
	v_mfma_f32_16x16x32_bf16 v[116:119], v[186:189], v[202:205], v[116:119]
	v_mfma_f32_16x16x32_bf16 v[108:111], v[194:197], v[202:205], v[108:111]
	v_mfma_f32_16x16x32_bf16 v[100:103], v[186:189], v[210:213], v[100:103]
	v_mfma_f32_16x16x32_bf16 v[92:95], v[194:197], v[210:213], v[92:95]
	v_mfma_f32_16x16x32_bf16 v[84:87], v[186:189], v[218:221], v[84:87]
	v_mfma_f32_16x16x32_bf16 v[76:79], v[194:197], v[218:221], v[76:79]
	v_mfma_f32_16x16x32_bf16 v[68:71], v[186:189], v[226:229], v[68:71]
	v_mfma_f32_16x16x32_bf16 v[64:67], v[194:197], v[226:229], v[64:67]
	s_barrier
	s_setprio 0
	s_add_i32 s86, s73, s63
	v_lshl_add_u64 v[182:183], s[56:57], 0, v[130:131]
	s_mov_b32 m0, s86
	ds_read_b128 v[198:201], v154 offset:16384
	v_xor_b32_e32 v253, 64, v154
	ds_read_b128 v[202:205], v253 offset:16384
	ds_read_b128 v[206:209], v154 offset:18432
	ds_read_b128 v[210:213], v253 offset:18432
	ds_read_b128 v[214:217], v154 offset:20480
	ds_read_b128 v[218:221], v253 offset:20480
	ds_read_b128 v[222:225], v154 offset:22528
	ds_read_b128 v[226:229], v253 offset:22528
	global_load_lds_dwordx4 v[182:183], off
	s_add_i32 m0, s86, 0x2000
	s_add_u32 s86, s56, 0x40000
	v_lshl_add_u64 v[230:231], s[56:57], 0, v[134:135]
	s_addc_u32 s87, s57, 0
	s_add_i32 s88, s74, s63
	global_load_lds_dwordx4 v[230:231], off
	v_lshl_add_u64 v[232:233], s[86:87], 0, v[130:131]
	s_mov_b32 m0, s88
	v_lshl_add_u64 v[234:235], s[58:59], 0, v[132:133]
	global_load_lds_dwordx4 v[232:233], off
	v_lshl_add_u64 v[232:233], s[86:87], 0, v[134:135]
	s_add_i32 m0, s88, 0x2000
	s_nop 0
	global_load_lds_dwordx4 v[232:233], off
	v_lshl_add_u64 v[232:233], s[58:59], 0, v[128:129]
	s_mov_b32 m0, s64
	s_nop 0
	global_load_lds_dwordx4 v[232:233], off
	s_mov_b32 m0, s65
	s_nop 0
	global_load_lds_dwordx4 v[234:235], off
	s_waitcnt vmcnt(24)
	s_waitcnt lgkmcnt(0)
	s_setprio 1
	s_barrier
	v_mfma_f32_16x16x32_bf16 v[60:63], v[162:165], v[198:201], 0
	v_mfma_f32_16x16x32_bf16 v[56:59], v[170:173], v[198:201], 0
	v_mfma_f32_16x16x32_bf16 v[48:51], v[162:165], v[206:209], 0
	v_mfma_f32_16x16x32_bf16 v[40:43], v[170:173], v[206:209], 0
	v_mfma_f32_16x16x32_bf16 v[32:35], v[162:165], v[214:217], 0
	v_mfma_f32_16x16x32_bf16 v[24:27], v[170:173], v[214:217], 0
	v_mfma_f32_16x16x32_bf16 v[16:19], v[162:165], v[222:225], 0
	v_mfma_f32_16x16x32_bf16 v[8:11], v[170:173], v[222:225], 0
	v_mfma_f32_16x16x32_bf16 v[60:63], v[166:169], v[202:205], v[60:63]
	v_mfma_f32_16x16x32_bf16 v[56:59], v[174:177], v[202:205], v[56:59]
	v_mfma_f32_16x16x32_bf16 v[48:51], v[166:169], v[210:213], v[48:51]
	v_mfma_f32_16x16x32_bf16 v[40:43], v[174:177], v[210:213], v[40:43]
	v_mfma_f32_16x16x32_bf16 v[32:35], v[166:169], v[218:221], v[32:35]
	v_mfma_f32_16x16x32_bf16 v[24:27], v[174:177], v[218:221], v[24:27]
	v_mfma_f32_16x16x32_bf16 v[16:19], v[166:169], v[226:229], v[16:19]
	v_mfma_f32_16x16x32_bf16 v[8:11], v[174:177], v[226:229], v[8:11]
	v_mfma_f32_16x16x32_bf16 v[52:55], v[178:181], v[198:201], 0
	v_mfma_f32_16x16x32_bf16 v[44:47], v[190:193], v[198:201], 0
	v_mfma_f32_16x16x32_bf16 v[36:39], v[178:181], v[206:209], 0
	v_mfma_f32_16x16x32_bf16 v[28:31], v[190:193], v[206:209], 0
	v_mfma_f32_16x16x32_bf16 v[20:23], v[178:181], v[214:217], 0
	v_mfma_f32_16x16x32_bf16 v[12:15], v[190:193], v[214:217], 0
	v_mfma_f32_16x16x32_bf16 v[4:7], v[178:181], v[222:225], 0
	v_mfma_f32_16x16x32_bf16 v[0:3], v[190:193], v[222:225], 0
	v_mfma_f32_16x16x32_bf16 v[52:55], v[186:189], v[202:205], v[52:55]
	v_mfma_f32_16x16x32_bf16 v[44:47], v[194:197], v[202:205], v[44:47]
	v_mfma_f32_16x16x32_bf16 v[36:39], v[186:189], v[210:213], v[36:39]
	v_mfma_f32_16x16x32_bf16 v[28:31], v[194:197], v[210:213], v[28:31]
	v_mfma_f32_16x16x32_bf16 v[20:23], v[186:189], v[218:221], v[20:23]
	v_mfma_f32_16x16x32_bf16 v[12:15], v[194:197], v[218:221], v[12:15]
	v_mfma_f32_16x16x32_bf16 v[4:7], v[186:189], v[226:229], v[4:7]
	v_mfma_f32_16x16x32_bf16 v[0:3], v[194:197], v[226:229], v[0:3]
	s_barrier
	s_setprio 0
	s_add_i32 s86, 0, 0x18000
	v_add_u32_e32 v146, s86, v149
	s_add_i32 s87, 0, 0x1c000
	ds_read_b128 v[162:165], v146
	v_xor_b32_e32 v253, 64, v146
	ds_read_b128 v[166:169], v253
	ds_read_b128 v[170:173], v146 offset:2048
	ds_read_b128 v[174:177], v253 offset:2048
	v_add_u32_e32 v146, s87, v149
	ds_read_b128 v[178:181], v146
	v_xor_b32_e32 v253, 64, v146
	ds_read_b128 v[186:189], v253
	ds_read_b128 v[190:193], v146 offset:2048
	ds_read_b128 v[194:197], v253 offset:2048
	s_add_u32 s58, s58, 0x40000
	s_addc_u32 s59, s59, 0
	s_mov_b32 m0, s66
	v_lshl_add_u64 v[236:237], s[58:59], 0, v[128:129]
	ds_read_b128 v[198:201], v154 offset:32768
	v_xor_b32_e32 v253, 64, v154
	ds_read_b128 v[202:205], v253 offset:32768
	ds_read_b128 v[206:209], v154 offset:34816
	ds_read_b128 v[210:213], v253 offset:34816
	ds_read_b128 v[214:217], v154 offset:36864
	ds_read_b128 v[218:221], v253 offset:36864
	ds_read_b128 v[222:225], v154 offset:38912
	ds_read_b128 v[226:229], v253 offset:38912
	global_load_lds_dwordx4 v[236:237], off
	v_lshl_add_u64 v[236:237], s[58:59], 0, v[132:133]
	s_mov_b32 m0, s67
	s_nop 0
	global_load_lds_dwordx4 v[236:237], off
	s_waitcnt vmcnt(8)
	s_waitcnt lgkmcnt(0)
	s_setprio 1
	s_barrier
	v_mfma_f32_16x16x32_bf16 v[124:127], v[162:165], v[198:201], v[124:127]
	v_mfma_f32_16x16x32_bf16 v[124:127], v[166:169], v[202:205], v[124:127]
	v_mfma_f32_16x16x32_bf16 v[120:123], v[174:177], v[202:205], v[120:123]
	v_mfma_f32_16x16x32_bf16 v[120:123], v[170:173], v[198:201], v[120:123]
	v_mfma_f32_16x16x32_bf16 v[104:107], v[170:173], v[206:209], v[104:107]
	v_mfma_f32_16x16x32_bf16 v[104:107], v[174:177], v[210:213], v[104:107]
	v_mfma_f32_16x16x32_bf16 v[112:115], v[166:169], v[210:213], v[112:115]
	v_mfma_f32_16x16x32_bf16 v[112:115], v[162:165], v[206:209], v[112:115]
	v_mfma_f32_16x16x32_bf16 v[96:99], v[162:165], v[214:217], v[96:99]
	v_mfma_f32_16x16x32_bf16 v[96:99], v[166:169], v[218:221], v[96:99]
	v_mfma_f32_16x16x32_bf16 v[88:91], v[174:177], v[218:221], v[88:91]
	v_mfma_f32_16x16x32_bf16 v[88:91], v[170:173], v[214:217], v[88:91]
	v_mfma_f32_16x16x32_bf16 v[72:75], v[170:173], v[222:225], v[72:75]
	v_mfma_f32_16x16x32_bf16 v[72:75], v[174:177], v[226:229], v[72:75]
	v_mfma_f32_16x16x32_bf16 v[80:83], v[166:169], v[226:229], v[80:83]
	v_mfma_f32_16x16x32_bf16 v[80:83], v[162:165], v[222:225], v[80:83]
	v_mfma_f32_16x16x32_bf16 v[116:119], v[178:181], v[198:201], v[116:119]
	v_mfma_f32_16x16x32_bf16 v[116:119], v[186:189], v[202:205], v[116:119]
	v_mfma_f32_16x16x32_bf16 v[108:111], v[194:197], v[202:205], v[108:111]
	v_mfma_f32_16x16x32_bf16 v[108:111], v[190:193], v[198:201], v[108:111]
	v_mfma_f32_16x16x32_bf16 v[92:95], v[190:193], v[206:209], v[92:95]
	v_mfma_f32_16x16x32_bf16 v[92:95], v[194:197], v[210:213], v[92:95]
	v_mfma_f32_16x16x32_bf16 v[100:103], v[186:189], v[210:213], v[100:103]
	v_mfma_f32_16x16x32_bf16 v[100:103], v[178:181], v[206:209], v[100:103]
	v_mfma_f32_16x16x32_bf16 v[84:87], v[178:181], v[214:217], v[84:87]
	v_mfma_f32_16x16x32_bf16 v[84:87], v[186:189], v[218:221], v[84:87]
	v_mfma_f32_16x16x32_bf16 v[76:79], v[194:197], v[218:221], v[76:79]
	v_mfma_f32_16x16x32_bf16 v[76:79], v[190:193], v[214:217], v[76:79]
	v_mfma_f32_16x16x32_bf16 v[64:67], v[190:193], v[222:225], v[64:67]
	v_mfma_f32_16x16x32_bf16 v[64:67], v[194:197], v[226:229], v[64:67]
	v_mfma_f32_16x16x32_bf16 v[68:71], v[186:189], v[226:229], v[68:71]
	v_mfma_f32_16x16x32_bf16 v[68:71], v[178:181], v[222:225], v[68:71]
	s_barrier
	s_setprio 0
	s_add_i32 s58, s86, s63
	v_lshl_add_u64 v[182:183], v[182:183], 0, s[22:23]
	s_mov_b32 m0, s58
	ds_read_b128 v[198:201], v154 offset:49152
	v_xor_b32_e32 v253, 64, v154
	ds_read_b128 v[202:205], v253 offset:49152
	ds_read_b128 v[206:209], v154 offset:51200
	ds_read_b128 v[210:213], v253 offset:51200
	ds_read_b128 v[214:217], v154 offset:53248
	ds_read_b128 v[218:221], v253 offset:53248
	ds_read_b128 v[222:225], v154 offset:55296
	ds_read_b128 v[226:229], v253 offset:55296
	global_load_lds_dwordx4 v[182:183], off
	s_add_i32 m0, s58, 0x2000
	s_add_u32 s56, s56, 0x40080
	v_lshl_add_u64 v[182:183], v[230:231], 0, s[22:23]
	s_addc_u32 s57, s57, 0
	s_add_i32 s58, s87, s63
	global_load_lds_dwordx4 v[182:183], off
	v_lshl_add_u64 v[182:183], s[56:57], 0, v[130:131]
	s_mov_b32 m0, s58
	s_nop 0
	global_load_lds_dwordx4 v[182:183], off
	v_lshl_add_u64 v[182:183], s[56:57], 0, v[134:135]
	s_add_i32 m0, s58, 0x2000
	s_nop 0
	global_load_lds_dwordx4 v[182:183], off
	v_lshl_add_u64 v[182:183], v[232:233], 0, s[22:23]
	s_mov_b32 m0, s69
	s_nop 0
	global_load_lds_dwordx4 v[182:183], off
	v_lshl_add_u64 v[182:183], v[234:235], 0, s[22:23]
	s_mov_b32 m0, s70
	s_nop 0
	global_load_lds_dwordx4 v[182:183], off
	s_waitcnt vmcnt(8)
	s_waitcnt lgkmcnt(0)
	s_setprio 1
	s_barrier
	v_mfma_f32_16x16x32_bf16 v[60:63], v[162:165], v[198:201], v[60:63]
	v_mfma_f32_16x16x32_bf16 v[60:63], v[166:169], v[202:205], v[60:63]
	v_mfma_f32_16x16x32_bf16 v[56:59], v[174:177], v[202:205], v[56:59]
	v_mfma_f32_16x16x32_bf16 v[56:59], v[170:173], v[198:201], v[56:59]
	v_mfma_f32_16x16x32_bf16 v[40:43], v[170:173], v[206:209], v[40:43]
	v_mfma_f32_16x16x32_bf16 v[40:43], v[174:177], v[210:213], v[40:43]
	v_mfma_f32_16x16x32_bf16 v[48:51], v[166:169], v[210:213], v[48:51]
	v_mfma_f32_16x16x32_bf16 v[48:51], v[162:165], v[206:209], v[48:51]
	v_mfma_f32_16x16x32_bf16 v[32:35], v[162:165], v[214:217], v[32:35]
	v_mfma_f32_16x16x32_bf16 v[32:35], v[166:169], v[218:221], v[32:35]
	v_mfma_f32_16x16x32_bf16 v[24:27], v[174:177], v[218:221], v[24:27]
	v_mfma_f32_16x16x32_bf16 v[24:27], v[170:173], v[214:217], v[24:27]
	v_mfma_f32_16x16x32_bf16 v[8:11], v[170:173], v[222:225], v[8:11]
	v_mfma_f32_16x16x32_bf16 v[8:11], v[174:177], v[226:229], v[8:11]
	v_mfma_f32_16x16x32_bf16 v[16:19], v[166:169], v[226:229], v[16:19]
	v_mfma_f32_16x16x32_bf16 v[16:19], v[162:165], v[222:225], v[16:19]
	v_mfma_f32_16x16x32_bf16 v[52:55], v[178:181], v[198:201], v[52:55]
	v_mfma_f32_16x16x32_bf16 v[52:55], v[186:189], v[202:205], v[52:55]
	v_mfma_f32_16x16x32_bf16 v[44:47], v[194:197], v[202:205], v[44:47]
	v_mfma_f32_16x16x32_bf16 v[44:47], v[190:193], v[198:201], v[44:47]
	v_mfma_f32_16x16x32_bf16 v[28:31], v[190:193], v[206:209], v[28:31]
	v_mfma_f32_16x16x32_bf16 v[28:31], v[194:197], v[210:213], v[28:31]
	v_mfma_f32_16x16x32_bf16 v[36:39], v[186:189], v[210:213], v[36:39]
	v_mfma_f32_16x16x32_bf16 v[36:39], v[178:181], v[206:209], v[36:39]
	v_mfma_f32_16x16x32_bf16 v[20:23], v[178:181], v[214:217], v[20:23]
	v_mfma_f32_16x16x32_bf16 v[20:23], v[186:189], v[218:221], v[20:23]
	v_mfma_f32_16x16x32_bf16 v[12:15], v[194:197], v[218:221], v[12:15]
	v_mfma_f32_16x16x32_bf16 v[12:15], v[190:193], v[214:217], v[12:15]
	v_mfma_f32_16x16x32_bf16 v[0:3], v[190:193], v[222:225], v[0:3]
	v_mfma_f32_16x16x32_bf16 v[0:3], v[194:197], v[226:229], v[0:3]
	v_mfma_f32_16x16x32_bf16 v[4:7], v[186:189], v[226:229], v[4:7]
	v_mfma_f32_16x16x32_bf16 v[4:7], v[178:181], v[222:225], v[4:7]
	s_barrier
	s_setprio 0
	s_add_i32 s85, s85, 2
	s_add_u32 s83, s83, 0x100
	s_addc_u32 s84, s84, 0
	s_add_u32 s54, s54, 0x100
	s_addc_u32 s55, s55, 0
	s_branch .LBB0_875
.Lfa_8:
	v_add_u32_e32 v146, s73, v149
	ds_read_b128 v[162:165], v146
	v_xor_b32_e32 v253, 64, v146
	ds_read_b128 v[166:169], v253
	ds_read_b128 v[170:173], v146 offset:2048
	ds_read_b128 v[174:177], v253 offset:2048
	v_add_u32_e32 v146, s74, v149
	ds_read_b128 v[178:181], v146
	v_xor_b32_e32 v253, 64, v146
	ds_read_b128 v[186:189], v253
	ds_read_b128 v[190:193], v146 offset:2048
	ds_read_b128 v[194:197], v253 offset:2048
	s_add_u32 s58, s54, 0xfffc0080
	s_addc_u32 s59, s55, -1
	s_and_b64 s[56:57], s[56:57], exec
	s_cselect_b32 s59, s49, s59
	s_cselect_b32 s58, s80, s58
	s_cselect_b32 s57, s81, s84
	s_cselect_b32 s56, s82, s83
	v_lshl_add_u64 v[182:183], s[54:55], 0, v[138:139]
	s_add_i32 m0, s64, 0xc000
	ds_read_b128 v[198:201], v154
	v_xor_b32_e32 v253, 64, v154
	ds_read_b128 v[202:205], v253
	ds_read_b128 v[206:209], v154 offset:2048
	ds_read_b128 v[210:213], v253 offset:2048
	ds_read_b128 v[214:217], v154 offset:4096
	ds_read_b128 v[218:221], v253 offset:4096
	ds_read_b128 v[222:225], v154 offset:6144
	ds_read_b128 v[226:229], v253 offset:6144
	global_load_lds_dwordx4 v[182:183], off
	v_lshl_add_u64 v[182:183], s[54:55], 0, v[136:137]
	s_add_i32 m0, s64, 0xe000
	s_nop 0
	global_load_lds_dwordx4 v[182:183], off
	s_waitcnt vmcnt(8)
	s_waitcnt lgkmcnt(0)
	s_setprio 1
	s_barrier
	v_mfma_f32_16x16x32_bf16 v[124:127], v[162:165], v[198:201], 0
	v_mfma_f32_16x16x32_bf16 v[120:123], v[170:173], v[198:201], 0
	v_mfma_f32_16x16x32_bf16 v[112:115], v[162:165], v[206:209], 0
	v_mfma_f32_16x16x32_bf16 v[104:107], v[170:173], v[206:209], 0
	v_mfma_f32_16x16x32_bf16 v[96:99], v[162:165], v[214:217], 0
	v_mfma_f32_16x16x32_bf16 v[88:91], v[170:173], v[214:217], 0
	v_mfma_f32_16x16x32_bf16 v[80:83], v[162:165], v[222:225], 0
	v_mfma_f32_16x16x32_bf16 v[72:75], v[170:173], v[222:225], 0
	v_mfma_f32_16x16x32_bf16 v[124:127], v[166:169], v[202:205], v[124:127]
	v_mfma_f32_16x16x32_bf16 v[120:123], v[174:177], v[202:205], v[120:123]
	v_mfma_f32_16x16x32_bf16 v[112:115], v[166:169], v[210:213], v[112:115]
	v_mfma_f32_16x16x32_bf16 v[104:107], v[174:177], v[210:213], v[104:107]
	v_mfma_f32_16x16x32_bf16 v[96:99], v[166:169], v[218:221], v[96:99]
	v_mfma_f32_16x16x32_bf16 v[88:91], v[174:177], v[218:221], v[88:91]
	v_mfma_f32_16x16x32_bf16 v[80:83], v[166:169], v[226:229], v[80:83]
	v_mfma_f32_16x16x32_bf16 v[72:75], v[174:177], v[226:229], v[72:75]
	v_mfma_f32_16x16x32_bf16 v[116:119], v[178:181], v[198:201], 0
	v_mfma_f32_16x16x32_bf16 v[108:111], v[190:193], v[198:201], 0
	v_mfma_f32_16x16x32_bf16 v[100:103], v[178:181], v[206:209], 0
	v_mfma_f32_16x16x32_bf16 v[92:95], v[190:193], v[206:209], 0
	v_mfma_f32_16x16x32_bf16 v[84:87], v[178:181], v[214:217], 0
	v_mfma_f32_16x16x32_bf16 v[76:79], v[190:193], v[214:217], 0
	v_mfma_f32_16x16x32_bf16 v[68:71], v[178:181], v[222:225], 0
	v_mfma_f32_16x16x32_bf16 v[64:67], v[190:193], v[222:225], 0
	v_mfma_f32_16x16x32_bf16 v[116:119], v[186:189], v[202:205], v[116:119]
	v_mfma_f32_16x16x32_bf16 v[108:111], v[194:197], v[202:205], v[108:111]
	v_mfma_f32_16x16x32_bf16 v[100:103], v[186:189], v[210:213], v[100:103]
	v_mfma_f32_16x16x32_bf16 v[92:95], v[194:197], v[210:213], v[92:95]
	v_mfma_f32_16x16x32_bf16 v[84:87], v[186:189], v[218:221], v[84:87]
	v_mfma_f32_16x16x32_bf16 v[76:79], v[194:197], v[218:221], v[76:79]
	v_mfma_f32_16x16x32_bf16 v[68:71], v[186:189], v[226:229], v[68:71]
	v_mfma_f32_16x16x32_bf16 v[64:67], v[194:197], v[226:229], v[64:67]
	s_barrier
	s_setprio 0
	s_add_i32 s86, s73, s63
	v_lshl_add_u64 v[182:183], s[56:57], 0, v[130:131]
	s_mov_b32 m0, s86
	ds_read_b128 v[198:201], v154 offset:16384
	v_xor_b32_e32 v253, 64, v154
	ds_read_b128 v[202:205], v253 offset:16384
	ds_read_b128 v[206:209], v154 offset:18432
	ds_read_b128 v[210:213], v253 offset:18432
	ds_read_b128 v[214:217], v154 offset:20480
	ds_read_b128 v[218:221], v253 offset:20480
	ds_read_b128 v[222:225], v154 offset:22528
	ds_read_b128 v[226:229], v253 offset:22528
	global_load_lds_dwordx4 v[182:183], off
	s_add_i32 m0, s86, 0x2000
	s_add_u32 s86, s56, 0x40000
	v_lshl_add_u64 v[230:231], s[56:57], 0, v[134:135]
	s_addc_u32 s87, s57, 0
	s_add_i32 s88, s74, s63
	global_load_lds_dwordx4 v[230:231], off
	v_lshl_add_u64 v[232:233], s[86:87], 0, v[130:131]
	s_mov_b32 m0, s88
	v_lshl_add_u64 v[234:235], s[58:59], 0, v[132:133]
	global_load_lds_dwordx4 v[232:233], off
	v_lshl_add_u64 v[232:233], s[86:87], 0, v[134:135]
	s_add_i32 m0, s88, 0x2000
	s_nop 0
	global_load_lds_dwordx4 v[232:233], off
	v_lshl_add_u64 v[232:233], s[58:59], 0, v[128:129]
	s_mov_b32 m0, s64
	s_nop 0
	global_load_lds_dwordx4 v[232:233], off
	s_mov_b32 m0, s65
	s_nop 0
	global_load_lds_dwordx4 v[234:235], off
	s_waitcnt vmcnt(8)
	s_waitcnt lgkmcnt(0)
	s_setprio 1
	s_barrier
	v_mfma_f32_16x16x32_bf16 v[60:63], v[162:165], v[198:201], 0
	v_mfma_f32_16x16x32_bf16 v[56:59], v[170:173], v[198:201], 0
	v_mfma_f32_16x16x32_bf16 v[48:51], v[162:165], v[206:209], 0
	v_mfma_f32_16x16x32_bf16 v[40:43], v[170:173], v[206:209], 0
	v_mfma_f32_16x16x32_bf16 v[32:35], v[162:165], v[214:217], 0
	v_mfma_f32_16x16x32_bf16 v[24:27], v[170:173], v[214:217], 0
	v_mfma_f32_16x16x32_bf16 v[16:19], v[162:165], v[222:225], 0
	v_mfma_f32_16x16x32_bf16 v[8:11], v[170:173], v[222:225], 0
	v_mfma_f32_16x16x32_bf16 v[60:63], v[166:169], v[202:205], v[60:63]
	v_mfma_f32_16x16x32_bf16 v[56:59], v[174:177], v[202:205], v[56:59]
	v_mfma_f32_16x16x32_bf16 v[48:51], v[166:169], v[210:213], v[48:51]
	v_mfma_f32_16x16x32_bf16 v[40:43], v[174:177], v[210:213], v[40:43]
	v_mfma_f32_16x16x32_bf16 v[32:35], v[166:169], v[218:221], v[32:35]
	v_mfma_f32_16x16x32_bf16 v[24:27], v[174:177], v[218:221], v[24:27]
	v_mfma_f32_16x16x32_bf16 v[16:19], v[166:169], v[226:229], v[16:19]
	v_mfma_f32_16x16x32_bf16 v[8:11], v[174:177], v[226:229], v[8:11]
	v_mfma_f32_16x16x32_bf16 v[52:55], v[178:181], v[198:201], 0
	v_mfma_f32_16x16x32_bf16 v[44:47], v[190:193], v[198:201], 0
	v_mfma_f32_16x16x32_bf16 v[36:39], v[178:181], v[206:209], 0
	v_mfma_f32_16x16x32_bf16 v[28:31], v[190:193], v[206:209], 0
	v_mfma_f32_16x16x32_bf16 v[20:23], v[178:181], v[214:217], 0
	v_mfma_f32_16x16x32_bf16 v[12:15], v[190:193], v[214:217], 0
	v_mfma_f32_16x16x32_bf16 v[4:7], v[178:181], v[222:225], 0
	v_mfma_f32_16x16x32_bf16 v[0:3], v[190:193], v[222:225], 0
	v_mfma_f32_16x16x32_bf16 v[52:55], v[186:189], v[202:205], v[52:55]
	v_mfma_f32_16x16x32_bf16 v[44:47], v[194:197], v[202:205], v[44:47]
	v_mfma_f32_16x16x32_bf16 v[36:39], v[186:189], v[210:213], v[36:39]
	v_mfma_f32_16x16x32_bf16 v[28:31], v[194:197], v[210:213], v[28:31]
	v_mfma_f32_16x16x32_bf16 v[20:23], v[186:189], v[218:221], v[20:23]
	v_mfma_f32_16x16x32_bf16 v[12:15], v[194:197], v[218:221], v[12:15]
	v_mfma_f32_16x16x32_bf16 v[4:7], v[186:189], v[226:229], v[4:7]
	v_mfma_f32_16x16x32_bf16 v[0:3], v[194:197], v[226:229], v[0:3]
	s_barrier
	s_setprio 0
	s_add_i32 s86, 0, 0x18000
	v_add_u32_e32 v146, s86, v149
	s_add_i32 s87, 0, 0x1c000
	ds_read_b128 v[162:165], v146
	v_xor_b32_e32 v253, 64, v146
	ds_read_b128 v[166:169], v253
	ds_read_b128 v[170:173], v146 offset:2048
	ds_read_b128 v[174:177], v253 offset:2048
	v_add_u32_e32 v146, s87, v149
	ds_read_b128 v[178:181], v146
	v_xor_b32_e32 v253, 64, v146
	ds_read_b128 v[186:189], v253
	ds_read_b128 v[190:193], v146 offset:2048
	ds_read_b128 v[194:197], v253 offset:2048
	s_add_u32 s58, s58, 0x40000
	s_addc_u32 s59, s59, 0
	s_mov_b32 m0, s66
	v_lshl_add_u64 v[236:237], s[58:59], 0, v[128:129]
	ds_read_b128 v[198:201], v154 offset:32768
	v_xor_b32_e32 v253, 64, v154
	ds_read_b128 v[202:205], v253 offset:32768
	ds_read_b128 v[206:209], v154 offset:34816
	ds_read_b128 v[210:213], v253 offset:34816
	ds_read_b128 v[214:217], v154 offset:36864
	ds_read_b128 v[218:221], v253 offset:36864
	ds_read_b128 v[222:225], v154 offset:38912
	ds_read_b128 v[226:229], v253 offset:38912
	global_load_lds_dwordx4 v[236:237], off
	v_lshl_add_u64 v[236:237], s[58:59], 0, v[132:133]
	s_mov_b32 m0, s67
	s_nop 0
	global_load_lds_dwordx4 v[236:237], off
	s_waitcnt vmcnt(8)
	s_waitcnt lgkmcnt(0)
	s_setprio 1
	s_barrier
	v_mfma_f32_16x16x32_bf16 v[124:127], v[162:165], v[198:201], v[124:127]
	v_mfma_f32_16x16x32_bf16 v[124:127], v[166:169], v[202:205], v[124:127]
	v_mfma_f32_16x16x32_bf16 v[120:123], v[174:177], v[202:205], v[120:123]
	v_mfma_f32_16x16x32_bf16 v[120:123], v[170:173], v[198:201], v[120:123]
	v_mfma_f32_16x16x32_bf16 v[104:107], v[170:173], v[206:209], v[104:107]
	v_mfma_f32_16x16x32_bf16 v[104:107], v[174:177], v[210:213], v[104:107]
	v_mfma_f32_16x16x32_bf16 v[112:115], v[166:169], v[210:213], v[112:115]
	v_mfma_f32_16x16x32_bf16 v[112:115], v[162:165], v[206:209], v[112:115]
	v_mfma_f32_16x16x32_bf16 v[96:99], v[162:165], v[214:217], v[96:99]
	v_mfma_f32_16x16x32_bf16 v[96:99], v[166:169], v[218:221], v[96:99]
	v_mfma_f32_16x16x32_bf16 v[88:91], v[174:177], v[218:221], v[88:91]
	v_mfma_f32_16x16x32_bf16 v[88:91], v[170:173], v[214:217], v[88:91]
	v_mfma_f32_16x16x32_bf16 v[72:75], v[170:173], v[222:225], v[72:75]
	v_mfma_f32_16x16x32_bf16 v[72:75], v[174:177], v[226:229], v[72:75]
	v_mfma_f32_16x16x32_bf16 v[80:83], v[166:169], v[226:229], v[80:83]
	v_mfma_f32_16x16x32_bf16 v[80:83], v[162:165], v[222:225], v[80:83]
	v_mfma_f32_16x16x32_bf16 v[116:119], v[178:181], v[198:201], v[116:119]
	v_mfma_f32_16x16x32_bf16 v[116:119], v[186:189], v[202:205], v[116:119]
	v_mfma_f32_16x16x32_bf16 v[108:111], v[194:197], v[202:205], v[108:111]
	v_mfma_f32_16x16x32_bf16 v[108:111], v[190:193], v[198:201], v[108:111]
	v_mfma_f32_16x16x32_bf16 v[92:95], v[190:193], v[206:209], v[92:95]
	v_mfma_f32_16x16x32_bf16 v[92:95], v[194:197], v[210:213], v[92:95]
	v_mfma_f32_16x16x32_bf16 v[100:103], v[186:189], v[210:213], v[100:103]
	v_mfma_f32_16x16x32_bf16 v[100:103], v[178:181], v[206:209], v[100:103]
	v_mfma_f32_16x16x32_bf16 v[84:87], v[178:181], v[214:217], v[84:87]
	v_mfma_f32_16x16x32_bf16 v[84:87], v[186:189], v[218:221], v[84:87]
	v_mfma_f32_16x16x32_bf16 v[76:79], v[194:197], v[218:221], v[76:79]
	v_mfma_f32_16x16x32_bf16 v[76:79], v[190:193], v[214:217], v[76:79]
	v_mfma_f32_16x16x32_bf16 v[64:67], v[190:193], v[222:225], v[64:67]
	v_mfma_f32_16x16x32_bf16 v[64:67], v[194:197], v[226:229], v[64:67]
	v_mfma_f32_16x16x32_bf16 v[68:71], v[186:189], v[226:229], v[68:71]
	v_mfma_f32_16x16x32_bf16 v[68:71], v[178:181], v[222:225], v[68:71]
	s_barrier
	s_setprio 0
	s_add_i32 s58, s86, s63
	v_lshl_add_u64 v[182:183], v[182:183], 0, s[22:23]
	s_mov_b32 m0, s58
	ds_read_b128 v[198:201], v154 offset:49152
	v_xor_b32_e32 v253, 64, v154
	ds_read_b128 v[202:205], v253 offset:49152
	ds_read_b128 v[206:209], v154 offset:51200
	ds_read_b128 v[210:213], v253 offset:51200
	ds_read_b128 v[214:217], v154 offset:53248
	ds_read_b128 v[218:221], v253 offset:53248
	ds_read_b128 v[222:225], v154 offset:55296
	ds_read_b128 v[226:229], v253 offset:55296
	global_load_lds_dwordx4 v[182:183], off
	s_add_i32 m0, s58, 0x2000
	s_add_u32 s56, s56, 0x40080
	v_lshl_add_u64 v[182:183], v[230:231], 0, s[22:23]
	s_addc_u32 s57, s57, 0
	s_add_i32 s58, s87, s63
	global_load_lds_dwordx4 v[182:183], off
	v_lshl_add_u64 v[182:183], s[56:57], 0, v[130:131]
	s_mov_b32 m0, s58
	s_nop 0
	global_load_lds_dwordx4 v[182:183], off
	v_lshl_add_u64 v[182:183], s[56:57], 0, v[134:135]
	s_add_i32 m0, s58, 0x2000
	s_nop 0
	global_load_lds_dwordx4 v[182:183], off
	v_lshl_add_u64 v[182:183], v[232:233], 0, s[22:23]
	s_mov_b32 m0, s69
	s_nop 0
	global_load_lds_dwordx4 v[182:183], off
	v_lshl_add_u64 v[182:183], v[234:235], 0, s[22:23]
	s_mov_b32 m0, s70
	s_nop 0
	global_load_lds_dwordx4 v[182:183], off
	s_waitcnt vmcnt(8)
	s_waitcnt lgkmcnt(0)
	s_setprio 1
	s_barrier
	v_mfma_f32_16x16x32_bf16 v[60:63], v[162:165], v[198:201], v[60:63]
	v_mfma_f32_16x16x32_bf16 v[60:63], v[166:169], v[202:205], v[60:63]
	v_mfma_f32_16x16x32_bf16 v[56:59], v[174:177], v[202:205], v[56:59]
	v_mfma_f32_16x16x32_bf16 v[56:59], v[170:173], v[198:201], v[56:59]
	v_mfma_f32_16x16x32_bf16 v[40:43], v[170:173], v[206:209], v[40:43]
	v_mfma_f32_16x16x32_bf16 v[40:43], v[174:177], v[210:213], v[40:43]
	v_mfma_f32_16x16x32_bf16 v[48:51], v[166:169], v[210:213], v[48:51]
	v_mfma_f32_16x16x32_bf16 v[48:51], v[162:165], v[206:209], v[48:51]
	v_mfma_f32_16x16x32_bf16 v[32:35], v[162:165], v[214:217], v[32:35]
	v_mfma_f32_16x16x32_bf16 v[32:35], v[166:169], v[218:221], v[32:35]
	v_mfma_f32_16x16x32_bf16 v[24:27], v[174:177], v[218:221], v[24:27]
	v_mfma_f32_16x16x32_bf16 v[24:27], v[170:173], v[214:217], v[24:27]
	v_mfma_f32_16x16x32_bf16 v[8:11], v[170:173], v[222:225], v[8:11]
	v_mfma_f32_16x16x32_bf16 v[8:11], v[174:177], v[226:229], v[8:11]
	v_mfma_f32_16x16x32_bf16 v[16:19], v[166:169], v[226:229], v[16:19]
	v_mfma_f32_16x16x32_bf16 v[16:19], v[162:165], v[222:225], v[16:19]
	v_mfma_f32_16x16x32_bf16 v[52:55], v[178:181], v[198:201], v[52:55]
	v_mfma_f32_16x16x32_bf16 v[52:55], v[186:189], v[202:205], v[52:55]
	v_mfma_f32_16x16x32_bf16 v[44:47], v[194:197], v[202:205], v[44:47]
	v_mfma_f32_16x16x32_bf16 v[44:47], v[190:193], v[198:201], v[44:47]
	v_mfma_f32_16x16x32_bf16 v[28:31], v[190:193], v[206:209], v[28:31]
	v_mfma_f32_16x16x32_bf16 v[28:31], v[194:197], v[210:213], v[28:31]
	v_mfma_f32_16x16x32_bf16 v[36:39], v[186:189], v[210:213], v[36:39]
	v_mfma_f32_16x16x32_bf16 v[36:39], v[178:181], v[206:209], v[36:39]
	v_mfma_f32_16x16x32_bf16 v[20:23], v[178:181], v[214:217], v[20:23]
	v_mfma_f32_16x16x32_bf16 v[20:23], v[186:189], v[218:221], v[20:23]
	v_mfma_f32_16x16x32_bf16 v[12:15], v[194:197], v[218:221], v[12:15]
	v_mfma_f32_16x16x32_bf16 v[12:15], v[190:193], v[214:217], v[12:15]
	v_mfma_f32_16x16x32_bf16 v[0:3], v[190:193], v[222:225], v[0:3]
	v_mfma_f32_16x16x32_bf16 v[0:3], v[194:197], v[226:229], v[0:3]
	v_mfma_f32_16x16x32_bf16 v[4:7], v[186:189], v[226:229], v[4:7]
	v_mfma_f32_16x16x32_bf16 v[4:7], v[178:181], v[222:225], v[4:7]
	s_barrier
	s_setprio 0
	s_add_i32 s85, s85, 2
	s_add_u32 s83, s83, 0x100
	s_addc_u32 s84, s84, 0
	s_add_u32 s54, s54, 0x100
	s_addc_u32 s55, s55, 0
	s_branch .LBB0_875
.LBB0_874:
	v_add_u32_e32 v146, s73, v149
	ds_read_b128 v[162:165], v146
	v_xor_b32_e32 v253, 64, v146
	ds_read_b128 v[166:169], v253
	ds_read_b128 v[170:173], v146 offset:2048
	ds_read_b128 v[174:177], v253 offset:2048
	v_add_u32_e32 v146, s74, v149
	ds_read_b128 v[178:181], v146
	v_xor_b32_e32 v253, 64, v146
	ds_read_b128 v[186:189], v253
	ds_read_b128 v[190:193], v146 offset:2048
	ds_read_b128 v[194:197], v253 offset:2048
	s_add_u32 s58, s54, 0xfffc0080
	s_addc_u32 s59, s55, -1
	s_and_b64 s[56:57], s[56:57], exec
	s_cselect_b32 s59, s49, s59
	s_cselect_b32 s58, s80, s58
	s_cselect_b32 s57, s81, s84
	s_cselect_b32 s56, s82, s83
	v_lshl_add_u64 v[182:183], s[54:55], 0, v[138:139]
	s_add_i32 m0, s64, 0xc000
	ds_read_b128 v[198:201], v154
	v_xor_b32_e32 v253, 64, v154
	ds_read_b128 v[202:205], v253
	ds_read_b128 v[206:209], v154 offset:2048
	ds_read_b128 v[210:213], v253 offset:2048
	ds_read_b128 v[214:217], v154 offset:4096
	ds_read_b128 v[218:221], v253 offset:4096
	ds_read_b128 v[222:225], v154 offset:6144
	ds_read_b128 v[226:229], v253 offset:6144
	global_load_lds_dwordx4 v[182:183], off
	v_lshl_add_u64 v[182:183], s[54:55], 0, v[136:137]
	s_add_i32 m0, s64, 0xe000
	s_nop 0
	global_load_lds_dwordx4 v[182:183], off
	s_waitcnt vmcnt(8)
	s_waitcnt lgkmcnt(0)
	s_setprio 1
	s_barrier
	v_mfma_f32_16x16x32_bf16 v[124:127], v[162:165], v[198:201], v[124:127]
	v_mfma_f32_16x16x32_bf16 v[124:127], v[166:169], v[202:205], v[124:127]
	v_mfma_f32_16x16x32_bf16 v[120:123], v[174:177], v[202:205], v[120:123]
	v_mfma_f32_16x16x32_bf16 v[120:123], v[170:173], v[198:201], v[120:123]
	v_mfma_f32_16x16x32_bf16 v[104:107], v[170:173], v[206:209], v[104:107]
	v_mfma_f32_16x16x32_bf16 v[104:107], v[174:177], v[210:213], v[104:107]
	v_mfma_f32_16x16x32_bf16 v[112:115], v[166:169], v[210:213], v[112:115]
	v_mfma_f32_16x16x32_bf16 v[112:115], v[162:165], v[206:209], v[112:115]
	v_mfma_f32_16x16x32_bf16 v[96:99], v[162:165], v[214:217], v[96:99]
	v_mfma_f32_16x16x32_bf16 v[96:99], v[166:169], v[218:221], v[96:99]
	v_mfma_f32_16x16x32_bf16 v[88:91], v[174:177], v[218:221], v[88:91]
	v_mfma_f32_16x16x32_bf16 v[88:91], v[170:173], v[214:217], v[88:91]
	v_mfma_f32_16x16x32_bf16 v[72:75], v[170:173], v[222:225], v[72:75]
	v_mfma_f32_16x16x32_bf16 v[72:75], v[174:177], v[226:229], v[72:75]
	v_mfma_f32_16x16x32_bf16 v[80:83], v[166:169], v[226:229], v[80:83]
	v_mfma_f32_16x16x32_bf16 v[80:83], v[162:165], v[222:225], v[80:83]
	v_mfma_f32_16x16x32_bf16 v[116:119], v[178:181], v[198:201], v[116:119]
	v_mfma_f32_16x16x32_bf16 v[116:119], v[186:189], v[202:205], v[116:119]
	v_mfma_f32_16x16x32_bf16 v[108:111], v[194:197], v[202:205], v[108:111]
	v_mfma_f32_16x16x32_bf16 v[108:111], v[190:193], v[198:201], v[108:111]
	v_mfma_f32_16x16x32_bf16 v[92:95], v[190:193], v[206:209], v[92:95]
	v_mfma_f32_16x16x32_bf16 v[92:95], v[194:197], v[210:213], v[92:95]
	v_mfma_f32_16x16x32_bf16 v[100:103], v[186:189], v[210:213], v[100:103]
	v_mfma_f32_16x16x32_bf16 v[100:103], v[178:181], v[206:209], v[100:103]
	v_mfma_f32_16x16x32_bf16 v[84:87], v[178:181], v[214:217], v[84:87]
	v_mfma_f32_16x16x32_bf16 v[84:87], v[186:189], v[218:221], v[84:87]
	v_mfma_f32_16x16x32_bf16 v[76:79], v[194:197], v[218:221], v[76:79]
	v_mfma_f32_16x16x32_bf16 v[76:79], v[190:193], v[214:217], v[76:79]
	v_mfma_f32_16x16x32_bf16 v[64:67], v[190:193], v[222:225], v[64:67]
	v_mfma_f32_16x16x32_bf16 v[64:67], v[194:197], v[226:229], v[64:67]
	v_mfma_f32_16x16x32_bf16 v[68:71], v[186:189], v[226:229], v[68:71]
	v_mfma_f32_16x16x32_bf16 v[68:71], v[178:181], v[222:225], v[68:71]
	s_barrier
	s_setprio 0
	s_add_i32 s86, s73, s63
	v_lshl_add_u64 v[182:183], s[56:57], 0, v[130:131]
	s_mov_b32 m0, s86
	ds_read_b128 v[198:201], v154 offset:16384
	v_xor_b32_e32 v253, 64, v154
	ds_read_b128 v[202:205], v253 offset:16384
	ds_read_b128 v[206:209], v154 offset:18432
	ds_read_b128 v[210:213], v253 offset:18432
	ds_read_b128 v[214:217], v154 offset:20480
	ds_read_b128 v[218:221], v253 offset:20480
	ds_read_b128 v[222:225], v154 offset:22528
	ds_read_b128 v[226:229], v253 offset:22528
	global_load_lds_dwordx4 v[182:183], off
	s_add_i32 m0, s86, 0x2000
	s_add_u32 s86, s56, 0x40000
	v_lshl_add_u64 v[230:231], s[56:57], 0, v[134:135]
	s_addc_u32 s87, s57, 0
	s_add_i32 s88, s74, s63
	global_load_lds_dwordx4 v[230:231], off
	v_lshl_add_u64 v[232:233], s[86:87], 0, v[130:131]
	s_mov_b32 m0, s88
	v_lshl_add_u64 v[234:235], s[58:59], 0, v[132:133]
	global_load_lds_dwordx4 v[232:233], off
	v_lshl_add_u64 v[232:233], s[86:87], 0, v[134:135]
	s_add_i32 m0, s88, 0x2000
	s_nop 0
	global_load_lds_dwordx4 v[232:233], off
	v_lshl_add_u64 v[232:233], s[58:59], 0, v[128:129]
	s_mov_b32 m0, s64
	s_nop 0
	global_load_lds_dwordx4 v[232:233], off
	s_mov_b32 m0, s65
	s_nop 0
	global_load_lds_dwordx4 v[234:235], off
	s_waitcnt vmcnt(8)
	s_waitcnt lgkmcnt(0)
	s_setprio 1
	s_barrier
	v_mfma_f32_16x16x32_bf16 v[60:63], v[162:165], v[198:201], v[60:63]
	v_mfma_f32_16x16x32_bf16 v[60:63], v[166:169], v[202:205], v[60:63]
	v_mfma_f32_16x16x32_bf16 v[56:59], v[174:177], v[202:205], v[56:59]
	v_mfma_f32_16x16x32_bf16 v[56:59], v[170:173], v[198:201], v[56:59]
	v_mfma_f32_16x16x32_bf16 v[40:43], v[170:173], v[206:209], v[40:43]
	v_mfma_f32_16x16x32_bf16 v[40:43], v[174:177], v[210:213], v[40:43]
	v_mfma_f32_16x16x32_bf16 v[48:51], v[166:169], v[210:213], v[48:51]
	v_mfma_f32_16x16x32_bf16 v[48:51], v[162:165], v[206:209], v[48:51]
	v_mfma_f32_16x16x32_bf16 v[32:35], v[162:165], v[214:217], v[32:35]
	v_mfma_f32_16x16x32_bf16 v[32:35], v[166:169], v[218:221], v[32:35]
	v_mfma_f32_16x16x32_bf16 v[24:27], v[174:177], v[218:221], v[24:27]
	v_mfma_f32_16x16x32_bf16 v[24:27], v[170:173], v[214:217], v[24:27]
	v_mfma_f32_16x16x32_bf16 v[8:11], v[170:173], v[222:225], v[8:11]
	v_mfma_f32_16x16x32_bf16 v[8:11], v[174:177], v[226:229], v[8:11]
	v_mfma_f32_16x16x32_bf16 v[16:19], v[166:169], v[226:229], v[16:19]
	v_mfma_f32_16x16x32_bf16 v[16:19], v[162:165], v[222:225], v[16:19]
	v_mfma_f32_16x16x32_bf16 v[52:55], v[178:181], v[198:201], v[52:55]
	v_mfma_f32_16x16x32_bf16 v[52:55], v[186:189], v[202:205], v[52:55]
	v_mfma_f32_16x16x32_bf16 v[44:47], v[194:197], v[202:205], v[44:47]
	v_mfma_f32_16x16x32_bf16 v[44:47], v[190:193], v[198:201], v[44:47]
	v_mfma_f32_16x16x32_bf16 v[28:31], v[190:193], v[206:209], v[28:31]
	v_mfma_f32_16x16x32_bf16 v[28:31], v[194:197], v[210:213], v[28:31]
	v_mfma_f32_16x16x32_bf16 v[36:39], v[186:189], v[210:213], v[36:39]
	v_mfma_f32_16x16x32_bf16 v[36:39], v[178:181], v[206:209], v[36:39]
	v_mfma_f32_16x16x32_bf16 v[20:23], v[178:181], v[214:217], v[20:23]
	v_mfma_f32_16x16x32_bf16 v[20:23], v[186:189], v[218:221], v[20:23]
	v_mfma_f32_16x16x32_bf16 v[12:15], v[194:197], v[218:221], v[12:15]
	v_mfma_f32_16x16x32_bf16 v[12:15], v[190:193], v[214:217], v[12:15]
	v_mfma_f32_16x16x32_bf16 v[0:3], v[190:193], v[222:225], v[0:3]
	v_mfma_f32_16x16x32_bf16 v[0:3], v[194:197], v[226:229], v[0:3]
	v_mfma_f32_16x16x32_bf16 v[4:7], v[186:189], v[226:229], v[4:7]
	v_mfma_f32_16x16x32_bf16 v[4:7], v[178:181], v[222:225], v[4:7]
	s_barrier
	s_setprio 0
	s_add_i32 s86, 0, 0x18000
	v_add_u32_e32 v146, s86, v149
	s_add_i32 s87, 0, 0x1c000
	ds_read_b128 v[162:165], v146
	v_xor_b32_e32 v253, 64, v146
	ds_read_b128 v[166:169], v253
	ds_read_b128 v[170:173], v146 offset:2048
	ds_read_b128 v[174:177], v253 offset:2048
	v_add_u32_e32 v146, s87, v149
	ds_read_b128 v[178:181], v146
	v_xor_b32_e32 v253, 64, v146
	ds_read_b128 v[186:189], v253
	ds_read_b128 v[190:193], v146 offset:2048
	ds_read_b128 v[194:197], v253 offset:2048
	s_add_u32 s58, s58, 0x40000
	s_addc_u32 s59, s59, 0
	s_mov_b32 m0, s66
	v_lshl_add_u64 v[236:237], s[58:59], 0, v[128:129]
	ds_read_b128 v[198:201], v154 offset:32768
	v_xor_b32_e32 v253, 64, v154
	ds_read_b128 v[202:205], v253 offset:32768
	ds_read_b128 v[206:209], v154 offset:34816
	ds_read_b128 v[210:213], v253 offset:34816
	ds_read_b128 v[214:217], v154 offset:36864
	ds_read_b128 v[218:221], v253 offset:36864
	ds_read_b128 v[222:225], v154 offset:38912
	ds_read_b128 v[226:229], v253 offset:38912
	global_load_lds_dwordx4 v[236:237], off
	v_lshl_add_u64 v[236:237], s[58:59], 0, v[132:133]
	s_mov_b32 m0, s67
	s_nop 0
	global_load_lds_dwordx4 v[236:237], off
	s_waitcnt vmcnt(8)
	s_waitcnt lgkmcnt(0)
	s_setprio 1
	s_barrier
	v_mfma_f32_16x16x32_bf16 v[124:127], v[162:165], v[198:201], v[124:127]
	v_mfma_f32_16x16x32_bf16 v[124:127], v[166:169], v[202:205], v[124:127]
	v_mfma_f32_16x16x32_bf16 v[120:123], v[174:177], v[202:205], v[120:123]
	v_mfma_f32_16x16x32_bf16 v[120:123], v[170:173], v[198:201], v[120:123]
	v_mfma_f32_16x16x32_bf16 v[104:107], v[170:173], v[206:209], v[104:107]
	v_mfma_f32_16x16x32_bf16 v[104:107], v[174:177], v[210:213], v[104:107]
	v_mfma_f32_16x16x32_bf16 v[112:115], v[166:169], v[210:213], v[112:115]
	v_mfma_f32_16x16x32_bf16 v[112:115], v[162:165], v[206:209], v[112:115]
	v_mfma_f32_16x16x32_bf16 v[96:99], v[162:165], v[214:217], v[96:99]
	v_mfma_f32_16x16x32_bf16 v[96:99], v[166:169], v[218:221], v[96:99]
	v_mfma_f32_16x16x32_bf16 v[88:91], v[174:177], v[218:221], v[88:91]
	v_mfma_f32_16x16x32_bf16 v[88:91], v[170:173], v[214:217], v[88:91]
	v_mfma_f32_16x16x32_bf16 v[72:75], v[170:173], v[222:225], v[72:75]
	v_mfma_f32_16x16x32_bf16 v[72:75], v[174:177], v[226:229], v[72:75]
	v_mfma_f32_16x16x32_bf16 v[80:83], v[166:169], v[226:229], v[80:83]
	v_mfma_f32_16x16x32_bf16 v[80:83], v[162:165], v[222:225], v[80:83]
	v_mfma_f32_16x16x32_bf16 v[116:119], v[178:181], v[198:201], v[116:119]
	v_mfma_f32_16x16x32_bf16 v[116:119], v[186:189], v[202:205], v[116:119]
	v_mfma_f32_16x16x32_bf16 v[108:111], v[194:197], v[202:205], v[108:111]
	v_mfma_f32_16x16x32_bf16 v[108:111], v[190:193], v[198:201], v[108:111]
	v_mfma_f32_16x16x32_bf16 v[92:95], v[190:193], v[206:209], v[92:95]
	v_mfma_f32_16x16x32_bf16 v[92:95], v[194:197], v[210:213], v[92:95]
	v_mfma_f32_16x16x32_bf16 v[100:103], v[186:189], v[210:213], v[100:103]
	v_mfma_f32_16x16x32_bf16 v[100:103], v[178:181], v[206:209], v[100:103]
	v_mfma_f32_16x16x32_bf16 v[84:87], v[178:181], v[214:217], v[84:87]
	v_mfma_f32_16x16x32_bf16 v[84:87], v[186:189], v[218:221], v[84:87]
	v_mfma_f32_16x16x32_bf16 v[76:79], v[194:197], v[218:221], v[76:79]
	v_mfma_f32_16x16x32_bf16 v[76:79], v[190:193], v[214:217], v[76:79]
	v_mfma_f32_16x16x32_bf16 v[64:67], v[190:193], v[222:225], v[64:67]
	v_mfma_f32_16x16x32_bf16 v[64:67], v[194:197], v[226:229], v[64:67]
	v_mfma_f32_16x16x32_bf16 v[68:71], v[186:189], v[226:229], v[68:71]
	v_mfma_f32_16x16x32_bf16 v[68:71], v[178:181], v[222:225], v[68:71]
	s_barrier
	s_setprio 0
	s_add_i32 s58, s86, s63
	v_lshl_add_u64 v[182:183], v[182:183], 0, s[22:23]
	s_mov_b32 m0, s58
	ds_read_b128 v[198:201], v154 offset:49152
	v_xor_b32_e32 v253, 64, v154
	ds_read_b128 v[202:205], v253 offset:49152
	ds_read_b128 v[206:209], v154 offset:51200
	ds_read_b128 v[210:213], v253 offset:51200
	ds_read_b128 v[214:217], v154 offset:53248
	ds_read_b128 v[218:221], v253 offset:53248
	ds_read_b128 v[222:225], v154 offset:55296
	ds_read_b128 v[226:229], v253 offset:55296
	global_load_lds_dwordx4 v[182:183], off
	s_add_i32 m0, s58, 0x2000
	s_add_u32 s56, s56, 0x40080
	v_lshl_add_u64 v[182:183], v[230:231], 0, s[22:23]
	s_addc_u32 s57, s57, 0
	s_add_i32 s58, s87, s63
	global_load_lds_dwordx4 v[182:183], off
	v_lshl_add_u64 v[182:183], s[56:57], 0, v[130:131]
	s_mov_b32 m0, s58
	s_nop 0
	global_load_lds_dwordx4 v[182:183], off
	v_lshl_add_u64 v[182:183], s[56:57], 0, v[134:135]
	s_add_i32 m0, s58, 0x2000
	s_nop 0
	global_load_lds_dwordx4 v[182:183], off
	v_lshl_add_u64 v[182:183], v[232:233], 0, s[22:23]
	s_mov_b32 m0, s69
	s_nop 0
	global_load_lds_dwordx4 v[182:183], off
	v_lshl_add_u64 v[182:183], v[234:235], 0, s[22:23]
	s_mov_b32 m0, s70
	s_nop 0
	global_load_lds_dwordx4 v[182:183], off
	s_waitcnt vmcnt(8)
	s_waitcnt lgkmcnt(0)
	s_setprio 1
	s_barrier
	v_mfma_f32_16x16x32_bf16 v[60:63], v[162:165], v[198:201], v[60:63]
	v_mfma_f32_16x16x32_bf16 v[60:63], v[166:169], v[202:205], v[60:63]
	v_mfma_f32_16x16x32_bf16 v[56:59], v[174:177], v[202:205], v[56:59]
	v_mfma_f32_16x16x32_bf16 v[56:59], v[170:173], v[198:201], v[56:59]
	v_mfma_f32_16x16x32_bf16 v[40:43], v[170:173], v[206:209], v[40:43]
	v_mfma_f32_16x16x32_bf16 v[40:43], v[174:177], v[210:213], v[40:43]
	v_mfma_f32_16x16x32_bf16 v[48:51], v[166:169], v[210:213], v[48:51]
	v_mfma_f32_16x16x32_bf16 v[48:51], v[162:165], v[206:209], v[48:51]
	v_mfma_f32_16x16x32_bf16 v[32:35], v[162:165], v[214:217], v[32:35]
	v_mfma_f32_16x16x32_bf16 v[32:35], v[166:169], v[218:221], v[32:35]
	v_mfma_f32_16x16x32_bf16 v[24:27], v[174:177], v[218:221], v[24:27]
	v_mfma_f32_16x16x32_bf16 v[24:27], v[170:173], v[214:217], v[24:27]
	v_mfma_f32_16x16x32_bf16 v[8:11], v[170:173], v[222:225], v[8:11]
	v_mfma_f32_16x16x32_bf16 v[8:11], v[174:177], v[226:229], v[8:11]
	v_mfma_f32_16x16x32_bf16 v[16:19], v[166:169], v[226:229], v[16:19]
	v_mfma_f32_16x16x32_bf16 v[16:19], v[162:165], v[222:225], v[16:19]
	v_mfma_f32_16x16x32_bf16 v[52:55], v[178:181], v[198:201], v[52:55]
	v_mfma_f32_16x16x32_bf16 v[52:55], v[186:189], v[202:205], v[52:55]
	v_mfma_f32_16x16x32_bf16 v[44:47], v[194:197], v[202:205], v[44:47]
	v_mfma_f32_16x16x32_bf16 v[44:47], v[190:193], v[198:201], v[44:47]
	v_mfma_f32_16x16x32_bf16 v[28:31], v[190:193], v[206:209], v[28:31]
	v_mfma_f32_16x16x32_bf16 v[28:31], v[194:197], v[210:213], v[28:31]
	v_mfma_f32_16x16x32_bf16 v[36:39], v[186:189], v[210:213], v[36:39]
	v_mfma_f32_16x16x32_bf16 v[36:39], v[178:181], v[206:209], v[36:39]
	v_mfma_f32_16x16x32_bf16 v[20:23], v[178:181], v[214:217], v[20:23]
	v_mfma_f32_16x16x32_bf16 v[20:23], v[186:189], v[218:221], v[20:23]
	v_mfma_f32_16x16x32_bf16 v[12:15], v[194:197], v[218:221], v[12:15]
	v_mfma_f32_16x16x32_bf16 v[12:15], v[190:193], v[214:217], v[12:15]
	v_mfma_f32_16x16x32_bf16 v[0:3], v[190:193], v[222:225], v[0:3]
	v_mfma_f32_16x16x32_bf16 v[0:3], v[194:197], v[226:229], v[0:3]
	v_mfma_f32_16x16x32_bf16 v[4:7], v[186:189], v[226:229], v[4:7]
	v_mfma_f32_16x16x32_bf16 v[4:7], v[178:181], v[222:225], v[4:7]
	s_barrier
	s_setprio 0
	s_add_i32 s85, s85, 2
	s_add_u32 s83, s83, 0x100
	s_addc_u32 s84, s84, 0
	s_add_u32 s54, s54, 0x100
	s_addc_u32 s55, s55, 0
	s_cmp_gt_u32 s85, 13
	s_cbranch_scc1 .LBB0_877

.LBB0_1010:
	s_ashr_i32 s51, s50, 31
	s_lshl_b64 s[52:53], s[50:51], 19
	s_add_u32 s52, s33, s52
	s_addc_u32 s53, s35, s53
	s_and_b64 s[54:55], s[12:13], exec
	s_cselect_b32 s15, s53, s61
	s_cselect_b32 s51, s52, s60
	s_ashr_i32 s49, s48, 31
	s_lshl_b64 s[54:55], s[48:49], 19
	s_add_u32 s54, s64, s54
	s_addc_u32 s55, s65, s55
	s_and_b64 s[62:63], s[12:13], exec
	s_cselect_b32 s49, s55, s59
	s_cselect_b32 s57, s54, s58
	s_add_u32 s78, s58, 0x100
	s_addc_u32 s79, s59, 0
	s_add_u32 s58, s60, 0x40080
	s_addc_u32 s59, s61, 0
	s_mov_b32 s80, -2
	s_waitcnt lgkmcnt(0)
	s_cmp_eq_u32 s71, 1
	s_cbranch_scc1 .Lfa_9
	ds_read_b128 v[128:131], v188
	v_xor_b32_e32 v253, 64, v188
	ds_read_b128 v[132:135], v253
	ds_read_b128 v[136:139], v188 offset:2048
	ds_read_b128 v[140:143], v253 offset:2048
	ds_read_b128 v[144:147], v189
	v_xor_b32_e32 v253, 64, v189
	ds_read_b128 v[148:151], v253
	ds_read_b128 v[172:175], v189 offset:2048
	ds_read_b128 v[176:179], v253 offset:2048
	s_add_u32 s60, s58, 0xfffc0080
	s_addc_u32 s61, s59, -1
	s_cmp_eq_u32 s80, 12
	s_cselect_b32 s63, s15, s61
	s_cselect_b32 s62, s51, s60
	s_cselect_b32 s61, s49, s79
	s_cselect_b32 s60, s57, s78
	v_lshl_add_u64 v[220:221], s[58:59], 0, v[166:167]
	s_add_i32 m0, s67, 0xc000
	ds_read_b128 v[180:183], v190
	v_xor_b32_e32 v253, 64, v190
	ds_read_b128 v[192:195], v253
	ds_read_b128 v[196:199], v190 offset:2048
	ds_read_b128 v[200:203], v253 offset:2048
	ds_read_b128 v[204:207], v190 offset:4096
	ds_read_b128 v[208:211], v253 offset:4096
	ds_read_b128 v[212:215], v190 offset:6144
	ds_read_b128 v[216:219], v253 offset:6144
	global_load_lds_dwordx4 v[220:221], off
	v_lshl_add_u64 v[220:221], s[58:59], 0, v[164:165]
	s_add_i32 m0, s67, 0xe000
	s_nop 0
	global_load_lds_dwordx4 v[220:221], off
	s_waitcnt vmcnt(24)
	s_waitcnt lgkmcnt(0)
	s_setprio 1
	s_barrier
	v_mfma_f32_16x16x32_bf16 v[124:127], v[128:131], v[180:183], 0
	v_mfma_f32_16x16x32_bf16 v[120:123], v[136:139], v[180:183], 0
	v_mfma_f32_16x16x32_bf16 v[108:111], v[128:131], v[196:199], 0
	v_mfma_f32_16x16x32_bf16 v[104:107], v[136:139], v[196:199], 0
	v_mfma_f32_16x16x32_bf16 v[92:95], v[128:131], v[204:207], 0
	v_mfma_f32_16x16x32_bf16 v[88:91], v[136:139], v[204:207], 0
	v_mfma_f32_16x16x32_bf16 v[76:79], v[128:131], v[212:215], 0
	v_mfma_f32_16x16x32_bf16 v[72:75], v[136:139], v[212:215], 0
	v_mfma_f32_16x16x32_bf16 v[124:127], v[132:135], v[192:195], v[124:127]
	v_mfma_f32_16x16x32_bf16 v[120:123], v[140:143], v[192:195], v[120:123]
	v_mfma_f32_16x16x32_bf16 v[108:111], v[132:135], v[200:203], v[108:111]
	v_mfma_f32_16x16x32_bf16 v[104:107], v[140:143], v[200:203], v[104:107]
	v_mfma_f32_16x16x32_bf16 v[92:95], v[132:135], v[208:211], v[92:95]
	v_mfma_f32_16x16x32_bf16 v[88:91], v[140:143], v[208:211], v[88:91]
	v_mfma_f32_16x16x32_bf16 v[76:79], v[132:135], v[216:219], v[76:79]
	v_mfma_f32_16x16x32_bf16 v[72:75], v[140:143], v[216:219], v[72:75]
	v_mfma_f32_16x16x32_bf16 v[116:119], v[144:147], v[180:183], 0
	v_mfma_f32_16x16x32_bf16 v[112:115], v[172:175], v[180:183], 0
	v_mfma_f32_16x16x32_bf16 v[100:103], v[144:147], v[196:199], 0
	v_mfma_f32_16x16x32_bf16 v[96:99], v[172:175], v[196:199], 0
	v_mfma_f32_16x16x32_bf16 v[84:87], v[144:147], v[204:207], 0
	v_mfma_f32_16x16x32_bf16 v[80:83], v[172:175], v[204:207], 0
	v_mfma_f32_16x16x32_bf16 v[68:71], v[144:147], v[212:215], 0
	v_mfma_f32_16x16x32_bf16 v[64:67], v[172:175], v[212:215], 0
	v_mfma_f32_16x16x32_bf16 v[116:119], v[148:151], v[192:195], v[116:119]
	v_mfma_f32_16x16x32_bf16 v[112:115], v[176:179], v[192:195], v[112:115]
	v_mfma_f32_16x16x32_bf16 v[100:103], v[148:151], v[200:203], v[100:103]
	v_mfma_f32_16x16x32_bf16 v[96:99], v[176:179], v[200:203], v[96:99]
	v_mfma_f32_16x16x32_bf16 v[84:87], v[148:151], v[208:211], v[84:87]
	v_mfma_f32_16x16x32_bf16 v[80:83], v[176:179], v[208:211], v[80:83]
	v_mfma_f32_16x16x32_bf16 v[68:71], v[148:151], v[216:219], v[68:71]
	v_mfma_f32_16x16x32_bf16 v[64:67], v[176:179], v[216:219], v[64:67]
	s_barrier
	s_setprio 0
	s_add_i32 s81, s76, s66
	v_lshl_add_u64 v[220:221], s[60:61], 0, v[154:155]
	s_mov_b32 m0, s81
	ds_read_b128 v[180:183], v190 offset:16384
	v_xor_b32_e32 v253, 64, v190
	ds_read_b128 v[192:195], v253 offset:16384
	ds_read_b128 v[196:199], v190 offset:18432
	ds_read_b128 v[200:203], v253 offset:18432
	ds_read_b128 v[204:207], v190 offset:20480
	ds_read_b128 v[208:211], v253 offset:20480
	ds_read_b128 v[212:215], v190 offset:22528
	ds_read_b128 v[216:219], v253 offset:22528
	global_load_lds_dwordx4 v[220:221], off
	s_add_i32 m0, s81, 0x2000
	s_add_u32 s82, s60, 0x40000
	v_lshl_add_u64 v[222:223], s[60:61], 0, v[162:163]
	s_addc_u32 s83, s61, 0
	s_add_i32 s81, s77, s66
	global_load_lds_dwordx4 v[222:223], off
	v_lshl_add_u64 v[224:225], s[82:83], 0, v[154:155]
	s_mov_b32 m0, s81
	v_lshl_add_u64 v[226:227], s[62:63], 0, v[160:161]
	global_load_lds_dwordx4 v[224:225], off
	v_lshl_add_u64 v[224:225], s[82:83], 0, v[162:163]
	s_add_i32 m0, s81, 0x2000
	s_nop 0
	global_load_lds_dwordx4 v[224:225], off
	v_lshl_add_u64 v[224:225], s[62:63], 0, v[152:153]
	s_mov_b32 m0, s67
	s_nop 0
	global_load_lds_dwordx4 v[224:225], off
	s_mov_b32 m0, s68
	s_nop 0
	global_load_lds_dwordx4 v[226:227], off
	s_waitcnt vmcnt(24)
	s_waitcnt lgkmcnt(0)
	s_setprio 1
	s_barrier
	v_mfma_f32_16x16x32_bf16 v[60:63], v[128:131], v[180:183], 0
	v_mfma_f32_16x16x32_bf16 v[56:59], v[136:139], v[180:183], 0
	v_mfma_f32_16x16x32_bf16 v[44:47], v[128:131], v[196:199], 0
	v_mfma_f32_16x16x32_bf16 v[40:43], v[136:139], v[196:199], 0
	v_mfma_f32_16x16x32_bf16 v[28:31], v[128:131], v[204:207], 0
	v_mfma_f32_16x16x32_bf16 v[24:27], v[136:139], v[204:207], 0
	v_mfma_f32_16x16x32_bf16 v[12:15], v[128:131], v[212:215], 0
	v_mfma_f32_16x16x32_bf16 v[8:11], v[136:139], v[212:215], 0
	v_mfma_f32_16x16x32_bf16 v[60:63], v[132:135], v[192:195], v[60:63]
	v_mfma_f32_16x16x32_bf16 v[56:59], v[140:143], v[192:195], v[56:59]
	v_mfma_f32_16x16x32_bf16 v[44:47], v[132:135], v[200:203], v[44:47]
	v_mfma_f32_16x16x32_bf16 v[40:43], v[140:143], v[200:203], v[40:43]
	v_mfma_f32_16x16x32_bf16 v[28:31], v[132:135], v[208:211], v[28:31]
	v_mfma_f32_16x16x32_bf16 v[24:27], v[140:143], v[208:211], v[24:27]
	v_mfma_f32_16x16x32_bf16 v[12:15], v[132:135], v[216:219], v[12:15]
	v_mfma_f32_16x16x32_bf16 v[8:11], v[140:143], v[216:219], v[8:11]
	v_mfma_f32_16x16x32_bf16 v[52:55], v[144:147], v[180:183], 0
	v_mfma_f32_16x16x32_bf16 v[48:51], v[172:175], v[180:183], 0
	v_mfma_f32_16x16x32_bf16 v[36:39], v[144:147], v[196:199], 0
	v_mfma_f32_16x16x32_bf16 v[32:35], v[172:175], v[196:199], 0
	v_mfma_f32_16x16x32_bf16 v[20:23], v[144:147], v[204:207], 0
	v_mfma_f32_16x16x32_bf16 v[16:19], v[172:175], v[204:207], 0
	v_mfma_f32_16x16x32_bf16 v[4:7], v[144:147], v[212:215], 0
	v_mfma_f32_16x16x32_bf16 v[0:3], v[172:175], v[212:215], 0
	v_mfma_f32_16x16x32_bf16 v[52:55], v[148:151], v[192:195], v[52:55]
	v_mfma_f32_16x16x32_bf16 v[48:51], v[176:179], v[192:195], v[48:51]
	v_mfma_f32_16x16x32_bf16 v[36:39], v[148:151], v[200:203], v[36:39]
	v_mfma_f32_16x16x32_bf16 v[32:35], v[176:179], v[200:203], v[32:35]
	v_mfma_f32_16x16x32_bf16 v[20:23], v[148:151], v[208:211], v[20:23]
	v_mfma_f32_16x16x32_bf16 v[16:19], v[176:179], v[208:211], v[16:19]
	v_mfma_f32_16x16x32_bf16 v[4:7], v[148:151], v[216:219], v[4:7]
	v_mfma_f32_16x16x32_bf16 v[0:3], v[176:179], v[216:219], v[0:3]
	s_barrier
	s_setprio 0
	s_add_i32 s81, 0, 0x18000
	s_add_i32 s82, 0, 0x1c000
	v_add_u32_e32 v140, s81, v185
	v_add_u32_e32 v176, s82, v185
	ds_read_b128 v[128:131], v140
	v_xor_b32_e32 v253, 64, v140
	ds_read_b128 v[132:135], v253
	ds_read_b128 v[136:139], v140 offset:2048
	ds_read_b128 v[140:143], v253 offset:2048
	ds_read_b128 v[144:147], v176
	v_xor_b32_e32 v253, 64, v176
	ds_read_b128 v[148:151], v253
	ds_read_b128 v[172:175], v176 offset:2048
	ds_read_b128 v[176:179], v253 offset:2048
	s_add_u32 s62, s62, 0x40000
	s_addc_u32 s63, s63, 0
	s_mov_b32 m0, s69
	v_lshl_add_u64 v[228:229], s[62:63], 0, v[152:153]
	ds_read_b128 v[180:183], v190 offset:32768
	v_xor_b32_e32 v253, 64, v190
	ds_read_b128 v[192:195], v253 offset:32768
	ds_read_b128 v[196:199], v190 offset:34816
	ds_read_b128 v[200:203], v253 offset:34816
	ds_read_b128 v[204:207], v190 offset:36864
	ds_read_b128 v[208:211], v253 offset:36864
	ds_read_b128 v[212:215], v190 offset:38912
	ds_read_b128 v[216:219], v253 offset:38912
	global_load_lds_dwordx4 v[228:229], off
	v_lshl_add_u64 v[228:229], s[62:63], 0, v[160:161]
	s_mov_b32 m0, s70
	s_nop 0
	global_load_lds_dwordx4 v[228:229], off
	s_waitcnt vmcnt(8)
	s_waitcnt lgkmcnt(0)
	s_setprio 1
	s_barrier
	v_mfma_f32_16x16x32_bf16 v[124:127], v[128:131], v[180:183], v[124:127]
	v_mfma_f32_16x16x32_bf16 v[124:127], v[132:135], v[192:195], v[124:127]
	v_mfma_f32_16x16x32_bf16 v[120:123], v[140:143], v[192:195], v[120:123]
	v_mfma_f32_16x16x32_bf16 v[120:123], v[136:139], v[180:183], v[120:123]
	v_mfma_f32_16x16x32_bf16 v[104:107], v[136:139], v[196:199], v[104:107]
	v_mfma_f32_16x16x32_bf16 v[104:107], v[140:143], v[200:203], v[104:107]
	v_mfma_f32_16x16x32_bf16 v[108:111], v[132:135], v[200:203], v[108:111]
	v_mfma_f32_16x16x32_bf16 v[108:111], v[128:131], v[196:199], v[108:111]
	v_mfma_f32_16x16x32_bf16 v[92:95], v[128:131], v[204:207], v[92:95]
	v_mfma_f32_16x16x32_bf16 v[92:95], v[132:135], v[208:211], v[92:95]
	v_mfma_f32_16x16x32_bf16 v[88:91], v[140:143], v[208:211], v[88:91]
	v_mfma_f32_16x16x32_bf16 v[88:91], v[136:139], v[204:207], v[88:91]
	v_mfma_f32_16x16x32_bf16 v[72:75], v[136:139], v[212:215], v[72:75]
	v_mfma_f32_16x16x32_bf16 v[72:75], v[140:143], v[216:219], v[72:75]
	v_mfma_f32_16x16x32_bf16 v[76:79], v[132:135], v[216:219], v[76:79]
	v_mfma_f32_16x16x32_bf16 v[76:79], v[128:131], v[212:215], v[76:79]
	v_mfma_f32_16x16x32_bf16 v[116:119], v[144:147], v[180:183], v[116:119]
	v_mfma_f32_16x16x32_bf16 v[116:119], v[148:151], v[192:195], v[116:119]
	v_mfma_f32_16x16x32_bf16 v[112:115], v[176:179], v[192:195], v[112:115]
	v_mfma_f32_16x16x32_bf16 v[112:115], v[172:175], v[180:183], v[112:115]
	v_mfma_f32_16x16x32_bf16 v[96:99], v[172:175], v[196:199], v[96:99]
	v_mfma_f32_16x16x32_bf16 v[96:99], v[176:179], v[200:203], v[96:99]
	v_mfma_f32_16x16x32_bf16 v[100:103], v[148:151], v[200:203], v[100:103]
	v_mfma_f32_16x16x32_bf16 v[100:103], v[144:147], v[196:199], v[100:103]
	v_mfma_f32_16x16x32_bf16 v[84:87], v[144:147], v[204:207], v[84:87]
	v_mfma_f32_16x16x32_bf16 v[84:87], v[148:151], v[208:211], v[84:87]
	v_mfma_f32_16x16x32_bf16 v[80:83], v[176:179], v[208:211], v[80:83]
	v_mfma_f32_16x16x32_bf16 v[80:83], v[172:175], v[204:207], v[80:83]
	v_mfma_f32_16x16x32_bf16 v[64:67], v[172:175], v[212:215], v[64:67]
	v_mfma_f32_16x16x32_bf16 v[64:67], v[176:179], v[216:219], v[64:67]
	v_mfma_f32_16x16x32_bf16 v[68:71], v[148:151], v[216:219], v[68:71]
	v_mfma_f32_16x16x32_bf16 v[68:71], v[144:147], v[212:215], v[68:71]
	s_barrier
	s_setprio 0
	s_add_i32 s62, s81, s66
	v_lshl_add_u64 v[220:221], v[220:221], 0, s[26:27]
	s_mov_b32 m0, s62
	ds_read_b128 v[180:183], v190 offset:49152
	v_xor_b32_e32 v253, 64, v190
	ds_read_b128 v[192:195], v253 offset:49152
	ds_read_b128 v[196:199], v190 offset:51200
	ds_read_b128 v[200:203], v253 offset:51200
	ds_read_b128 v[204:207], v190 offset:53248
	ds_read_b128 v[208:211], v253 offset:53248
	ds_read_b128 v[212:215], v190 offset:55296
	ds_read_b128 v[216:219], v253 offset:55296
	global_load_lds_dwordx4 v[220:221], off
	s_add_i32 m0, s62, 0x2000
	s_add_u32 s60, s60, 0x40080
	v_lshl_add_u64 v[220:221], v[222:223], 0, s[26:27]
	s_addc_u32 s61, s61, 0
	s_add_i32 s62, s82, s66
	global_load_lds_dwordx4 v[220:221], off
	v_lshl_add_u64 v[220:221], s[60:61], 0, v[154:155]
	s_mov_b32 m0, s62
	s_nop 0
	global_load_lds_dwordx4 v[220:221], off
	v_lshl_add_u64 v[220:221], s[60:61], 0, v[162:163]
	s_add_i32 m0, s62, 0x2000
	s_nop 0
	global_load_lds_dwordx4 v[220:221], off
	v_lshl_add_u64 v[220:221], v[224:225], 0, s[26:27]
	s_mov_b32 m0, s3
	s_nop 0
	global_load_lds_dwordx4 v[220:221], off
	v_lshl_add_u64 v[220:221], v[226:227], 0, s[26:27]
	s_mov_b32 m0, s72
	s_nop 0
	global_load_lds_dwordx4 v[220:221], off
	s_waitcnt vmcnt(8)
	s_waitcnt lgkmcnt(0)
	s_setprio 1
	s_barrier
	v_mfma_f32_16x16x32_bf16 v[60:63], v[128:131], v[180:183], v[60:63]
	v_mfma_f32_16x16x32_bf16 v[60:63], v[132:135], v[192:195], v[60:63]
	v_mfma_f32_16x16x32_bf16 v[56:59], v[140:143], v[192:195], v[56:59]
	v_mfma_f32_16x16x32_bf16 v[56:59], v[136:139], v[180:183], v[56:59]
	v_mfma_f32_16x16x32_bf16 v[40:43], v[136:139], v[196:199], v[40:43]
	v_mfma_f32_16x16x32_bf16 v[40:43], v[140:143], v[200:203], v[40:43]
	v_mfma_f32_16x16x32_bf16 v[44:47], v[132:135], v[200:203], v[44:47]
	v_mfma_f32_16x16x32_bf16 v[44:47], v[128:131], v[196:199], v[44:47]
	v_mfma_f32_16x16x32_bf16 v[28:31], v[128:131], v[204:207], v[28:31]
	v_mfma_f32_16x16x32_bf16 v[28:31], v[132:135], v[208:211], v[28:31]
	v_mfma_f32_16x16x32_bf16 v[24:27], v[140:143], v[208:211], v[24:27]
	v_mfma_f32_16x16x32_bf16 v[24:27], v[136:139], v[204:207], v[24:27]
	v_mfma_f32_16x16x32_bf16 v[8:11], v[136:139], v[212:215], v[8:11]
	v_mfma_f32_16x16x32_bf16 v[8:11], v[140:143], v[216:219], v[8:11]
	v_mfma_f32_16x16x32_bf16 v[12:15], v[132:135], v[216:219], v[12:15]
	v_mfma_f32_16x16x32_bf16 v[12:15], v[128:131], v[212:215], v[12:15]
	v_mfma_f32_16x16x32_bf16 v[52:55], v[144:147], v[180:183], v[52:55]
	v_mfma_f32_16x16x32_bf16 v[52:55], v[148:151], v[192:195], v[52:55]
	v_mfma_f32_16x16x32_bf16 v[48:51], v[176:179], v[192:195], v[48:51]
	v_mfma_f32_16x16x32_bf16 v[48:51], v[172:175], v[180:183], v[48:51]
	v_mfma_f32_16x16x32_bf16 v[32:35], v[172:175], v[196:199], v[32:35]
	v_mfma_f32_16x16x32_bf16 v[32:35], v[176:179], v[200:203], v[32:35]
	v_mfma_f32_16x16x32_bf16 v[36:39], v[148:151], v[200:203], v[36:39]
	v_mfma_f32_16x16x32_bf16 v[36:39], v[144:147], v[196:199], v[36:39]
	v_mfma_f32_16x16x32_bf16 v[20:23], v[144:147], v[204:207], v[20:23]
	v_mfma_f32_16x16x32_bf16 v[20:23], v[148:151], v[208:211], v[20:23]
	v_mfma_f32_16x16x32_bf16 v[16:19], v[176:179], v[208:211], v[16:19]
	v_mfma_f32_16x16x32_bf16 v[16:19], v[172:175], v[204:207], v[16:19]
	v_mfma_f32_16x16x32_bf16 v[0:3], v[172:175], v[212:215], v[0:3]
	v_mfma_f32_16x16x32_bf16 v[0:3], v[176:179], v[216:219], v[0:3]
	v_mfma_f32_16x16x32_bf16 v[4:7], v[148:151], v[216:219], v[4:7]
	v_mfma_f32_16x16x32_bf16 v[4:7], v[144:147], v[212:215], v[4:7]
	s_barrier
	s_setprio 0
	s_add_i32 s80, s80, 2
	s_add_u32 s78, s78, 0x100
	s_addc_u32 s79, s79, 0
	s_add_u32 s58, s58, 0x100
	s_addc_u32 s59, s59, 0
	s_cmp_gt_u32 s80, 13
	s_branch .LBB0_1011
.Lfa_9:
	ds_read_b128 v[128:131], v188
	v_xor_b32_e32 v253, 64, v188
	ds_read_b128 v[132:135], v253
	ds_read_b128 v[136:139], v188 offset:2048
	ds_read_b128 v[140:143], v253 offset:2048
	ds_read_b128 v[144:147], v189
	v_xor_b32_e32 v253, 64, v189
	ds_read_b128 v[148:151], v253
	ds_read_b128 v[172:175], v189 offset:2048
	ds_read_b128 v[176:179], v253 offset:2048
	s_add_u32 s60, s58, 0xfffc0080
	s_addc_u32 s61, s59, -1
	s_cmp_eq_u32 s80, 12
	s_cselect_b32 s63, s15, s61
	s_cselect_b32 s62, s51, s60
	s_cselect_b32 s61, s49, s79
	s_cselect_b32 s60, s57, s78
	v_lshl_add_u64 v[220:221], s[58:59], 0, v[166:167]
	s_add_i32 m0, s67, 0xc000
	ds_read_b128 v[180:183], v190
	v_xor_b32_e32 v253, 64, v190
	ds_read_b128 v[192:195], v253
	ds_read_b128 v[196:199], v190 offset:2048
	ds_read_b128 v[200:203], v253 offset:2048
	ds_read_b128 v[204:207], v190 offset:4096
	ds_read_b128 v[208:211], v253 offset:4096
	ds_read_b128 v[212:215], v190 offset:6144
	ds_read_b128 v[216:219], v253 offset:6144
	global_load_lds_dwordx4 v[220:221], off
	v_lshl_add_u64 v[220:221], s[58:59], 0, v[164:165]
	s_add_i32 m0, s67, 0xe000
	s_nop 0
	global_load_lds_dwordx4 v[220:221], off
	s_waitcnt vmcnt(8)
	s_waitcnt lgkmcnt(0)
	s_setprio 1
	s_barrier
	v_mfma_f32_16x16x32_bf16 v[124:127], v[128:131], v[180:183], 0
	v_mfma_f32_16x16x32_bf16 v[120:123], v[136:139], v[180:183], 0
	v_mfma_f32_16x16x32_bf16 v[108:111], v[128:131], v[196:199], 0
	v_mfma_f32_16x16x32_bf16 v[104:107], v[136:139], v[196:199], 0
	v_mfma_f32_16x16x32_bf16 v[92:95], v[128:131], v[204:207], 0
	v_mfma_f32_16x16x32_bf16 v[88:91], v[136:139], v[204:207], 0
	v_mfma_f32_16x16x32_bf16 v[76:79], v[128:131], v[212:215], 0
	v_mfma_f32_16x16x32_bf16 v[72:75], v[136:139], v[212:215], 0
	v_mfma_f32_16x16x32_bf16 v[124:127], v[132:135], v[192:195], v[124:127]
	v_mfma_f32_16x16x32_bf16 v[120:123], v[140:143], v[192:195], v[120:123]
	v_mfma_f32_16x16x32_bf16 v[108:111], v[132:135], v[200:203], v[108:111]
	v_mfma_f32_16x16x32_bf16 v[104:107], v[140:143], v[200:203], v[104:107]
	v_mfma_f32_16x16x32_bf16 v[92:95], v[132:135], v[208:211], v[92:95]
	v_mfma_f32_16x16x32_bf16 v[88:91], v[140:143], v[208:211], v[88:91]
	v_mfma_f32_16x16x32_bf16 v[76:79], v[132:135], v[216:219], v[76:79]
	v_mfma_f32_16x16x32_bf16 v[72:75], v[140:143], v[216:219], v[72:75]
	v_mfma_f32_16x16x32_bf16 v[116:119], v[144:147], v[180:183], 0
	v_mfma_f32_16x16x32_bf16 v[112:115], v[172:175], v[180:183], 0
	v_mfma_f32_16x16x32_bf16 v[100:103], v[144:147], v[196:199], 0
	v_mfma_f32_16x16x32_bf16 v[96:99], v[172:175], v[196:199], 0
	v_mfma_f32_16x16x32_bf16 v[84:87], v[144:147], v[204:207], 0
	v_mfma_f32_16x16x32_bf16 v[80:83], v[172:175], v[204:207], 0
	v_mfma_f32_16x16x32_bf16 v[68:71], v[144:147], v[212:215], 0
	v_mfma_f32_16x16x32_bf16 v[64:67], v[172:175], v[212:215], 0
	v_mfma_f32_16x16x32_bf16 v[116:119], v[148:151], v[192:195], v[116:119]
	v_mfma_f32_16x16x32_bf16 v[112:115], v[176:179], v[192:195], v[112:115]
	v_mfma_f32_16x16x32_bf16 v[100:103], v[148:151], v[200:203], v[100:103]
	v_mfma_f32_16x16x32_bf16 v[96:99], v[176:179], v[200:203], v[96:99]
	v_mfma_f32_16x16x32_bf16 v[84:87], v[148:151], v[208:211], v[84:87]
	v_mfma_f32_16x16x32_bf16 v[80:83], v[176:179], v[208:211], v[80:83]
	v_mfma_f32_16x16x32_bf16 v[68:71], v[148:151], v[216:219], v[68:71]
	v_mfma_f32_16x16x32_bf16 v[64:67], v[176:179], v[216:219], v[64:67]
	s_barrier
	s_setprio 0
	s_add_i32 s81, s76, s66
	v_lshl_add_u64 v[220:221], s[60:61], 0, v[154:155]
	s_mov_b32 m0, s81
	ds_read_b128 v[180:183], v190 offset:16384
	v_xor_b32_e32 v253, 64, v190
	ds_read_b128 v[192:195], v253 offset:16384
	ds_read_b128 v[196:199], v190 offset:18432
	ds_read_b128 v[200:203], v253 offset:18432
	ds_read_b128 v[204:207], v190 offset:20480
	ds_read_b128 v[208:211], v253 offset:20480
	ds_read_b128 v[212:215], v190 offset:22528
	ds_read_b128 v[216:219], v253 offset:22528
	global_load_lds_dwordx4 v[220:221], off
	s_add_i32 m0, s81, 0x2000
	s_add_u32 s82, s60, 0x40000
	v_lshl_add_u64 v[222:223], s[60:61], 0, v[162:163]
	s_addc_u32 s83, s61, 0
	s_add_i32 s81, s77, s66
	global_load_lds_dwordx4 v[222:223], off
	v_lshl_add_u64 v[224:225], s[82:83], 0, v[154:155]
	s_mov_b32 m0, s81
	v_lshl_add_u64 v[226:227], s[62:63], 0, v[160:161]
	global_load_lds_dwordx4 v[224:225], off
	v_lshl_add_u64 v[224:225], s[82:83], 0, v[162:163]
	s_add_i32 m0, s81, 0x2000
	s_nop 0
	global_load_lds_dwordx4 v[224:225], off
	v_lshl_add_u64 v[224:225], s[62:63], 0, v[152:153]
	s_mov_b32 m0, s67
	s_nop 0
	global_load_lds_dwordx4 v[224:225], off
	s_mov_b32 m0, s68
	s_nop 0
	global_load_lds_dwordx4 v[226:227], off
	s_waitcnt vmcnt(8)
	s_waitcnt lgkmcnt(0)
	s_setprio 1
	s_barrier
	v_mfma_f32_16x16x32_bf16 v[60:63], v[128:131], v[180:183], 0
	v_mfma_f32_16x16x32_bf16 v[56:59], v[136:139], v[180:183], 0
	v_mfma_f32_16x16x32_bf16 v[44:47], v[128:131], v[196:199], 0
	v_mfma_f32_16x16x32_bf16 v[40:43], v[136:139], v[196:199], 0
	v_mfma_f32_16x16x32_bf16 v[28:31], v[128:131], v[204:207], 0
	v_mfma_f32_16x16x32_bf16 v[24:27], v[136:139], v[204:207], 0
	v_mfma_f32_16x16x32_bf16 v[12:15], v[128:131], v[212:215], 0
	v_mfma_f32_16x16x32_bf16 v[8:11], v[136:139], v[212:215], 0
	v_mfma_f32_16x16x32_bf16 v[60:63], v[132:135], v[192:195], v[60:63]
	v_mfma_f32_16x16x32_bf16 v[56:59], v[140:143], v[192:195], v[56:59]
	v_mfma_f32_16x16x32_bf16 v[44:47], v[132:135], v[200:203], v[44:47]
	v_mfma_f32_16x16x32_bf16 v[40:43], v[140:143], v[200:203], v[40:43]
	v_mfma_f32_16x16x32_bf16 v[28:31], v[132:135], v[208:211], v[28:31]
	v_mfma_f32_16x16x32_bf16 v[24:27], v[140:143], v[208:211], v[24:27]
	v_mfma_f32_16x16x32_bf16 v[12:15], v[132:135], v[216:219], v[12:15]
	v_mfma_f32_16x16x32_bf16 v[8:11], v[140:143], v[216:219], v[8:11]
	v_mfma_f32_16x16x32_bf16 v[52:55], v[144:147], v[180:183], 0
	v_mfma_f32_16x16x32_bf16 v[48:51], v[172:175], v[180:183], 0
	v_mfma_f32_16x16x32_bf16 v[36:39], v[144:147], v[196:199], 0
	v_mfma_f32_16x16x32_bf16 v[32:35], v[172:175], v[196:199], 0
	v_mfma_f32_16x16x32_bf16 v[20:23], v[144:147], v[204:207], 0
	v_mfma_f32_16x16x32_bf16 v[16:19], v[172:175], v[204:207], 0
	v_mfma_f32_16x16x32_bf16 v[4:7], v[144:147], v[212:215], 0
	v_mfma_f32_16x16x32_bf16 v[0:3], v[172:175], v[212:215], 0
	v_mfma_f32_16x16x32_bf16 v[52:55], v[148:151], v[192:195], v[52:55]
	v_mfma_f32_16x16x32_bf16 v[48:51], v[176:179], v[192:195], v[48:51]
	v_mfma_f32_16x16x32_bf16 v[36:39], v[148:151], v[200:203], v[36:39]
	v_mfma_f32_16x16x32_bf16 v[32:35], v[176:179], v[200:203], v[32:35]
	v_mfma_f32_16x16x32_bf16 v[20:23], v[148:151], v[208:211], v[20:23]
	v_mfma_f32_16x16x32_bf16 v[16:19], v[176:179], v[208:211], v[16:19]
	v_mfma_f32_16x16x32_bf16 v[4:7], v[148:151], v[216:219], v[4:7]
	v_mfma_f32_16x16x32_bf16 v[0:3], v[176:179], v[216:219], v[0:3]
	s_barrier
	s_setprio 0
	s_add_i32 s81, 0, 0x18000
	s_add_i32 s82, 0, 0x1c000
	v_add_u32_e32 v140, s81, v185
	v_add_u32_e32 v176, s82, v185
	ds_read_b128 v[128:131], v140
	v_xor_b32_e32 v253, 64, v140
	ds_read_b128 v[132:135], v253
	ds_read_b128 v[136:139], v140 offset:2048
	ds_read_b128 v[140:143], v253 offset:2048
	ds_read_b128 v[144:147], v176
	v_xor_b32_e32 v253, 64, v176
	ds_read_b128 v[148:151], v253
	ds_read_b128 v[172:175], v176 offset:2048
	ds_read_b128 v[176:179], v253 offset:2048
	s_add_u32 s62, s62, 0x40000
	s_addc_u32 s63, s63, 0
	s_mov_b32 m0, s69
	v_lshl_add_u64 v[228:229], s[62:63], 0, v[152:153]
	ds_read_b128 v[180:183], v190 offset:32768
	v_xor_b32_e32 v253, 64, v190
	ds_read_b128 v[192:195], v253 offset:32768
	ds_read_b128 v[196:199], v190 offset:34816
	ds_read_b128 v[200:203], v253 offset:34816
	ds_read_b128 v[204:207], v190 offset:36864
	ds_read_b128 v[208:211], v253 offset:36864
	ds_read_b128 v[212:215], v190 offset:38912
	ds_read_b128 v[216:219], v253 offset:38912
	global_load_lds_dwordx4 v[228:229], off
	v_lshl_add_u64 v[228:229], s[62:63], 0, v[160:161]
	s_mov_b32 m0, s70
	s_nop 0
	global_load_lds_dwordx4 v[228:229], off
	s_waitcnt vmcnt(8)
	s_waitcnt lgkmcnt(0)
	s_setprio 1
	s_barrier
	v_mfma_f32_16x16x32_bf16 v[124:127], v[128:131], v[180:183], v[124:127]
	v_mfma_f32_16x16x32_bf16 v[124:127], v[132:135], v[192:195], v[124:127]
	v_mfma_f32_16x16x32_bf16 v[120:123], v[140:143], v[192:195], v[120:123]
	v_mfma_f32_16x16x32_bf16 v[120:123], v[136:139], v[180:183], v[120:123]
	v_mfma_f32_16x16x32_bf16 v[104:107], v[136:139], v[196:199], v[104:107]
	v_mfma_f32_16x16x32_bf16 v[104:107], v[140:143], v[200:203], v[104:107]
	v_mfma_f32_16x16x32_bf16 v[108:111], v[132:135], v[200:203], v[108:111]
	v_mfma_f32_16x16x32_bf16 v[108:111], v[128:131], v[196:199], v[108:111]
	v_mfma_f32_16x16x32_bf16 v[92:95], v[128:131], v[204:207], v[92:95]
	v_mfma_f32_16x16x32_bf16 v[92:95], v[132:135], v[208:211], v[92:95]
	v_mfma_f32_16x16x32_bf16 v[88:91], v[140:143], v[208:211], v[88:91]
	v_mfma_f32_16x16x32_bf16 v[88:91], v[136:139], v[204:207], v[88:91]
	v_mfma_f32_16x16x32_bf16 v[72:75], v[136:139], v[212:215], v[72:75]
	v_mfma_f32_16x16x32_bf16 v[72:75], v[140:143], v[216:219], v[72:75]
	v_mfma_f32_16x16x32_bf16 v[76:79], v[132:135], v[216:219], v[76:79]
	v_mfma_f32_16x16x32_bf16 v[76:79], v[128:131], v[212:215], v[76:79]
	v_mfma_f32_16x16x32_bf16 v[116:119], v[144:147], v[180:183], v[116:119]
	v_mfma_f32_16x16x32_bf16 v[116:119], v[148:151], v[192:195], v[116:119]
	v_mfma_f32_16x16x32_bf16 v[112:115], v[176:179], v[192:195], v[112:115]
	v_mfma_f32_16x16x32_bf16 v[112:115], v[172:175], v[180:183], v[112:115]
	v_mfma_f32_16x16x32_bf16 v[96:99], v[172:175], v[196:199], v[96:99]
	v_mfma_f32_16x16x32_bf16 v[96:99], v[176:179], v[200:203], v[96:99]
	v_mfma_f32_16x16x32_bf16 v[100:103], v[148:151], v[200:203], v[100:103]
	v_mfma_f32_16x16x32_bf16 v[100:103], v[144:147], v[196:199], v[100:103]
	v_mfma_f32_16x16x32_bf16 v[84:87], v[144:147], v[204:207], v[84:87]
	v_mfma_f32_16x16x32_bf16 v[84:87], v[148:151], v[208:211], v[84:87]
	v_mfma_f32_16x16x32_bf16 v[80:83], v[176:179], v[208:211], v[80:83]
	v_mfma_f32_16x16x32_bf16 v[80:83], v[172:175], v[204:207], v[80:83]
	v_mfma_f32_16x16x32_bf16 v[64:67], v[172:175], v[212:215], v[64:67]
	v_mfma_f32_16x16x32_bf16 v[64:67], v[176:179], v[216:219], v[64:67]
	v_mfma_f32_16x16x32_bf16 v[68:71], v[148:151], v[216:219], v[68:71]
	v_mfma_f32_16x16x32_bf16 v[68:71], v[144:147], v[212:215], v[68:71]
	s_barrier
	s_setprio 0
	s_add_i32 s62, s81, s66
	v_lshl_add_u64 v[220:221], v[220:221], 0, s[26:27]
	s_mov_b32 m0, s62
	ds_read_b128 v[180:183], v190 offset:49152
	v_xor_b32_e32 v253, 64, v190
	ds_read_b128 v[192:195], v253 offset:49152
	ds_read_b128 v[196:199], v190 offset:51200
	ds_read_b128 v[200:203], v253 offset:51200
	ds_read_b128 v[204:207], v190 offset:53248
	ds_read_b128 v[208:211], v253 offset:53248
	ds_read_b128 v[212:215], v190 offset:55296
	ds_read_b128 v[216:219], v253 offset:55296
	global_load_lds_dwordx4 v[220:221], off
	s_add_i32 m0, s62, 0x2000
	s_add_u32 s60, s60, 0x40080
	v_lshl_add_u64 v[220:221], v[222:223], 0, s[26:27]
	s_addc_u32 s61, s61, 0
	s_add_i32 s62, s82, s66
	global_load_lds_dwordx4 v[220:221], off
	v_lshl_add_u64 v[220:221], s[60:61], 0, v[154:155]
	s_mov_b32 m0, s62
	s_nop 0
	global_load_lds_dwordx4 v[220:221], off
	v_lshl_add_u64 v[220:221], s[60:61], 0, v[162:163]
	s_add_i32 m0, s62, 0x2000
	s_nop 0
	global_load_lds_dwordx4 v[220:221], off
	v_lshl_add_u64 v[220:221], v[224:225], 0, s[26:27]
	s_mov_b32 m0, s3
	s_nop 0
	global_load_lds_dwordx4 v[220:221], off
	v_lshl_add_u64 v[220:221], v[226:227], 0, s[26:27]
	s_mov_b32 m0, s72
	s_nop 0
	global_load_lds_dwordx4 v[220:221], off
	s_waitcnt vmcnt(8)
	s_waitcnt lgkmcnt(0)
	s_setprio 1
	s_barrier
	v_mfma_f32_16x16x32_bf16 v[60:63], v[128:131], v[180:183], v[60:63]
	v_mfma_f32_16x16x32_bf16 v[60:63], v[132:135], v[192:195], v[60:63]
	v_mfma_f32_16x16x32_bf16 v[56:59], v[140:143], v[192:195], v[56:59]
	v_mfma_f32_16x16x32_bf16 v[56:59], v[136:139], v[180:183], v[56:59]
	v_mfma_f32_16x16x32_bf16 v[40:43], v[136:139], v[196:199], v[40:43]
	v_mfma_f32_16x16x32_bf16 v[40:43], v[140:143], v[200:203], v[40:43]
	v_mfma_f32_16x16x32_bf16 v[44:47], v[132:135], v[200:203], v[44:47]
	v_mfma_f32_16x16x32_bf16 v[44:47], v[128:131], v[196:199], v[44:47]
	v_mfma_f32_16x16x32_bf16 v[28:31], v[128:131], v[204:207], v[28:31]
	v_mfma_f32_16x16x32_bf16 v[28:31], v[132:135], v[208:211], v[28:31]
	v_mfma_f32_16x16x32_bf16 v[24:27], v[140:143], v[208:211], v[24:27]
	v_mfma_f32_16x16x32_bf16 v[24:27], v[136:139], v[204:207], v[24:27]
	v_mfma_f32_16x16x32_bf16 v[8:11], v[136:139], v[212:215], v[8:11]
	v_mfma_f32_16x16x32_bf16 v[8:11], v[140:143], v[216:219], v[8:11]
	v_mfma_f32_16x16x32_bf16 v[12:15], v[132:135], v[216:219], v[12:15]
	v_mfma_f32_16x16x32_bf16 v[12:15], v[128:131], v[212:215], v[12:15]
	v_mfma_f32_16x16x32_bf16 v[52:55], v[144:147], v[180:183], v[52:55]
	v_mfma_f32_16x16x32_bf16 v[52:55], v[148:151], v[192:195], v[52:55]
	v_mfma_f32_16x16x32_bf16 v[48:51], v[176:179], v[192:195], v[48:51]
	v_mfma_f32_16x16x32_bf16 v[48:51], v[172:175], v[180:183], v[48:51]
	v_mfma_f32_16x16x32_bf16 v[32:35], v[172:175], v[196:199], v[32:35]
	v_mfma_f32_16x16x32_bf16 v[32:35], v[176:179], v[200:203], v[32:35]
	v_mfma_f32_16x16x32_bf16 v[36:39], v[148:151], v[200:203], v[36:39]
	v_mfma_f32_16x16x32_bf16 v[36:39], v[144:147], v[196:199], v[36:39]
	v_mfma_f32_16x16x32_bf16 v[20:23], v[144:147], v[204:207], v[20:23]
	v_mfma_f32_16x16x32_bf16 v[20:23], v[148:151], v[208:211], v[20:23]
	v_mfma_f32_16x16x32_bf16 v[16:19], v[176:179], v[208:211], v[16:19]
	v_mfma_f32_16x16x32_bf16 v[16:19], v[172:175], v[204:207], v[16:19]
	v_mfma_f32_16x16x32_bf16 v[0:3], v[172:175], v[212:215], v[0:3]
	v_mfma_f32_16x16x32_bf16 v[0:3], v[176:179], v[216:219], v[0:3]
	v_mfma_f32_16x16x32_bf16 v[4:7], v[148:151], v[216:219], v[4:7]
	v_mfma_f32_16x16x32_bf16 v[4:7], v[144:147], v[212:215], v[4:7]
	s_barrier
	s_setprio 0
	s_add_i32 s80, s80, 2
	s_add_u32 s78, s78, 0x100
	s_addc_u32 s79, s79, 0
	s_add_u32 s58, s58, 0x100
	s_addc_u32 s59, s59, 0
	s_cmp_gt_u32 s80, 13
.LBB0_1011:
	ds_read_b128 v[128:131], v188
	v_xor_b32_e32 v253, 64, v188
	ds_read_b128 v[132:135], v253
	ds_read_b128 v[136:139], v188 offset:2048
	ds_read_b128 v[140:143], v253 offset:2048
	ds_read_b128 v[144:147], v189
	v_xor_b32_e32 v253, 64, v189
	ds_read_b128 v[148:151], v253
	ds_read_b128 v[172:175], v189 offset:2048
	ds_read_b128 v[176:179], v253 offset:2048
	s_add_u32 s60, s58, 0xfffc0080
	s_addc_u32 s61, s59, -1
	s_cmp_eq_u32 s80, 12
	s_cselect_b32 s63, s15, s61
	s_cselect_b32 s62, s51, s60
	s_cselect_b32 s61, s49, s79
	s_cselect_b32 s60, s57, s78
	v_lshl_add_u64 v[220:221], s[58:59], 0, v[166:167]
	s_add_i32 m0, s67, 0xc000
	ds_read_b128 v[180:183], v190
	v_xor_b32_e32 v253, 64, v190
	ds_read_b128 v[192:195], v253
	ds_read_b128 v[196:199], v190 offset:2048
	ds_read_b128 v[200:203], v253 offset:2048
	ds_read_b128 v[204:207], v190 offset:4096
	ds_read_b128 v[208:211], v253 offset:4096
	ds_read_b128 v[212:215], v190 offset:6144
	ds_read_b128 v[216:219], v253 offset:6144
	global_load_lds_dwordx4 v[220:221], off
	v_lshl_add_u64 v[220:221], s[58:59], 0, v[164:165]
	s_add_i32 m0, s67, 0xe000
	s_nop 0
	global_load_lds_dwordx4 v[220:221], off
	s_waitcnt vmcnt(8)
	s_waitcnt lgkmcnt(0)
	s_setprio 1
	s_barrier
	v_mfma_f32_16x16x32_bf16 v[124:127], v[128:131], v[180:183], v[124:127]
	v_mfma_f32_16x16x32_bf16 v[124:127], v[132:135], v[192:195], v[124:127]
	v_mfma_f32_16x16x32_bf16 v[120:123], v[140:143], v[192:195], v[120:123]
	v_mfma_f32_16x16x32_bf16 v[120:123], v[136:139], v[180:183], v[120:123]
	v_mfma_f32_16x16x32_bf16 v[104:107], v[136:139], v[196:199], v[104:107]
	v_mfma_f32_16x16x32_bf16 v[104:107], v[140:143], v[200:203], v[104:107]
	v_mfma_f32_16x16x32_bf16 v[108:111], v[132:135], v[200:203], v[108:111]
	v_mfma_f32_16x16x32_bf16 v[108:111], v[128:131], v[196:199], v[108:111]
	v_mfma_f32_16x16x32_bf16 v[92:95], v[128:131], v[204:207], v[92:95]
	v_mfma_f32_16x16x32_bf16 v[92:95], v[132:135], v[208:211], v[92:95]
	v_mfma_f32_16x16x32_bf16 v[88:91], v[140:143], v[208:211], v[88:91]
	v_mfma_f32_16x16x32_bf16 v[88:91], v[136:139], v[204:207], v[88:91]
	v_mfma_f32_16x16x32_bf16 v[72:75], v[136:139], v[212:215], v[72:75]
	v_mfma_f32_16x16x32_bf16 v[72:75], v[140:143], v[216:219], v[72:75]
	v_mfma_f32_16x16x32_bf16 v[76:79], v[132:135], v[216:219], v[76:79]
	v_mfma_f32_16x16x32_bf16 v[76:79], v[128:131], v[212:215], v[76:79]
	v_mfma_f32_16x16x32_bf16 v[116:119], v[144:147], v[180:183], v[116:119]
	v_mfma_f32_16x16x32_bf16 v[116:119], v[148:151], v[192:195], v[116:119]
	v_mfma_f32_16x16x32_bf16 v[112:115], v[176:179], v[192:195], v[112:115]
	v_mfma_f32_16x16x32_bf16 v[112:115], v[172:175], v[180:183], v[112:115]
	v_mfma_f32_16x16x32_bf16 v[96:99], v[172:175], v[196:199], v[96:99]
	v_mfma_f32_16x16x32_bf16 v[96:99], v[176:179], v[200:203], v[96:99]
	v_mfma_f32_16x16x32_bf16 v[100:103], v[148:151], v[200:203], v[100:103]
	v_mfma_f32_16x16x32_bf16 v[100:103], v[144:147], v[196:199], v[100:103]
	v_mfma_f32_16x16x32_bf16 v[84:87], v[144:147], v[204:207], v[84:87]
	v_mfma_f32_16x16x32_bf16 v[84:87], v[148:151], v[208:211], v[84:87]
	v_mfma_f32_16x16x32_bf16 v[80:83], v[176:179], v[208:211], v[80:83]
	v_mfma_f32_16x16x32_bf16 v[80:83], v[172:175], v[204:207], v[80:83]
	v_mfma_f32_16x16x32_bf16 v[64:67], v[172:175], v[212:215], v[64:67]
	v_mfma_f32_16x16x32_bf16 v[64:67], v[176:179], v[216:219], v[64:67]
	v_mfma_f32_16x16x32_bf16 v[68:71], v[148:151], v[216:219], v[68:71]
	v_mfma_f32_16x16x32_bf16 v[68:71], v[144:147], v[212:215], v[68:71]
	s_barrier
	s_setprio 0
	s_add_i32 s81, s76, s66
	v_lshl_add_u64 v[220:221], s[60:61], 0, v[154:155]
	s_mov_b32 m0, s81
	ds_read_b128 v[180:183], v190 offset:16384
	v_xor_b32_e32 v253, 64, v190
	ds_read_b128 v[192:195], v253 offset:16384
	ds_read_b128 v[196:199], v190 offset:18432
	ds_read_b128 v[200:203], v253 offset:18432
	ds_read_b128 v[204:207], v190 offset:20480
	ds_read_b128 v[208:211], v253 offset:20480
	ds_read_b128 v[212:215], v190 offset:22528
	ds_read_b128 v[216:219], v253 offset:22528
	global_load_lds_dwordx4 v[220:221], off
	s_add_i32 m0, s81, 0x2000
	s_add_u32 s82, s60, 0x40000
	v_lshl_add_u64 v[222:223], s[60:61], 0, v[162:163]
	s_addc_u32 s83, s61, 0
	s_add_i32 s81, s77, s66
	global_load_lds_dwordx4 v[222:223], off
	v_lshl_add_u64 v[224:225], s[82:83], 0, v[154:155]
	s_mov_b32 m0, s81
	v_lshl_add_u64 v[226:227], s[62:63], 0, v[160:161]
	global_load_lds_dwordx4 v[224:225], off
	v_lshl_add_u64 v[224:225], s[82:83], 0, v[162:163]
	s_add_i32 m0, s81, 0x2000
	s_nop 0
	global_load_lds_dwordx4 v[224:225], off
	v_lshl_add_u64 v[224:225], s[62:63], 0, v[152:153]
	s_mov_b32 m0, s67
	s_nop 0
	global_load_lds_dwordx4 v[224:225], off
	s_mov_b32 m0, s68
	s_nop 0
	global_load_lds_dwordx4 v[226:227], off
	s_waitcnt vmcnt(8)
	s_waitcnt lgkmcnt(0)
	s_setprio 1
	s_barrier
	v_mfma_f32_16x16x32_bf16 v[60:63], v[128:131], v[180:183], v[60:63]
	v_mfma_f32_16x16x32_bf16 v[60:63], v[132:135], v[192:195], v[60:63]
	v_mfma_f32_16x16x32_bf16 v[56:59], v[140:143], v[192:195], v[56:59]
	v_mfma_f32_16x16x32_bf16 v[56:59], v[136:139], v[180:183], v[56:59]
	v_mfma_f32_16x16x32_bf16 v[40:43], v[136:139], v[196:199], v[40:43]
	v_mfma_f32_16x16x32_bf16 v[40:43], v[140:143], v[200:203], v[40:43]
	v_mfma_f32_16x16x32_bf16 v[44:47], v[132:135], v[200:203], v[44:47]
	v_mfma_f32_16x16x32_bf16 v[44:47], v[128:131], v[196:199], v[44:47]
	v_mfma_f32_16x16x32_bf16 v[28:31], v[128:131], v[204:207], v[28:31]
	v_mfma_f32_16x16x32_bf16 v[28:31], v[132:135], v[208:211], v[28:31]
	v_mfma_f32_16x16x32_bf16 v[24:27], v[140:143], v[208:211], v[24:27]
	v_mfma_f32_16x16x32_bf16 v[24:27], v[136:139], v[204:207], v[24:27]
	v_mfma_f32_16x16x32_bf16 v[8:11], v[136:139], v[212:215], v[8:11]
	v_mfma_f32_16x16x32_bf16 v[8:11], v[140:143], v[216:219], v[8:11]
	v_mfma_f32_16x16x32_bf16 v[12:15], v[132:135], v[216:219], v[12:15]
	v_mfma_f32_16x16x32_bf16 v[12:15], v[128:131], v[212:215], v[12:15]
	v_mfma_f32_16x16x32_bf16 v[52:55], v[144:147], v[180:183], v[52:55]
	v_mfma_f32_16x16x32_bf16 v[52:55], v[148:151], v[192:195], v[52:55]
	v_mfma_f32_16x16x32_bf16 v[48:51], v[176:179], v[192:195], v[48:51]
	v_mfma_f32_16x16x32_bf16 v[48:51], v[172:175], v[180:183], v[48:51]
	v_mfma_f32_16x16x32_bf16 v[32:35], v[172:175], v[196:199], v[32:35]
	v_mfma_f32_16x16x32_bf16 v[32:35], v[176:179], v[200:203], v[32:35]
	v_mfma_f32_16x16x32_bf16 v[36:39], v[148:151], v[200:203], v[36:39]
	v_mfma_f32_16x16x32_bf16 v[36:39], v[144:147], v[196:199], v[36:39]
	v_mfma_f32_16x16x32_bf16 v[20:23], v[144:147], v[204:207], v[20:23]
	v_mfma_f32_16x16x32_bf16 v[20:23], v[148:151], v[208:211], v[20:23]
	v_mfma_f32_16x16x32_bf16 v[16:19], v[176:179], v[208:211], v[16:19]
	v_mfma_f32_16x16x32_bf16 v[16:19], v[172:175], v[204:207], v[16:19]
	v_mfma_f32_16x16x32_bf16 v[0:3], v[172:175], v[212:215], v[0:3]
	v_mfma_f32_16x16x32_bf16 v[0:3], v[176:179], v[216:219], v[0:3]
	v_mfma_f32_16x16x32_bf16 v[4:7], v[148:151], v[216:219], v[4:7]
	v_mfma_f32_16x16x32_bf16 v[4:7], v[144:147], v[212:215], v[4:7]
	s_barrier
	s_setprio 0
	s_add_i32 s81, 0, 0x18000
	s_add_i32 s82, 0, 0x1c000
	v_add_u32_e32 v140, s81, v185
	v_add_u32_e32 v176, s82, v185
	ds_read_b128 v[128:131], v140
	v_xor_b32_e32 v253, 64, v140
	ds_read_b128 v[132:135], v253
	ds_read_b128 v[136:139], v140 offset:2048
	ds_read_b128 v[140:143], v253 offset:2048
	ds_read_b128 v[144:147], v176
	v_xor_b32_e32 v253, 64, v176
	ds_read_b128 v[148:151], v253
	ds_read_b128 v[172:175], v176 offset:2048
	ds_read_b128 v[176:179], v253 offset:2048
	s_add_u32 s62, s62, 0x40000
	s_addc_u32 s63, s63, 0
	s_mov_b32 m0, s69
	v_lshl_add_u64 v[228:229], s[62:63], 0, v[152:153]
	ds_read_b128 v[180:183], v190 offset:32768
	v_xor_b32_e32 v253, 64, v190
	ds_read_b128 v[192:195], v253 offset:32768
	ds_read_b128 v[196:199], v190 offset:34816
	ds_read_b128 v[200:203], v253 offset:34816
	ds_read_b128 v[204:207], v190 offset:36864
	ds_read_b128 v[208:211], v253 offset:36864
	ds_read_b128 v[212:215], v190 offset:38912
	ds_read_b128 v[216:219], v253 offset:38912
	global_load_lds_dwordx4 v[228:229], off
	v_lshl_add_u64 v[228:229], s[62:63], 0, v[160:161]
	s_mov_b32 m0, s70
	s_nop 0
	global_load_lds_dwordx4 v[228:229], off
	s_waitcnt vmcnt(8)
	s_waitcnt lgkmcnt(0)
	s_setprio 1
	s_barrier
	v_mfma_f32_16x16x32_bf16 v[124:127], v[128:131], v[180:183], v[124:127]
	v_mfma_f32_16x16x32_bf16 v[124:127], v[132:135], v[192:195], v[124:127]
	v_mfma_f32_16x16x32_bf16 v[120:123], v[140:143], v[192:195], v[120:123]
	v_mfma_f32_16x16x32_bf16 v[120:123], v[136:139], v[180:183], v[120:123]
	v_mfma_f32_16x16x32_bf16 v[104:107], v[136:139], v[196:199], v[104:107]
	v_mfma_f32_16x16x32_bf16 v[104:107], v[140:143], v[200:203], v[104:107]
	v_mfma_f32_16x16x32_bf16 v[108:111], v[132:135], v[200:203], v[108:111]
	v_mfma_f32_16x16x32_bf16 v[108:111], v[128:131], v[196:199], v[108:111]
	v_mfma_f32_16x16x32_bf16 v[92:95], v[128:131], v[204:207], v[92:95]
	v_mfma_f32_16x16x32_bf16 v[92:95], v[132:135], v[208:211], v[92:95]
	v_mfma_f32_16x16x32_bf16 v[88:91], v[140:143], v[208:211], v[88:91]
	v_mfma_f32_16x16x32_bf16 v[88:91], v[136:139], v[204:207], v[88:91]
	v_mfma_f32_16x16x32_bf16 v[72:75], v[136:139], v[212:215], v[72:75]
	v_mfma_f32_16x16x32_bf16 v[72:75], v[140:143], v[216:219], v[72:75]
	v_mfma_f32_16x16x32_bf16 v[76:79], v[132:135], v[216:219], v[76:79]
	v_mfma_f32_16x16x32_bf16 v[76:79], v[128:131], v[212:215], v[76:79]
	v_mfma_f32_16x16x32_bf16 v[116:119], v[144:147], v[180:183], v[116:119]
	v_mfma_f32_16x16x32_bf16 v[116:119], v[148:151], v[192:195], v[116:119]
	v_mfma_f32_16x16x32_bf16 v[112:115], v[176:179], v[192:195], v[112:115]
	v_mfma_f32_16x16x32_bf16 v[112:115], v[172:175], v[180:183], v[112:115]
	v_mfma_f32_16x16x32_bf16 v[96:99], v[172:175], v[196:199], v[96:99]
	v_mfma_f32_16x16x32_bf16 v[96:99], v[176:179], v[200:203], v[96:99]
	v_mfma_f32_16x16x32_bf16 v[100:103], v[148:151], v[200:203], v[100:103]
	v_mfma_f32_16x16x32_bf16 v[100:103], v[144:147], v[196:199], v[100:103]
	v_mfma_f32_16x16x32_bf16 v[84:87], v[144:147], v[204:207], v[84:87]
	v_mfma_f32_16x16x32_bf16 v[84:87], v[148:151], v[208:211], v[84:87]
	v_mfma_f32_16x16x32_bf16 v[80:83], v[176:179], v[208:211], v[80:83]
	v_mfma_f32_16x16x32_bf16 v[80:83], v[172:175], v[204:207], v[80:83]
	v_mfma_f32_16x16x32_bf16 v[64:67], v[172:175], v[212:215], v[64:67]
	v_mfma_f32_16x16x32_bf16 v[64:67], v[176:179], v[216:219], v[64:67]
	v_mfma_f32_16x16x32_bf16 v[68:71], v[148:151], v[216:219], v[68:71]
	v_mfma_f32_16x16x32_bf16 v[68:71], v[144:147], v[212:215], v[68:71]
	s_barrier
	s_setprio 0
	s_add_i32 s62, s81, s66
	v_lshl_add_u64 v[220:221], v[220:221], 0, s[26:27]
	s_mov_b32 m0, s62
	ds_read_b128 v[180:183], v190 offset:49152
	v_xor_b32_e32 v253, 64, v190
	ds_read_b128 v[192:195], v253 offset:49152
	ds_read_b128 v[196:199], v190 offset:51200
	ds_read_b128 v[200:203], v253 offset:51200
	ds_read_b128 v[204:207], v190 offset:53248
	ds_read_b128 v[208:211], v253 offset:53248
	ds_read_b128 v[212:215], v190 offset:55296
	ds_read_b128 v[216:219], v253 offset:55296
	global_load_lds_dwordx4 v[220:221], off
	s_add_i32 m0, s62, 0x2000
	s_add_u32 s60, s60, 0x40080
	v_lshl_add_u64 v[220:221], v[222:223], 0, s[26:27]
	s_addc_u32 s61, s61, 0
	s_add_i32 s62, s82, s66
	global_load_lds_dwordx4 v[220:221], off
	v_lshl_add_u64 v[220:221], s[60:61], 0, v[154:155]
	s_mov_b32 m0, s62
	s_nop 0
	global_load_lds_dwordx4 v[220:221], off
	v_lshl_add_u64 v[220:221], s[60:61], 0, v[162:163]
	s_add_i32 m0, s62, 0x2000
	s_nop 0
	global_load_lds_dwordx4 v[220:221], off
	v_lshl_add_u64 v[220:221], v[224:225], 0, s[26:27]
	s_mov_b32 m0, s3
	s_nop 0
	global_load_lds_dwordx4 v[220:221], off
	v_lshl_add_u64 v[220:221], v[226:227], 0, s[26:27]
	s_mov_b32 m0, s72
	s_nop 0
	global_load_lds_dwordx4 v[220:221], off
	s_waitcnt vmcnt(8)
	s_waitcnt lgkmcnt(0)
	s_setprio 1
	s_barrier
	v_mfma_f32_16x16x32_bf16 v[60:63], v[128:131], v[180:183], v[60:63]
	v_mfma_f32_16x16x32_bf16 v[60:63], v[132:135], v[192:195], v[60:63]
	v_mfma_f32_16x16x32_bf16 v[56:59], v[140:143], v[192:195], v[56:59]
	v_mfma_f32_16x16x32_bf16 v[56:59], v[136:139], v[180:183], v[56:59]
	v_mfma_f32_16x16x32_bf16 v[40:43], v[136:139], v[196:199], v[40:43]
	v_mfma_f32_16x16x32_bf16 v[40:43], v[140:143], v[200:203], v[40:43]
	v_mfma_f32_16x16x32_bf16 v[44:47], v[132:135], v[200:203], v[44:47]
	v_mfma_f32_16x16x32_bf16 v[44:47], v[128:131], v[196:199], v[44:47]
	v_mfma_f32_16x16x32_bf16 v[28:31], v[128:131], v[204:207], v[28:31]
	v_mfma_f32_16x16x32_bf16 v[28:31], v[132:135], v[208:211], v[28:31]
	v_mfma_f32_16x16x32_bf16 v[24:27], v[140:143], v[208:211], v[24:27]
	v_mfma_f32_16x16x32_bf16 v[24:27], v[136:139], v[204:207], v[24:27]
	v_mfma_f32_16x16x32_bf16 v[8:11], v[136:139], v[212:215], v[8:11]
	v_mfma_f32_16x16x32_bf16 v[8:11], v[140:143], v[216:219], v[8:11]
	v_mfma_f32_16x16x32_bf16 v[12:15], v[132:135], v[216:219], v[12:15]
	v_mfma_f32_16x16x32_bf16 v[12:15], v[128:131], v[212:215], v[12:15]
	v_mfma_f32_16x16x32_bf16 v[52:55], v[144:147], v[180:183], v[52:55]
	v_mfma_f32_16x16x32_bf16 v[52:55], v[148:151], v[192:195], v[52:55]
	v_mfma_f32_16x16x32_bf16 v[48:51], v[176:179], v[192:195], v[48:51]
	v_mfma_f32_16x16x32_bf16 v[48:51], v[172:175], v[180:183], v[48:51]
	v_mfma_f32_16x16x32_bf16 v[32:35], v[172:175], v[196:199], v[32:35]
	v_mfma_f32_16x16x32_bf16 v[32:35], v[176:179], v[200:203], v[32:35]
	v_mfma_f32_16x16x32_bf16 v[36:39], v[148:151], v[200:203], v[36:39]
	v_mfma_f32_16x16x32_bf16 v[36:39], v[144:147], v[196:199], v[36:39]
	v_mfma_f32_16x16x32_bf16 v[20:23], v[144:147], v[204:207], v[20:23]
	v_mfma_f32_16x16x32_bf16 v[20:23], v[148:151], v[208:211], v[20:23]
	v_mfma_f32_16x16x32_bf16 v[16:19], v[176:179], v[208:211], v[16:19]
	v_mfma_f32_16x16x32_bf16 v[16:19], v[172:175], v[204:207], v[16:19]
	v_mfma_f32_16x16x32_bf16 v[0:3], v[172:175], v[212:215], v[0:3]
	v_mfma_f32_16x16x32_bf16 v[0:3], v[176:179], v[216:219], v[0:3]
	v_mfma_f32_16x16x32_bf16 v[4:7], v[148:151], v[216:219], v[4:7]
	v_mfma_f32_16x16x32_bf16 v[4:7], v[144:147], v[212:215], v[4:7]
	s_barrier
	s_setprio 0
	s_add_i32 s80, s80, 2
	s_add_u32 s78, s78, 0x100
	s_addc_u32 s79, s79, 0
	s_add_u32 s58, s58, 0x100
	s_addc_u32 s59, s59, 0
	s_cmp_gt_u32 s80, 13
	s_cbranch_scc0 .LBB0_1011
	s_and_b64 vcc, exec, s[28:29]
	s_cbranch_vccz .LBB0_1014
	s_barrier

.LBB0_1096:
	s_ashr_i32 s25, s24, 31
	s_lshl_b64 s[26:27], s[24:25], 19
	s_add_u32 s26, s3, s26
	s_addc_u32 s27, s33, s27
	s_and_b64 s[28:29], s[6:7], exec
	s_cselect_b32 s25, s27, s47
	s_cselect_b32 s65, s26, s46
	s_ashr_i32 s23, s22, 31
	s_lshl_b64 s[28:29], s[22:23], 19
	s_add_u32 s28, s35, s28
	s_addc_u32 s29, s48, s29
	s_and_b64 s[66:67], s[6:7], exec
	s_cselect_b32 s66, s29, s45
	s_cselect_b32 s67, s28, s44
	s_lshl_b32 s23, s30, 8
	v_add_u32_e32 v0, s23, v148
	s_add_u32 s68, s44, 0x100
	v_ashrrev_i32_e32 v1, 31, v0
	s_addc_u32 s69, s45, 0
	v_lshl_add_u64 v[144:145], v[0:1], 4, s[12:13]
	s_add_u32 s30, s46, 0x40080
	s_addc_u32 s31, s47, 0
	s_mov_b32 s70, -2
	s_mov_b64 s[44:45], 0
	s_cmp_eq_u32 s56, 1
	s_cbranch_scc1 .Lfa_10
	v_add_u32_e32 v153, s61, v147
	ds_read_b128 v[160:163], v153
	v_xor_b32_e32 v253, 64, v153
	ds_read_b128 v[164:167], v253
	ds_read_b128 v[168:171], v153 offset:2048
	ds_read_b128 v[172:175], v253 offset:2048
	v_add_u32_e32 v153, s62, v147
	ds_read_b128 v[176:179], v153
	v_xor_b32_e32 v253, 64, v153
	ds_read_b128 v[180:183], v253
	ds_read_b128 v[184:187], v153 offset:2048
	ds_read_b128 v[188:191], v253 offset:2048
	s_add_u32 s46, s30, 0xfffc0080
	s_addc_u32 s47, s31, -1
	s_and_b64 s[44:45], s[44:45], exec
	s_cselect_b32 s47, s25, s47
	s_cselect_b32 s46, s65, s46
	s_cselect_b32 s45, s66, s69
	s_cselect_b32 s44, s67, s68
	v_lshl_add_u64 v[154:155], s[30:31], 0, v[138:139]
	s_add_i32 m0, s52, 0xc000
	ds_read_b128 v[192:195], v150
	v_xor_b32_e32 v253, 64, v150
	ds_read_b128 v[196:199], v253
	ds_read_b128 v[200:203], v150 offset:2048
	ds_read_b128 v[204:207], v253 offset:2048
	ds_read_b128 v[208:211], v150 offset:4096
	ds_read_b128 v[212:215], v253 offset:4096
	ds_read_b128 v[216:219], v150 offset:6144
	ds_read_b128 v[220:223], v253 offset:6144
	global_load_lds_dwordx4 v[154:155], off
	v_lshl_add_u64 v[154:155], s[30:31], 0, v[136:137]
	s_add_i32 m0, s52, 0xe000
	s_nop 0
	global_load_lds_dwordx4 v[154:155], off
	s_waitcnt vmcnt(16)
	s_waitcnt lgkmcnt(0)
	s_setprio 1
	s_barrier
	v_mfma_f32_16x16x32_bf16 v[124:127], v[160:163], v[192:195], 0
	v_mfma_f32_16x16x32_bf16 v[116:119], v[168:171], v[192:195], 0
	v_mfma_f32_16x16x32_bf16 v[108:111], v[160:163], v[200:203], 0
	v_mfma_f32_16x16x32_bf16 v[100:103], v[168:171], v[200:203], 0
	v_mfma_f32_16x16x32_bf16 v[92:95], v[160:163], v[208:211], 0
	v_mfma_f32_16x16x32_bf16 v[84:87], v[168:171], v[208:211], 0
	v_mfma_f32_16x16x32_bf16 v[76:79], v[160:163], v[216:219], 0
	v_mfma_f32_16x16x32_bf16 v[68:71], v[168:171], v[216:219], 0
	v_mfma_f32_16x16x32_bf16 v[124:127], v[164:167], v[196:199], v[124:127]
	v_mfma_f32_16x16x32_bf16 v[116:119], v[172:175], v[196:199], v[116:119]
	v_mfma_f32_16x16x32_bf16 v[108:111], v[164:167], v[204:207], v[108:111]
	v_mfma_f32_16x16x32_bf16 v[100:103], v[172:175], v[204:207], v[100:103]
	v_mfma_f32_16x16x32_bf16 v[92:95], v[164:167], v[212:215], v[92:95]
	v_mfma_f32_16x16x32_bf16 v[84:87], v[172:175], v[212:215], v[84:87]
	v_mfma_f32_16x16x32_bf16 v[76:79], v[164:167], v[220:223], v[76:79]
	v_mfma_f32_16x16x32_bf16 v[68:71], v[172:175], v[220:223], v[68:71]
	v_mfma_f32_16x16x32_bf16 v[120:123], v[176:179], v[192:195], 0
	v_mfma_f32_16x16x32_bf16 v[112:115], v[184:187], v[192:195], 0
	v_mfma_f32_16x16x32_bf16 v[104:107], v[176:179], v[200:203], 0
	v_mfma_f32_16x16x32_bf16 v[96:99], v[184:187], v[200:203], 0
	v_mfma_f32_16x16x32_bf16 v[88:91], v[176:179], v[208:211], 0
	v_mfma_f32_16x16x32_bf16 v[80:83], v[184:187], v[208:211], 0
	v_mfma_f32_16x16x32_bf16 v[72:75], v[176:179], v[216:219], 0
	v_mfma_f32_16x16x32_bf16 v[64:67], v[184:187], v[216:219], 0
	v_mfma_f32_16x16x32_bf16 v[120:123], v[180:183], v[196:199], v[120:123]
	v_mfma_f32_16x16x32_bf16 v[112:115], v[188:191], v[196:199], v[112:115]
	v_mfma_f32_16x16x32_bf16 v[104:107], v[180:183], v[204:207], v[104:107]
	v_mfma_f32_16x16x32_bf16 v[96:99], v[188:191], v[204:207], v[96:99]
	v_mfma_f32_16x16x32_bf16 v[88:91], v[180:183], v[212:215], v[88:91]
	v_mfma_f32_16x16x32_bf16 v[80:83], v[188:191], v[212:215], v[80:83]
	v_mfma_f32_16x16x32_bf16 v[72:75], v[180:183], v[220:223], v[72:75]
	v_mfma_f32_16x16x32_bf16 v[64:67], v[188:191], v[220:223], v[64:67]
	s_barrier
	s_setprio 0
	s_add_i32 s71, s61, s49
	v_lshl_add_u64 v[154:155], s[44:45], 0, v[132:133]
	s_mov_b32 m0, s71
	ds_read_b128 v[192:195], v150 offset:16384
	v_xor_b32_e32 v253, 64, v150
	ds_read_b128 v[196:199], v253 offset:16384
	ds_read_b128 v[200:203], v150 offset:18432
	ds_read_b128 v[204:207], v253 offset:18432
	ds_read_b128 v[208:211], v150 offset:20480
	ds_read_b128 v[212:215], v253 offset:20480
	ds_read_b128 v[216:219], v150 offset:22528
	ds_read_b128 v[220:223], v253 offset:22528
	global_load_lds_dwordx4 v[154:155], off
	s_add_i32 m0, s71, 0x2000
	s_add_u32 s72, s44, 0x40000
	v_lshl_add_u64 v[224:225], s[44:45], 0, v[128:129]
	s_addc_u32 s73, s45, 0
	s_add_i32 s71, s62, s49
	global_load_lds_dwordx4 v[224:225], off
	v_lshl_add_u64 v[226:227], s[72:73], 0, v[132:133]
	s_mov_b32 m0, s71
	v_lshl_add_u64 v[228:229], s[46:47], 0, v[130:131]
	global_load_lds_dwordx4 v[226:227], off
	v_lshl_add_u64 v[226:227], s[72:73], 0, v[128:129]
	s_add_i32 m0, s71, 0x2000
	s_nop 0
	global_load_lds_dwordx4 v[226:227], off
	v_lshl_add_u64 v[226:227], s[46:47], 0, v[134:135]
	s_mov_b32 m0, s52
	s_nop 0
	global_load_lds_dwordx4 v[226:227], off
	s_mov_b32 m0, s53
	s_nop 0
	global_load_lds_dwordx4 v[228:229], off
	s_waitcnt vmcnt(16)
	s_waitcnt lgkmcnt(0)
	s_setprio 1
	s_barrier
	v_mfma_f32_16x16x32_bf16 v[60:63], v[160:163], v[192:195], 0
	v_mfma_f32_16x16x32_bf16 v[52:55], v[168:171], v[192:195], 0
	v_mfma_f32_16x16x32_bf16 v[44:47], v[160:163], v[200:203], 0
	v_mfma_f32_16x16x32_bf16 v[36:39], v[168:171], v[200:203], 0
	v_mfma_f32_16x16x32_bf16 v[28:31], v[160:163], v[208:211], 0
	v_mfma_f32_16x16x32_bf16 v[20:23], v[168:171], v[208:211], 0
	v_mfma_f32_16x16x32_bf16 v[12:15], v[160:163], v[216:219], 0
	v_mfma_f32_16x16x32_bf16 v[4:7], v[168:171], v[216:219], 0
	v_mfma_f32_16x16x32_bf16 v[60:63], v[164:167], v[196:199], v[60:63]
	v_mfma_f32_16x16x32_bf16 v[52:55], v[172:175], v[196:199], v[52:55]
	v_mfma_f32_16x16x32_bf16 v[44:47], v[164:167], v[204:207], v[44:47]
	v_mfma_f32_16x16x32_bf16 v[36:39], v[172:175], v[204:207], v[36:39]
	v_mfma_f32_16x16x32_bf16 v[28:31], v[164:167], v[212:215], v[28:31]
	v_mfma_f32_16x16x32_bf16 v[20:23], v[172:175], v[212:215], v[20:23]
	v_mfma_f32_16x16x32_bf16 v[12:15], v[164:167], v[220:223], v[12:15]
	v_mfma_f32_16x16x32_bf16 v[4:7], v[172:175], v[220:223], v[4:7]
	v_mfma_f32_16x16x32_bf16 v[56:59], v[176:179], v[192:195], 0
	v_mfma_f32_16x16x32_bf16 v[48:51], v[184:187], v[192:195], 0
	v_mfma_f32_16x16x32_bf16 v[40:43], v[176:179], v[200:203], 0
	v_mfma_f32_16x16x32_bf16 v[32:35], v[184:187], v[200:203], 0
	v_mfma_f32_16x16x32_bf16 v[24:27], v[176:179], v[208:211], 0
	v_mfma_f32_16x16x32_bf16 v[16:19], v[184:187], v[208:211], 0
	v_mfma_f32_16x16x32_bf16 v[8:11], v[176:179], v[216:219], 0
	v_mfma_f32_16x16x32_bf16 v[0:3], v[184:187], v[216:219], 0
	v_mfma_f32_16x16x32_bf16 v[56:59], v[180:183], v[196:199], v[56:59]
	v_mfma_f32_16x16x32_bf16 v[48:51], v[188:191], v[196:199], v[48:51]
	v_mfma_f32_16x16x32_bf16 v[40:43], v[180:183], v[204:207], v[40:43]
	v_mfma_f32_16x16x32_bf16 v[32:35], v[188:191], v[204:207], v[32:35]
	v_mfma_f32_16x16x32_bf16 v[24:27], v[180:183], v[212:215], v[24:27]
	v_mfma_f32_16x16x32_bf16 v[16:19], v[188:191], v[212:215], v[16:19]
	v_mfma_f32_16x16x32_bf16 v[8:11], v[180:183], v[220:223], v[8:11]
	v_mfma_f32_16x16x32_bf16 v[0:3], v[188:191], v[220:223], v[0:3]
	s_barrier
	s_setprio 0
	s_add_i32 s71, 0, 0x18000
	v_add_u32_e32 v153, s71, v147
	s_add_i32 s72, 0, 0x1c000
	ds_read_b128 v[160:163], v153
	v_xor_b32_e32 v253, 64, v153
	ds_read_b128 v[164:167], v253
	ds_read_b128 v[168:171], v153 offset:2048
	ds_read_b128 v[172:175], v253 offset:2048
	v_add_u32_e32 v153, s72, v147
	ds_read_b128 v[176:179], v153
	v_xor_b32_e32 v253, 64, v153
	ds_read_b128 v[180:183], v253
	ds_read_b128 v[184:187], v153 offset:2048
	ds_read_b128 v[188:191], v253 offset:2048
	s_add_u32 s46, s46, 0x40000
	s_addc_u32 s47, s47, 0
	s_mov_b32 m0, s54
	v_lshl_add_u64 v[230:231], s[46:47], 0, v[134:135]
	ds_read_b128 v[192:195], v150 offset:32768
	v_xor_b32_e32 v253, 64, v150
	ds_read_b128 v[196:199], v253 offset:32768
	ds_read_b128 v[200:203], v150 offset:34816
	ds_read_b128 v[204:207], v253 offset:34816
	ds_read_b128 v[208:211], v150 offset:36864
	ds_read_b128 v[212:215], v253 offset:36864
	ds_read_b128 v[216:219], v150 offset:38912
	ds_read_b128 v[220:223], v253 offset:38912
	global_load_lds_dwordx4 v[230:231], off
	v_lshl_add_u64 v[230:231], s[46:47], 0, v[130:131]
	s_mov_b32 m0, s55
	s_nop 0
	global_load_lds_dwordx4 v[230:231], off
	s_waitcnt vmcnt(8)
	s_waitcnt lgkmcnt(0)
	s_setprio 1
	s_barrier
	v_mfma_f32_16x16x32_bf16 v[124:127], v[160:163], v[192:195], v[124:127]
	v_mfma_f32_16x16x32_bf16 v[124:127], v[164:167], v[196:199], v[124:127]
	v_mfma_f32_16x16x32_bf16 v[116:119], v[172:175], v[196:199], v[116:119]
	v_mfma_f32_16x16x32_bf16 v[116:119], v[168:171], v[192:195], v[116:119]
	v_mfma_f32_16x16x32_bf16 v[100:103], v[168:171], v[200:203], v[100:103]
	v_mfma_f32_16x16x32_bf16 v[100:103], v[172:175], v[204:207], v[100:103]
	v_mfma_f32_16x16x32_bf16 v[108:111], v[164:167], v[204:207], v[108:111]
	v_mfma_f32_16x16x32_bf16 v[108:111], v[160:163], v[200:203], v[108:111]
	v_mfma_f32_16x16x32_bf16 v[92:95], v[160:163], v[208:211], v[92:95]
	v_mfma_f32_16x16x32_bf16 v[92:95], v[164:167], v[212:215], v[92:95]
	v_mfma_f32_16x16x32_bf16 v[84:87], v[172:175], v[212:215], v[84:87]
	v_mfma_f32_16x16x32_bf16 v[84:87], v[168:171], v[208:211], v[84:87]
	v_mfma_f32_16x16x32_bf16 v[68:71], v[168:171], v[216:219], v[68:71]
	v_mfma_f32_16x16x32_bf16 v[68:71], v[172:175], v[220:223], v[68:71]
	v_mfma_f32_16x16x32_bf16 v[76:79], v[164:167], v[220:223], v[76:79]
	v_mfma_f32_16x16x32_bf16 v[76:79], v[160:163], v[216:219], v[76:79]
	v_mfma_f32_16x16x32_bf16 v[120:123], v[176:179], v[192:195], v[120:123]
	v_mfma_f32_16x16x32_bf16 v[120:123], v[180:183], v[196:199], v[120:123]
	v_mfma_f32_16x16x32_bf16 v[112:115], v[188:191], v[196:199], v[112:115]
	v_mfma_f32_16x16x32_bf16 v[112:115], v[184:187], v[192:195], v[112:115]
	v_mfma_f32_16x16x32_bf16 v[96:99], v[184:187], v[200:203], v[96:99]
	v_mfma_f32_16x16x32_bf16 v[96:99], v[188:191], v[204:207], v[96:99]
	v_mfma_f32_16x16x32_bf16 v[104:107], v[180:183], v[204:207], v[104:107]
	v_mfma_f32_16x16x32_bf16 v[104:107], v[176:179], v[200:203], v[104:107]
	v_mfma_f32_16x16x32_bf16 v[88:91], v[176:179], v[208:211], v[88:91]
	v_mfma_f32_16x16x32_bf16 v[88:91], v[180:183], v[212:215], v[88:91]
	v_mfma_f32_16x16x32_bf16 v[80:83], v[188:191], v[212:215], v[80:83]
	v_mfma_f32_16x16x32_bf16 v[80:83], v[184:187], v[208:211], v[80:83]
	v_mfma_f32_16x16x32_bf16 v[64:67], v[184:187], v[216:219], v[64:67]
	v_mfma_f32_16x16x32_bf16 v[64:67], v[188:191], v[220:223], v[64:67]
	v_mfma_f32_16x16x32_bf16 v[72:75], v[180:183], v[220:223], v[72:75]
	v_mfma_f32_16x16x32_bf16 v[72:75], v[176:179], v[216:219], v[72:75]
	s_barrier
	s_setprio 0
	s_add_i32 s46, s71, s49
	v_lshl_add_u64 v[154:155], v[154:155], 0, s[14:15]
	s_mov_b32 m0, s46
	ds_read_b128 v[192:195], v150 offset:49152
	v_xor_b32_e32 v253, 64, v150
	ds_read_b128 v[196:199], v253 offset:49152
	ds_read_b128 v[200:203], v150 offset:51200
	ds_read_b128 v[204:207], v253 offset:51200
	ds_read_b128 v[208:211], v150 offset:53248
	ds_read_b128 v[212:215], v253 offset:53248
	ds_read_b128 v[216:219], v150 offset:55296
	ds_read_b128 v[220:223], v253 offset:55296
	global_load_lds_dwordx4 v[154:155], off
	s_add_i32 m0, s46, 0x2000
	s_add_u32 s44, s44, 0x40080
	v_lshl_add_u64 v[154:155], v[224:225], 0, s[14:15]
	s_addc_u32 s45, s45, 0
	s_add_i32 s46, s72, s49
	global_load_lds_dwordx4 v[154:155], off
	v_lshl_add_u64 v[154:155], s[44:45], 0, v[132:133]
	s_mov_b32 m0, s46
	s_nop 0
	global_load_lds_dwordx4 v[154:155], off
	v_lshl_add_u64 v[154:155], s[44:45], 0, v[128:129]
	s_add_i32 m0, s46, 0x2000
	s_nop 0
	global_load_lds_dwordx4 v[154:155], off
	v_lshl_add_u64 v[154:155], v[226:227], 0, s[14:15]
	s_mov_b32 m0, s57
	s_nop 0
	global_load_lds_dwordx4 v[154:155], off
	v_lshl_add_u64 v[154:155], v[228:229], 0, s[14:15]
	s_mov_b32 m0, s58
	s_nop 0
	global_load_lds_dwordx4 v[154:155], off
	s_waitcnt vmcnt(8)
	s_waitcnt lgkmcnt(0)
	s_setprio 1
	s_barrier
	v_mfma_f32_16x16x32_bf16 v[60:63], v[160:163], v[192:195], v[60:63]
	v_mfma_f32_16x16x32_bf16 v[60:63], v[164:167], v[196:199], v[60:63]
	v_mfma_f32_16x16x32_bf16 v[52:55], v[172:175], v[196:199], v[52:55]
	v_mfma_f32_16x16x32_bf16 v[52:55], v[168:171], v[192:195], v[52:55]
	v_mfma_f32_16x16x32_bf16 v[36:39], v[168:171], v[200:203], v[36:39]
	v_mfma_f32_16x16x32_bf16 v[36:39], v[172:175], v[204:207], v[36:39]
	v_mfma_f32_16x16x32_bf16 v[44:47], v[164:167], v[204:207], v[44:47]
	v_mfma_f32_16x16x32_bf16 v[44:47], v[160:163], v[200:203], v[44:47]
	v_mfma_f32_16x16x32_bf16 v[28:31], v[160:163], v[208:211], v[28:31]
	v_mfma_f32_16x16x32_bf16 v[28:31], v[164:167], v[212:215], v[28:31]
	v_mfma_f32_16x16x32_bf16 v[20:23], v[172:175], v[212:215], v[20:23]
	v_mfma_f32_16x16x32_bf16 v[20:23], v[168:171], v[208:211], v[20:23]
	v_mfma_f32_16x16x32_bf16 v[4:7], v[168:171], v[216:219], v[4:7]
	v_mfma_f32_16x16x32_bf16 v[4:7], v[172:175], v[220:223], v[4:7]
	v_mfma_f32_16x16x32_bf16 v[12:15], v[164:167], v[220:223], v[12:15]
	v_mfma_f32_16x16x32_bf16 v[12:15], v[160:163], v[216:219], v[12:15]
	v_mfma_f32_16x16x32_bf16 v[56:59], v[176:179], v[192:195], v[56:59]
	v_mfma_f32_16x16x32_bf16 v[56:59], v[180:183], v[196:199], v[56:59]
	v_mfma_f32_16x16x32_bf16 v[48:51], v[188:191], v[196:199], v[48:51]
	v_mfma_f32_16x16x32_bf16 v[48:51], v[184:187], v[192:195], v[48:51]
	v_mfma_f32_16x16x32_bf16 v[32:35], v[184:187], v[200:203], v[32:35]
	v_mfma_f32_16x16x32_bf16 v[32:35], v[188:191], v[204:207], v[32:35]
	v_mfma_f32_16x16x32_bf16 v[40:43], v[180:183], v[204:207], v[40:43]
	v_mfma_f32_16x16x32_bf16 v[40:43], v[176:179], v[200:203], v[40:43]
	v_mfma_f32_16x16x32_bf16 v[24:27], v[176:179], v[208:211], v[24:27]
	v_mfma_f32_16x16x32_bf16 v[24:27], v[180:183], v[212:215], v[24:27]
	v_mfma_f32_16x16x32_bf16 v[16:19], v[188:191], v[212:215], v[16:19]
	v_mfma_f32_16x16x32_bf16 v[16:19], v[184:187], v[208:211], v[16:19]
	v_mfma_f32_16x16x32_bf16 v[0:3], v[184:187], v[216:219], v[0:3]
	v_mfma_f32_16x16x32_bf16 v[0:3], v[188:191], v[220:223], v[0:3]
	v_mfma_f32_16x16x32_bf16 v[8:11], v[180:183], v[220:223], v[8:11]
	v_mfma_f32_16x16x32_bf16 v[8:11], v[176:179], v[216:219], v[8:11]
	s_barrier
	s_setprio 0
	s_add_i32 s70, s70, 2
	s_add_u32 s68, s68, 0x100
	s_addc_u32 s69, s69, 0
	s_add_u32 s30, s30, 0x100
	s_addc_u32 s31, s31, 0
	s_branch .LBB0_1098
.Lfa_10:
	v_add_u32_e32 v153, s61, v147
	ds_read_b128 v[160:163], v153
	v_xor_b32_e32 v253, 64, v153
	ds_read_b128 v[164:167], v253
	ds_read_b128 v[168:171], v153 offset:2048
	ds_read_b128 v[172:175], v253 offset:2048
	v_add_u32_e32 v153, s62, v147
	ds_read_b128 v[176:179], v153
	v_xor_b32_e32 v253, 64, v153
	ds_read_b128 v[180:183], v253
	ds_read_b128 v[184:187], v153 offset:2048
	ds_read_b128 v[188:191], v253 offset:2048
	s_add_u32 s46, s30, 0xfffc0080
	s_addc_u32 s47, s31, -1
	s_and_b64 s[44:45], s[44:45], exec
	s_cselect_b32 s47, s25, s47
	s_cselect_b32 s46, s65, s46
	s_cselect_b32 s45, s66, s69
	s_cselect_b32 s44, s67, s68
	v_lshl_add_u64 v[154:155], s[30:31], 0, v[138:139]
	s_add_i32 m0, s52, 0xc000
	ds_read_b128 v[192:195], v150
	v_xor_b32_e32 v253, 64, v150
	ds_read_b128 v[196:199], v253
	ds_read_b128 v[200:203], v150 offset:2048
	ds_read_b128 v[204:207], v253 offset:2048
	ds_read_b128 v[208:211], v150 offset:4096
	ds_read_b128 v[212:215], v253 offset:4096
	ds_read_b128 v[216:219], v150 offset:6144
	ds_read_b128 v[220:223], v253 offset:6144
	global_load_lds_dwordx4 v[154:155], off
	v_lshl_add_u64 v[154:155], s[30:31], 0, v[136:137]
	s_add_i32 m0, s52, 0xe000
	s_nop 0
	global_load_lds_dwordx4 v[154:155], off
	s_waitcnt vmcnt(8)
	s_waitcnt lgkmcnt(0)
	s_setprio 1
	s_barrier
	v_mfma_f32_16x16x32_bf16 v[124:127], v[160:163], v[192:195], 0
	v_mfma_f32_16x16x32_bf16 v[116:119], v[168:171], v[192:195], 0
	v_mfma_f32_16x16x32_bf16 v[108:111], v[160:163], v[200:203], 0
	v_mfma_f32_16x16x32_bf16 v[100:103], v[168:171], v[200:203], 0
	v_mfma_f32_16x16x32_bf16 v[92:95], v[160:163], v[208:211], 0
	v_mfma_f32_16x16x32_bf16 v[84:87], v[168:171], v[208:211], 0
	v_mfma_f32_16x16x32_bf16 v[76:79], v[160:163], v[216:219], 0
	v_mfma_f32_16x16x32_bf16 v[68:71], v[168:171], v[216:219], 0
	v_mfma_f32_16x16x32_bf16 v[124:127], v[164:167], v[196:199], v[124:127]
	v_mfma_f32_16x16x32_bf16 v[116:119], v[172:175], v[196:199], v[116:119]
	v_mfma_f32_16x16x32_bf16 v[108:111], v[164:167], v[204:207], v[108:111]
	v_mfma_f32_16x16x32_bf16 v[100:103], v[172:175], v[204:207], v[100:103]
	v_mfma_f32_16x16x32_bf16 v[92:95], v[164:167], v[212:215], v[92:95]
	v_mfma_f32_16x16x32_bf16 v[84:87], v[172:175], v[212:215], v[84:87]
	v_mfma_f32_16x16x32_bf16 v[76:79], v[164:167], v[220:223], v[76:79]
	v_mfma_f32_16x16x32_bf16 v[68:71], v[172:175], v[220:223], v[68:71]
	v_mfma_f32_16x16x32_bf16 v[120:123], v[176:179], v[192:195], 0
	v_mfma_f32_16x16x32_bf16 v[112:115], v[184:187], v[192:195], 0
	v_mfma_f32_16x16x32_bf16 v[104:107], v[176:179], v[200:203], 0
	v_mfma_f32_16x16x32_bf16 v[96:99], v[184:187], v[200:203], 0
	v_mfma_f32_16x16x32_bf16 v[88:91], v[176:179], v[208:211], 0
	v_mfma_f32_16x16x32_bf16 v[80:83], v[184:187], v[208:211], 0
	v_mfma_f32_16x16x32_bf16 v[72:75], v[176:179], v[216:219], 0
	v_mfma_f32_16x16x32_bf16 v[64:67], v[184:187], v[216:219], 0
	v_mfma_f32_16x16x32_bf16 v[120:123], v[180:183], v[196:199], v[120:123]
	v_mfma_f32_16x16x32_bf16 v[112:115], v[188:191], v[196:199], v[112:115]
	v_mfma_f32_16x16x32_bf16 v[104:107], v[180:183], v[204:207], v[104:107]
	v_mfma_f32_16x16x32_bf16 v[96:99], v[188:191], v[204:207], v[96:99]
	v_mfma_f32_16x16x32_bf16 v[88:91], v[180:183], v[212:215], v[88:91]
	v_mfma_f32_16x16x32_bf16 v[80:83], v[188:191], v[212:215], v[80:83]
	v_mfma_f32_16x16x32_bf16 v[72:75], v[180:183], v[220:223], v[72:75]
	v_mfma_f32_16x16x32_bf16 v[64:67], v[188:191], v[220:223], v[64:67]
	s_barrier
	s_setprio 0
	s_add_i32 s71, s61, s49
	v_lshl_add_u64 v[154:155], s[44:45], 0, v[132:133]
	s_mov_b32 m0, s71
	ds_read_b128 v[192:195], v150 offset:16384
	v_xor_b32_e32 v253, 64, v150
	ds_read_b128 v[196:199], v253 offset:16384
	ds_read_b128 v[200:203], v150 offset:18432
	ds_read_b128 v[204:207], v253 offset:18432
	ds_read_b128 v[208:211], v150 offset:20480
	ds_read_b128 v[212:215], v253 offset:20480
	ds_read_b128 v[216:219], v150 offset:22528
	ds_read_b128 v[220:223], v253 offset:22528
	global_load_lds_dwordx4 v[154:155], off
	s_add_i32 m0, s71, 0x2000
	s_add_u32 s72, s44, 0x40000
	v_lshl_add_u64 v[224:225], s[44:45], 0, v[128:129]
	s_addc_u32 s73, s45, 0
	s_add_i32 s71, s62, s49
	global_load_lds_dwordx4 v[224:225], off
	v_lshl_add_u64 v[226:227], s[72:73], 0, v[132:133]
	s_mov_b32 m0, s71
	v_lshl_add_u64 v[228:229], s[46:47], 0, v[130:131]
	global_load_lds_dwordx4 v[226:227], off
	v_lshl_add_u64 v[226:227], s[72:73], 0, v[128:129]
	s_add_i32 m0, s71, 0x2000
	s_nop 0
	global_load_lds_dwordx4 v[226:227], off
	v_lshl_add_u64 v[226:227], s[46:47], 0, v[134:135]
	s_mov_b32 m0, s52
	s_nop 0
	global_load_lds_dwordx4 v[226:227], off
	s_mov_b32 m0, s53
	s_nop 0
	global_load_lds_dwordx4 v[228:229], off
	s_waitcnt vmcnt(8)
	s_waitcnt lgkmcnt(0)
	s_setprio 1
	s_barrier
	v_mfma_f32_16x16x32_bf16 v[60:63], v[160:163], v[192:195], 0
	v_mfma_f32_16x16x32_bf16 v[52:55], v[168:171], v[192:195], 0
	v_mfma_f32_16x16x32_bf16 v[44:47], v[160:163], v[200:203], 0
	v_mfma_f32_16x16x32_bf16 v[36:39], v[168:171], v[200:203], 0
	v_mfma_f32_16x16x32_bf16 v[28:31], v[160:163], v[208:211], 0
	v_mfma_f32_16x16x32_bf16 v[20:23], v[168:171], v[208:211], 0
	v_mfma_f32_16x16x32_bf16 v[12:15], v[160:163], v[216:219], 0
	v_mfma_f32_16x16x32_bf16 v[4:7], v[168:171], v[216:219], 0
	v_mfma_f32_16x16x32_bf16 v[60:63], v[164:167], v[196:199], v[60:63]
	v_mfma_f32_16x16x32_bf16 v[52:55], v[172:175], v[196:199], v[52:55]
	v_mfma_f32_16x16x32_bf16 v[44:47], v[164:167], v[204:207], v[44:47]
	v_mfma_f32_16x16x32_bf16 v[36:39], v[172:175], v[204:207], v[36:39]
	v_mfma_f32_16x16x32_bf16 v[28:31], v[164:167], v[212:215], v[28:31]
	v_mfma_f32_16x16x32_bf16 v[20:23], v[172:175], v[212:215], v[20:23]
	v_mfma_f32_16x16x32_bf16 v[12:15], v[164:167], v[220:223], v[12:15]
	v_mfma_f32_16x16x32_bf16 v[4:7], v[172:175], v[220:223], v[4:7]
	v_mfma_f32_16x16x32_bf16 v[56:59], v[176:179], v[192:195], 0
	v_mfma_f32_16x16x32_bf16 v[48:51], v[184:187], v[192:195], 0
	v_mfma_f32_16x16x32_bf16 v[40:43], v[176:179], v[200:203], 0
	v_mfma_f32_16x16x32_bf16 v[32:35], v[184:187], v[200:203], 0
	v_mfma_f32_16x16x32_bf16 v[24:27], v[176:179], v[208:211], 0
	v_mfma_f32_16x16x32_bf16 v[16:19], v[184:187], v[208:211], 0
	v_mfma_f32_16x16x32_bf16 v[8:11], v[176:179], v[216:219], 0
	v_mfma_f32_16x16x32_bf16 v[0:3], v[184:187], v[216:219], 0
	v_mfma_f32_16x16x32_bf16 v[56:59], v[180:183], v[196:199], v[56:59]
	v_mfma_f32_16x16x32_bf16 v[48:51], v[188:191], v[196:199], v[48:51]
	v_mfma_f32_16x16x32_bf16 v[40:43], v[180:183], v[204:207], v[40:43]
	v_mfma_f32_16x16x32_bf16 v[32:35], v[188:191], v[204:207], v[32:35]
	v_mfma_f32_16x16x32_bf16 v[24:27], v[180:183], v[212:215], v[24:27]
	v_mfma_f32_16x16x32_bf16 v[16:19], v[188:191], v[212:215], v[16:19]
	v_mfma_f32_16x16x32_bf16 v[8:11], v[180:183], v[220:223], v[8:11]
	v_mfma_f32_16x16x32_bf16 v[0:3], v[188:191], v[220:223], v[0:3]
	s_barrier
	s_setprio 0
	s_add_i32 s71, 0, 0x18000
	v_add_u32_e32 v153, s71, v147
	s_add_i32 s72, 0, 0x1c000
	ds_read_b128 v[160:163], v153
	v_xor_b32_e32 v253, 64, v153
	ds_read_b128 v[164:167], v253
	ds_read_b128 v[168:171], v153 offset:2048
	ds_read_b128 v[172:175], v253 offset:2048
	v_add_u32_e32 v153, s72, v147
	ds_read_b128 v[176:179], v153
	v_xor_b32_e32 v253, 64, v153
	ds_read_b128 v[180:183], v253
	ds_read_b128 v[184:187], v153 offset:2048
	ds_read_b128 v[188:191], v253 offset:2048
	s_add_u32 s46, s46, 0x40000
	s_addc_u32 s47, s47, 0
	s_mov_b32 m0, s54
	v_lshl_add_u64 v[230:231], s[46:47], 0, v[134:135]
	ds_read_b128 v[192:195], v150 offset:32768
	v_xor_b32_e32 v253, 64, v150
	ds_read_b128 v[196:199], v253 offset:32768
	ds_read_b128 v[200:203], v150 offset:34816
	ds_read_b128 v[204:207], v253 offset:34816
	ds_read_b128 v[208:211], v150 offset:36864
	ds_read_b128 v[212:215], v253 offset:36864
	ds_read_b128 v[216:219], v150 offset:38912
	ds_read_b128 v[220:223], v253 offset:38912
	global_load_lds_dwordx4 v[230:231], off
	v_lshl_add_u64 v[230:231], s[46:47], 0, v[130:131]
	s_mov_b32 m0, s55
	s_nop 0
	global_load_lds_dwordx4 v[230:231], off
	s_waitcnt vmcnt(8)
	s_waitcnt lgkmcnt(0)
	s_setprio 1
	s_barrier
	v_mfma_f32_16x16x32_bf16 v[124:127], v[160:163], v[192:195], v[124:127]
	v_mfma_f32_16x16x32_bf16 v[124:127], v[164:167], v[196:199], v[124:127]
	v_mfma_f32_16x16x32_bf16 v[116:119], v[172:175], v[196:199], v[116:119]
	v_mfma_f32_16x16x32_bf16 v[116:119], v[168:171], v[192:195], v[116:119]
	v_mfma_f32_16x16x32_bf16 v[100:103], v[168:171], v[200:203], v[100:103]
	v_mfma_f32_16x16x32_bf16 v[100:103], v[172:175], v[204:207], v[100:103]
	v_mfma_f32_16x16x32_bf16 v[108:111], v[164:167], v[204:207], v[108:111]
	v_mfma_f32_16x16x32_bf16 v[108:111], v[160:163], v[200:203], v[108:111]
	v_mfma_f32_16x16x32_bf16 v[92:95], v[160:163], v[208:211], v[92:95]
	v_mfma_f32_16x16x32_bf16 v[92:95], v[164:167], v[212:215], v[92:95]
	v_mfma_f32_16x16x32_bf16 v[84:87], v[172:175], v[212:215], v[84:87]
	v_mfma_f32_16x16x32_bf16 v[84:87], v[168:171], v[208:211], v[84:87]
	v_mfma_f32_16x16x32_bf16 v[68:71], v[168:171], v[216:219], v[68:71]
	v_mfma_f32_16x16x32_bf16 v[68:71], v[172:175], v[220:223], v[68:71]
	v_mfma_f32_16x16x32_bf16 v[76:79], v[164:167], v[220:223], v[76:79]
	v_mfma_f32_16x16x32_bf16 v[76:79], v[160:163], v[216:219], v[76:79]
	v_mfma_f32_16x16x32_bf16 v[120:123], v[176:179], v[192:195], v[120:123]
	v_mfma_f32_16x16x32_bf16 v[120:123], v[180:183], v[196:199], v[120:123]
	v_mfma_f32_16x16x32_bf16 v[112:115], v[188:191], v[196:199], v[112:115]
	v_mfma_f32_16x16x32_bf16 v[112:115], v[184:187], v[192:195], v[112:115]
	v_mfma_f32_16x16x32_bf16 v[96:99], v[184:187], v[200:203], v[96:99]
	v_mfma_f32_16x16x32_bf16 v[96:99], v[188:191], v[204:207], v[96:99]
	v_mfma_f32_16x16x32_bf16 v[104:107], v[180:183], v[204:207], v[104:107]
	v_mfma_f32_16x16x32_bf16 v[104:107], v[176:179], v[200:203], v[104:107]
	v_mfma_f32_16x16x32_bf16 v[88:91], v[176:179], v[208:211], v[88:91]
	v_mfma_f32_16x16x32_bf16 v[88:91], v[180:183], v[212:215], v[88:91]
	v_mfma_f32_16x16x32_bf16 v[80:83], v[188:191], v[212:215], v[80:83]
	v_mfma_f32_16x16x32_bf16 v[80:83], v[184:187], v[208:211], v[80:83]
	v_mfma_f32_16x16x32_bf16 v[64:67], v[184:187], v[216:219], v[64:67]
	v_mfma_f32_16x16x32_bf16 v[64:67], v[188:191], v[220:223], v[64:67]
	v_mfma_f32_16x16x32_bf16 v[72:75], v[180:183], v[220:223], v[72:75]
	v_mfma_f32_16x16x32_bf16 v[72:75], v[176:179], v[216:219], v[72:75]
	s_barrier
	s_setprio 0
	s_add_i32 s46, s71, s49
	v_lshl_add_u64 v[154:155], v[154:155], 0, s[14:15]
	s_mov_b32 m0, s46
	ds_read_b128 v[192:195], v150 offset:49152
	v_xor_b32_e32 v253, 64, v150
	ds_read_b128 v[196:199], v253 offset:49152
	ds_read_b128 v[200:203], v150 offset:51200
	ds_read_b128 v[204:207], v253 offset:51200
	ds_read_b128 v[208:211], v150 offset:53248
	ds_read_b128 v[212:215], v253 offset:53248
	ds_read_b128 v[216:219], v150 offset:55296
	ds_read_b128 v[220:223], v253 offset:55296
	global_load_lds_dwordx4 v[154:155], off
	s_add_i32 m0, s46, 0x2000
	s_add_u32 s44, s44, 0x40080
	v_lshl_add_u64 v[154:155], v[224:225], 0, s[14:15]
	s_addc_u32 s45, s45, 0
	s_add_i32 s46, s72, s49
	global_load_lds_dwordx4 v[154:155], off
	v_lshl_add_u64 v[154:155], s[44:45], 0, v[132:133]
	s_mov_b32 m0, s46
	s_nop 0
	global_load_lds_dwordx4 v[154:155], off
	v_lshl_add_u64 v[154:155], s[44:45], 0, v[128:129]
	s_add_i32 m0, s46, 0x2000
	s_nop 0
	global_load_lds_dwordx4 v[154:155], off
	v_lshl_add_u64 v[154:155], v[226:227], 0, s[14:15]
	s_mov_b32 m0, s57
	s_nop 0
	global_load_lds_dwordx4 v[154:155], off
	v_lshl_add_u64 v[154:155], v[228:229], 0, s[14:15]
	s_mov_b32 m0, s58
	s_nop 0
	global_load_lds_dwordx4 v[154:155], off
	s_waitcnt vmcnt(8)
	s_waitcnt lgkmcnt(0)
	s_setprio 1
	s_barrier
	v_mfma_f32_16x16x32_bf16 v[60:63], v[160:163], v[192:195], v[60:63]
	v_mfma_f32_16x16x32_bf16 v[60:63], v[164:167], v[196:199], v[60:63]
	v_mfma_f32_16x16x32_bf16 v[52:55], v[172:175], v[196:199], v[52:55]
	v_mfma_f32_16x16x32_bf16 v[52:55], v[168:171], v[192:195], v[52:55]
	v_mfma_f32_16x16x32_bf16 v[36:39], v[168:171], v[200:203], v[36:39]
	v_mfma_f32_16x16x32_bf16 v[36:39], v[172:175], v[204:207], v[36:39]
	v_mfma_f32_16x16x32_bf16 v[44:47], v[164:167], v[204:207], v[44:47]
	v_mfma_f32_16x16x32_bf16 v[44:47], v[160:163], v[200:203], v[44:47]
	v_mfma_f32_16x16x32_bf16 v[28:31], v[160:163], v[208:211], v[28:31]
	v_mfma_f32_16x16x32_bf16 v[28:31], v[164:167], v[212:215], v[28:31]
	v_mfma_f32_16x16x32_bf16 v[20:23], v[172:175], v[212:215], v[20:23]
	v_mfma_f32_16x16x32_bf16 v[20:23], v[168:171], v[208:211], v[20:23]
	v_mfma_f32_16x16x32_bf16 v[4:7], v[168:171], v[216:219], v[4:7]
	v_mfma_f32_16x16x32_bf16 v[4:7], v[172:175], v[220:223], v[4:7]
	v_mfma_f32_16x16x32_bf16 v[12:15], v[164:167], v[220:223], v[12:15]
	v_mfma_f32_16x16x32_bf16 v[12:15], v[160:163], v[216:219], v[12:15]
	v_mfma_f32_16x16x32_bf16 v[56:59], v[176:179], v[192:195], v[56:59]
	v_mfma_f32_16x16x32_bf16 v[56:59], v[180:183], v[196:199], v[56:59]
	v_mfma_f32_16x16x32_bf16 v[48:51], v[188:191], v[196:199], v[48:51]
	v_mfma_f32_16x16x32_bf16 v[48:51], v[184:187], v[192:195], v[48:51]
	v_mfma_f32_16x16x32_bf16 v[32:35], v[184:187], v[200:203], v[32:35]
	v_mfma_f32_16x16x32_bf16 v[32:35], v[188:191], v[204:207], v[32:35]
	v_mfma_f32_16x16x32_bf16 v[40:43], v[180:183], v[204:207], v[40:43]
	v_mfma_f32_16x16x32_bf16 v[40:43], v[176:179], v[200:203], v[40:43]
	v_mfma_f32_16x16x32_bf16 v[24:27], v[176:179], v[208:211], v[24:27]
	v_mfma_f32_16x16x32_bf16 v[24:27], v[180:183], v[212:215], v[24:27]
	v_mfma_f32_16x16x32_bf16 v[16:19], v[188:191], v[212:215], v[16:19]
	v_mfma_f32_16x16x32_bf16 v[16:19], v[184:187], v[208:211], v[16:19]
	v_mfma_f32_16x16x32_bf16 v[0:3], v[184:187], v[216:219], v[0:3]
	v_mfma_f32_16x16x32_bf16 v[0:3], v[188:191], v[220:223], v[0:3]
	v_mfma_f32_16x16x32_bf16 v[8:11], v[180:183], v[220:223], v[8:11]
	v_mfma_f32_16x16x32_bf16 v[8:11], v[176:179], v[216:219], v[8:11]
	s_barrier
	s_setprio 0
	s_add_i32 s70, s70, 2
	s_add_u32 s68, s68, 0x100
	s_addc_u32 s69, s69, 0
	s_add_u32 s30, s30, 0x100
	s_addc_u32 s31, s31, 0
	s_branch .LBB0_1098
.LBB0_1097:
	v_add_u32_e32 v153, s61, v147
	ds_read_b128 v[160:163], v153
	v_xor_b32_e32 v253, 64, v153
	ds_read_b128 v[164:167], v253
	ds_read_b128 v[168:171], v153 offset:2048
	ds_read_b128 v[172:175], v253 offset:2048
	v_add_u32_e32 v153, s62, v147
	ds_read_b128 v[176:179], v153
	v_xor_b32_e32 v253, 64, v153
	ds_read_b128 v[180:183], v253
	ds_read_b128 v[184:187], v153 offset:2048
	ds_read_b128 v[188:191], v253 offset:2048
	s_add_u32 s46, s30, 0xfffc0080
	s_addc_u32 s47, s31, -1
	s_and_b64 s[44:45], s[44:45], exec
	s_cselect_b32 s47, s25, s47
	s_cselect_b32 s46, s65, s46
	s_cselect_b32 s45, s66, s69
	s_cselect_b32 s44, s67, s68
	v_lshl_add_u64 v[154:155], s[30:31], 0, v[138:139]
	s_add_i32 m0, s52, 0xc000
	ds_read_b128 v[192:195], v150
	v_xor_b32_e32 v253, 64, v150
	ds_read_b128 v[196:199], v253
	ds_read_b128 v[200:203], v150 offset:2048
	ds_read_b128 v[204:207], v253 offset:2048
	ds_read_b128 v[208:211], v150 offset:4096
	ds_read_b128 v[212:215], v253 offset:4096
	ds_read_b128 v[216:219], v150 offset:6144
	ds_read_b128 v[220:223], v253 offset:6144
	global_load_lds_dwordx4 v[154:155], off
	v_lshl_add_u64 v[154:155], s[30:31], 0, v[136:137]
	s_add_i32 m0, s52, 0xe000
	s_nop 0
	global_load_lds_dwordx4 v[154:155], off
	s_waitcnt vmcnt(8)
	s_waitcnt lgkmcnt(0)
	s_setprio 1
	s_barrier
	v_mfma_f32_16x16x32_bf16 v[124:127], v[160:163], v[192:195], v[124:127]
	v_mfma_f32_16x16x32_bf16 v[124:127], v[164:167], v[196:199], v[124:127]
	v_mfma_f32_16x16x32_bf16 v[116:119], v[172:175], v[196:199], v[116:119]
	v_mfma_f32_16x16x32_bf16 v[116:119], v[168:171], v[192:195], v[116:119]
	v_mfma_f32_16x16x32_bf16 v[100:103], v[168:171], v[200:203], v[100:103]
	v_mfma_f32_16x16x32_bf16 v[100:103], v[172:175], v[204:207], v[100:103]
	v_mfma_f32_16x16x32_bf16 v[108:111], v[164:167], v[204:207], v[108:111]
	v_mfma_f32_16x16x32_bf16 v[108:111], v[160:163], v[200:203], v[108:111]
	v_mfma_f32_16x16x32_bf16 v[92:95], v[160:163], v[208:211], v[92:95]
	v_mfma_f32_16x16x32_bf16 v[92:95], v[164:167], v[212:215], v[92:95]
	v_mfma_f32_16x16x32_bf16 v[84:87], v[172:175], v[212:215], v[84:87]
	v_mfma_f32_16x16x32_bf16 v[84:87], v[168:171], v[208:211], v[84:87]
	v_mfma_f32_16x16x32_bf16 v[68:71], v[168:171], v[216:219], v[68:71]
	v_mfma_f32_16x16x32_bf16 v[68:71], v[172:175], v[220:223], v[68:71]
	v_mfma_f32_16x16x32_bf16 v[76:79], v[164:167], v[220:223], v[76:79]
	v_mfma_f32_16x16x32_bf16 v[76:79], v[160:163], v[216:219], v[76:79]
	v_mfma_f32_16x16x32_bf16 v[120:123], v[176:179], v[192:195], v[120:123]
	v_mfma_f32_16x16x32_bf16 v[120:123], v[180:183], v[196:199], v[120:123]
	v_mfma_f32_16x16x32_bf16 v[112:115], v[188:191], v[196:199], v[112:115]
	v_mfma_f32_16x16x32_bf16 v[112:115], v[184:187], v[192:195], v[112:115]
	v_mfma_f32_16x16x32_bf16 v[96:99], v[184:187], v[200:203], v[96:99]
	v_mfma_f32_16x16x32_bf16 v[96:99], v[188:191], v[204:207], v[96:99]
	v_mfma_f32_16x16x32_bf16 v[104:107], v[180:183], v[204:207], v[104:107]
	v_mfma_f32_16x16x32_bf16 v[104:107], v[176:179], v[200:203], v[104:107]
	v_mfma_f32_16x16x32_bf16 v[88:91], v[176:179], v[208:211], v[88:91]
	v_mfma_f32_16x16x32_bf16 v[88:91], v[180:183], v[212:215], v[88:91]
	v_mfma_f32_16x16x32_bf16 v[80:83], v[188:191], v[212:215], v[80:83]
	v_mfma_f32_16x16x32_bf16 v[80:83], v[184:187], v[208:211], v[80:83]
	v_mfma_f32_16x16x32_bf16 v[64:67], v[184:187], v[216:219], v[64:67]
	v_mfma_f32_16x16x32_bf16 v[64:67], v[188:191], v[220:223], v[64:67]
	v_mfma_f32_16x16x32_bf16 v[72:75], v[180:183], v[220:223], v[72:75]
	v_mfma_f32_16x16x32_bf16 v[72:75], v[176:179], v[216:219], v[72:75]
	s_barrier
	s_setprio 0
	s_add_i32 s71, s61, s49
	v_lshl_add_u64 v[154:155], s[44:45], 0, v[132:133]
	s_mov_b32 m0, s71
	ds_read_b128 v[192:195], v150 offset:16384
	v_xor_b32_e32 v253, 64, v150
	ds_read_b128 v[196:199], v253 offset:16384
	ds_read_b128 v[200:203], v150 offset:18432
	ds_read_b128 v[204:207], v253 offset:18432
	ds_read_b128 v[208:211], v150 offset:20480
	ds_read_b128 v[212:215], v253 offset:20480
	ds_read_b128 v[216:219], v150 offset:22528
	ds_read_b128 v[220:223], v253 offset:22528
	global_load_lds_dwordx4 v[154:155], off
	s_add_i32 m0, s71, 0x2000
	s_add_u32 s72, s44, 0x40000
	v_lshl_add_u64 v[224:225], s[44:45], 0, v[128:129]
	s_addc_u32 s73, s45, 0
	s_add_i32 s71, s62, s49
	global_load_lds_dwordx4 v[224:225], off
	v_lshl_add_u64 v[226:227], s[72:73], 0, v[132:133]
	s_mov_b32 m0, s71
	v_lshl_add_u64 v[228:229], s[46:47], 0, v[130:131]
	global_load_lds_dwordx4 v[226:227], off
	v_lshl_add_u64 v[226:227], s[72:73], 0, v[128:129]
	s_add_i32 m0, s71, 0x2000
	s_nop 0
	global_load_lds_dwordx4 v[226:227], off
	v_lshl_add_u64 v[226:227], s[46:47], 0, v[134:135]
	s_mov_b32 m0, s52
	s_nop 0
	global_load_lds_dwordx4 v[226:227], off
	s_mov_b32 m0, s53
	s_nop 0
	global_load_lds_dwordx4 v[228:229], off
	s_waitcnt vmcnt(8)
	s_waitcnt lgkmcnt(0)
	s_setprio 1
	s_barrier
	v_mfma_f32_16x16x32_bf16 v[60:63], v[160:163], v[192:195], v[60:63]
	v_mfma_f32_16x16x32_bf16 v[60:63], v[164:167], v[196:199], v[60:63]
	v_mfma_f32_16x16x32_bf16 v[52:55], v[172:175], v[196:199], v[52:55]
	v_mfma_f32_16x16x32_bf16 v[52:55], v[168:171], v[192:195], v[52:55]
	v_mfma_f32_16x16x32_bf16 v[36:39], v[168:171], v[200:203], v[36:39]
	v_mfma_f32_16x16x32_bf16 v[36:39], v[172:175], v[204:207], v[36:39]
	v_mfma_f32_16x16x32_bf16 v[44:47], v[164:167], v[204:207], v[44:47]
	v_mfma_f32_16x16x32_bf16 v[44:47], v[160:163], v[200:203], v[44:47]
	v_mfma_f32_16x16x32_bf16 v[28:31], v[160:163], v[208:211], v[28:31]
	v_mfma_f32_16x16x32_bf16 v[28:31], v[164:167], v[212:215], v[28:31]
	v_mfma_f32_16x16x32_bf16 v[20:23], v[172:175], v[212:215], v[20:23]
	v_mfma_f32_16x16x32_bf16 v[20:23], v[168:171], v[208:211], v[20:23]
	v_mfma_f32_16x16x32_bf16 v[4:7], v[168:171], v[216:219], v[4:7]
	v_mfma_f32_16x16x32_bf16 v[4:7], v[172:175], v[220:223], v[4:7]
	v_mfma_f32_16x16x32_bf16 v[12:15], v[164:167], v[220:223], v[12:15]
	v_mfma_f32_16x16x32_bf16 v[12:15], v[160:163], v[216:219], v[12:15]
	v_mfma_f32_16x16x32_bf16 v[56:59], v[176:179], v[192:195], v[56:59]
	v_mfma_f32_16x16x32_bf16 v[56:59], v[180:183], v[196:199], v[56:59]
	v_mfma_f32_16x16x32_bf16 v[48:51], v[188:191], v[196:199], v[48:51]
	v_mfma_f32_16x16x32_bf16 v[48:51], v[184:187], v[192:195], v[48:51]
	v_mfma_f32_16x16x32_bf16 v[32:35], v[184:187], v[200:203], v[32:35]
	v_mfma_f32_16x16x32_bf16 v[32:35], v[188:191], v[204:207], v[32:35]
	v_mfma_f32_16x16x32_bf16 v[40:43], v[180:183], v[204:207], v[40:43]
	v_mfma_f32_16x16x32_bf16 v[40:43], v[176:179], v[200:203], v[40:43]
	v_mfma_f32_16x16x32_bf16 v[24:27], v[176:179], v[208:211], v[24:27]
	v_mfma_f32_16x16x32_bf16 v[24:27], v[180:183], v[212:215], v[24:27]
	v_mfma_f32_16x16x32_bf16 v[16:19], v[188:191], v[212:215], v[16:19]
	v_mfma_f32_16x16x32_bf16 v[16:19], v[184:187], v[208:211], v[16:19]
	v_mfma_f32_16x16x32_bf16 v[0:3], v[184:187], v[216:219], v[0:3]
	v_mfma_f32_16x16x32_bf16 v[0:3], v[188:191], v[220:223], v[0:3]
	v_mfma_f32_16x16x32_bf16 v[8:11], v[180:183], v[220:223], v[8:11]
	v_mfma_f32_16x16x32_bf16 v[8:11], v[176:179], v[216:219], v[8:11]
	s_barrier
	s_setprio 0
	s_add_i32 s71, 0, 0x18000
	v_add_u32_e32 v153, s71, v147
	s_add_i32 s72, 0, 0x1c000
	ds_read_b128 v[160:163], v153
	v_xor_b32_e32 v253, 64, v153
	ds_read_b128 v[164:167], v253
	ds_read_b128 v[168:171], v153 offset:2048
	ds_read_b128 v[172:175], v253 offset:2048
	v_add_u32_e32 v153, s72, v147
	ds_read_b128 v[176:179], v153
	v_xor_b32_e32 v253, 64, v153
	ds_read_b128 v[180:183], v253
	ds_read_b128 v[184:187], v153 offset:2048
	ds_read_b128 v[188:191], v253 offset:2048
	s_add_u32 s46, s46, 0x40000
	s_addc_u32 s47, s47, 0
	s_mov_b32 m0, s54
	v_lshl_add_u64 v[230:231], s[46:47], 0, v[134:135]
	ds_read_b128 v[192:195], v150 offset:32768
	v_xor_b32_e32 v253, 64, v150
	ds_read_b128 v[196:199], v253 offset:32768
	ds_read_b128 v[200:203], v150 offset:34816
	ds_read_b128 v[204:207], v253 offset:34816
	ds_read_b128 v[208:211], v150 offset:36864
	ds_read_b128 v[212:215], v253 offset:36864
	ds_read_b128 v[216:219], v150 offset:38912
	ds_read_b128 v[220:223], v253 offset:38912
	global_load_lds_dwordx4 v[230:231], off
	v_lshl_add_u64 v[230:231], s[46:47], 0, v[130:131]
	s_mov_b32 m0, s55
	s_nop 0
	global_load_lds_dwordx4 v[230:231], off
	s_waitcnt vmcnt(8)
	s_waitcnt lgkmcnt(0)
	s_setprio 1
	s_barrier
	v_mfma_f32_16x16x32_bf16 v[124:127], v[160:163], v[192:195], v[124:127]
	v_mfma_f32_16x16x32_bf16 v[124:127], v[164:167], v[196:199], v[124:127]
	v_mfma_f32_16x16x32_bf16 v[116:119], v[172:175], v[196:199], v[116:119]
	v_mfma_f32_16x16x32_bf16 v[116:119], v[168:171], v[192:195], v[116:119]
	v_mfma_f32_16x16x32_bf16 v[100:103], v[168:171], v[200:203], v[100:103]
	v_mfma_f32_16x16x32_bf16 v[100:103], v[172:175], v[204:207], v[100:103]
	v_mfma_f32_16x16x32_bf16 v[108:111], v[164:167], v[204:207], v[108:111]
	v_mfma_f32_16x16x32_bf16 v[108:111], v[160:163], v[200:203], v[108:111]
	v_mfma_f32_16x16x32_bf16 v[92:95], v[160:163], v[208:211], v[92:95]
	v_mfma_f32_16x16x32_bf16 v[92:95], v[164:167], v[212:215], v[92:95]
	v_mfma_f32_16x16x32_bf16 v[84:87], v[172:175], v[212:215], v[84:87]
	v_mfma_f32_16x16x32_bf16 v[84:87], v[168:171], v[208:211], v[84:87]
	v_mfma_f32_16x16x32_bf16 v[68:71], v[168:171], v[216:219], v[68:71]
	v_mfma_f32_16x16x32_bf16 v[68:71], v[172:175], v[220:223], v[68:71]
	v_mfma_f32_16x16x32_bf16 v[76:79], v[164:167], v[220:223], v[76:79]
	v_mfma_f32_16x16x32_bf16 v[76:79], v[160:163], v[216:219], v[76:79]
	v_mfma_f32_16x16x32_bf16 v[120:123], v[176:179], v[192:195], v[120:123]
	v_mfma_f32_16x16x32_bf16 v[120:123], v[180:183], v[196:199], v[120:123]
	v_mfma_f32_16x16x32_bf16 v[112:115], v[188:191], v[196:199], v[112:115]
	v_mfma_f32_16x16x32_bf16 v[112:115], v[184:187], v[192:195], v[112:115]
	v_mfma_f32_16x16x32_bf16 v[96:99], v[184:187], v[200:203], v[96:99]
	v_mfma_f32_16x16x32_bf16 v[96:99], v[188:191], v[204:207], v[96:99]
	v_mfma_f32_16x16x32_bf16 v[104:107], v[180:183], v[204:207], v[104:107]
	v_mfma_f32_16x16x32_bf16 v[104:107], v[176:179], v[200:203], v[104:107]
	v_mfma_f32_16x16x32_bf16 v[88:91], v[176:179], v[208:211], v[88:91]
	v_mfma_f32_16x16x32_bf16 v[88:91], v[180:183], v[212:215], v[88:91]
	v_mfma_f32_16x16x32_bf16 v[80:83], v[188:191], v[212:215], v[80:83]
	v_mfma_f32_16x16x32_bf16 v[80:83], v[184:187], v[208:211], v[80:83]
	v_mfma_f32_16x16x32_bf16 v[64:67], v[184:187], v[216:219], v[64:67]
	v_mfma_f32_16x16x32_bf16 v[64:67], v[188:191], v[220:223], v[64:67]
	v_mfma_f32_16x16x32_bf16 v[72:75], v[180:183], v[220:223], v[72:75]
	v_mfma_f32_16x16x32_bf16 v[72:75], v[176:179], v[216:219], v[72:75]
	s_barrier
	s_setprio 0
	s_add_i32 s46, s71, s49
	v_lshl_add_u64 v[154:155], v[154:155], 0, s[14:15]
	s_mov_b32 m0, s46
	ds_read_b128 v[192:195], v150 offset:49152
	v_xor_b32_e32 v253, 64, v150
	ds_read_b128 v[196:199], v253 offset:49152
	ds_read_b128 v[200:203], v150 offset:51200
	ds_read_b128 v[204:207], v253 offset:51200
	ds_read_b128 v[208:211], v150 offset:53248
	ds_read_b128 v[212:215], v253 offset:53248
	ds_read_b128 v[216:219], v150 offset:55296
	ds_read_b128 v[220:223], v253 offset:55296
	global_load_lds_dwordx4 v[154:155], off
	s_add_i32 m0, s46, 0x2000
	s_add_u32 s44, s44, 0x40080
	v_lshl_add_u64 v[154:155], v[224:225], 0, s[14:15]
	s_addc_u32 s45, s45, 0
	s_add_i32 s46, s72, s49
	global_load_lds_dwordx4 v[154:155], off
	v_lshl_add_u64 v[154:155], s[44:45], 0, v[132:133]
	s_mov_b32 m0, s46
	s_nop 0
	global_load_lds_dwordx4 v[154:155], off
	v_lshl_add_u64 v[154:155], s[44:45], 0, v[128:129]
	s_add_i32 m0, s46, 0x2000
	s_nop 0
	global_load_lds_dwordx4 v[154:155], off
	v_lshl_add_u64 v[154:155], v[226:227], 0, s[14:15]
	s_mov_b32 m0, s57
	s_nop 0
	global_load_lds_dwordx4 v[154:155], off
	v_lshl_add_u64 v[154:155], v[228:229], 0, s[14:15]
	s_mov_b32 m0, s58
	s_nop 0
	global_load_lds_dwordx4 v[154:155], off
	s_waitcnt vmcnt(8)
	s_waitcnt lgkmcnt(0)
	s_setprio 1
	s_barrier
	v_mfma_f32_16x16x32_bf16 v[60:63], v[160:163], v[192:195], v[60:63]
	v_mfma_f32_16x16x32_bf16 v[60:63], v[164:167], v[196:199], v[60:63]
	v_mfma_f32_16x16x32_bf16 v[52:55], v[172:175], v[196:199], v[52:55]
	v_mfma_f32_16x16x32_bf16 v[52:55], v[168:171], v[192:195], v[52:55]
	v_mfma_f32_16x16x32_bf16 v[36:39], v[168:171], v[200:203], v[36:39]
	v_mfma_f32_16x16x32_bf16 v[36:39], v[172:175], v[204:207], v[36:39]
	v_mfma_f32_16x16x32_bf16 v[44:47], v[164:167], v[204:207], v[44:47]
	v_mfma_f32_16x16x32_bf16 v[44:47], v[160:163], v[200:203], v[44:47]
	v_mfma_f32_16x16x32_bf16 v[28:31], v[160:163], v[208:211], v[28:31]
	v_mfma_f32_16x16x32_bf16 v[28:31], v[164:167], v[212:215], v[28:31]
	v_mfma_f32_16x16x32_bf16 v[20:23], v[172:175], v[212:215], v[20:23]
	v_mfma_f32_16x16x32_bf16 v[20:23], v[168:171], v[208:211], v[20:23]
	v_mfma_f32_16x16x32_bf16 v[4:7], v[168:171], v[216:219], v[4:7]
	v_mfma_f32_16x16x32_bf16 v[4:7], v[172:175], v[220:223], v[4:7]
	v_mfma_f32_16x16x32_bf16 v[12:15], v[164:167], v[220:223], v[12:15]
	v_mfma_f32_16x16x32_bf16 v[12:15], v[160:163], v[216:219], v[12:15]
	v_mfma_f32_16x16x32_bf16 v[56:59], v[176:179], v[192:195], v[56:59]
	v_mfma_f32_16x16x32_bf16 v[56:59], v[180:183], v[196:199], v[56:59]
	v_mfma_f32_16x16x32_bf16 v[48:51], v[188:191], v[196:199], v[48:51]
	v_mfma_f32_16x16x32_bf16 v[48:51], v[184:187], v[192:195], v[48:51]
	v_mfma_f32_16x16x32_bf16 v[32:35], v[184:187], v[200:203], v[32:35]
	v_mfma_f32_16x16x32_bf16 v[32:35], v[188:191], v[204:207], v[32:35]
	v_mfma_f32_16x16x32_bf16 v[40:43], v[180:183], v[204:207], v[40:43]
	v_mfma_f32_16x16x32_bf16 v[40:43], v[176:179], v[200:203], v[40:43]
	v_mfma_f32_16x16x32_bf16 v[24:27], v[176:179], v[208:211], v[24:27]
	v_mfma_f32_16x16x32_bf16 v[24:27], v[180:183], v[212:215], v[24:27]
	v_mfma_f32_16x16x32_bf16 v[16:19], v[188:191], v[212:215], v[16:19]
	v_mfma_f32_16x16x32_bf16 v[16:19], v[184:187], v[208:211], v[16:19]
	v_mfma_f32_16x16x32_bf16 v[0:3], v[184:187], v[216:219], v[0:3]
	v_mfma_f32_16x16x32_bf16 v[0:3], v[188:191], v[220:223], v[0:3]
	v_mfma_f32_16x16x32_bf16 v[8:11], v[180:183], v[220:223], v[8:11]
	v_mfma_f32_16x16x32_bf16 v[8:11], v[176:179], v[216:219], v[8:11]
	s_barrier
	s_setprio 0
	s_add_i32 s70, s70, 2
	s_add_u32 s68, s68, 0x100
	s_addc_u32 s69, s69, 0
	s_add_u32 s30, s30, 0x100
	s_addc_u32 s31, s31, 0
	s_cmp_gt_u32 s70, 13
	s_cbranch_scc1 .LBB0_1100

.Llast_10:
	v_add_u32_e32 v153, s61, v147
	ds_read_b128 v[160:163], v153
	v_xor_b32_e32 v253, 64, v153
	ds_read_b128 v[164:167], v253
	ds_read_b128 v[168:171], v153 offset:2048
	ds_read_b128 v[172:175], v253 offset:2048
	v_add_u32_e32 v153, s62, v147
	ds_read_b128 v[176:179], v153
	v_xor_b32_e32 v253, 64, v153
	ds_read_b128 v[180:183], v253
	ds_read_b128 v[184:187], v153 offset:2048
	ds_read_b128 v[188:191], v253 offset:2048
	s_add_u32 s46, s30, 0xfffc0080
	s_addc_u32 s47, s31, -1
	s_and_b64 s[44:45], s[44:45], exec
	s_cselect_b32 s47, s25, s47
	s_cselect_b32 s46, s65, s46
	s_cselect_b32 s45, s66, s69
	s_cselect_b32 s44, s67, s68
	v_lshl_add_u64 v[154:155], s[30:31], 0, v[138:139]
	s_add_i32 m0, s52, 0xc000
	ds_read_b128 v[192:195], v150
	v_xor_b32_e32 v253, 64, v150
	ds_read_b128 v[196:199], v253
	ds_read_b128 v[200:203], v150 offset:2048
	ds_read_b128 v[204:207], v253 offset:2048
	ds_read_b128 v[208:211], v150 offset:4096
	ds_read_b128 v[212:215], v253 offset:4096
	ds_read_b128 v[216:219], v150 offset:6144
	ds_read_b128 v[220:223], v253 offset:6144
	global_load_lds_dwordx4 v[154:155], off
	v_lshl_add_u64 v[154:155], s[30:31], 0, v[136:137]
	s_add_i32 m0, s52, 0xe000
	s_nop 0
	global_load_lds_dwordx4 v[154:155], off
	s_waitcnt vmcnt(8)
	s_waitcnt lgkmcnt(0)
	s_setprio 1
	s_barrier
	v_mfma_f32_16x16x32_bf16 v[124:127], v[160:163], v[192:195], v[124:127]
	v_mfma_f32_16x16x32_bf16 v[124:127], v[164:167], v[196:199], v[124:127]
	v_mfma_f32_16x16x32_bf16 v[116:119], v[172:175], v[196:199], v[116:119]
	v_mfma_f32_16x16x32_bf16 v[116:119], v[168:171], v[192:195], v[116:119]
	v_mfma_f32_16x16x32_bf16 v[100:103], v[168:171], v[200:203], v[100:103]
	v_mfma_f32_16x16x32_bf16 v[100:103], v[172:175], v[204:207], v[100:103]
	v_mfma_f32_16x16x32_bf16 v[108:111], v[164:167], v[204:207], v[108:111]
	v_mfma_f32_16x16x32_bf16 v[108:111], v[160:163], v[200:203], v[108:111]
	v_mfma_f32_16x16x32_bf16 v[92:95], v[160:163], v[208:211], v[92:95]
	v_mfma_f32_16x16x32_bf16 v[92:95], v[164:167], v[212:215], v[92:95]
	v_mfma_f32_16x16x32_bf16 v[84:87], v[172:175], v[212:215], v[84:87]
	v_mfma_f32_16x16x32_bf16 v[84:87], v[168:171], v[208:211], v[84:87]
	v_mfma_f32_16x16x32_bf16 v[68:71], v[168:171], v[216:219], v[68:71]
	v_mfma_f32_16x16x32_bf16 v[68:71], v[172:175], v[220:223], v[68:71]
	v_mfma_f32_16x16x32_bf16 v[76:79], v[164:167], v[220:223], v[76:79]
	v_mfma_f32_16x16x32_bf16 v[76:79], v[160:163], v[216:219], v[76:79]
	v_mfma_f32_16x16x32_bf16 v[120:123], v[176:179], v[192:195], v[120:123]
	v_mfma_f32_16x16x32_bf16 v[120:123], v[180:183], v[196:199], v[120:123]
	v_mfma_f32_16x16x32_bf16 v[112:115], v[188:191], v[196:199], v[112:115]
	v_mfma_f32_16x16x32_bf16 v[112:115], v[184:187], v[192:195], v[112:115]
	v_mfma_f32_16x16x32_bf16 v[96:99], v[184:187], v[200:203], v[96:99]
	v_mfma_f32_16x16x32_bf16 v[96:99], v[188:191], v[204:207], v[96:99]
	v_mfma_f32_16x16x32_bf16 v[104:107], v[180:183], v[204:207], v[104:107]
	v_mfma_f32_16x16x32_bf16 v[104:107], v[176:179], v[200:203], v[104:107]
	v_mfma_f32_16x16x32_bf16 v[88:91], v[176:179], v[208:211], v[88:91]
	v_mfma_f32_16x16x32_bf16 v[88:91], v[180:183], v[212:215], v[88:91]
	v_mfma_f32_16x16x32_bf16 v[80:83], v[188:191], v[212:215], v[80:83]
	v_mfma_f32_16x16x32_bf16 v[80:83], v[184:187], v[208:211], v[80:83]
	v_mfma_f32_16x16x32_bf16 v[64:67], v[184:187], v[216:219], v[64:67]
	v_mfma_f32_16x16x32_bf16 v[64:67], v[188:191], v[220:223], v[64:67]
	v_mfma_f32_16x16x32_bf16 v[72:75], v[180:183], v[220:223], v[72:75]
	v_mfma_f32_16x16x32_bf16 v[72:75], v[176:179], v[216:219], v[72:75]
	s_barrier
	s_setprio 0
	s_add_i32 s71, s61, s49
	v_lshl_add_u64 v[154:155], s[44:45], 0, v[132:133]
	s_mov_b32 m0, s71
	ds_read_b128 v[192:195], v150 offset:16384
	v_xor_b32_e32 v253, 64, v150
	ds_read_b128 v[196:199], v253 offset:16384
	ds_read_b128 v[200:203], v150 offset:18432
	ds_read_b128 v[204:207], v253 offset:18432
	ds_read_b128 v[208:211], v150 offset:20480
	ds_read_b128 v[212:215], v253 offset:20480
	ds_read_b128 v[216:219], v150 offset:22528
	ds_read_b128 v[220:223], v253 offset:22528
	global_load_lds_dwordx4 v[154:155], off
	s_add_i32 m0, s71, 0x2000
	s_add_u32 s72, s44, 0x40000
	v_lshl_add_u64 v[224:225], s[44:45], 0, v[128:129]
	s_addc_u32 s73, s45, 0
	s_add_i32 s71, s62, s49
	global_load_lds_dwordx4 v[224:225], off
	v_lshl_add_u64 v[226:227], s[72:73], 0, v[132:133]
	s_mov_b32 m0, s71
	v_lshl_add_u64 v[228:229], s[46:47], 0, v[130:131]
	global_load_lds_dwordx4 v[226:227], off
	v_lshl_add_u64 v[226:227], s[72:73], 0, v[128:129]
	s_add_i32 m0, s71, 0x2000
	s_nop 0
	global_load_lds_dwordx4 v[226:227], off
	v_lshl_add_u64 v[226:227], s[46:47], 0, v[134:135]
	s_mov_b32 m0, s52
	s_nop 0
	global_load_lds_dwordx4 v[226:227], off
	s_mov_b32 m0, s53
	s_nop 0
	global_load_lds_dwordx4 v[228:229], off
	s_waitcnt vmcnt(8)
	s_waitcnt lgkmcnt(0)
	s_setprio 1
	s_barrier
	v_mfma_f32_16x16x32_bf16 v[60:63], v[160:163], v[192:195], v[60:63]
	v_mfma_f32_16x16x32_bf16 v[60:63], v[164:167], v[196:199], v[60:63]
	v_mfma_f32_16x16x32_bf16 v[52:55], v[172:175], v[196:199], v[52:55]
	v_mfma_f32_16x16x32_bf16 v[52:55], v[168:171], v[192:195], v[52:55]
	v_mfma_f32_16x16x32_bf16 v[36:39], v[168:171], v[200:203], v[36:39]
	v_mfma_f32_16x16x32_bf16 v[36:39], v[172:175], v[204:207], v[36:39]
	v_mfma_f32_16x16x32_bf16 v[44:47], v[164:167], v[204:207], v[44:47]
	v_mfma_f32_16x16x32_bf16 v[44:47], v[160:163], v[200:203], v[44:47]
	v_mfma_f32_16x16x32_bf16 v[28:31], v[160:163], v[208:211], v[28:31]
	v_mfma_f32_16x16x32_bf16 v[28:31], v[164:167], v[212:215], v[28:31]
	v_mfma_f32_16x16x32_bf16 v[20:23], v[172:175], v[212:215], v[20:23]
	v_mfma_f32_16x16x32_bf16 v[20:23], v[168:171], v[208:211], v[20:23]
	v_mfma_f32_16x16x32_bf16 v[4:7], v[168:171], v[216:219], v[4:7]
	v_mfma_f32_16x16x32_bf16 v[4:7], v[172:175], v[220:223], v[4:7]
	v_mfma_f32_16x16x32_bf16 v[12:15], v[164:167], v[220:223], v[12:15]
	v_mfma_f32_16x16x32_bf16 v[12:15], v[160:163], v[216:219], v[12:15]
	v_mfma_f32_16x16x32_bf16 v[56:59], v[176:179], v[192:195], v[56:59]
	v_mfma_f32_16x16x32_bf16 v[56:59], v[180:183], v[196:199], v[56:59]
	v_mfma_f32_16x16x32_bf16 v[48:51], v[188:191], v[196:199], v[48:51]
	v_mfma_f32_16x16x32_bf16 v[48:51], v[184:187], v[192:195], v[48:51]
	v_mfma_f32_16x16x32_bf16 v[32:35], v[184:187], v[200:203], v[32:35]
	v_mfma_f32_16x16x32_bf16 v[32:35], v[188:191], v[204:207], v[32:35]
	v_mfma_f32_16x16x32_bf16 v[40:43], v[180:183], v[204:207], v[40:43]
	v_mfma_f32_16x16x32_bf16 v[40:43], v[176:179], v[200:203], v[40:43]
	v_mfma_f32_16x16x32_bf16 v[24:27], v[176:179], v[208:211], v[24:27]
	v_mfma_f32_16x16x32_bf16 v[24:27], v[180:183], v[212:215], v[24:27]
	v_mfma_f32_16x16x32_bf16 v[16:19], v[188:191], v[212:215], v[16:19]
	v_mfma_f32_16x16x32_bf16 v[16:19], v[184:187], v[208:211], v[16:19]
	v_mfma_f32_16x16x32_bf16 v[0:3], v[184:187], v[216:219], v[0:3]
	v_mfma_f32_16x16x32_bf16 v[0:3], v[188:191], v[220:223], v[0:3]
	v_mfma_f32_16x16x32_bf16 v[8:11], v[180:183], v[220:223], v[8:11]
	v_mfma_f32_16x16x32_bf16 v[8:11], v[176:179], v[216:219], v[8:11]
	s_barrier
	s_setprio 0
	s_add_i32 s71, 0, 0x18000
	v_add_u32_e32 v153, s71, v147
	s_add_i32 s72, 0, 0x1c000
	ds_read_b128 v[160:163], v153
	v_xor_b32_e32 v253, 64, v153
	ds_read_b128 v[164:167], v253
	ds_read_b128 v[168:171], v153 offset:2048
	ds_read_b128 v[172:175], v253 offset:2048
	v_add_u32_e32 v153, s72, v147
	ds_read_b128 v[176:179], v153
	v_xor_b32_e32 v253, 64, v153
	ds_read_b128 v[180:183], v253
	ds_read_b128 v[184:187], v153 offset:2048
	ds_read_b128 v[188:191], v253 offset:2048
	s_add_u32 s46, s46, 0x40000
	s_addc_u32 s47, s47, 0
	s_mov_b32 m0, s54
	v_lshl_add_u64 v[230:231], s[46:47], 0, v[134:135]
	ds_read_b128 v[192:195], v150 offset:32768
	v_xor_b32_e32 v253, 64, v150
	ds_read_b128 v[196:199], v253 offset:32768
	ds_read_b128 v[200:203], v150 offset:34816
	ds_read_b128 v[204:207], v253 offset:34816
	ds_read_b128 v[208:211], v150 offset:36864
	ds_read_b128 v[212:215], v253 offset:36864
	ds_read_b128 v[216:219], v150 offset:38912
	ds_read_b128 v[220:223], v253 offset:38912
	global_load_lds_dwordx4 v[230:231], off
	v_lshl_add_u64 v[230:231], s[46:47], 0, v[130:131]
	s_mov_b32 m0, s55
	s_nop 0
	global_load_lds_dwordx4 v[230:231], off
	s_waitcnt vmcnt(8)
	s_waitcnt lgkmcnt(0)
	s_setprio 1
	s_barrier
	v_mfma_f32_16x16x32_bf16 v[124:127], v[160:163], v[192:195], v[124:127]
	v_mfma_f32_16x16x32_bf16 v[124:127], v[164:167], v[196:199], v[124:127]
	v_mfma_f32_16x16x32_bf16 v[116:119], v[172:175], v[196:199], v[116:119]
	v_mfma_f32_16x16x32_bf16 v[116:119], v[168:171], v[192:195], v[116:119]
	v_mfma_f32_16x16x32_bf16 v[100:103], v[168:171], v[200:203], v[100:103]
	v_mfma_f32_16x16x32_bf16 v[100:103], v[172:175], v[204:207], v[100:103]
	v_mfma_f32_16x16x32_bf16 v[108:111], v[164:167], v[204:207], v[108:111]
	v_mfma_f32_16x16x32_bf16 v[108:111], v[160:163], v[200:203], v[108:111]
	v_mfma_f32_16x16x32_bf16 v[92:95], v[160:163], v[208:211], v[92:95]
	v_mfma_f32_16x16x32_bf16 v[92:95], v[164:167], v[212:215], v[92:95]
	v_mfma_f32_16x16x32_bf16 v[84:87], v[172:175], v[212:215], v[84:87]
	v_mfma_f32_16x16x32_bf16 v[84:87], v[168:171], v[208:211], v[84:87]
	v_mfma_f32_16x16x32_bf16 v[68:71], v[168:171], v[216:219], v[68:71]
	v_mfma_f32_16x16x32_bf16 v[68:71], v[172:175], v[220:223], v[68:71]
	v_mfma_f32_16x16x32_bf16 v[76:79], v[164:167], v[220:223], v[76:79]
	v_mfma_f32_16x16x32_bf16 v[76:79], v[160:163], v[216:219], v[76:79]
	v_mfma_f32_16x16x32_bf16 v[120:123], v[176:179], v[192:195], v[120:123]
	v_mfma_f32_16x16x32_bf16 v[120:123], v[180:183], v[196:199], v[120:123]
	v_mfma_f32_16x16x32_bf16 v[112:115], v[188:191], v[196:199], v[112:115]
	v_mfma_f32_16x16x32_bf16 v[112:115], v[184:187], v[192:195], v[112:115]
	v_mfma_f32_16x16x32_bf16 v[96:99], v[184:187], v[200:203], v[96:99]
	v_mfma_f32_16x16x32_bf16 v[96:99], v[188:191], v[204:207], v[96:99]
	v_mfma_f32_16x16x32_bf16 v[104:107], v[180:183], v[204:207], v[104:107]
	v_mfma_f32_16x16x32_bf16 v[104:107], v[176:179], v[200:203], v[104:107]
	v_mfma_f32_16x16x32_bf16 v[88:91], v[176:179], v[208:211], v[88:91]
	v_mfma_f32_16x16x32_bf16 v[88:91], v[180:183], v[212:215], v[88:91]
	v_mfma_f32_16x16x32_bf16 v[80:83], v[188:191], v[212:215], v[80:83]
	v_mfma_f32_16x16x32_bf16 v[80:83], v[184:187], v[208:211], v[80:83]
	v_mfma_f32_16x16x32_bf16 v[64:67], v[184:187], v[216:219], v[64:67]
	v_mfma_f32_16x16x32_bf16 v[64:67], v[188:191], v[220:223], v[64:67]
	v_mfma_f32_16x16x32_bf16 v[72:75], v[180:183], v[220:223], v[72:75]
	v_mfma_f32_16x16x32_bf16 v[72:75], v[176:179], v[216:219], v[72:75]
	s_barrier
	s_setprio 0
	v_add_u32_e32 v234, 0x21000, v151
	ds_read_b128 v[236:239], v234
	ds_read_b128 v[240:243], v234 offset:256
	ds_read_b128 v[244:247], v234 offset:512
	ds_read_b128 v[248:251], v234 offset:768
	v_add_u32_e32 v235, s23, v146
	v_mul_u32_u24_e32 v235, 0x1600, v235
	v_lshl_or_b32 v234, s64, 7, v149
	v_lshl_add_u32 v235, v234, 1, v235
	s_add_i32 s46, s71, s49
	v_lshl_add_u64 v[154:155], v[154:155], 0, s[14:15]
	s_mov_b32 m0, s46
	ds_read_b128 v[192:195], v150 offset:49152
	v_xor_b32_e32 v253, 64, v150
	ds_read_b128 v[196:199], v253 offset:49152
	ds_read_b128 v[200:203], v150 offset:51200
	ds_read_b128 v[204:207], v253 offset:51200
	ds_read_b128 v[208:211], v150 offset:53248
	ds_read_b128 v[212:215], v253 offset:53248
	ds_read_b128 v[216:219], v150 offset:55296
	ds_read_b128 v[220:223], v253 offset:55296
	global_load_lds_dwordx4 v[154:155], off
	s_add_i32 m0, s46, 0x2000
	s_add_u32 s44, s44, 0x40080
	v_lshl_add_u64 v[154:155], v[224:225], 0, s[14:15]
	s_addc_u32 s45, s45, 0
	s_add_i32 s46, s72, s49
	global_load_lds_dwordx4 v[154:155], off
	v_lshl_add_u64 v[154:155], s[44:45], 0, v[132:133]
	s_mov_b32 m0, s46
	s_nop 0
	global_load_lds_dwordx4 v[154:155], off
	v_lshl_add_u64 v[154:155], s[44:45], 0, v[128:129]
	s_add_i32 m0, s46, 0x2000
	s_nop 0
	global_load_lds_dwordx4 v[154:155], off
	v_lshl_add_u64 v[154:155], v[226:227], 0, s[14:15]
	s_mov_b32 m0, s57
	s_nop 0
	global_load_lds_dwordx4 v[154:155], off
	v_lshl_add_u64 v[154:155], v[228:229], 0, s[14:15]
	s_mov_b32 m0, s58
	s_nop 0
	global_load_lds_dwordx4 v[154:155], off
	s_waitcnt lgkmcnt(8)
	v_add_f32_e32 v236, v236, v237
	v_add_f32_e32 v238, v238, v239
	v_add_f32_e32 v240, v240, v241
	v_add_f32_e32 v242, v242, v243
	v_add_f32_e32 v244, v244, v245
	v_add_f32_e32 v246, v246, v247
	v_add_f32_e32 v248, v248, v249
	v_add_f32_e32 v250, v250, v251
	v_add_f32_e32 v236, v236, v238
	v_add_f32_e32 v240, v240, v242
	v_add_f32_e32 v244, v244, v246
	v_add_f32_e32 v248, v248, v250
	v_fmamk_f32 v236, v236, 0x3a800000, v152
	v_fmamk_f32 v240, v240, 0x3a800000, v152
	v_fmamk_f32 v244, v244, 0x3a800000, v152
	v_fmamk_f32 v248, v248, 0x3a800000, v152
	v_rsq_f32_e32 v236, v236
	v_rsq_f32_e32 v240, v240
	v_rsq_f32_e32 v244, v244
	v_rsq_f32_e32 v248, v248
	v_mul_f32_e32 v252, 0xbfb8aa3b, v236
	v_mul_f32_e32 v254, v236, v236
	v_rcp_f32_e32 v254, v254
	v_pk_mul_f32 v[120:121], v[124:125], v[120:121]
	v_pk_mul_f32 v[122:123], v[126:127], v[122:123]
	v_pk_mul_f32 v[112:113], v[116:117], v[112:113]
	v_pk_mul_f32 v[114:115], v[118:119], v[114:115]
	v_pk_mul_f32 v[124:125], v[124:125], v[252:253] op_sel_hi:[1,0]
	v_pk_mul_f32 v[126:127], v[126:127], v[252:253] op_sel_hi:[1,0]
	v_pk_mul_f32 v[116:117], v[116:117], v[252:253] op_sel_hi:[1,0]
	v_pk_mul_f32 v[118:119], v[118:119], v[252:253] op_sel_hi:[1,0]
	v_exp_f32_e32 v124, v124
	v_exp_f32_e32 v125, v125
	v_exp_f32_e32 v126, v126
	v_exp_f32_e32 v127, v127
	v_exp_f32_e32 v116, v116
	v_exp_f32_e32 v117, v117
	v_exp_f32_e32 v118, v118
	v_exp_f32_e32 v119, v119
	v_pk_fma_f32 v[124:125], v[124:125], v[254:255], v[254:255] op_sel_hi:[1,0,0]
	v_pk_fma_f32 v[126:127], v[126:127], v[254:255], v[254:255] op_sel_hi:[1,0,0]
	v_pk_fma_f32 v[116:117], v[116:117], v[254:255], v[254:255] op_sel_hi:[1,0,0]
	v_pk_fma_f32 v[118:119], v[118:119], v[254:255], v[254:255] op_sel_hi:[1,0,0]
	v_rcp_f32_e32 v124, v124
	v_rcp_f32_e32 v125, v125
	v_rcp_f32_e32 v126, v126
	v_rcp_f32_e32 v127, v127
	v_rcp_f32_e32 v116, v116
	v_rcp_f32_e32 v117, v117
	v_rcp_f32_e32 v118, v118
	v_rcp_f32_e32 v119, v119
	v_pk_mul_f32 v[120:121], v[120:121], v[124:125]
	v_pk_mul_f32 v[122:123], v[122:123], v[126:127]
	v_pk_mul_f32 v[112:113], v[112:113], v[116:117]
	v_pk_mul_f32 v[114:115], v[114:115], v[118:119]
	v_cvt_pk_bf16_f32 v120, v120, v121
	v_cvt_pk_bf16_f32 v121, v122, v123
	v_cvt_pk_bf16_f32 v122, v112, v113
	v_cvt_pk_bf16_f32 v123, v114, v115
	global_store_dwordx4 v235, v[120:123], s[10:11]
	v_add_u32_e32 v234, 0x16000, v235
	v_mul_f32_e32 v252, 0xbfb8aa3b, v240
	v_mul_f32_e32 v254, v240, v240
	v_rcp_f32_e32 v254, v254
	v_pk_mul_f32 v[104:105], v[108:109], v[104:105]
	v_pk_mul_f32 v[106:107], v[110:111], v[106:107]
	v_pk_mul_f32 v[96:97], v[100:101], v[96:97]
	v_pk_mul_f32 v[98:99], v[102:103], v[98:99]
	v_pk_mul_f32 v[108:109], v[108:109], v[252:253] op_sel_hi:[1,0]
	v_pk_mul_f32 v[110:111], v[110:111], v[252:253] op_sel_hi:[1,0]
	v_pk_mul_f32 v[100:101], v[100:101], v[252:253] op_sel_hi:[1,0]
	v_pk_mul_f32 v[102:103], v[102:103], v[252:253] op_sel_hi:[1,0]
	v_exp_f32_e32 v108, v108
	v_exp_f32_e32 v109, v109
	v_exp_f32_e32 v110, v110
	v_exp_f32_e32 v111, v111
	v_exp_f32_e32 v100, v100
	v_exp_f32_e32 v101, v101
	v_exp_f32_e32 v102, v102
	v_exp_f32_e32 v103, v103
	v_pk_fma_f32 v[108:109], v[108:109], v[254:255], v[254:255] op_sel_hi:[1,0,0]
	v_pk_fma_f32 v[110:111], v[110:111], v[254:255], v[254:255] op_sel_hi:[1,0,0]
	v_pk_fma_f32 v[100:101], v[100:101], v[254:255], v[254:255] op_sel_hi:[1,0,0]
	v_pk_fma_f32 v[102:103], v[102:103], v[254:255], v[254:255] op_sel_hi:[1,0,0]
	v_rcp_f32_e32 v108, v108
	v_rcp_f32_e32 v109, v109
	v_rcp_f32_e32 v110, v110
	v_rcp_f32_e32 v111, v111
	v_rcp_f32_e32 v100, v100
	v_rcp_f32_e32 v101, v101
	v_rcp_f32_e32 v102, v102
	v_rcp_f32_e32 v103, v103
	v_pk_mul_f32 v[104:105], v[104:105], v[108:109]
	v_pk_mul_f32 v[106:107], v[106:107], v[110:111]
	v_pk_mul_f32 v[96:97], v[96:97], v[100:101]
	v_pk_mul_f32 v[98:99], v[98:99], v[102:103]
	v_cvt_pk_bf16_f32 v104, v104, v105
	v_cvt_pk_bf16_f32 v105, v106, v107
	v_cvt_pk_bf16_f32 v106, v96, v97
	v_cvt_pk_bf16_f32 v107, v98, v99
	global_store_dwordx4 v234, v[104:107], s[10:11]
	v_add_u32_e32 v235, 0x16000, v234
	v_mul_f32_e32 v252, 0xbfb8aa3b, v244
	v_mul_f32_e32 v254, v244, v244
	v_rcp_f32_e32 v254, v254
	v_pk_mul_f32 v[88:89], v[92:93], v[88:89]
	v_pk_mul_f32 v[90:91], v[94:95], v[90:91]
	v_pk_mul_f32 v[80:81], v[84:85], v[80:81]
	v_pk_mul_f32 v[82:83], v[86:87], v[82:83]
	v_pk_mul_f32 v[92:93], v[92:93], v[252:253] op_sel_hi:[1,0]
	v_pk_mul_f32 v[94:95], v[94:95], v[252:253] op_sel_hi:[1,0]
	v_pk_mul_f32 v[84:85], v[84:85], v[252:253] op_sel_hi:[1,0]
	v_pk_mul_f32 v[86:87], v[86:87], v[252:253] op_sel_hi:[1,0]
	v_exp_f32_e32 v92, v92
	v_exp_f32_e32 v93, v93
	v_exp_f32_e32 v94, v94
	v_exp_f32_e32 v95, v95
	v_exp_f32_e32 v84, v84
	v_exp_f32_e32 v85, v85
	v_exp_f32_e32 v86, v86
	v_exp_f32_e32 v87, v87
	v_pk_fma_f32 v[92:93], v[92:93], v[254:255], v[254:255] op_sel_hi:[1,0,0]
	v_pk_fma_f32 v[94:95], v[94:95], v[254:255], v[254:255] op_sel_hi:[1,0,0]
	v_pk_fma_f32 v[84:85], v[84:85], v[254:255], v[254:255] op_sel_hi:[1,0,0]
	v_pk_fma_f32 v[86:87], v[86:87], v[254:255], v[254:255] op_sel_hi:[1,0,0]
	v_rcp_f32_e32 v92, v92
	v_rcp_f32_e32 v93, v93
	v_rcp_f32_e32 v94, v94
	v_rcp_f32_e32 v95, v95
	v_rcp_f32_e32 v84, v84
	v_rcp_f32_e32 v85, v85
	v_rcp_f32_e32 v86, v86
	v_rcp_f32_e32 v87, v87
	v_pk_mul_f32 v[88:89], v[88:89], v[92:93]
	v_pk_mul_f32 v[90:91], v[90:91], v[94:95]
	v_pk_mul_f32 v[80:81], v[80:81], v[84:85]
	v_pk_mul_f32 v[82:83], v[82:83], v[86:87]
	v_cvt_pk_bf16_f32 v88, v88, v89
	v_cvt_pk_bf16_f32 v89, v90, v91
	v_cvt_pk_bf16_f32 v90, v80, v81
	v_cvt_pk_bf16_f32 v91, v82, v83
	global_store_dwordx4 v235, v[88:91], s[10:11]
	v_add_u32_e32 v234, 0x16000, v235
	v_mul_f32_e32 v252, 0xbfb8aa3b, v248
	v_mul_f32_e32 v254, v248, v248
	v_rcp_f32_e32 v254, v254
	v_pk_mul_f32 v[72:73], v[76:77], v[72:73]
	v_pk_mul_f32 v[74:75], v[78:79], v[74:75]
	v_pk_mul_f32 v[64:65], v[68:69], v[64:65]
	v_pk_mul_f32 v[66:67], v[70:71], v[66:67]
	v_pk_mul_f32 v[76:77], v[76:77], v[252:253] op_sel_hi:[1,0]
	v_pk_mul_f32 v[78:79], v[78:79], v[252:253] op_sel_hi:[1,0]
	v_pk_mul_f32 v[68:69], v[68:69], v[252:253] op_sel_hi:[1,0]
	v_pk_mul_f32 v[70:71], v[70:71], v[252:253] op_sel_hi:[1,0]
	v_exp_f32_e32 v76, v76
	v_exp_f32_e32 v77, v77
	v_exp_f32_e32 v78, v78
	v_exp_f32_e32 v79, v79
	v_exp_f32_e32 v68, v68
	v_exp_f32_e32 v69, v69
	v_exp_f32_e32 v70, v70
	v_exp_f32_e32 v71, v71
	v_pk_fma_f32 v[76:77], v[76:77], v[254:255], v[254:255] op_sel_hi:[1,0,0]
	v_pk_fma_f32 v[78:79], v[78:79], v[254:255], v[254:255] op_sel_hi:[1,0,0]
	v_pk_fma_f32 v[68:69], v[68:69], v[254:255], v[254:255] op_sel_hi:[1,0,0]
	v_pk_fma_f32 v[70:71], v[70:71], v[254:255], v[254:255] op_sel_hi:[1,0,0]
	v_rcp_f32_e32 v76, v76
	v_rcp_f32_e32 v77, v77
	v_rcp_f32_e32 v78, v78
	v_rcp_f32_e32 v79, v79
	v_rcp_f32_e32 v68, v68
	v_rcp_f32_e32 v69, v69
	v_rcp_f32_e32 v70, v70
	v_rcp_f32_e32 v71, v71
	v_pk_mul_f32 v[72:73], v[72:73], v[76:77]
	v_pk_mul_f32 v[74:75], v[74:75], v[78:79]
	v_pk_mul_f32 v[64:65], v[64:65], v[68:69]
	v_pk_mul_f32 v[66:67], v[66:67], v[70:71]
	v_cvt_pk_bf16_f32 v72, v72, v73
	v_cvt_pk_bf16_f32 v73, v74, v75
	v_cvt_pk_bf16_f32 v74, v64, v65
	v_cvt_pk_bf16_f32 v75, v66, v67
	global_store_dwordx4 v234, v[72:75], s[10:11]
	s_waitcnt vmcnt(12)
	s_waitcnt lgkmcnt(0)
	s_setprio 1
	s_barrier
	v_mfma_f32_16x16x32_bf16 v[60:63], v[160:163], v[192:195], v[60:63]
	v_mfma_f32_16x16x32_bf16 v[60:63], v[164:167], v[196:199], v[60:63]
	v_mfma_f32_16x16x32_bf16 v[52:55], v[172:175], v[196:199], v[52:55]
	v_mfma_f32_16x16x32_bf16 v[52:55], v[168:171], v[192:195], v[52:55]
	v_mfma_f32_16x16x32_bf16 v[36:39], v[168:171], v[200:203], v[36:39]
	v_mfma_f32_16x16x32_bf16 v[36:39], v[172:175], v[204:207], v[36:39]
	v_mfma_f32_16x16x32_bf16 v[44:47], v[164:167], v[204:207], v[44:47]
	v_mfma_f32_16x16x32_bf16 v[44:47], v[160:163], v[200:203], v[44:47]
	v_mfma_f32_16x16x32_bf16 v[28:31], v[160:163], v[208:211], v[28:31]
	v_mfma_f32_16x16x32_bf16 v[28:31], v[164:167], v[212:215], v[28:31]
	v_mfma_f32_16x16x32_bf16 v[20:23], v[172:175], v[212:215], v[20:23]
	v_mfma_f32_16x16x32_bf16 v[20:23], v[168:171], v[208:211], v[20:23]
	v_mfma_f32_16x16x32_bf16 v[4:7], v[168:171], v[216:219], v[4:7]
	v_mfma_f32_16x16x32_bf16 v[4:7], v[172:175], v[220:223], v[4:7]
	v_mfma_f32_16x16x32_bf16 v[12:15], v[164:167], v[220:223], v[12:15]
	v_mfma_f32_16x16x32_bf16 v[12:15], v[160:163], v[216:219], v[12:15]
	v_mfma_f32_16x16x32_bf16 v[56:59], v[176:179], v[192:195], v[56:59]
	v_mfma_f32_16x16x32_bf16 v[56:59], v[180:183], v[196:199], v[56:59]
	v_mfma_f32_16x16x32_bf16 v[48:51], v[188:191], v[196:199], v[48:51]
	v_mfma_f32_16x16x32_bf16 v[48:51], v[184:187], v[192:195], v[48:51]
	v_mfma_f32_16x16x32_bf16 v[32:35], v[184:187], v[200:203], v[32:35]
	v_mfma_f32_16x16x32_bf16 v[32:35], v[188:191], v[204:207], v[32:35]
	v_mfma_f32_16x16x32_bf16 v[40:43], v[180:183], v[204:207], v[40:43]
	v_mfma_f32_16x16x32_bf16 v[40:43], v[176:179], v[200:203], v[40:43]
	v_mfma_f32_16x16x32_bf16 v[24:27], v[176:179], v[208:211], v[24:27]
	v_mfma_f32_16x16x32_bf16 v[24:27], v[180:183], v[212:215], v[24:27]
	v_mfma_f32_16x16x32_bf16 v[16:19], v[188:191], v[212:215], v[16:19]
	v_mfma_f32_16x16x32_bf16 v[16:19], v[184:187], v[208:211], v[16:19]
	v_mfma_f32_16x16x32_bf16 v[0:3], v[184:187], v[216:219], v[0:3]
	v_mfma_f32_16x16x32_bf16 v[0:3], v[188:191], v[220:223], v[0:3]
	v_mfma_f32_16x16x32_bf16 v[8:11], v[180:183], v[220:223], v[8:11]
	v_mfma_f32_16x16x32_bf16 v[8:11], v[176:179], v[216:219], v[8:11]
	s_barrier
	s_setprio 0
	s_add_i32 s70, s70, 2
	s_add_u32 s68, s68, 0x100
	s_addc_u32 s69, s69, 0
	s_add_u32 s30, s30, 0x100
	s_addc_u32 s31, s31, 0

.LBB0_1180:
	s_add_u32 s72, s50, 0x100
	s_addc_u32 s73, s51, 0
	s_mov_b32 s74, -2
	s_waitcnt lgkmcnt(0)
	s_cmp_eq_u32 s63, 1
	s_cbranch_scc1 .Lfa_11
	ds_read_b128 v[128:131], v188
	v_xor_b32_e32 v253, 64, v188
	ds_read_b128 v[132:135], v253
	ds_read_b128 v[136:139], v188 offset:2048
	ds_read_b128 v[140:143], v253 offset:2048
	ds_read_b128 v[144:147], v189
	v_xor_b32_e32 v253, 64, v189
	ds_read_b128 v[148:151], v253
	ds_read_b128 v[172:175], v189 offset:2048
	ds_read_b128 v[176:179], v253 offset:2048
	s_add_u32 s50, s48, 0x100
	s_addc_u32 s51, s49, 0
	s_cmp_eq_u32 s74, 40
	s_cselect_b32 s55, s11, s51
	s_cselect_b32 s54, s10, s50
	s_cselect_b32 s53, s47, s73
	s_cselect_b32 s52, s46, s72
	v_lshl_add_u64 v[220:221], s[48:49], 0, v[166:167]
	s_add_i32 m0, s59, 0xc000
	ds_read_b128 v[180:183], v190
	v_xor_b32_e32 v253, 64, v190
	ds_read_b128 v[192:195], v253
	ds_read_b128 v[196:199], v190 offset:2048
	ds_read_b128 v[200:203], v253 offset:2048
	ds_read_b128 v[204:207], v190 offset:4096
	ds_read_b128 v[208:211], v253 offset:4096
	ds_read_b128 v[212:215], v190 offset:6144
	ds_read_b128 v[216:219], v253 offset:6144
	global_load_lds_dwordx4 v[220:221], off
	v_lshl_add_u64 v[220:221], s[48:49], 0, v[164:165]
	s_add_i32 m0, s59, 0xe000
	s_nop 0
	global_load_lds_dwordx4 v[220:221], off
	s_waitcnt vmcnt(24)
	s_waitcnt lgkmcnt(0)
	s_setprio 1
	s_barrier
	v_mfma_f32_16x16x32_bf16 v[124:127], v[128:131], v[180:183], 0
	v_mfma_f32_16x16x32_bf16 v[120:123], v[136:139], v[180:183], 0
	v_mfma_f32_16x16x32_bf16 v[108:111], v[128:131], v[196:199], 0
	v_mfma_f32_16x16x32_bf16 v[104:107], v[136:139], v[196:199], 0
	v_mfma_f32_16x16x32_bf16 v[92:95], v[128:131], v[204:207], 0
	v_mfma_f32_16x16x32_bf16 v[88:91], v[136:139], v[204:207], 0
	v_mfma_f32_16x16x32_bf16 v[76:79], v[128:131], v[212:215], 0
	v_mfma_f32_16x16x32_bf16 v[72:75], v[136:139], v[212:215], 0
	v_mfma_f32_16x16x32_bf16 v[124:127], v[132:135], v[192:195], v[124:127]
	v_mfma_f32_16x16x32_bf16 v[120:123], v[140:143], v[192:195], v[120:123]
	v_mfma_f32_16x16x32_bf16 v[108:111], v[132:135], v[200:203], v[108:111]
	v_mfma_f32_16x16x32_bf16 v[104:107], v[140:143], v[200:203], v[104:107]
	v_mfma_f32_16x16x32_bf16 v[92:95], v[132:135], v[208:211], v[92:95]
	v_mfma_f32_16x16x32_bf16 v[88:91], v[140:143], v[208:211], v[88:91]
	v_mfma_f32_16x16x32_bf16 v[76:79], v[132:135], v[216:219], v[76:79]
	v_mfma_f32_16x16x32_bf16 v[72:75], v[140:143], v[216:219], v[72:75]
	v_mfma_f32_16x16x32_bf16 v[116:119], v[144:147], v[180:183], 0
	v_mfma_f32_16x16x32_bf16 v[112:115], v[172:175], v[180:183], 0
	v_mfma_f32_16x16x32_bf16 v[100:103], v[144:147], v[196:199], 0
	v_mfma_f32_16x16x32_bf16 v[96:99], v[172:175], v[196:199], 0
	v_mfma_f32_16x16x32_bf16 v[84:87], v[144:147], v[204:207], 0
	v_mfma_f32_16x16x32_bf16 v[80:83], v[172:175], v[204:207], 0
	v_mfma_f32_16x16x32_bf16 v[68:71], v[144:147], v[212:215], 0
	v_mfma_f32_16x16x32_bf16 v[64:67], v[172:175], v[212:215], 0
	v_mfma_f32_16x16x32_bf16 v[116:119], v[148:151], v[192:195], v[116:119]
	v_mfma_f32_16x16x32_bf16 v[112:115], v[176:179], v[192:195], v[112:115]
	v_mfma_f32_16x16x32_bf16 v[100:103], v[148:151], v[200:203], v[100:103]
	v_mfma_f32_16x16x32_bf16 v[96:99], v[176:179], v[200:203], v[96:99]
	v_mfma_f32_16x16x32_bf16 v[84:87], v[148:151], v[208:211], v[84:87]
	v_mfma_f32_16x16x32_bf16 v[80:83], v[176:179], v[208:211], v[80:83]
	v_mfma_f32_16x16x32_bf16 v[68:71], v[148:151], v[216:219], v[68:71]
	v_mfma_f32_16x16x32_bf16 v[64:67], v[176:179], v[216:219], v[64:67]
	s_barrier
	s_setprio 0
	s_add_i32 s48, s68, s58
	v_lshl_add_u64 v[220:221], s[52:53], 0, v[154:155]
	s_mov_b32 m0, s48
	ds_read_b128 v[180:183], v190 offset:16384
	v_xor_b32_e32 v253, 64, v190
	ds_read_b128 v[192:195], v253 offset:16384
	ds_read_b128 v[196:199], v190 offset:18432
	ds_read_b128 v[200:203], v253 offset:18432
	ds_read_b128 v[204:207], v190 offset:20480
	ds_read_b128 v[208:211], v253 offset:20480
	ds_read_b128 v[212:215], v190 offset:22528
	ds_read_b128 v[216:219], v253 offset:22528
	global_load_lds_dwordx4 v[220:221], off
	s_add_i32 m0, s48, 0x2000
	s_add_u32 s48, s52, 0xb0000
	v_lshl_add_u64 v[222:223], s[52:53], 0, v[162:163]
	s_addc_u32 s49, s53, 0
	s_add_i32 s75, s69, s58
	global_load_lds_dwordx4 v[222:223], off
	v_lshl_add_u64 v[224:225], s[48:49], 0, v[154:155]
	s_mov_b32 m0, s75
	v_lshl_add_u64 v[226:227], s[54:55], 0, v[160:161]
	global_load_lds_dwordx4 v[224:225], off
	v_lshl_add_u64 v[224:225], s[48:49], 0, v[162:163]
	s_add_i32 m0, s75, 0x2000
	s_nop 0
	global_load_lds_dwordx4 v[224:225], off
	v_lshl_add_u64 v[224:225], s[54:55], 0, v[152:153]
	s_mov_b32 m0, s59
	s_nop 0
	global_load_lds_dwordx4 v[224:225], off
	s_mov_b32 m0, s60
	s_nop 0
	global_load_lds_dwordx4 v[226:227], off
	s_waitcnt vmcnt(24)
	s_waitcnt lgkmcnt(0)
	s_setprio 1
	s_barrier
	v_mfma_f32_16x16x32_bf16 v[60:63], v[128:131], v[180:183], 0
	v_mfma_f32_16x16x32_bf16 v[56:59], v[136:139], v[180:183], 0
	v_mfma_f32_16x16x32_bf16 v[44:47], v[128:131], v[196:199], 0
	v_mfma_f32_16x16x32_bf16 v[40:43], v[136:139], v[196:199], 0
	v_mfma_f32_16x16x32_bf16 v[28:31], v[128:131], v[204:207], 0
	v_mfma_f32_16x16x32_bf16 v[24:27], v[136:139], v[204:207], 0
	v_mfma_f32_16x16x32_bf16 v[12:15], v[128:131], v[212:215], 0
	v_mfma_f32_16x16x32_bf16 v[8:11], v[136:139], v[212:215], 0
	v_mfma_f32_16x16x32_bf16 v[60:63], v[132:135], v[192:195], v[60:63]
	v_mfma_f32_16x16x32_bf16 v[56:59], v[140:143], v[192:195], v[56:59]
	v_mfma_f32_16x16x32_bf16 v[44:47], v[132:135], v[200:203], v[44:47]
	v_mfma_f32_16x16x32_bf16 v[40:43], v[140:143], v[200:203], v[40:43]
	v_mfma_f32_16x16x32_bf16 v[28:31], v[132:135], v[208:211], v[28:31]
	v_mfma_f32_16x16x32_bf16 v[24:27], v[140:143], v[208:211], v[24:27]
	v_mfma_f32_16x16x32_bf16 v[12:15], v[132:135], v[216:219], v[12:15]
	v_mfma_f32_16x16x32_bf16 v[8:11], v[140:143], v[216:219], v[8:11]
	v_mfma_f32_16x16x32_bf16 v[52:55], v[144:147], v[180:183], 0
	v_mfma_f32_16x16x32_bf16 v[48:51], v[172:175], v[180:183], 0
	v_mfma_f32_16x16x32_bf16 v[36:39], v[144:147], v[196:199], 0
	v_mfma_f32_16x16x32_bf16 v[32:35], v[172:175], v[196:199], 0
	v_mfma_f32_16x16x32_bf16 v[20:23], v[144:147], v[204:207], 0
	v_mfma_f32_16x16x32_bf16 v[16:19], v[172:175], v[204:207], 0
	v_mfma_f32_16x16x32_bf16 v[4:7], v[144:147], v[212:215], 0
	v_mfma_f32_16x16x32_bf16 v[0:3], v[172:175], v[212:215], 0
	v_mfma_f32_16x16x32_bf16 v[52:55], v[148:151], v[192:195], v[52:55]
	v_mfma_f32_16x16x32_bf16 v[48:51], v[176:179], v[192:195], v[48:51]
	v_mfma_f32_16x16x32_bf16 v[36:39], v[148:151], v[200:203], v[36:39]
	v_mfma_f32_16x16x32_bf16 v[32:35], v[176:179], v[200:203], v[32:35]
	v_mfma_f32_16x16x32_bf16 v[20:23], v[148:151], v[208:211], v[20:23]
	v_mfma_f32_16x16x32_bf16 v[16:19], v[176:179], v[208:211], v[16:19]
	v_mfma_f32_16x16x32_bf16 v[4:7], v[148:151], v[216:219], v[4:7]
	v_mfma_f32_16x16x32_bf16 v[0:3], v[176:179], v[216:219], v[0:3]
	s_barrier
	s_setprio 0
	s_add_i32 s75, 0, 0x18000
	s_add_i32 s76, 0, 0x1c000
	v_add_u32_e32 v140, s75, v185
	v_add_u32_e32 v176, s76, v185
	ds_read_b128 v[128:131], v140
	v_xor_b32_e32 v253, 64, v140
	ds_read_b128 v[132:135], v253
	ds_read_b128 v[136:139], v140 offset:2048
	ds_read_b128 v[140:143], v253 offset:2048
	ds_read_b128 v[144:147], v176
	v_xor_b32_e32 v253, 64, v176
	ds_read_b128 v[148:151], v253
	ds_read_b128 v[172:175], v176 offset:2048
	ds_read_b128 v[176:179], v253 offset:2048
	s_add_u32 s48, s54, 0xb0000
	s_addc_u32 s49, s55, 0
	s_mov_b32 m0, s61
	v_lshl_add_u64 v[228:229], s[48:49], 0, v[152:153]
	ds_read_b128 v[180:183], v190 offset:32768
	v_xor_b32_e32 v253, 64, v190
	ds_read_b128 v[192:195], v253 offset:32768
	ds_read_b128 v[196:199], v190 offset:34816
	ds_read_b128 v[200:203], v253 offset:34816
	ds_read_b128 v[204:207], v190 offset:36864
	ds_read_b128 v[208:211], v253 offset:36864
	ds_read_b128 v[212:215], v190 offset:38912
	ds_read_b128 v[216:219], v253 offset:38912
	global_load_lds_dwordx4 v[228:229], off
	v_lshl_add_u64 v[228:229], s[48:49], 0, v[160:161]
	s_mov_b32 m0, s62
	s_nop 0
	global_load_lds_dwordx4 v[228:229], off
	s_waitcnt vmcnt(8)
	s_waitcnt lgkmcnt(0)
	s_setprio 1
	s_barrier
	v_mfma_f32_16x16x32_bf16 v[124:127], v[128:131], v[180:183], v[124:127]
	v_mfma_f32_16x16x32_bf16 v[124:127], v[132:135], v[192:195], v[124:127]
	v_mfma_f32_16x16x32_bf16 v[120:123], v[140:143], v[192:195], v[120:123]
	v_mfma_f32_16x16x32_bf16 v[120:123], v[136:139], v[180:183], v[120:123]
	v_mfma_f32_16x16x32_bf16 v[104:107], v[136:139], v[196:199], v[104:107]
	v_mfma_f32_16x16x32_bf16 v[104:107], v[140:143], v[200:203], v[104:107]
	v_mfma_f32_16x16x32_bf16 v[108:111], v[132:135], v[200:203], v[108:111]
	v_mfma_f32_16x16x32_bf16 v[108:111], v[128:131], v[196:199], v[108:111]
	v_mfma_f32_16x16x32_bf16 v[92:95], v[128:131], v[204:207], v[92:95]
	v_mfma_f32_16x16x32_bf16 v[92:95], v[132:135], v[208:211], v[92:95]
	v_mfma_f32_16x16x32_bf16 v[88:91], v[140:143], v[208:211], v[88:91]
	v_mfma_f32_16x16x32_bf16 v[88:91], v[136:139], v[204:207], v[88:91]
	v_mfma_f32_16x16x32_bf16 v[72:75], v[136:139], v[212:215], v[72:75]
	v_mfma_f32_16x16x32_bf16 v[72:75], v[140:143], v[216:219], v[72:75]
	v_mfma_f32_16x16x32_bf16 v[76:79], v[132:135], v[216:219], v[76:79]
	v_mfma_f32_16x16x32_bf16 v[76:79], v[128:131], v[212:215], v[76:79]
	v_mfma_f32_16x16x32_bf16 v[116:119], v[144:147], v[180:183], v[116:119]
	v_mfma_f32_16x16x32_bf16 v[116:119], v[148:151], v[192:195], v[116:119]
	v_mfma_f32_16x16x32_bf16 v[112:115], v[176:179], v[192:195], v[112:115]
	v_mfma_f32_16x16x32_bf16 v[112:115], v[172:175], v[180:183], v[112:115]
	v_mfma_f32_16x16x32_bf16 v[96:99], v[172:175], v[196:199], v[96:99]
	v_mfma_f32_16x16x32_bf16 v[96:99], v[176:179], v[200:203], v[96:99]
	v_mfma_f32_16x16x32_bf16 v[100:103], v[148:151], v[200:203], v[100:103]
	v_mfma_f32_16x16x32_bf16 v[100:103], v[144:147], v[196:199], v[100:103]
	v_mfma_f32_16x16x32_bf16 v[84:87], v[144:147], v[204:207], v[84:87]
	v_mfma_f32_16x16x32_bf16 v[84:87], v[148:151], v[208:211], v[84:87]
	v_mfma_f32_16x16x32_bf16 v[80:83], v[176:179], v[208:211], v[80:83]
	v_mfma_f32_16x16x32_bf16 v[80:83], v[172:175], v[204:207], v[80:83]
	v_mfma_f32_16x16x32_bf16 v[64:67], v[172:175], v[212:215], v[64:67]
	v_mfma_f32_16x16x32_bf16 v[64:67], v[176:179], v[216:219], v[64:67]
	v_mfma_f32_16x16x32_bf16 v[68:71], v[148:151], v[216:219], v[68:71]
	v_mfma_f32_16x16x32_bf16 v[68:71], v[144:147], v[212:215], v[68:71]
	s_barrier
	s_setprio 0
	s_add_i32 s48, s75, s58
	v_lshl_add_u64 v[220:221], v[220:221], 0, s[22:23]
	s_mov_b32 m0, s48
	ds_read_b128 v[180:183], v190 offset:49152
	v_xor_b32_e32 v253, 64, v190
	ds_read_b128 v[192:195], v253 offset:49152
	ds_read_b128 v[196:199], v190 offset:51200
	ds_read_b128 v[200:203], v253 offset:51200
	ds_read_b128 v[204:207], v190 offset:53248
	ds_read_b128 v[208:211], v253 offset:53248
	ds_read_b128 v[212:215], v190 offset:55296
	ds_read_b128 v[216:219], v253 offset:55296
	global_load_lds_dwordx4 v[220:221], off
	s_add_i32 m0, s48, 0x2000
	s_add_u32 s48, s52, 0xb0080
	v_lshl_add_u64 v[220:221], v[222:223], 0, s[22:23]
	s_addc_u32 s49, s53, 0
	s_add_i32 s52, s76, s58
	global_load_lds_dwordx4 v[220:221], off
	v_lshl_add_u64 v[220:221], s[48:49], 0, v[154:155]
	s_mov_b32 m0, s52
	s_nop 0
	global_load_lds_dwordx4 v[220:221], off
	v_lshl_add_u64 v[220:221], s[48:49], 0, v[162:163]
	s_add_i32 m0, s52, 0x2000
	s_nop 0
	global_load_lds_dwordx4 v[220:221], off
	v_lshl_add_u64 v[220:221], v[224:225], 0, s[22:23]
	s_mov_b32 m0, s3
	s_nop 0
	global_load_lds_dwordx4 v[220:221], off
	v_lshl_add_u64 v[220:221], v[226:227], 0, s[22:23]
	s_mov_b32 m0, s64
	s_nop 0
	global_load_lds_dwordx4 v[220:221], off
	s_waitcnt vmcnt(8)
	s_waitcnt lgkmcnt(0)
	s_setprio 1
	s_barrier
	v_mfma_f32_16x16x32_bf16 v[60:63], v[128:131], v[180:183], v[60:63]
	v_mfma_f32_16x16x32_bf16 v[60:63], v[132:135], v[192:195], v[60:63]
	v_mfma_f32_16x16x32_bf16 v[56:59], v[140:143], v[192:195], v[56:59]
	v_mfma_f32_16x16x32_bf16 v[56:59], v[136:139], v[180:183], v[56:59]
	v_mfma_f32_16x16x32_bf16 v[40:43], v[136:139], v[196:199], v[40:43]
	v_mfma_f32_16x16x32_bf16 v[40:43], v[140:143], v[200:203], v[40:43]
	v_mfma_f32_16x16x32_bf16 v[44:47], v[132:135], v[200:203], v[44:47]
	v_mfma_f32_16x16x32_bf16 v[44:47], v[128:131], v[196:199], v[44:47]
	v_mfma_f32_16x16x32_bf16 v[28:31], v[128:131], v[204:207], v[28:31]
	v_mfma_f32_16x16x32_bf16 v[28:31], v[132:135], v[208:211], v[28:31]
	v_mfma_f32_16x16x32_bf16 v[24:27], v[140:143], v[208:211], v[24:27]
	v_mfma_f32_16x16x32_bf16 v[24:27], v[136:139], v[204:207], v[24:27]
	v_mfma_f32_16x16x32_bf16 v[8:11], v[136:139], v[212:215], v[8:11]
	v_mfma_f32_16x16x32_bf16 v[8:11], v[140:143], v[216:219], v[8:11]
	v_mfma_f32_16x16x32_bf16 v[12:15], v[132:135], v[216:219], v[12:15]
	v_mfma_f32_16x16x32_bf16 v[12:15], v[128:131], v[212:215], v[12:15]
	v_mfma_f32_16x16x32_bf16 v[52:55], v[144:147], v[180:183], v[52:55]
	v_mfma_f32_16x16x32_bf16 v[52:55], v[148:151], v[192:195], v[52:55]
	v_mfma_f32_16x16x32_bf16 v[48:51], v[176:179], v[192:195], v[48:51]
	v_mfma_f32_16x16x32_bf16 v[48:51], v[172:175], v[180:183], v[48:51]
	v_mfma_f32_16x16x32_bf16 v[32:35], v[172:175], v[196:199], v[32:35]
	v_mfma_f32_16x16x32_bf16 v[32:35], v[176:179], v[200:203], v[32:35]
	v_mfma_f32_16x16x32_bf16 v[36:39], v[148:151], v[200:203], v[36:39]
	v_mfma_f32_16x16x32_bf16 v[36:39], v[144:147], v[196:199], v[36:39]
	v_mfma_f32_16x16x32_bf16 v[20:23], v[144:147], v[204:207], v[20:23]
	v_mfma_f32_16x16x32_bf16 v[20:23], v[148:151], v[208:211], v[20:23]
	v_mfma_f32_16x16x32_bf16 v[16:19], v[176:179], v[208:211], v[16:19]
	v_mfma_f32_16x16x32_bf16 v[16:19], v[172:175], v[204:207], v[16:19]
	v_mfma_f32_16x16x32_bf16 v[0:3], v[172:175], v[212:215], v[0:3]
	v_mfma_f32_16x16x32_bf16 v[0:3], v[176:179], v[216:219], v[0:3]
	v_mfma_f32_16x16x32_bf16 v[4:7], v[148:151], v[216:219], v[4:7]
	v_mfma_f32_16x16x32_bf16 v[4:7], v[144:147], v[212:215], v[4:7]
	s_barrier
	s_setprio 0
	s_add_i32 s74, s74, 2
	s_add_u32 s72, s72, 0x100
	s_addc_u32 s73, s73, 0
	s_cmp_gt_u32 s74, 41
	s_mov_b64 s[48:49], s[50:51]
	s_branch .LBB0_1181
.Lfa_11:
	ds_read_b128 v[128:131], v188
	v_xor_b32_e32 v253, 64, v188
	ds_read_b128 v[132:135], v253
	ds_read_b128 v[136:139], v188 offset:2048
	ds_read_b128 v[140:143], v253 offset:2048
	ds_read_b128 v[144:147], v189
	v_xor_b32_e32 v253, 64, v189
	ds_read_b128 v[148:151], v253
	ds_read_b128 v[172:175], v189 offset:2048
	ds_read_b128 v[176:179], v253 offset:2048
	s_add_u32 s50, s48, 0x100
	s_addc_u32 s51, s49, 0
	s_cmp_eq_u32 s74, 40
	s_cselect_b32 s55, s11, s51
	s_cselect_b32 s54, s10, s50
	s_cselect_b32 s53, s47, s73
	s_cselect_b32 s52, s46, s72
	v_lshl_add_u64 v[220:221], s[48:49], 0, v[166:167]
	s_add_i32 m0, s59, 0xc000
	ds_read_b128 v[180:183], v190
	v_xor_b32_e32 v253, 64, v190
	ds_read_b128 v[192:195], v253
	ds_read_b128 v[196:199], v190 offset:2048
	ds_read_b128 v[200:203], v253 offset:2048
	ds_read_b128 v[204:207], v190 offset:4096
	ds_read_b128 v[208:211], v253 offset:4096
	ds_read_b128 v[212:215], v190 offset:6144
	ds_read_b128 v[216:219], v253 offset:6144
	global_load_lds_dwordx4 v[220:221], off
	v_lshl_add_u64 v[220:221], s[48:49], 0, v[164:165]
	s_add_i32 m0, s59, 0xe000
	s_nop 0
	global_load_lds_dwordx4 v[220:221], off
	s_waitcnt vmcnt(8)
	s_waitcnt lgkmcnt(0)
	s_setprio 1
	s_barrier
	v_mfma_f32_16x16x32_bf16 v[124:127], v[128:131], v[180:183], 0
	v_mfma_f32_16x16x32_bf16 v[120:123], v[136:139], v[180:183], 0
	v_mfma_f32_16x16x32_bf16 v[108:111], v[128:131], v[196:199], 0
	v_mfma_f32_16x16x32_bf16 v[104:107], v[136:139], v[196:199], 0
	v_mfma_f32_16x16x32_bf16 v[92:95], v[128:131], v[204:207], 0
	v_mfma_f32_16x16x32_bf16 v[88:91], v[136:139], v[204:207], 0
	v_mfma_f32_16x16x32_bf16 v[76:79], v[128:131], v[212:215], 0
	v_mfma_f32_16x16x32_bf16 v[72:75], v[136:139], v[212:215], 0
	v_mfma_f32_16x16x32_bf16 v[124:127], v[132:135], v[192:195], v[124:127]
	v_mfma_f32_16x16x32_bf16 v[120:123], v[140:143], v[192:195], v[120:123]
	v_mfma_f32_16x16x32_bf16 v[108:111], v[132:135], v[200:203], v[108:111]
	v_mfma_f32_16x16x32_bf16 v[104:107], v[140:143], v[200:203], v[104:107]
	v_mfma_f32_16x16x32_bf16 v[92:95], v[132:135], v[208:211], v[92:95]
	v_mfma_f32_16x16x32_bf16 v[88:91], v[140:143], v[208:211], v[88:91]
	v_mfma_f32_16x16x32_bf16 v[76:79], v[132:135], v[216:219], v[76:79]
	v_mfma_f32_16x16x32_bf16 v[72:75], v[140:143], v[216:219], v[72:75]
	v_mfma_f32_16x16x32_bf16 v[116:119], v[144:147], v[180:183], 0
	v_mfma_f32_16x16x32_bf16 v[112:115], v[172:175], v[180:183], 0
	v_mfma_f32_16x16x32_bf16 v[100:103], v[144:147], v[196:199], 0
	v_mfma_f32_16x16x32_bf16 v[96:99], v[172:175], v[196:199], 0
	v_mfma_f32_16x16x32_bf16 v[84:87], v[144:147], v[204:207], 0
	v_mfma_f32_16x16x32_bf16 v[80:83], v[172:175], v[204:207], 0
	v_mfma_f32_16x16x32_bf16 v[68:71], v[144:147], v[212:215], 0
	v_mfma_f32_16x16x32_bf16 v[64:67], v[172:175], v[212:215], 0
	v_mfma_f32_16x16x32_bf16 v[116:119], v[148:151], v[192:195], v[116:119]
	v_mfma_f32_16x16x32_bf16 v[112:115], v[176:179], v[192:195], v[112:115]
	v_mfma_f32_16x16x32_bf16 v[100:103], v[148:151], v[200:203], v[100:103]
	v_mfma_f32_16x16x32_bf16 v[96:99], v[176:179], v[200:203], v[96:99]
	v_mfma_f32_16x16x32_bf16 v[84:87], v[148:151], v[208:211], v[84:87]
	v_mfma_f32_16x16x32_bf16 v[80:83], v[176:179], v[208:211], v[80:83]
	v_mfma_f32_16x16x32_bf16 v[68:71], v[148:151], v[216:219], v[68:71]
	v_mfma_f32_16x16x32_bf16 v[64:67], v[176:179], v[216:219], v[64:67]
	s_barrier
	s_setprio 0
	s_add_i32 s48, s68, s58
	v_lshl_add_u64 v[220:221], s[52:53], 0, v[154:155]
	s_mov_b32 m0, s48
	ds_read_b128 v[180:183], v190 offset:16384
	v_xor_b32_e32 v253, 64, v190
	ds_read_b128 v[192:195], v253 offset:16384
	ds_read_b128 v[196:199], v190 offset:18432
	ds_read_b128 v[200:203], v253 offset:18432
	ds_read_b128 v[204:207], v190 offset:20480
	ds_read_b128 v[208:211], v253 offset:20480
	ds_read_b128 v[212:215], v190 offset:22528
	ds_read_b128 v[216:219], v253 offset:22528
	global_load_lds_dwordx4 v[220:221], off
	s_add_i32 m0, s48, 0x2000
	s_add_u32 s48, s52, 0xb0000
	v_lshl_add_u64 v[222:223], s[52:53], 0, v[162:163]
	s_addc_u32 s49, s53, 0
	s_add_i32 s75, s69, s58
	global_load_lds_dwordx4 v[222:223], off
	v_lshl_add_u64 v[224:225], s[48:49], 0, v[154:155]
	s_mov_b32 m0, s75
	v_lshl_add_u64 v[226:227], s[54:55], 0, v[160:161]
	global_load_lds_dwordx4 v[224:225], off
	v_lshl_add_u64 v[224:225], s[48:49], 0, v[162:163]
	s_add_i32 m0, s75, 0x2000
	s_nop 0
	global_load_lds_dwordx4 v[224:225], off
	v_lshl_add_u64 v[224:225], s[54:55], 0, v[152:153]
	s_mov_b32 m0, s59
	s_nop 0
	global_load_lds_dwordx4 v[224:225], off
	s_mov_b32 m0, s60
	s_nop 0
	global_load_lds_dwordx4 v[226:227], off
	s_waitcnt vmcnt(8)
	s_waitcnt lgkmcnt(0)
	s_setprio 1
	s_barrier
	v_mfma_f32_16x16x32_bf16 v[60:63], v[128:131], v[180:183], 0
	v_mfma_f32_16x16x32_bf16 v[56:59], v[136:139], v[180:183], 0
	v_mfma_f32_16x16x32_bf16 v[44:47], v[128:131], v[196:199], 0
	v_mfma_f32_16x16x32_bf16 v[40:43], v[136:139], v[196:199], 0
	v_mfma_f32_16x16x32_bf16 v[28:31], v[128:131], v[204:207], 0
	v_mfma_f32_16x16x32_bf16 v[24:27], v[136:139], v[204:207], 0
	v_mfma_f32_16x16x32_bf16 v[12:15], v[128:131], v[212:215], 0
	v_mfma_f32_16x16x32_bf16 v[8:11], v[136:139], v[212:215], 0
	v_mfma_f32_16x16x32_bf16 v[60:63], v[132:135], v[192:195], v[60:63]
	v_mfma_f32_16x16x32_bf16 v[56:59], v[140:143], v[192:195], v[56:59]
	v_mfma_f32_16x16x32_bf16 v[44:47], v[132:135], v[200:203], v[44:47]
	v_mfma_f32_16x16x32_bf16 v[40:43], v[140:143], v[200:203], v[40:43]
	v_mfma_f32_16x16x32_bf16 v[28:31], v[132:135], v[208:211], v[28:31]
	v_mfma_f32_16x16x32_bf16 v[24:27], v[140:143], v[208:211], v[24:27]
	v_mfma_f32_16x16x32_bf16 v[12:15], v[132:135], v[216:219], v[12:15]
	v_mfma_f32_16x16x32_bf16 v[8:11], v[140:143], v[216:219], v[8:11]
	v_mfma_f32_16x16x32_bf16 v[52:55], v[144:147], v[180:183], 0
	v_mfma_f32_16x16x32_bf16 v[48:51], v[172:175], v[180:183], 0
	v_mfma_f32_16x16x32_bf16 v[36:39], v[144:147], v[196:199], 0
	v_mfma_f32_16x16x32_bf16 v[32:35], v[172:175], v[196:199], 0
	v_mfma_f32_16x16x32_bf16 v[20:23], v[144:147], v[204:207], 0
	v_mfma_f32_16x16x32_bf16 v[16:19], v[172:175], v[204:207], 0
	v_mfma_f32_16x16x32_bf16 v[4:7], v[144:147], v[212:215], 0
	v_mfma_f32_16x16x32_bf16 v[0:3], v[172:175], v[212:215], 0
	v_mfma_f32_16x16x32_bf16 v[52:55], v[148:151], v[192:195], v[52:55]
	v_mfma_f32_16x16x32_bf16 v[48:51], v[176:179], v[192:195], v[48:51]
	v_mfma_f32_16x16x32_bf16 v[36:39], v[148:151], v[200:203], v[36:39]
	v_mfma_f32_16x16x32_bf16 v[32:35], v[176:179], v[200:203], v[32:35]
	v_mfma_f32_16x16x32_bf16 v[20:23], v[148:151], v[208:211], v[20:23]
	v_mfma_f32_16x16x32_bf16 v[16:19], v[176:179], v[208:211], v[16:19]
	v_mfma_f32_16x16x32_bf16 v[4:7], v[148:151], v[216:219], v[4:7]
	v_mfma_f32_16x16x32_bf16 v[0:3], v[176:179], v[216:219], v[0:3]
	s_barrier
	s_setprio 0
	s_add_i32 s75, 0, 0x18000
	s_add_i32 s76, 0, 0x1c000
	v_add_u32_e32 v140, s75, v185
	v_add_u32_e32 v176, s76, v185
	ds_read_b128 v[128:131], v140
	v_xor_b32_e32 v253, 64, v140
	ds_read_b128 v[132:135], v253
	ds_read_b128 v[136:139], v140 offset:2048
	ds_read_b128 v[140:143], v253 offset:2048
	ds_read_b128 v[144:147], v176
	v_xor_b32_e32 v253, 64, v176
	ds_read_b128 v[148:151], v253
	ds_read_b128 v[172:175], v176 offset:2048
	ds_read_b128 v[176:179], v253 offset:2048
	s_add_u32 s48, s54, 0xb0000
	s_addc_u32 s49, s55, 0
	s_mov_b32 m0, s61
	v_lshl_add_u64 v[228:229], s[48:49], 0, v[152:153]
	ds_read_b128 v[180:183], v190 offset:32768
	v_xor_b32_e32 v253, 64, v190
	ds_read_b128 v[192:195], v253 offset:32768
	ds_read_b128 v[196:199], v190 offset:34816
	ds_read_b128 v[200:203], v253 offset:34816
	ds_read_b128 v[204:207], v190 offset:36864
	ds_read_b128 v[208:211], v253 offset:36864
	ds_read_b128 v[212:215], v190 offset:38912
	ds_read_b128 v[216:219], v253 offset:38912
	global_load_lds_dwordx4 v[228:229], off
	v_lshl_add_u64 v[228:229], s[48:49], 0, v[160:161]
	s_mov_b32 m0, s62
	s_nop 0
	global_load_lds_dwordx4 v[228:229], off
	s_waitcnt vmcnt(8)
	s_waitcnt lgkmcnt(0)
	s_setprio 1
	s_barrier
	v_mfma_f32_16x16x32_bf16 v[124:127], v[128:131], v[180:183], v[124:127]
	v_mfma_f32_16x16x32_bf16 v[124:127], v[132:135], v[192:195], v[124:127]
	v_mfma_f32_16x16x32_bf16 v[120:123], v[140:143], v[192:195], v[120:123]
	v_mfma_f32_16x16x32_bf16 v[120:123], v[136:139], v[180:183], v[120:123]
	v_mfma_f32_16x16x32_bf16 v[104:107], v[136:139], v[196:199], v[104:107]
	v_mfma_f32_16x16x32_bf16 v[104:107], v[140:143], v[200:203], v[104:107]
	v_mfma_f32_16x16x32_bf16 v[108:111], v[132:135], v[200:203], v[108:111]
	v_mfma_f32_16x16x32_bf16 v[108:111], v[128:131], v[196:199], v[108:111]
	v_mfma_f32_16x16x32_bf16 v[92:95], v[128:131], v[204:207], v[92:95]
	v_mfma_f32_16x16x32_bf16 v[92:95], v[132:135], v[208:211], v[92:95]
	v_mfma_f32_16x16x32_bf16 v[88:91], v[140:143], v[208:211], v[88:91]
	v_mfma_f32_16x16x32_bf16 v[88:91], v[136:139], v[204:207], v[88:91]
	v_mfma_f32_16x16x32_bf16 v[72:75], v[136:139], v[212:215], v[72:75]
	v_mfma_f32_16x16x32_bf16 v[72:75], v[140:143], v[216:219], v[72:75]
	v_mfma_f32_16x16x32_bf16 v[76:79], v[132:135], v[216:219], v[76:79]
	v_mfma_f32_16x16x32_bf16 v[76:79], v[128:131], v[212:215], v[76:79]
	v_mfma_f32_16x16x32_bf16 v[116:119], v[144:147], v[180:183], v[116:119]
	v_mfma_f32_16x16x32_bf16 v[116:119], v[148:151], v[192:195], v[116:119]
	v_mfma_f32_16x16x32_bf16 v[112:115], v[176:179], v[192:195], v[112:115]
	v_mfma_f32_16x16x32_bf16 v[112:115], v[172:175], v[180:183], v[112:115]
	v_mfma_f32_16x16x32_bf16 v[96:99], v[172:175], v[196:199], v[96:99]
	v_mfma_f32_16x16x32_bf16 v[96:99], v[176:179], v[200:203], v[96:99]
	v_mfma_f32_16x16x32_bf16 v[100:103], v[148:151], v[200:203], v[100:103]
	v_mfma_f32_16x16x32_bf16 v[100:103], v[144:147], v[196:199], v[100:103]
	v_mfma_f32_16x16x32_bf16 v[84:87], v[144:147], v[204:207], v[84:87]
	v_mfma_f32_16x16x32_bf16 v[84:87], v[148:151], v[208:211], v[84:87]
	v_mfma_f32_16x16x32_bf16 v[80:83], v[176:179], v[208:211], v[80:83]
	v_mfma_f32_16x16x32_bf16 v[80:83], v[172:175], v[204:207], v[80:83]
	v_mfma_f32_16x16x32_bf16 v[64:67], v[172:175], v[212:215], v[64:67]
	v_mfma_f32_16x16x32_bf16 v[64:67], v[176:179], v[216:219], v[64:67]
	v_mfma_f32_16x16x32_bf16 v[68:71], v[148:151], v[216:219], v[68:71]
	v_mfma_f32_16x16x32_bf16 v[68:71], v[144:147], v[212:215], v[68:71]
	s_barrier
	s_setprio 0
	s_add_i32 s48, s75, s58
	v_lshl_add_u64 v[220:221], v[220:221], 0, s[22:23]
	s_mov_b32 m0, s48
	ds_read_b128 v[180:183], v190 offset:49152
	v_xor_b32_e32 v253, 64, v190
	ds_read_b128 v[192:195], v253 offset:49152
	ds_read_b128 v[196:199], v190 offset:51200
	ds_read_b128 v[200:203], v253 offset:51200
	ds_read_b128 v[204:207], v190 offset:53248
	ds_read_b128 v[208:211], v253 offset:53248
	ds_read_b128 v[212:215], v190 offset:55296
	ds_read_b128 v[216:219], v253 offset:55296
	global_load_lds_dwordx4 v[220:221], off
	s_add_i32 m0, s48, 0x2000
	s_add_u32 s48, s52, 0xb0080
	v_lshl_add_u64 v[220:221], v[222:223], 0, s[22:23]
	s_addc_u32 s49, s53, 0
	s_add_i32 s52, s76, s58
	global_load_lds_dwordx4 v[220:221], off
	v_lshl_add_u64 v[220:221], s[48:49], 0, v[154:155]
	s_mov_b32 m0, s52
	s_nop 0
	global_load_lds_dwordx4 v[220:221], off
	v_lshl_add_u64 v[220:221], s[48:49], 0, v[162:163]
	s_add_i32 m0, s52, 0x2000
	s_nop 0
	global_load_lds_dwordx4 v[220:221], off
	v_lshl_add_u64 v[220:221], v[224:225], 0, s[22:23]
	s_mov_b32 m0, s3
	s_nop 0
	global_load_lds_dwordx4 v[220:221], off
	v_lshl_add_u64 v[220:221], v[226:227], 0, s[22:23]
	s_mov_b32 m0, s64
	s_nop 0
	global_load_lds_dwordx4 v[220:221], off
	s_waitcnt vmcnt(8)
	s_waitcnt lgkmcnt(0)
	s_setprio 1
	s_barrier
	v_mfma_f32_16x16x32_bf16 v[60:63], v[128:131], v[180:183], v[60:63]
	v_mfma_f32_16x16x32_bf16 v[60:63], v[132:135], v[192:195], v[60:63]
	v_mfma_f32_16x16x32_bf16 v[56:59], v[140:143], v[192:195], v[56:59]
	v_mfma_f32_16x16x32_bf16 v[56:59], v[136:139], v[180:183], v[56:59]
	v_mfma_f32_16x16x32_bf16 v[40:43], v[136:139], v[196:199], v[40:43]
	v_mfma_f32_16x16x32_bf16 v[40:43], v[140:143], v[200:203], v[40:43]
	v_mfma_f32_16x16x32_bf16 v[44:47], v[132:135], v[200:203], v[44:47]
	v_mfma_f32_16x16x32_bf16 v[44:47], v[128:131], v[196:199], v[44:47]
	v_mfma_f32_16x16x32_bf16 v[28:31], v[128:131], v[204:207], v[28:31]
	v_mfma_f32_16x16x32_bf16 v[28:31], v[132:135], v[208:211], v[28:31]
	v_mfma_f32_16x16x32_bf16 v[24:27], v[140:143], v[208:211], v[24:27]
	v_mfma_f32_16x16x32_bf16 v[24:27], v[136:139], v[204:207], v[24:27]
	v_mfma_f32_16x16x32_bf16 v[8:11], v[136:139], v[212:215], v[8:11]
	v_mfma_f32_16x16x32_bf16 v[8:11], v[140:143], v[216:219], v[8:11]
	v_mfma_f32_16x16x32_bf16 v[12:15], v[132:135], v[216:219], v[12:15]
	v_mfma_f32_16x16x32_bf16 v[12:15], v[128:131], v[212:215], v[12:15]
	v_mfma_f32_16x16x32_bf16 v[52:55], v[144:147], v[180:183], v[52:55]
	v_mfma_f32_16x16x32_bf16 v[52:55], v[148:151], v[192:195], v[52:55]
	v_mfma_f32_16x16x32_bf16 v[48:51], v[176:179], v[192:195], v[48:51]
	v_mfma_f32_16x16x32_bf16 v[48:51], v[172:175], v[180:183], v[48:51]
	v_mfma_f32_16x16x32_bf16 v[32:35], v[172:175], v[196:199], v[32:35]
	v_mfma_f32_16x16x32_bf16 v[32:35], v[176:179], v[200:203], v[32:35]
	v_mfma_f32_16x16x32_bf16 v[36:39], v[148:151], v[200:203], v[36:39]
	v_mfma_f32_16x16x32_bf16 v[36:39], v[144:147], v[196:199], v[36:39]
	v_mfma_f32_16x16x32_bf16 v[20:23], v[144:147], v[204:207], v[20:23]
	v_mfma_f32_16x16x32_bf16 v[20:23], v[148:151], v[208:211], v[20:23]
	v_mfma_f32_16x16x32_bf16 v[16:19], v[176:179], v[208:211], v[16:19]
	v_mfma_f32_16x16x32_bf16 v[16:19], v[172:175], v[204:207], v[16:19]
	v_mfma_f32_16x16x32_bf16 v[0:3], v[172:175], v[212:215], v[0:3]
	v_mfma_f32_16x16x32_bf16 v[0:3], v[176:179], v[216:219], v[0:3]
	v_mfma_f32_16x16x32_bf16 v[4:7], v[148:151], v[216:219], v[4:7]
	v_mfma_f32_16x16x32_bf16 v[4:7], v[144:147], v[212:215], v[4:7]
	s_barrier
	s_setprio 0
	s_add_i32 s74, s74, 2
	s_add_u32 s72, s72, 0x100
	s_addc_u32 s73, s73, 0
	s_cmp_gt_u32 s74, 41
	s_mov_b64 s[48:49], s[50:51]
.LBB0_1181:
	ds_read_b128 v[128:131], v188
	v_xor_b32_e32 v253, 64, v188
	ds_read_b128 v[132:135], v253
	ds_read_b128 v[136:139], v188 offset:2048
	ds_read_b128 v[140:143], v253 offset:2048
	ds_read_b128 v[144:147], v189
	v_xor_b32_e32 v253, 64, v189
	ds_read_b128 v[148:151], v253
	ds_read_b128 v[172:175], v189 offset:2048
	ds_read_b128 v[176:179], v253 offset:2048
	s_add_u32 s50, s48, 0x100
	s_addc_u32 s51, s49, 0
	s_cmp_eq_u32 s74, 40
	s_cselect_b32 s55, s11, s51
	s_cselect_b32 s54, s10, s50
	s_cselect_b32 s53, s47, s73
	s_cselect_b32 s52, s46, s72
	v_lshl_add_u64 v[220:221], s[48:49], 0, v[166:167]
	s_add_i32 m0, s59, 0xc000
	ds_read_b128 v[180:183], v190
	v_xor_b32_e32 v253, 64, v190
	ds_read_b128 v[192:195], v253
	ds_read_b128 v[196:199], v190 offset:2048
	ds_read_b128 v[200:203], v253 offset:2048
	ds_read_b128 v[204:207], v190 offset:4096
	ds_read_b128 v[208:211], v253 offset:4096
	ds_read_b128 v[212:215], v190 offset:6144
	ds_read_b128 v[216:219], v253 offset:6144
	global_load_lds_dwordx4 v[220:221], off
	v_lshl_add_u64 v[220:221], s[48:49], 0, v[164:165]
	s_add_i32 m0, s59, 0xe000
	s_nop 0
	global_load_lds_dwordx4 v[220:221], off
	s_waitcnt vmcnt(8)
	s_waitcnt lgkmcnt(0)
	s_setprio 1
	s_barrier
	v_mfma_f32_16x16x32_bf16 v[124:127], v[128:131], v[180:183], v[124:127]
	v_mfma_f32_16x16x32_bf16 v[124:127], v[132:135], v[192:195], v[124:127]
	v_mfma_f32_16x16x32_bf16 v[120:123], v[140:143], v[192:195], v[120:123]
	v_mfma_f32_16x16x32_bf16 v[120:123], v[136:139], v[180:183], v[120:123]
	v_mfma_f32_16x16x32_bf16 v[104:107], v[136:139], v[196:199], v[104:107]
	v_mfma_f32_16x16x32_bf16 v[104:107], v[140:143], v[200:203], v[104:107]
	v_mfma_f32_16x16x32_bf16 v[108:111], v[132:135], v[200:203], v[108:111]
	v_mfma_f32_16x16x32_bf16 v[108:111], v[128:131], v[196:199], v[108:111]
	v_mfma_f32_16x16x32_bf16 v[92:95], v[128:131], v[204:207], v[92:95]
	v_mfma_f32_16x16x32_bf16 v[92:95], v[132:135], v[208:211], v[92:95]
	v_mfma_f32_16x16x32_bf16 v[88:91], v[140:143], v[208:211], v[88:91]
	v_mfma_f32_16x16x32_bf16 v[88:91], v[136:139], v[204:207], v[88:91]
	v_mfma_f32_16x16x32_bf16 v[72:75], v[136:139], v[212:215], v[72:75]
	v_mfma_f32_16x16x32_bf16 v[72:75], v[140:143], v[216:219], v[72:75]
	v_mfma_f32_16x16x32_bf16 v[76:79], v[132:135], v[216:219], v[76:79]
	v_mfma_f32_16x16x32_bf16 v[76:79], v[128:131], v[212:215], v[76:79]
	v_mfma_f32_16x16x32_bf16 v[116:119], v[144:147], v[180:183], v[116:119]
	v_mfma_f32_16x16x32_bf16 v[116:119], v[148:151], v[192:195], v[116:119]
	v_mfma_f32_16x16x32_bf16 v[112:115], v[176:179], v[192:195], v[112:115]
	v_mfma_f32_16x16x32_bf16 v[112:115], v[172:175], v[180:183], v[112:115]
	v_mfma_f32_16x16x32_bf16 v[96:99], v[172:175], v[196:199], v[96:99]
	v_mfma_f32_16x16x32_bf16 v[96:99], v[176:179], v[200:203], v[96:99]
	v_mfma_f32_16x16x32_bf16 v[100:103], v[148:151], v[200:203], v[100:103]
	v_mfma_f32_16x16x32_bf16 v[100:103], v[144:147], v[196:199], v[100:103]
	v_mfma_f32_16x16x32_bf16 v[84:87], v[144:147], v[204:207], v[84:87]
	v_mfma_f32_16x16x32_bf16 v[84:87], v[148:151], v[208:211], v[84:87]
	v_mfma_f32_16x16x32_bf16 v[80:83], v[176:179], v[208:211], v[80:83]
	v_mfma_f32_16x16x32_bf16 v[80:83], v[172:175], v[204:207], v[80:83]
	v_mfma_f32_16x16x32_bf16 v[64:67], v[172:175], v[212:215], v[64:67]
	v_mfma_f32_16x16x32_bf16 v[64:67], v[176:179], v[216:219], v[64:67]
	v_mfma_f32_16x16x32_bf16 v[68:71], v[148:151], v[216:219], v[68:71]
	v_mfma_f32_16x16x32_bf16 v[68:71], v[144:147], v[212:215], v[68:71]
	s_barrier
	s_setprio 0
	s_add_i32 s48, s68, s58
	v_lshl_add_u64 v[220:221], s[52:53], 0, v[154:155]
	s_mov_b32 m0, s48
	ds_read_b128 v[180:183], v190 offset:16384
	v_xor_b32_e32 v253, 64, v190
	ds_read_b128 v[192:195], v253 offset:16384
	ds_read_b128 v[196:199], v190 offset:18432
	ds_read_b128 v[200:203], v253 offset:18432
	ds_read_b128 v[204:207], v190 offset:20480
	ds_read_b128 v[208:211], v253 offset:20480
	ds_read_b128 v[212:215], v190 offset:22528
	ds_read_b128 v[216:219], v253 offset:22528
	global_load_lds_dwordx4 v[220:221], off
	s_add_i32 m0, s48, 0x2000
	s_add_u32 s48, s52, 0xb0000
	v_lshl_add_u64 v[222:223], s[52:53], 0, v[162:163]
	s_addc_u32 s49, s53, 0
	s_add_i32 s75, s69, s58
	global_load_lds_dwordx4 v[222:223], off
	v_lshl_add_u64 v[224:225], s[48:49], 0, v[154:155]
	s_mov_b32 m0, s75
	v_lshl_add_u64 v[226:227], s[54:55], 0, v[160:161]
	global_load_lds_dwordx4 v[224:225], off
	v_lshl_add_u64 v[224:225], s[48:49], 0, v[162:163]
	s_add_i32 m0, s75, 0x2000
	s_nop 0
	global_load_lds_dwordx4 v[224:225], off
	v_lshl_add_u64 v[224:225], s[54:55], 0, v[152:153]
	s_mov_b32 m0, s59
	s_nop 0
	global_load_lds_dwordx4 v[224:225], off
	s_mov_b32 m0, s60
	s_nop 0
	global_load_lds_dwordx4 v[226:227], off
	s_waitcnt vmcnt(8)
	s_waitcnt lgkmcnt(0)
	s_setprio 1
	s_barrier
	v_mfma_f32_16x16x32_bf16 v[60:63], v[128:131], v[180:183], v[60:63]
	v_mfma_f32_16x16x32_bf16 v[60:63], v[132:135], v[192:195], v[60:63]
	v_mfma_f32_16x16x32_bf16 v[56:59], v[140:143], v[192:195], v[56:59]
	v_mfma_f32_16x16x32_bf16 v[56:59], v[136:139], v[180:183], v[56:59]
	v_mfma_f32_16x16x32_bf16 v[40:43], v[136:139], v[196:199], v[40:43]
	v_mfma_f32_16x16x32_bf16 v[40:43], v[140:143], v[200:203], v[40:43]
	v_mfma_f32_16x16x32_bf16 v[44:47], v[132:135], v[200:203], v[44:47]
	v_mfma_f32_16x16x32_bf16 v[44:47], v[128:131], v[196:199], v[44:47]
	v_mfma_f32_16x16x32_bf16 v[28:31], v[128:131], v[204:207], v[28:31]
	v_mfma_f32_16x16x32_bf16 v[28:31], v[132:135], v[208:211], v[28:31]
	v_mfma_f32_16x16x32_bf16 v[24:27], v[140:143], v[208:211], v[24:27]
	v_mfma_f32_16x16x32_bf16 v[24:27], v[136:139], v[204:207], v[24:27]
	v_mfma_f32_16x16x32_bf16 v[8:11], v[136:139], v[212:215], v[8:11]
	v_mfma_f32_16x16x32_bf16 v[8:11], v[140:143], v[216:219], v[8:11]
	v_mfma_f32_16x16x32_bf16 v[12:15], v[132:135], v[216:219], v[12:15]
	v_mfma_f32_16x16x32_bf16 v[12:15], v[128:131], v[212:215], v[12:15]
	v_mfma_f32_16x16x32_bf16 v[52:55], v[144:147], v[180:183], v[52:55]
	v_mfma_f32_16x16x32_bf16 v[52:55], v[148:151], v[192:195], v[52:55]
	v_mfma_f32_16x16x32_bf16 v[48:51], v[176:179], v[192:195], v[48:51]
	v_mfma_f32_16x16x32_bf16 v[48:51], v[172:175], v[180:183], v[48:51]
	v_mfma_f32_16x16x32_bf16 v[32:35], v[172:175], v[196:199], v[32:35]
	v_mfma_f32_16x16x32_bf16 v[32:35], v[176:179], v[200:203], v[32:35]
	v_mfma_f32_16x16x32_bf16 v[36:39], v[148:151], v[200:203], v[36:39]
	v_mfma_f32_16x16x32_bf16 v[36:39], v[144:147], v[196:199], v[36:39]
	v_mfma_f32_16x16x32_bf16 v[20:23], v[144:147], v[204:207], v[20:23]
	v_mfma_f32_16x16x32_bf16 v[20:23], v[148:151], v[208:211], v[20:23]
	v_mfma_f32_16x16x32_bf16 v[16:19], v[176:179], v[208:211], v[16:19]
	v_mfma_f32_16x16x32_bf16 v[16:19], v[172:175], v[204:207], v[16:19]
	v_mfma_f32_16x16x32_bf16 v[0:3], v[172:175], v[212:215], v[0:3]
	v_mfma_f32_16x16x32_bf16 v[0:3], v[176:179], v[216:219], v[0:3]
	v_mfma_f32_16x16x32_bf16 v[4:7], v[148:151], v[216:219], v[4:7]
	v_mfma_f32_16x16x32_bf16 v[4:7], v[144:147], v[212:215], v[4:7]
	s_barrier
	s_setprio 0
	s_add_i32 s75, 0, 0x18000
	s_add_i32 s76, 0, 0x1c000
	v_add_u32_e32 v140, s75, v185
	v_add_u32_e32 v176, s76, v185
	ds_read_b128 v[128:131], v140
	v_xor_b32_e32 v253, 64, v140
	ds_read_b128 v[132:135], v253
	ds_read_b128 v[136:139], v140 offset:2048
	ds_read_b128 v[140:143], v253 offset:2048
	ds_read_b128 v[144:147], v176
	v_xor_b32_e32 v253, 64, v176
	ds_read_b128 v[148:151], v253
	ds_read_b128 v[172:175], v176 offset:2048
	ds_read_b128 v[176:179], v253 offset:2048
	s_add_u32 s48, s54, 0xb0000
	s_addc_u32 s49, s55, 0
	s_mov_b32 m0, s61
	v_lshl_add_u64 v[228:229], s[48:49], 0, v[152:153]
	ds_read_b128 v[180:183], v190 offset:32768
	v_xor_b32_e32 v253, 64, v190
	ds_read_b128 v[192:195], v253 offset:32768
	ds_read_b128 v[196:199], v190 offset:34816
	ds_read_b128 v[200:203], v253 offset:34816
	ds_read_b128 v[204:207], v190 offset:36864
	ds_read_b128 v[208:211], v253 offset:36864
	ds_read_b128 v[212:215], v190 offset:38912
	ds_read_b128 v[216:219], v253 offset:38912
	global_load_lds_dwordx4 v[228:229], off
	v_lshl_add_u64 v[228:229], s[48:49], 0, v[160:161]
	s_mov_b32 m0, s62
	s_nop 0
	global_load_lds_dwordx4 v[228:229], off
	s_waitcnt vmcnt(8)
	s_waitcnt lgkmcnt(0)
	s_setprio 1
	s_barrier
	v_mfma_f32_16x16x32_bf16 v[124:127], v[128:131], v[180:183], v[124:127]
	v_mfma_f32_16x16x32_bf16 v[124:127], v[132:135], v[192:195], v[124:127]
	v_mfma_f32_16x16x32_bf16 v[120:123], v[140:143], v[192:195], v[120:123]
	v_mfma_f32_16x16x32_bf16 v[120:123], v[136:139], v[180:183], v[120:123]
	v_mfma_f32_16x16x32_bf16 v[104:107], v[136:139], v[196:199], v[104:107]
	v_mfma_f32_16x16x32_bf16 v[104:107], v[140:143], v[200:203], v[104:107]
	v_mfma_f32_16x16x32_bf16 v[108:111], v[132:135], v[200:203], v[108:111]
	v_mfma_f32_16x16x32_bf16 v[108:111], v[128:131], v[196:199], v[108:111]
	v_mfma_f32_16x16x32_bf16 v[92:95], v[128:131], v[204:207], v[92:95]
	v_mfma_f32_16x16x32_bf16 v[92:95], v[132:135], v[208:211], v[92:95]
	v_mfma_f32_16x16x32_bf16 v[88:91], v[140:143], v[208:211], v[88:91]
	v_mfma_f32_16x16x32_bf16 v[88:91], v[136:139], v[204:207], v[88:91]
	v_mfma_f32_16x16x32_bf16 v[72:75], v[136:139], v[212:215], v[72:75]
	v_mfma_f32_16x16x32_bf16 v[72:75], v[140:143], v[216:219], v[72:75]
	v_mfma_f32_16x16x32_bf16 v[76:79], v[132:135], v[216:219], v[76:79]
	v_mfma_f32_16x16x32_bf16 v[76:79], v[128:131], v[212:215], v[76:79]
	v_mfma_f32_16x16x32_bf16 v[116:119], v[144:147], v[180:183], v[116:119]
	v_mfma_f32_16x16x32_bf16 v[116:119], v[148:151], v[192:195], v[116:119]
	v_mfma_f32_16x16x32_bf16 v[112:115], v[176:179], v[192:195], v[112:115]
	v_mfma_f32_16x16x32_bf16 v[112:115], v[172:175], v[180:183], v[112:115]
	v_mfma_f32_16x16x32_bf16 v[96:99], v[172:175], v[196:199], v[96:99]
	v_mfma_f32_16x16x32_bf16 v[96:99], v[176:179], v[200:203], v[96:99]
	v_mfma_f32_16x16x32_bf16 v[100:103], v[148:151], v[200:203], v[100:103]
	v_mfma_f32_16x16x32_bf16 v[100:103], v[144:147], v[196:199], v[100:103]
	v_mfma_f32_16x16x32_bf16 v[84:87], v[144:147], v[204:207], v[84:87]
	v_mfma_f32_16x16x32_bf16 v[84:87], v[148:151], v[208:211], v[84:87]
	v_mfma_f32_16x16x32_bf16 v[80:83], v[176:179], v[208:211], v[80:83]
	v_mfma_f32_16x16x32_bf16 v[80:83], v[172:175], v[204:207], v[80:83]
	v_mfma_f32_16x16x32_bf16 v[64:67], v[172:175], v[212:215], v[64:67]
	v_mfma_f32_16x16x32_bf16 v[64:67], v[176:179], v[216:219], v[64:67]
	v_mfma_f32_16x16x32_bf16 v[68:71], v[148:151], v[216:219], v[68:71]
	v_mfma_f32_16x16x32_bf16 v[68:71], v[144:147], v[212:215], v[68:71]
	s_barrier
	s_setprio 0
	s_add_i32 s48, s75, s58
	v_lshl_add_u64 v[220:221], v[220:221], 0, s[22:23]
	s_mov_b32 m0, s48
	ds_read_b128 v[180:183], v190 offset:49152
	v_xor_b32_e32 v253, 64, v190
	ds_read_b128 v[192:195], v253 offset:49152
	ds_read_b128 v[196:199], v190 offset:51200
	ds_read_b128 v[200:203], v253 offset:51200
	ds_read_b128 v[204:207], v190 offset:53248
	ds_read_b128 v[208:211], v253 offset:53248
	ds_read_b128 v[212:215], v190 offset:55296
	ds_read_b128 v[216:219], v253 offset:55296
	global_load_lds_dwordx4 v[220:221], off
	s_add_i32 m0, s48, 0x2000
	s_add_u32 s48, s52, 0xb0080
	v_lshl_add_u64 v[220:221], v[222:223], 0, s[22:23]
	s_addc_u32 s49, s53, 0
	s_add_i32 s52, s76, s58
	global_load_lds_dwordx4 v[220:221], off
	v_lshl_add_u64 v[220:221], s[48:49], 0, v[154:155]
	s_mov_b32 m0, s52
	s_nop 0
	global_load_lds_dwordx4 v[220:221], off
	v_lshl_add_u64 v[220:221], s[48:49], 0, v[162:163]
	s_add_i32 m0, s52, 0x2000
	s_nop 0
	global_load_lds_dwordx4 v[220:221], off
	v_lshl_add_u64 v[220:221], v[224:225], 0, s[22:23]
	s_mov_b32 m0, s3
	s_nop 0
	global_load_lds_dwordx4 v[220:221], off
	v_lshl_add_u64 v[220:221], v[226:227], 0, s[22:23]
	s_mov_b32 m0, s64
	s_nop 0
	global_load_lds_dwordx4 v[220:221], off
	s_waitcnt vmcnt(8)
	s_waitcnt lgkmcnt(0)
	s_setprio 1
	s_barrier
	v_mfma_f32_16x16x32_bf16 v[60:63], v[128:131], v[180:183], v[60:63]
	v_mfma_f32_16x16x32_bf16 v[60:63], v[132:135], v[192:195], v[60:63]
	v_mfma_f32_16x16x32_bf16 v[56:59], v[140:143], v[192:195], v[56:59]
	v_mfma_f32_16x16x32_bf16 v[56:59], v[136:139], v[180:183], v[56:59]
	v_mfma_f32_16x16x32_bf16 v[40:43], v[136:139], v[196:199], v[40:43]
	v_mfma_f32_16x16x32_bf16 v[40:43], v[140:143], v[200:203], v[40:43]
	v_mfma_f32_16x16x32_bf16 v[44:47], v[132:135], v[200:203], v[44:47]
	v_mfma_f32_16x16x32_bf16 v[44:47], v[128:131], v[196:199], v[44:47]
	v_mfma_f32_16x16x32_bf16 v[28:31], v[128:131], v[204:207], v[28:31]
	v_mfma_f32_16x16x32_bf16 v[28:31], v[132:135], v[208:211], v[28:31]
	v_mfma_f32_16x16x32_bf16 v[24:27], v[140:143], v[208:211], v[24:27]
	v_mfma_f32_16x16x32_bf16 v[24:27], v[136:139], v[204:207], v[24:27]
	v_mfma_f32_16x16x32_bf16 v[8:11], v[136:139], v[212:215], v[8:11]
	v_mfma_f32_16x16x32_bf16 v[8:11], v[140:143], v[216:219], v[8:11]
	v_mfma_f32_16x16x32_bf16 v[12:15], v[132:135], v[216:219], v[12:15]
	v_mfma_f32_16x16x32_bf16 v[12:15], v[128:131], v[212:215], v[12:15]
	v_mfma_f32_16x16x32_bf16 v[52:55], v[144:147], v[180:183], v[52:55]
	v_mfma_f32_16x16x32_bf16 v[52:55], v[148:151], v[192:195], v[52:55]
	v_mfma_f32_16x16x32_bf16 v[48:51], v[176:179], v[192:195], v[48:51]
	v_mfma_f32_16x16x32_bf16 v[48:51], v[172:175], v[180:183], v[48:51]
	v_mfma_f32_16x16x32_bf16 v[32:35], v[172:175], v[196:199], v[32:35]
	v_mfma_f32_16x16x32_bf16 v[32:35], v[176:179], v[200:203], v[32:35]
	v_mfma_f32_16x16x32_bf16 v[36:39], v[148:151], v[200:203], v[36:39]
	v_mfma_f32_16x16x32_bf16 v[36:39], v[144:147], v[196:199], v[36:39]
	v_mfma_f32_16x16x32_bf16 v[20:23], v[144:147], v[204:207], v[20:23]
	v_mfma_f32_16x16x32_bf16 v[20:23], v[148:151], v[208:211], v[20:23]
	v_mfma_f32_16x16x32_bf16 v[16:19], v[176:179], v[208:211], v[16:19]
	v_mfma_f32_16x16x32_bf16 v[16:19], v[172:175], v[204:207], v[16:19]
	v_mfma_f32_16x16x32_bf16 v[0:3], v[172:175], v[212:215], v[0:3]
	v_mfma_f32_16x16x32_bf16 v[0:3], v[176:179], v[216:219], v[0:3]
	v_mfma_f32_16x16x32_bf16 v[4:7], v[148:151], v[216:219], v[4:7]
	v_mfma_f32_16x16x32_bf16 v[4:7], v[144:147], v[212:215], v[4:7]
	s_barrier
	s_setprio 0
	s_add_i32 s74, s74, 2
	s_add_u32 s72, s72, 0x100
	s_addc_u32 s73, s73, 0
	s_cmp_gt_u32 s74, 41
	s_mov_b64 s[48:49], s[50:51]
	s_cbranch_scc0 .LBB0_1181
	s_and_b64 vcc, exec, s[24:25]
	s_cbranch_vccz .LBB0_1184
	s_barrier
